# v28_dupwait
# baseline (speedup 1.0000x reference)
; #define LDA(dst, b, h)                                                                                    \
;   _Pragma("unroll") for (int m = 0; m < 4; ++m) _Pragma("unroll") for (int k = 0; k < 2; ++k)             \
;       dst[m][k] = *reinterpret_cast<const bf16x8*>((char*)SA(b, h) + lds_byte(wr * 64 + m * 16 + fr, k * 32 + fq * 8))
; #define LDB(dst, b, h)                                                                                    \
;   _Pragma("unroll") for (int n = 0; n < 2; ++n) _Pragma("unroll") for (int k = 0; k < 2; ++k)             \
;       dst[n][k] = *reinterpret_cast<const bf16x8*>((char*)SB(b, h) + lds_byte(wc * 32 + n * 16 + fr, k * 32 + fq * 8))
; #define WAIT_V(n) asm volatile("s_waitcnt vmcnt(" #n ")" ::: "memory")
; #define WAIT_L(n) asm volatile("s_waitcnt lgkmcnt(" #n ")" ::: "memory")
; #define BAR __builtin_amdgcn_s_barrier()
; #define SCHED __builtin_amdgcn_sched_barrier(0)
; template <int EPI> ...
;     ...
;     LDB(B0, 0, 0); SCHED; LDA(At, 0, 0); STAGE(SA(1, 1), A, brow + HALF, t + 1);
;     WAIT_L(8); BAR; WAIT_L(0); MMA(0, 0, At, B0); BAR; SCHED;
;     LDB(B1, 0, 1); STAGE(SB(0, 0), Bt, bcol, t + 2);
;     BAR; WAIT_L(0); MMA(0, 1, At, B1); BAR;
;     LDA(At, 0, 1); STAGE(SA(0, 0), A, brow, t + 2);
;     BAR; WAIT_L(0); MMA(1, 0, At, B0); BAR; SCHED;
;     STAGE(SB(0, 1), Bt, bcol + HALF, t + 2);
;     WAIT_V(6); BAR; MMA(1, 1, At, B1); BAR;
.LBB0_141:
	ds_read_b128 v[160:163], v159
	ds_read_b128 v[164:167], v159 offset:1024
	ds_read_b128 v[178:181], v159 offset:2048
	ds_read_b128 v[182:185], v159 offset:3072
	s_add_u32 s16, s10, s14
	s_addc_u32 s17, s11, s15
	ds_read_b128 v[186:189], v138
	ds_read_b128 v[190:193], v138 offset:1024
	ds_read_b128 v[194:197], v137
	ds_read_b128 v[198:201], v137 offset:1024
	ds_read_b128 v[202:205], v136
	ds_read_b128 v[206:209], v136 offset:1024
	ds_read_b128 v[210:213], v135
	ds_read_b128 v[214:217], v135 offset:1024
	s_add_u32 m0, s32, 0xc000
	s_add_u32 s98, s16, 0x40080
	s_addc_u32 s99, s17, 0
	global_load_lds_dwordx4 v253, s[98:99]
	s_add_u32 m0, s32, 0xe000
	s_nop 0
	global_load_lds_dwordx4 v252, s[98:99]
	s_waitcnt lgkmcnt(8)
	s_barrier
	s_waitcnt lgkmcnt(0)
	s_setprio 1
	v_mfma_f32_16x16x32_bf16 v[124:127], v[186:189], v[160:163], v[124:127]
	v_mfma_f32_16x16x32_bf16 v[120:123], v[186:189], v[178:181], v[120:123]
	v_mfma_f32_16x16x32_bf16 v[116:119], v[194:197], v[160:163], v[116:119]
	v_mfma_f32_16x16x32_bf16 v[112:115], v[194:197], v[178:181], v[112:115]
	v_mfma_f32_16x16x32_bf16 v[108:111], v[202:205], v[160:163], v[108:111]
	v_mfma_f32_16x16x32_bf16 v[104:107], v[202:205], v[178:181], v[104:107]
	v_mfma_f32_16x16x32_bf16 v[100:103], v[210:213], v[160:163], v[100:103]
	v_mfma_f32_16x16x32_bf16 v[96:99], v[210:213], v[178:181], v[96:99]
	v_mfma_f32_16x16x32_bf16 v[124:127], v[190:193], v[164:167], v[124:127]
	v_mfma_f32_16x16x32_bf16 v[120:123], v[190:193], v[182:185], v[120:123]
	v_mfma_f32_16x16x32_bf16 v[116:119], v[198:201], v[164:167], v[116:119]
	v_mfma_f32_16x16x32_bf16 v[112:115], v[198:201], v[182:185], v[112:115]
	v_mfma_f32_16x16x32_bf16 v[108:111], v[206:209], v[164:167], v[108:111]
	v_mfma_f32_16x16x32_bf16 v[104:107], v[206:209], v[182:185], v[104:107]
	v_mfma_f32_16x16x32_bf16 v[100:103], v[214:217], v[164:167], v[100:103]
	v_mfma_f32_16x16x32_bf16 v[96:99], v[214:217], v[182:185], v[96:99]
	s_setprio 0
	s_barrier
	s_add_u32 s18, s8, s14
	s_addc_u32 s19, s9, s15
	ds_read_b128 v[218:221], v155
	ds_read_b128 v[222:225], v155 offset:1024
	ds_read_b128 v[226:229], v155 offset:2048
	ds_read_b128 v[230:233], v155 offset:3072
	s_add_u32 m0, s32, 0x10000
	s_add_u32 s98, s18, 0x100
	s_addc_u32 s99, s19, 0
	global_load_lds_dwordx4 v253, s[98:99]
	s_add_u32 m0, s32, 0x12000
	s_nop 0
	global_load_lds_dwordx4 v252, s[98:99]
	s_barrier
	s_waitcnt lgkmcnt(0)
	s_setprio 1
	v_mfma_f32_16x16x32_bf16 v[92:95], v[186:189], v[218:221], v[92:95]
	v_mfma_f32_16x16x32_bf16 v[88:91], v[186:189], v[226:229], v[88:91]
	v_mfma_f32_16x16x32_bf16 v[84:87], v[194:197], v[218:221], v[84:87]
	v_mfma_f32_16x16x32_bf16 v[80:83], v[194:197], v[226:229], v[80:83]
	v_mfma_f32_16x16x32_bf16 v[76:79], v[202:205], v[218:221], v[76:79]
	v_mfma_f32_16x16x32_bf16 v[72:75], v[202:205], v[226:229], v[72:75]
	v_mfma_f32_16x16x32_bf16 v[68:71], v[210:213], v[218:221], v[68:71]
	v_mfma_f32_16x16x32_bf16 v[64:67], v[210:213], v[226:229], v[64:67]
	v_mfma_f32_16x16x32_bf16 v[92:95], v[190:193], v[222:225], v[92:95]
	v_mfma_f32_16x16x32_bf16 v[88:91], v[190:193], v[230:233], v[88:91]
	v_mfma_f32_16x16x32_bf16 v[84:87], v[198:201], v[222:225], v[84:87]
	v_mfma_f32_16x16x32_bf16 v[80:83], v[198:201], v[230:233], v[80:83]
	v_mfma_f32_16x16x32_bf16 v[76:79], v[206:209], v[222:225], v[76:79]
	v_mfma_f32_16x16x32_bf16 v[72:75], v[206:209], v[230:233], v[72:75]
	v_mfma_f32_16x16x32_bf16 v[68:71], v[214:217], v[222:225], v[68:71]
	v_mfma_f32_16x16x32_bf16 v[64:67], v[214:217], v[230:233], v[64:67]
	s_setprio 0
	s_barrier
	ds_read_b128 v[186:189], v138 offset:16384
	ds_read_b128 v[190:193], v138 offset:17408
	ds_read_b128 v[194:197], v137 offset:16384
	ds_read_b128 v[198:201], v137 offset:17408
	ds_read_b128 v[202:205], v136 offset:16384
	ds_read_b128 v[206:209], v136 offset:17408
	ds_read_b128 v[210:213], v135 offset:16384
	ds_read_b128 v[214:217], v135 offset:17408
	s_mov_b32 m0, s32
	s_add_u32 s98, s16, 0x100
	s_addc_u32 s99, s17, 0
	global_load_lds_dwordx4 v253, s[98:99]
	s_add_u32 m0, s32, 0x2000
	s_nop 0
	global_load_lds_dwordx4 v252, s[98:99]
	s_barrier
	s_waitcnt lgkmcnt(0)
	s_setprio 1
	v_mfma_f32_16x16x32_bf16 v[60:63], v[186:189], v[160:163], v[60:63]
	v_mfma_f32_16x16x32_bf16 v[56:59], v[186:189], v[178:181], v[56:59]
	v_mfma_f32_16x16x32_bf16 v[52:55], v[194:197], v[160:163], v[52:55]
	v_mfma_f32_16x16x32_bf16 v[48:51], v[194:197], v[178:181], v[48:51]
	v_mfma_f32_16x16x32_bf16 v[44:47], v[202:205], v[160:163], v[44:47]
	v_mfma_f32_16x16x32_bf16 v[40:43], v[202:205], v[178:181], v[40:43]
	v_mfma_f32_16x16x32_bf16 v[36:39], v[210:213], v[160:163], v[36:39]
	v_mfma_f32_16x16x32_bf16 v[32:35], v[210:213], v[178:181], v[32:35]
	v_mfma_f32_16x16x32_bf16 v[60:63], v[190:193], v[164:167], v[60:63]
	v_mfma_f32_16x16x32_bf16 v[56:59], v[190:193], v[182:185], v[56:59]
	v_mfma_f32_16x16x32_bf16 v[52:55], v[198:201], v[164:167], v[52:55]
	v_mfma_f32_16x16x32_bf16 v[48:51], v[198:201], v[182:185], v[48:51]
	v_mfma_f32_16x16x32_bf16 v[44:47], v[206:209], v[164:167], v[44:47]
	v_mfma_f32_16x16x32_bf16 v[40:43], v[206:209], v[182:185], v[40:43]
	v_mfma_f32_16x16x32_bf16 v[36:39], v[214:217], v[164:167], v[36:39]
	v_mfma_f32_16x16x32_bf16 v[32:35], v[214:217], v[182:185], v[32:35]
	s_setprio 0
	s_barrier
	s_add_u32 m0, s32, 0x14000
	s_add_u32 s98, s18, 0x40100
	s_addc_u32 s99, s19, 0
	global_load_lds_dwordx4 v253, s[98:99]
	s_add_u32 m0, s32, 0x16000
	s_nop 0
	global_load_lds_dwordx4 v252, s[98:99]
	s_waitcnt vmcnt(6)
	s_barrier
; #define LDA(dst, b, h)                                                                                    \
;   _Pragma("unroll") for (int m = 0; m < 4; ++m) _Pragma("unroll") for (int k = 0; k < 2; ++k)             \
;       dst[m][k] = *reinterpret_cast<const bf16x8*>((char*)SA(b, h) + lds_byte(wr * 64 + m * 16 + fr, k * 32 + fq * 8))
; #define LDB(dst, b, h)                                                                                    \
;   _Pragma("unroll") for (int n = 0; n < 2; ++n) _Pragma("unroll") for (int k = 0; k < 2; ++k)             \
;       dst[n][k] = *reinterpret_cast<const bf16x8*>((char*)SB(b, h) + lds_byte(wc * 32 + n * 16 + fr, k * 32 + fq * 8))
; #define WAIT_V(n) asm volatile("s_waitcnt vmcnt(" #n ")" ::: "memory")
; #define WAIT_L(n) asm volatile("s_waitcnt lgkmcnt(" #n ")" ::: "memory")
; #define BAR __builtin_amdgcn_s_barrier()
; #define SCHED __builtin_amdgcn_sched_barrier(0)
; template <int EPI> ...
;     ...
;     WAIT_V(6); BAR; MMA(1, 1, At, B1); BAR;
;     LDB(B0, 1, 0); SCHED; LDA(At, 1, 0); STAGE(SA(0, 1), A, brow + HALF, t + 2);
;     WAIT_L(8); BAR; WAIT_L(0); MMA(0, 0, At, B0); BAR; SCHED;
;     LDB(B1, 1, 1); STAGE(SB(1, 0), Bt, bcol, t + 3);
;     BAR; WAIT_L(0); MMA(0, 1, At, B1); BAR;
;     LDA(At, 1, 1); STAGE(SA(1, 0), A, brow, t + 3);
	s_setprio 1
	v_mfma_f32_16x16x32_bf16 v[28:31], v[186:189], v[218:221], v[28:31]
	v_mfma_f32_16x16x32_bf16 v[24:27], v[186:189], v[226:229], v[24:27]
	v_mfma_f32_16x16x32_bf16 v[20:23], v[194:197], v[218:221], v[20:23]
	v_mfma_f32_16x16x32_bf16 v[16:19], v[194:197], v[226:229], v[16:19]
	v_mfma_f32_16x16x32_bf16 v[12:15], v[202:205], v[218:221], v[12:15]
	v_mfma_f32_16x16x32_bf16 v[8:11], v[202:205], v[226:229], v[8:11]
	v_mfma_f32_16x16x32_bf16 v[4:7], v[210:213], v[218:221], v[4:7]
	v_mfma_f32_16x16x32_bf16 v[0:3], v[210:213], v[226:229], v[0:3]
	v_mfma_f32_16x16x32_bf16 v[28:31], v[190:193], v[222:225], v[28:31]
	v_mfma_f32_16x16x32_bf16 v[24:27], v[190:193], v[230:233], v[24:27]
	v_mfma_f32_16x16x32_bf16 v[20:23], v[198:201], v[222:225], v[20:23]
	v_mfma_f32_16x16x32_bf16 v[16:19], v[198:201], v[230:233], v[16:19]
	v_mfma_f32_16x16x32_bf16 v[12:15], v[206:209], v[222:225], v[12:15]
	v_mfma_f32_16x16x32_bf16 v[8:11], v[206:209], v[230:233], v[8:11]
	v_mfma_f32_16x16x32_bf16 v[4:7], v[214:217], v[222:225], v[4:7]
	v_mfma_f32_16x16x32_bf16 v[0:3], v[214:217], v[230:233], v[0:3]
	s_setprio 0
	s_barrier
	ds_read_b128 v[160:163], v143
	ds_read_b128 v[164:167], v143 offset:1024
	ds_read_b128 v[178:181], v143 offset:2048
	ds_read_b128 v[182:185], v143 offset:3072
	ds_read_b128 v[186:189], v138 offset:32768
	ds_read_b128 v[190:193], v138 offset:33792
	ds_read_b128 v[194:197], v137 offset:32768
	ds_read_b128 v[198:201], v137 offset:33792
	ds_read_b128 v[202:205], v136 offset:32768
	ds_read_b128 v[206:209], v136 offset:33792
	ds_read_b128 v[210:213], v135 offset:32768
	ds_read_b128 v[214:217], v135 offset:33792
	s_add_u32 m0, s32, 0x4000
	s_add_u32 s98, s16, 0x40100
	s_addc_u32 s99, s17, 0
	global_load_lds_dwordx4 v253, s[98:99]
	s_add_u32 m0, s32, 0x6000
	s_nop 0
	global_load_lds_dwordx4 v252, s[98:99]
	s_waitcnt lgkmcnt(8)
	s_barrier
	s_waitcnt lgkmcnt(0)
	s_setprio 1
	v_mfma_f32_16x16x32_bf16 v[124:127], v[186:189], v[160:163], v[124:127]
	v_mfma_f32_16x16x32_bf16 v[120:123], v[186:189], v[178:181], v[120:123]
	v_mfma_f32_16x16x32_bf16 v[116:119], v[194:197], v[160:163], v[116:119]
	v_mfma_f32_16x16x32_bf16 v[112:115], v[194:197], v[178:181], v[112:115]
	v_mfma_f32_16x16x32_bf16 v[108:111], v[202:205], v[160:163], v[108:111]
	v_mfma_f32_16x16x32_bf16 v[104:107], v[202:205], v[178:181], v[104:107]
	v_mfma_f32_16x16x32_bf16 v[100:103], v[210:213], v[160:163], v[100:103]
	v_mfma_f32_16x16x32_bf16 v[96:99], v[210:213], v[178:181], v[96:99]
	v_mfma_f32_16x16x32_bf16 v[124:127], v[190:193], v[164:167], v[124:127]
	v_mfma_f32_16x16x32_bf16 v[120:123], v[190:193], v[182:185], v[120:123]
	v_mfma_f32_16x16x32_bf16 v[116:119], v[198:201], v[164:167], v[116:119]
	v_mfma_f32_16x16x32_bf16 v[112:115], v[198:201], v[182:185], v[112:115]
	v_mfma_f32_16x16x32_bf16 v[108:111], v[206:209], v[164:167], v[108:111]
	v_mfma_f32_16x16x32_bf16 v[104:107], v[206:209], v[182:185], v[104:107]
	v_mfma_f32_16x16x32_bf16 v[100:103], v[214:217], v[164:167], v[100:103]
	v_mfma_f32_16x16x32_bf16 v[96:99], v[214:217], v[182:185], v[96:99]
	s_setprio 0
	s_barrier
	ds_read_b128 v[218:221], v140
	ds_read_b128 v[222:225], v140 offset:1024
	ds_read_b128 v[226:229], v140 offset:2048
	ds_read_b128 v[230:233], v140 offset:3072
	s_add_u32 m0, s32, 0x18000
	s_add_u32 s98, s18, 0x180
	s_addc_u32 s99, s19, 0
	global_load_lds_dwordx4 v253, s[98:99]
	s_add_u32 m0, s32, 0x1a000
	s_nop 0
	global_load_lds_dwordx4 v252, s[98:99]
	s_barrier
	s_waitcnt lgkmcnt(0)
	s_setprio 1
	v_mfma_f32_16x16x32_bf16 v[92:95], v[186:189], v[218:221], v[92:95]
	v_mfma_f32_16x16x32_bf16 v[88:91], v[186:189], v[226:229], v[88:91]
	v_mfma_f32_16x16x32_bf16 v[84:87], v[194:197], v[218:221], v[84:87]
	v_mfma_f32_16x16x32_bf16 v[80:83], v[194:197], v[226:229], v[80:83]
	v_mfma_f32_16x16x32_bf16 v[76:79], v[202:205], v[218:221], v[76:79]
	v_mfma_f32_16x16x32_bf16 v[72:75], v[202:205], v[226:229], v[72:75]
	v_mfma_f32_16x16x32_bf16 v[68:71], v[210:213], v[218:221], v[68:71]
	v_mfma_f32_16x16x32_bf16 v[64:67], v[210:213], v[226:229], v[64:67]
	v_mfma_f32_16x16x32_bf16 v[92:95], v[190:193], v[222:225], v[92:95]
	v_mfma_f32_16x16x32_bf16 v[88:91], v[190:193], v[230:233], v[88:91]
	v_mfma_f32_16x16x32_bf16 v[84:87], v[198:201], v[222:225], v[84:87]
	v_mfma_f32_16x16x32_bf16 v[80:83], v[198:201], v[230:233], v[80:83]
	v_mfma_f32_16x16x32_bf16 v[76:79], v[206:209], v[222:225], v[76:79]
	v_mfma_f32_16x16x32_bf16 v[72:75], v[206:209], v[230:233], v[72:75]
	v_mfma_f32_16x16x32_bf16 v[68:71], v[214:217], v[222:225], v[68:71]
	v_mfma_f32_16x16x32_bf16 v[64:67], v[214:217], v[230:233], v[64:67]
	s_setprio 0
	s_barrier
	ds_read_b128 v[186:189], v138 offset:49152
	ds_read_b128 v[190:193], v138 offset:50176
	ds_read_b128 v[194:197], v137 offset:49152
	ds_read_b128 v[198:201], v137 offset:50176
	ds_read_b128 v[202:205], v136 offset:49152
	ds_read_b128 v[206:209], v136 offset:50176
	ds_read_b128 v[210:213], v135 offset:49152
	ds_read_b128 v[214:217], v135 offset:50176
	s_add_u32 m0, s32, 0x8000
	s_add_u32 s98, s16, 0x180
	s_addc_u32 s99, s17, 0
	global_load_lds_dwordx4 v253, s[98:99]
	s_nop 0
	s_add_u32 m0, s32, 0xa000
	s_nop 0
	global_load_lds_dwordx4 v252, s[98:99]
	s_barrier
; #define LDA(dst, b, h)                                                                                    \
;   _Pragma("unroll") for (int m = 0; m < 4; ++m) _Pragma("unroll") for (int k = 0; k < 2; ++k)             \
;       dst[m][k] = *reinterpret_cast<const bf16x8*>((char*)SA(b, h) + lds_byte(wr * 64 + m * 16 + fr, k * 32 + fq * 8))
; #define LDB(dst, b, h)                                                                                    \
;   _Pragma("unroll") for (int n = 0; n < 2; ++n) _Pragma("unroll") for (int k = 0; k < 2; ++k)             \
;       dst[n][k] = *reinterpret_cast<const bf16x8*>((char*)SB(b, h) + lds_byte(wc * 32 + n * 16 + fr, k * 32 + fq * 8))
; #define WAIT_V(n) asm volatile("s_waitcnt vmcnt(" #n ")" ::: "memory")
; #define WAIT_L(n) asm volatile("s_waitcnt lgkmcnt(" #n ")" ::: "memory")
; #define BAR __builtin_amdgcn_s_barrier()
; #define SCHED __builtin_amdgcn_sched_barrier(0)
; template <int EPI> ...
;     ...
;     LDA(At, 1, 1); STAGE(SA(1, 0), A, brow, t + 3);
;     BAR; WAIT_L(0); MMA(1, 0, At, B0); BAR; SCHED;
;     STAGE(SB(1, 1), Bt, bcol + HALF, t + 3);
;     WAIT_V(6); BAR; MMA(1, 1, At, B1); BAR;
;   }
;   {
;     LDB(B0, 0, 0); LDA(At, 0, 0); STAGE(SA(1, 1), A, brow + HALF, nt - 1);
;     BAR; WAIT_L(0); MMA(0, 0, At, B0); BAR;
;     LDB(B1, 0, 1); BAR; WAIT_L(0); MMA(0, 1, At, B1); BAR;
	s_waitcnt lgkmcnt(0)
	s_setprio 1
	v_mfma_f32_16x16x32_bf16 v[60:63], v[186:189], v[160:163], v[60:63]
	v_mfma_f32_16x16x32_bf16 v[56:59], v[186:189], v[178:181], v[56:59]
	v_mfma_f32_16x16x32_bf16 v[52:55], v[194:197], v[160:163], v[52:55]
	v_mfma_f32_16x16x32_bf16 v[48:51], v[194:197], v[178:181], v[48:51]
	v_mfma_f32_16x16x32_bf16 v[44:47], v[202:205], v[160:163], v[44:47]
	v_mfma_f32_16x16x32_bf16 v[40:43], v[202:205], v[178:181], v[40:43]
	v_mfma_f32_16x16x32_bf16 v[36:39], v[210:213], v[160:163], v[36:39]
	v_mfma_f32_16x16x32_bf16 v[32:35], v[210:213], v[178:181], v[32:35]
	v_mfma_f32_16x16x32_bf16 v[60:63], v[190:193], v[164:167], v[60:63]
	v_mfma_f32_16x16x32_bf16 v[56:59], v[190:193], v[182:185], v[56:59]
	v_mfma_f32_16x16x32_bf16 v[52:55], v[198:201], v[164:167], v[52:55]
	v_mfma_f32_16x16x32_bf16 v[48:51], v[198:201], v[182:185], v[48:51]
	v_mfma_f32_16x16x32_bf16 v[44:47], v[206:209], v[164:167], v[44:47]
	v_mfma_f32_16x16x32_bf16 v[40:43], v[206:209], v[182:185], v[40:43]
	v_mfma_f32_16x16x32_bf16 v[36:39], v[214:217], v[164:167], v[36:39]
	v_mfma_f32_16x16x32_bf16 v[32:35], v[214:217], v[182:185], v[32:35]
	s_setprio 0
	s_barrier
	s_add_u32 m0, s32, 0x1c000
	s_add_u32 s98, s18, 0x40180
	s_addc_u32 s99, s19, 0
	global_load_lds_dwordx4 v253, s[98:99]
	s_add_u32 m0, s32, 0x1e000
	s_nop 0
	global_load_lds_dwordx4 v252, s[98:99]
	s_waitcnt vmcnt(6)
	s_barrier
	s_setprio 1
	v_mfma_f32_16x16x32_bf16 v[28:31], v[186:189], v[218:221], v[28:31]
	v_mfma_f32_16x16x32_bf16 v[24:27], v[186:189], v[226:229], v[24:27]
	v_mfma_f32_16x16x32_bf16 v[20:23], v[194:197], v[218:221], v[20:23]
	v_mfma_f32_16x16x32_bf16 v[16:19], v[194:197], v[226:229], v[16:19]
	v_mfma_f32_16x16x32_bf16 v[12:15], v[202:205], v[218:221], v[12:15]
	v_mfma_f32_16x16x32_bf16 v[8:11], v[202:205], v[226:229], v[8:11]
	v_mfma_f32_16x16x32_bf16 v[4:7], v[210:213], v[218:221], v[4:7]
	v_mfma_f32_16x16x32_bf16 v[0:3], v[210:213], v[226:229], v[0:3]
	v_mfma_f32_16x16x32_bf16 v[28:31], v[190:193], v[222:225], v[28:31]
	v_mfma_f32_16x16x32_bf16 v[24:27], v[190:193], v[230:233], v[24:27]
	v_mfma_f32_16x16x32_bf16 v[20:23], v[198:201], v[222:225], v[20:23]
	v_mfma_f32_16x16x32_bf16 v[16:19], v[198:201], v[230:233], v[16:19]
	v_mfma_f32_16x16x32_bf16 v[12:15], v[206:209], v[222:225], v[12:15]
	v_mfma_f32_16x16x32_bf16 v[8:11], v[206:209], v[230:233], v[8:11]
	v_mfma_f32_16x16x32_bf16 v[4:7], v[214:217], v[222:225], v[4:7]
	v_mfma_f32_16x16x32_bf16 v[0:3], v[214:217], v[230:233], v[0:3]
	s_setprio 0
	s_add_i32 s62, s62, 2
	s_add_u32 s14, s14, 0x100
	s_addc_u32 s15, s15, 0
	s_cmp_lt_u32 s62, 12
	s_barrier
	s_cbranch_scc1 .LBB0_141
	ds_read_b128 v[144:147], v159
	ds_read_b128 v[160:163], v159 offset:1024
	ds_read_b128 v[164:167], v159 offset:2048
	ds_read_b128 v[178:181], v159 offset:3072
	ds_read_b128 v[182:185], v138
	ds_read_b128 v[186:189], v138 offset:1024
	ds_read_b128 v[190:193], v137
	ds_read_b128 v[194:197], v137 offset:1024
	ds_read_b128 v[198:201], v136
	ds_read_b128 v[202:205], v136 offset:1024
	ds_read_b128 v[206:209], v135
	ds_read_b128 v[210:213], v135 offset:1024
	v_mov_b32_e32 v129, v149
	v_lshl_add_u64 v[128:129], v[128:129], 1, s[12:13]
	s_mov_b64 s[10:11], 0x780
	v_readfirstlane_b32 s8, v158
	v_lshl_add_u64 v[128:129], v[128:129], 0, s[10:11]
	s_mov_b32 m0, s8
	v_mov_b32_e32 v131, v149
	global_load_lds_dwordx4 v[128:129], off
	v_readfirstlane_b32 s8, v157
	v_lshl_add_u64 v[128:129], v[130:131], 1, s[12:13]
	v_lshl_add_u64 v[128:129], v[128:129], 0, s[10:11]
	s_mov_b32 m0, s8
	s_nop 0
	global_load_lds_dwordx4 v[128:129], off
	s_barrier
	s_waitcnt lgkmcnt(0)
	s_setprio 1
	v_mfma_f32_16x16x32_bf16 v[124:127], v[182:185], v[144:147], v[124:127]
	v_mfma_f32_16x16x32_bf16 v[120:123], v[182:185], v[164:167], v[120:123]
	v_mfma_f32_16x16x32_bf16 v[116:119], v[190:193], v[144:147], v[116:119]
	v_mfma_f32_16x16x32_bf16 v[112:115], v[190:193], v[164:167], v[112:115]
	v_mfma_f32_16x16x32_bf16 v[108:111], v[198:201], v[144:147], v[108:111]
	v_mfma_f32_16x16x32_bf16 v[104:107], v[198:201], v[164:167], v[104:107]
	v_mfma_f32_16x16x32_bf16 v[96:99], v[206:209], v[164:167], v[96:99]
	v_mfma_f32_16x16x32_bf16 v[124:127], v[186:189], v[160:163], v[124:127]
	v_mfma_f32_16x16x32_bf16 v[120:123], v[186:189], v[178:181], v[120:123]
	v_mfma_f32_16x16x32_bf16 v[116:119], v[194:197], v[160:163], v[116:119]
	v_mfma_f32_16x16x32_bf16 v[112:115], v[194:197], v[178:181], v[112:115]
	v_mfma_f32_16x16x32_bf16 v[108:111], v[202:205], v[160:163], v[108:111]
	v_mfma_f32_16x16x32_bf16 v[104:107], v[202:205], v[178:181], v[104:107]
	v_mfma_f32_16x16x32_bf16 v[100:103], v[206:209], v[144:147], v[100:103]
	v_mfma_f32_16x16x32_bf16 v[96:99], v[210:213], v[178:181], v[96:99]
	v_mfma_f32_16x16x32_bf16 v[128:131], v[210:213], v[160:163], v[100:103]
	s_setprio 0
	s_barrier
	s_nop 3
	ds_read_b128 v[100:103], v155
	ds_read_b128 v[156:159], v155 offset:1024
	ds_read_b128 v[214:217], v155 offset:2048
	ds_read_b128 v[152:155], v155 offset:3072
	s_barrier
	s_waitcnt lgkmcnt(0)
	s_setprio 1
	v_mfma_f32_16x16x32_bf16 v[88:91], v[182:185], v[214:217], v[88:91]
	v_mfma_f32_16x16x32_bf16 v[92:95], v[182:185], v[100:103], v[92:95]
	v_mfma_f32_16x16x32_bf16 v[88:91], v[186:189], v[152:155], v[88:91]
	v_mfma_f32_16x16x32_bf16 v[84:87], v[190:193], v[100:103], v[84:87]
	v_mfma_f32_16x16x32_bf16 v[80:83], v[190:193], v[214:217], v[80:83]
	v_mfma_f32_16x16x32_bf16 v[76:79], v[198:201], v[100:103], v[76:79]
	v_mfma_f32_16x16x32_bf16 v[72:75], v[198:201], v[214:217], v[72:75]
	v_mfma_f32_16x16x32_bf16 v[68:71], v[206:209], v[100:103], v[68:71]
	v_mfma_f32_16x16x32_bf16 v[64:67], v[206:209], v[214:217], v[64:67]
	v_mfma_f32_16x16x32_bf16 v[218:221], v[186:189], v[156:159], v[92:95]
	v_mfma_f32_16x16x32_bf16 v[182:185], v[194:197], v[156:159], v[84:87]
	v_mfma_f32_16x16x32_bf16 v[186:189], v[194:197], v[152:155], v[80:83]
	v_mfma_f32_16x16x32_bf16 v[190:193], v[202:205], v[156:159], v[76:79]
	v_mfma_f32_16x16x32_bf16 v[194:197], v[202:205], v[152:155], v[72:75]
	v_mfma_f32_16x16x32_bf16 v[198:201], v[210:213], v[156:159], v[68:71]
	v_mfma_f32_16x16x32_bf16 v[202:205], v[210:213], v[152:155], v[64:67]
	s_setprio 0
	s_barrier
; #define LDA(dst, b, h)                                                                                    \
;   _Pragma("unroll") for (int m = 0; m < 4; ++m) _Pragma("unroll") for (int k = 0; k < 2; ++k)             \
;       dst[m][k] = *reinterpret_cast<const bf16x8*>((char*)SA(b, h) + lds_byte(wr * 64 + m * 16 + fr, k * 32 + fq * 8))
; #define LDB(dst, b, h)                                                                                    \
;   _Pragma("unroll") for (int n = 0; n < 2; ++n) _Pragma("unroll") for (int k = 0; k < 2; ++k)             \
;       dst[n][k] = *reinterpret_cast<const bf16x8*>((char*)SB(b, h) + lds_byte(wc * 32 + n * 16 + fr, k * 32 + fq * 8))
; #define WAIT_V(n) asm volatile("s_waitcnt vmcnt(" #n ")" ::: "memory")
; #define WAIT_L(n) asm volatile("s_waitcnt lgkmcnt(" #n ")" ::: "memory")
; #define BAR __builtin_amdgcn_s_barrier()
; template <int EPI> ...
;     ...
;     LDA(At, 0, 1); WAIT_V(4); BAR; WAIT_L(0); MMA(1, 0, At, B0); MMA(1, 1, At, B1); BAR;
;   }
;   {
;     LDB(B0, 1, 0); LDA(At, 1, 0); WAIT_V(2); BAR; WAIT_L(0); MMA(0, 0, At, B0); BAR;
	s_nop 0
	ds_read_b128 v[64:67], v138 offset:16384
	ds_read_b128 v[68:71], v138 offset:17408
	ds_read_b128 v[72:75], v137 offset:16384
	ds_read_b128 v[76:79], v137 offset:17408
	ds_read_b128 v[80:83], v136 offset:16384
	ds_read_b128 v[84:87], v136 offset:17408
	ds_read_b128 v[92:95], v135 offset:16384
	ds_read_b128 v[206:209], v135 offset:17408
	s_waitcnt vmcnt(4)
	s_barrier
	s_waitcnt lgkmcnt(0)
	s_setprio 1
	v_mfma_f32_16x16x32_bf16 v[60:63], v[64:67], v[144:147], v[60:63]
	v_mfma_f32_16x16x32_bf16 v[56:59], v[64:67], v[164:167], v[56:59]
	v_mfma_f32_16x16x32_bf16 v[52:55], v[72:75], v[144:147], v[52:55]
	v_mfma_f32_16x16x32_bf16 v[48:51], v[72:75], v[164:167], v[48:51]
	v_mfma_f32_16x16x32_bf16 v[44:47], v[80:83], v[144:147], v[44:47]
	v_mfma_f32_16x16x32_bf16 v[40:43], v[80:83], v[164:167], v[40:43]
	v_mfma_f32_16x16x32_bf16 v[36:39], v[92:95], v[144:147], v[36:39]
	v_mfma_f32_16x16x32_bf16 v[32:35], v[92:95], v[164:167], v[32:35]
	v_mfma_f32_16x16x32_bf16 v[60:63], v[68:71], v[160:163], v[60:63]
	v_mfma_f32_16x16x32_bf16 v[56:59], v[68:71], v[178:181], v[56:59]
	v_mfma_f32_16x16x32_bf16 v[52:55], v[76:79], v[160:163], v[52:55]
	v_mfma_f32_16x16x32_bf16 v[48:51], v[76:79], v[178:181], v[48:51]
	v_mfma_f32_16x16x32_bf16 v[44:47], v[84:87], v[160:163], v[44:47]
	v_mfma_f32_16x16x32_bf16 v[40:43], v[84:87], v[178:181], v[40:43]
	v_mfma_f32_16x16x32_bf16 v[36:39], v[206:209], v[160:163], v[36:39]
	v_mfma_f32_16x16x32_bf16 v[32:35], v[206:209], v[178:181], v[32:35]
	s_setprio 0
	s_setprio 1
	v_mfma_f32_16x16x32_bf16 v[28:31], v[64:67], v[100:103], v[28:31]
	v_mfma_f32_16x16x32_bf16 v[24:27], v[64:67], v[214:217], v[24:27]
	v_mfma_f32_16x16x32_bf16 v[20:23], v[72:75], v[100:103], v[20:23]
	v_mfma_f32_16x16x32_bf16 v[16:19], v[72:75], v[214:217], v[16:19]
	v_mfma_f32_16x16x32_bf16 v[12:15], v[80:83], v[100:103], v[12:15]
	v_mfma_f32_16x16x32_bf16 v[8:11], v[80:83], v[214:217], v[8:11]
	v_mfma_f32_16x16x32_bf16 v[4:7], v[92:95], v[100:103], v[4:7]
	v_mfma_f32_16x16x32_bf16 v[0:3], v[92:95], v[214:217], v[0:3]
	v_mfma_f32_16x16x32_bf16 v[144:147], v[68:71], v[156:159], v[28:31]
	v_mfma_f32_16x16x32_bf16 v[160:163], v[68:71], v[152:155], v[24:27]
	v_mfma_f32_16x16x32_bf16 v[164:167], v[76:79], v[156:159], v[20:23]
	v_mfma_f32_16x16x32_bf16 v[178:181], v[76:79], v[152:155], v[16:19]
	v_mfma_f32_16x16x32_bf16 v[210:213], v[84:87], v[156:159], v[12:15]
	v_mfma_f32_16x16x32_bf16 v[222:225], v[84:87], v[152:155], v[8:11]
	v_mfma_f32_16x16x32_bf16 v[156:159], v[206:209], v[156:159], v[4:7]
	v_mfma_f32_16x16x32_bf16 v[152:155], v[206:209], v[152:155], v[0:3]
	s_setprio 0
	s_barrier
	s_nop 0
	ds_read_b128 v[0:3], v143
	ds_read_b128 v[4:7], v143 offset:1024
	ds_read_b128 v[206:209], v143 offset:2048
	ds_read_b128 v[214:217], v143 offset:3072
	ds_read_b128 v[8:11], v138 offset:32768
	ds_read_b128 v[12:15], v138 offset:33792
	ds_read_b128 v[16:19], v137 offset:32768
	ds_read_b128 v[20:23], v137 offset:33792
	ds_read_b128 v[24:27], v136 offset:32768
	ds_read_b128 v[28:31], v136 offset:33792
	ds_read_b128 v[226:229], v135 offset:32768
	ds_read_b128 v[230:233], v135 offset:33792
	s_waitcnt vmcnt(2)
	s_barrier
	s_waitcnt lgkmcnt(0)
	s_setprio 1
	v_mfma_f32_16x16x32_bf16 v[64:67], v[8:11], v[0:3], v[124:127]
	v_mfma_f32_16x16x32_bf16 v[92:95], v[12:15], v[4:7], v[64:67]
	v_mfma_f32_16x16x32_bf16 v[64:67], v[8:11], v[206:209], v[120:123]
	v_mfma_f32_16x16x32_bf16 v[100:103], v[12:15], v[214:217], v[64:67]
	v_mfma_f32_16x16x32_bf16 v[64:67], v[16:19], v[0:3], v[116:119]
	v_mfma_f32_16x16x32_bf16 v[80:83], v[20:23], v[4:7], v[64:67]
	v_mfma_f32_16x16x32_bf16 v[64:67], v[16:19], v[206:209], v[112:115]
	v_mfma_f32_16x16x32_bf16 v[84:87], v[20:23], v[214:217], v[64:67]
	v_mfma_f32_16x16x32_bf16 v[64:67], v[24:27], v[0:3], v[108:111]
	v_mfma_f32_16x16x32_bf16 v[72:75], v[28:31], v[4:7], v[64:67]
	v_mfma_f32_16x16x32_bf16 v[64:67], v[24:27], v[206:209], v[104:107]
	v_mfma_f32_16x16x32_bf16 v[76:79], v[28:31], v[214:217], v[64:67]
	v_mfma_f32_16x16x32_bf16 v[64:67], v[226:229], v[0:3], v[128:131]
	v_mfma_f32_16x16x32_bf16 v[68:71], v[226:229], v[206:209], v[96:99]
	v_mfma_f32_16x16x32_bf16 v[64:67], v[230:233], v[4:7], v[64:67]
	v_mfma_f32_16x16x32_bf16 v[68:71], v[230:233], v[214:217], v[68:71]
	s_setprio 0
	s_barrier
; #define LDA(dst, b, h)                                                                                    \
;   _Pragma("unroll") for (int m = 0; m < 4; ++m) _Pragma("unroll") for (int k = 0; k < 2; ++k)             \
;       dst[m][k] = *reinterpret_cast<const bf16x8*>((char*)SA(b, h) + lds_byte(wr * 64 + m * 16 + fr, k * 32 + fq * 8))
; #define LDB(dst, b, h)                                                                                    \
;   _Pragma("unroll") for (int n = 0; n < 2; ++n) _Pragma("unroll") for (int k = 0; k < 2; ++k)             \
;       dst[n][k] = *reinterpret_cast<const bf16x8*>((char*)SB(b, h) + lds_byte(wc * 32 + n * 16 + fr, k * 32 + fq * 8))
; #define WAIT_V(n) asm volatile("s_waitcnt vmcnt(" #n ")" ::: "memory")
; #define WAIT_L(n) asm volatile("s_waitcnt lgkmcnt(" #n ")" ::: "memory")
; #define BAR __builtin_amdgcn_s_barrier()
; template <int EPI> ...
;     ...
;     LDB(B1, 1, 1); WAIT_V(0); BAR; WAIT_L(0); MMA(0, 1, At, B1); BAR;
;     LDA(At, 1, 1); BAR; WAIT_L(0); MMA(1, 0, At, B0); MMA(1, 1, At, B1); BAR;
;   }
;   if (wr == 0) BAR;
	ds_read_b128 v[128:131], v140
	ds_read_b128 v[234:237], v140 offset:1024
	ds_read_b128 v[238:241], v140 offset:2048
	ds_read_b128 v[140:143], v140 offset:3072
	s_waitcnt vmcnt(0)
	s_barrier
	s_waitcnt lgkmcnt(0)
	s_setprio 1
	v_mfma_f32_16x16x32_bf16 v[96:99], v[8:11], v[128:131], v[218:221]
	v_mfma_f32_16x16x32_bf16 v[8:11], v[8:11], v[238:241], v[88:91]
	v_mfma_f32_16x16x32_bf16 v[124:127], v[12:15], v[140:143], v[8:11]
	v_mfma_f32_16x16x32_bf16 v[8:11], v[16:19], v[128:131], v[182:185]
	v_mfma_f32_16x16x32_bf16 v[112:115], v[20:23], v[234:237], v[8:11]
	v_mfma_f32_16x16x32_bf16 v[8:11], v[16:19], v[238:241], v[186:189]
	v_mfma_f32_16x16x32_bf16 v[116:119], v[20:23], v[140:143], v[8:11]
	v_mfma_f32_16x16x32_bf16 v[8:11], v[24:27], v[128:131], v[190:193]
	v_mfma_f32_16x16x32_bf16 v[104:107], v[28:31], v[234:237], v[8:11]
	v_mfma_f32_16x16x32_bf16 v[8:11], v[24:27], v[238:241], v[194:197]
	v_mfma_f32_16x16x32_bf16 v[108:111], v[28:31], v[140:143], v[8:11]
	v_mfma_f32_16x16x32_bf16 v[8:11], v[226:229], v[128:131], v[198:201]
	v_mfma_f32_16x16x32_bf16 v[88:91], v[230:233], v[234:237], v[8:11]
	v_mfma_f32_16x16x32_bf16 v[8:11], v[226:229], v[238:241], v[202:205]
	v_mfma_f32_16x16x32_bf16 v[120:123], v[12:15], v[234:237], v[96:99]
	v_mfma_f32_16x16x32_bf16 v[96:99], v[230:233], v[140:143], v[8:11]
	s_setprio 0
	s_barrier
	ds_read_b128 v[182:185], v138 offset:49152
	ds_read_b128 v[186:189], v138 offset:50176
	ds_read_b128 v[190:193], v137 offset:49152
	ds_read_b128 v[194:197], v137 offset:50176
	ds_read_b128 v[198:201], v136 offset:49152
	ds_read_b128 v[136:139], v136 offset:50176
	ds_read_b128 v[202:205], v135 offset:49152
	ds_read_b128 v[218:221], v135 offset:50176
	s_barrier
	s_waitcnt lgkmcnt(0)
	s_setprio 1
	v_mfma_f32_16x16x32_bf16 v[8:11], v[182:185], v[0:3], v[60:63]
	v_mfma_f32_16x16x32_bf16 v[24:27], v[186:189], v[4:7], v[8:11]
	v_mfma_f32_16x16x32_bf16 v[8:11], v[182:185], v[206:209], v[56:59]
	v_mfma_f32_16x16x32_bf16 v[28:31], v[186:189], v[214:217], v[8:11]
	v_mfma_f32_16x16x32_bf16 v[8:11], v[190:193], v[0:3], v[52:55]
	v_mfma_f32_16x16x32_bf16 v[16:19], v[194:197], v[4:7], v[8:11]
	v_mfma_f32_16x16x32_bf16 v[8:11], v[190:193], v[206:209], v[48:51]
	v_mfma_f32_16x16x32_bf16 v[20:23], v[194:197], v[214:217], v[8:11]
	v_mfma_f32_16x16x32_bf16 v[8:11], v[198:201], v[0:3], v[44:47]
	v_mfma_f32_16x16x32_bf16 v[0:3], v[202:205], v[0:3], v[36:39]
	v_mfma_f32_16x16x32_bf16 v[8:11], v[136:139], v[4:7], v[8:11]
	v_mfma_f32_16x16x32_bf16 v[12:15], v[198:201], v[206:209], v[40:43]
	v_mfma_f32_16x16x32_bf16 v[0:3], v[218:221], v[4:7], v[0:3]
	v_mfma_f32_16x16x32_bf16 v[4:7], v[202:205], v[206:209], v[32:35]
	v_mfma_f32_16x16x32_bf16 v[12:15], v[136:139], v[214:217], v[12:15]
	v_mfma_f32_16x16x32_bf16 v[4:7], v[218:221], v[214:217], v[4:7]
	s_setprio 0
	s_setprio 1
	v_mfma_f32_16x16x32_bf16 v[32:35], v[182:185], v[128:131], v[144:147]
	v_mfma_f32_16x16x32_bf16 v[56:59], v[186:189], v[234:237], v[32:35]
	v_mfma_f32_16x16x32_bf16 v[32:35], v[182:185], v[238:241], v[160:163]
	v_mfma_f32_16x16x32_bf16 v[60:63], v[186:189], v[140:143], v[32:35]
	v_mfma_f32_16x16x32_bf16 v[32:35], v[190:193], v[128:131], v[164:167]
	v_mfma_f32_16x16x32_bf16 v[48:51], v[194:197], v[234:237], v[32:35]
	v_mfma_f32_16x16x32_bf16 v[32:35], v[190:193], v[238:241], v[178:181]
	v_mfma_f32_16x16x32_bf16 v[52:55], v[194:197], v[140:143], v[32:35]
	v_mfma_f32_16x16x32_bf16 v[32:35], v[198:201], v[128:131], v[210:213]
	v_mfma_f32_16x16x32_bf16 v[40:43], v[136:139], v[234:237], v[32:35]
	v_mfma_f32_16x16x32_bf16 v[32:35], v[198:201], v[238:241], v[222:225]
	v_mfma_f32_16x16x32_bf16 v[44:47], v[136:139], v[140:143], v[32:35]
	v_mfma_f32_16x16x32_bf16 v[32:35], v[202:205], v[128:131], v[156:159]
	v_mfma_f32_16x16x32_bf16 v[36:39], v[202:205], v[238:241], v[152:155]
	v_mfma_f32_16x16x32_bf16 v[32:35], v[218:221], v[234:237], v[32:35]
	v_mfma_f32_16x16x32_bf16 v[36:39], v[218:221], v[140:143], v[36:39]
	s_setprio 0
	s_cmpk_gt_u32 s34, 0xff
	s_barrier
	s_cbranch_scc1 .LBB0_135
	s_barrier
	s_branch .LBB0_135

; #define LDA(dst, b, h)                                                                                    \
;   _Pragma("unroll") for (int m = 0; m < 4; ++m) _Pragma("unroll") for (int k = 0; k < 2; ++k)             \
;       dst[m][k] = *reinterpret_cast<const bf16x8*>((char*)SA(b, h) + lds_byte(wr * 64 + m * 16 + fr, k * 32 + fq * 8))
; #define LDB(dst, b, h)                                                                                    \
;   _Pragma("unroll") for (int n = 0; n < 2; ++n) _Pragma("unroll") for (int k = 0; k < 2; ++k)             \
;       dst[n][k] = *reinterpret_cast<const bf16x8*>((char*)SB(b, h) + lds_byte(wc * 32 + n * 16 + fr, k * 32 + fq * 8))
; #define WAIT_V(n) asm volatile("s_waitcnt vmcnt(" #n ")" ::: "memory")
; #define WAIT_L(n) asm volatile("s_waitcnt lgkmcnt(" #n ")" ::: "memory")
; #define BAR __builtin_amdgcn_s_barrier()
; #define SCHED __builtin_amdgcn_sched_barrier(0)
; template <int EPI> ...
;     ...
;     LDB(B0, 0, 0); SCHED; LDA(At, 0, 0); STAGE(SA(1, 1), A, brow + HALF, t + 1);
;     WAIT_L(8); BAR; WAIT_L(0); MMA(0, 0, At, B0); BAR; SCHED;
;     LDB(B1, 0, 1); STAGE(SB(0, 0), Bt, bcol, t + 2);
;     BAR; WAIT_L(0); MMA(0, 1, At, B1); BAR;
;     LDA(At, 0, 1); STAGE(SA(0, 0), A, brow, t + 2);
;     BAR; WAIT_L(0); MMA(1, 0, At, B0); BAR; SCHED;
;     STAGE(SB(0, 1), Bt, bcol + HALF, t + 2);
;     WAIT_V(6); BAR; MMA(1, 1, At, B1); BAR;
.LBB0_166:
	ds_read_b128 v[162:165], v155
	ds_read_b128 v[178:181], v155 offset:1024
	ds_read_b128 v[182:185], v155 offset:2048
	ds_read_b128 v[186:189], v155 offset:3072
	s_add_u32 s22, s4, s20
	v_add_u32_e32 v156, s66, v154
	v_add_u32_e32 v157, s67, v154
	v_add_u32_e32 v158, s69, v154
	s_addc_u32 s23, s5, s21
	v_add_u32_e32 v159, 0xc000, v129
	ds_read_b128 v[190:193], v135
	ds_read_b128 v[194:197], v135 offset:1024
	ds_read_b128 v[198:201], v156
	ds_read_b128 v[202:205], v156 offset:1024
	ds_read_b128 v[206:209], v157
	ds_read_b128 v[210:213], v157 offset:1024
	ds_read_b128 v[214:217], v158
	ds_read_b128 v[218:221], v158 offset:1024
	s_add_u32 m0, s32, 0xc000
	s_add_u32 s98, s22, 0xb0080
	s_addc_u32 s99, s23, 0
	global_load_lds_dwordx4 v253, s[98:99]
	s_nop 0
	v_add_u32_e32 v160, 0xe000, v129
	s_nop 0
	s_add_u32 m0, s32, 0xe000
	s_nop 0
	global_load_lds_dwordx4 v252, s[98:99]
	s_waitcnt lgkmcnt(8)
	s_barrier
	s_waitcnt lgkmcnt(0)
	s_setprio 1
	v_mfma_f32_16x16x32_bf16 v[124:127], v[190:193], v[162:165], v[124:127]
	v_mfma_f32_16x16x32_bf16 v[120:123], v[190:193], v[182:185], v[120:123]
	v_mfma_f32_16x16x32_bf16 v[116:119], v[198:201], v[162:165], v[116:119]
	v_mfma_f32_16x16x32_bf16 v[112:115], v[198:201], v[182:185], v[112:115]
	v_mfma_f32_16x16x32_bf16 v[108:111], v[206:209], v[162:165], v[108:111]
	v_mfma_f32_16x16x32_bf16 v[104:107], v[206:209], v[182:185], v[104:107]
	v_mfma_f32_16x16x32_bf16 v[100:103], v[214:217], v[162:165], v[100:103]
	v_mfma_f32_16x16x32_bf16 v[96:99], v[214:217], v[182:185], v[96:99]
	v_mfma_f32_16x16x32_bf16 v[124:127], v[194:197], v[178:181], v[124:127]
	v_mfma_f32_16x16x32_bf16 v[120:123], v[194:197], v[186:189], v[120:123]
	v_mfma_f32_16x16x32_bf16 v[116:119], v[202:205], v[178:181], v[116:119]
	v_mfma_f32_16x16x32_bf16 v[112:115], v[202:205], v[186:189], v[112:115]
	v_mfma_f32_16x16x32_bf16 v[108:111], v[210:213], v[178:181], v[108:111]
	v_mfma_f32_16x16x32_bf16 v[104:107], v[210:213], v[186:189], v[104:107]
	v_mfma_f32_16x16x32_bf16 v[100:103], v[218:221], v[178:181], v[100:103]
	v_mfma_f32_16x16x32_bf16 v[96:99], v[218:221], v[186:189], v[96:99]
	s_setprio 0
	s_barrier
	s_add_u32 s30, s0, s20
	s_addc_u32 s31, s1, s21
	ds_read_b128 v[222:225], v152
	ds_read_b128 v[226:229], v152 offset:1024
	ds_read_b128 v[230:233], v152 offset:2048
	ds_read_b128 v[234:237], v152 offset:3072
	s_add_u32 m0, s32, 0x10000
	s_add_u32 s98, s30, 0x100
	s_addc_u32 s99, s31, 0
	global_load_lds_dwordx4 v253, s[98:99]
	s_add_u32 m0, s32, 0x12000
	s_nop 0
	global_load_lds_dwordx4 v252, s[98:99]
	s_barrier
	s_waitcnt lgkmcnt(0)
	s_setprio 1
	v_mfma_f32_16x16x32_bf16 v[92:95], v[190:193], v[222:225], v[92:95]
	v_mfma_f32_16x16x32_bf16 v[88:91], v[190:193], v[230:233], v[88:91]
	v_mfma_f32_16x16x32_bf16 v[84:87], v[198:201], v[222:225], v[84:87]
	v_mfma_f32_16x16x32_bf16 v[80:83], v[198:201], v[230:233], v[80:83]
	v_mfma_f32_16x16x32_bf16 v[76:79], v[206:209], v[222:225], v[76:79]
	v_mfma_f32_16x16x32_bf16 v[72:75], v[206:209], v[230:233], v[72:75]
	v_mfma_f32_16x16x32_bf16 v[68:71], v[214:217], v[222:225], v[68:71]
	v_mfma_f32_16x16x32_bf16 v[64:67], v[214:217], v[230:233], v[64:67]
	v_mfma_f32_16x16x32_bf16 v[92:95], v[194:197], v[226:229], v[92:95]
	v_mfma_f32_16x16x32_bf16 v[88:91], v[194:197], v[234:237], v[88:91]
	v_mfma_f32_16x16x32_bf16 v[84:87], v[202:205], v[226:229], v[84:87]
	v_mfma_f32_16x16x32_bf16 v[80:83], v[202:205], v[234:237], v[80:83]
	v_mfma_f32_16x16x32_bf16 v[76:79], v[210:213], v[226:229], v[76:79]
	v_mfma_f32_16x16x32_bf16 v[72:75], v[210:213], v[234:237], v[72:75]
	v_mfma_f32_16x16x32_bf16 v[68:71], v[218:221], v[226:229], v[68:71]
	v_mfma_f32_16x16x32_bf16 v[64:67], v[218:221], v[234:237], v[64:67]
	s_setprio 0
	s_barrier
	ds_read_b128 v[190:193], v135 offset:16384
	ds_read_b128 v[194:197], v135 offset:17408
	ds_read_b128 v[198:201], v156 offset:16384
	ds_read_b128 v[202:205], v156 offset:17408
	ds_read_b128 v[206:209], v157 offset:16384
	ds_read_b128 v[210:213], v157 offset:17408
	ds_read_b128 v[214:217], v158 offset:16384
	ds_read_b128 v[218:221], v158 offset:17408
	s_mov_b32 m0, s32
	s_add_u32 s98, s22, 0x100
	s_addc_u32 s99, s23, 0
	global_load_lds_dwordx4 v253, s[98:99]
	s_add_u32 m0, s32, 0x2000
	s_nop 0
	global_load_lds_dwordx4 v252, s[98:99]
	s_barrier
	s_waitcnt lgkmcnt(0)
	s_setprio 1
	v_mfma_f32_16x16x32_bf16 v[60:63], v[190:193], v[162:165], v[60:63]
	v_mfma_f32_16x16x32_bf16 v[56:59], v[190:193], v[182:185], v[56:59]
	v_mfma_f32_16x16x32_bf16 v[52:55], v[198:201], v[162:165], v[52:55]
	v_mfma_f32_16x16x32_bf16 v[48:51], v[198:201], v[182:185], v[48:51]
	v_mfma_f32_16x16x32_bf16 v[44:47], v[206:209], v[162:165], v[44:47]
	v_mfma_f32_16x16x32_bf16 v[40:43], v[206:209], v[182:185], v[40:43]
	v_mfma_f32_16x16x32_bf16 v[36:39], v[214:217], v[162:165], v[36:39]
	v_mfma_f32_16x16x32_bf16 v[32:35], v[214:217], v[182:185], v[32:35]
	v_mfma_f32_16x16x32_bf16 v[60:63], v[194:197], v[178:181], v[60:63]
	v_mfma_f32_16x16x32_bf16 v[56:59], v[194:197], v[186:189], v[56:59]
	v_mfma_f32_16x16x32_bf16 v[52:55], v[202:205], v[178:181], v[52:55]
	v_mfma_f32_16x16x32_bf16 v[48:51], v[202:205], v[186:189], v[48:51]
	v_mfma_f32_16x16x32_bf16 v[44:47], v[210:213], v[178:181], v[44:47]
	v_mfma_f32_16x16x32_bf16 v[40:43], v[210:213], v[186:189], v[40:43]
	v_mfma_f32_16x16x32_bf16 v[36:39], v[218:221], v[178:181], v[36:39]
	v_mfma_f32_16x16x32_bf16 v[32:35], v[218:221], v[186:189], v[32:35]
	s_setprio 0
	s_barrier
	s_add_u32 m0, s32, 0x14000
	s_add_u32 s98, s30, 0xb0100
	s_addc_u32 s99, s31, 0
	global_load_lds_dwordx4 v253, s[98:99]
	s_add_u32 m0, s32, 0x16000
	s_nop 0
	global_load_lds_dwordx4 v252, s[98:99]
	s_waitcnt vmcnt(6)
	s_barrier
; #define LDA(dst, b, h)                                                                                    \
;   _Pragma("unroll") for (int m = 0; m < 4; ++m) _Pragma("unroll") for (int k = 0; k < 2; ++k)             \
;       dst[m][k] = *reinterpret_cast<const bf16x8*>((char*)SA(b, h) + lds_byte(wr * 64 + m * 16 + fr, k * 32 + fq * 8))
; #define LDB(dst, b, h)                                                                                    \
;   _Pragma("unroll") for (int n = 0; n < 2; ++n) _Pragma("unroll") for (int k = 0; k < 2; ++k)             \
;       dst[n][k] = *reinterpret_cast<const bf16x8*>((char*)SB(b, h) + lds_byte(wc * 32 + n * 16 + fr, k * 32 + fq * 8))
; #define WAIT_V(n) asm volatile("s_waitcnt vmcnt(" #n ")" ::: "memory")
; #define WAIT_L(n) asm volatile("s_waitcnt lgkmcnt(" #n ")" ::: "memory")
; #define BAR __builtin_amdgcn_s_barrier()
; #define SCHED __builtin_amdgcn_sched_barrier(0)
; template <int EPI> ...
;     ...
;     WAIT_V(6); BAR; MMA(1, 1, At, B1); BAR;
;     LDB(B0, 1, 0); SCHED; LDA(At, 1, 0); STAGE(SA(0, 1), A, brow + HALF, t + 2);
;     WAIT_L(8); BAR; WAIT_L(0); MMA(0, 0, At, B0); BAR; SCHED;
;     LDB(B1, 1, 1); STAGE(SB(1, 0), Bt, bcol, t + 3);
;     BAR; WAIT_L(0); MMA(0, 1, At, B1); BAR;
;     LDA(At, 1, 1); STAGE(SA(1, 0), A, brow, t + 3);
;     BAR; WAIT_L(0); MMA(1, 0, At, B0); BAR; SCHED;
	s_setprio 1
	v_mfma_f32_16x16x32_bf16 v[28:31], v[190:193], v[222:225], v[28:31]
	v_mfma_f32_16x16x32_bf16 v[24:27], v[190:193], v[230:233], v[24:27]
	v_mfma_f32_16x16x32_bf16 v[20:23], v[198:201], v[222:225], v[20:23]
	v_mfma_f32_16x16x32_bf16 v[16:19], v[198:201], v[230:233], v[16:19]
	v_mfma_f32_16x16x32_bf16 v[12:15], v[206:209], v[222:225], v[12:15]
	v_mfma_f32_16x16x32_bf16 v[8:11], v[206:209], v[230:233], v[8:11]
	v_mfma_f32_16x16x32_bf16 v[4:7], v[214:217], v[222:225], v[4:7]
	v_mfma_f32_16x16x32_bf16 v[0:3], v[214:217], v[230:233], v[0:3]
	v_mfma_f32_16x16x32_bf16 v[28:31], v[194:197], v[226:229], v[28:31]
	v_mfma_f32_16x16x32_bf16 v[24:27], v[194:197], v[234:237], v[24:27]
	v_mfma_f32_16x16x32_bf16 v[20:23], v[202:205], v[226:229], v[20:23]
	v_mfma_f32_16x16x32_bf16 v[16:19], v[202:205], v[234:237], v[16:19]
	v_mfma_f32_16x16x32_bf16 v[12:15], v[210:213], v[226:229], v[12:15]
	v_mfma_f32_16x16x32_bf16 v[8:11], v[210:213], v[234:237], v[8:11]
	v_mfma_f32_16x16x32_bf16 v[4:7], v[218:221], v[226:229], v[4:7]
	v_mfma_f32_16x16x32_bf16 v[0:3], v[218:221], v[234:237], v[0:3]
	s_setprio 0
	s_barrier
	ds_read_b128 v[162:165], v140
	ds_read_b128 v[178:181], v140 offset:1024
	ds_read_b128 v[182:185], v140 offset:2048
	ds_read_b128 v[186:189], v140 offset:3072
	ds_read_b128 v[190:193], v135 offset:32768
	ds_read_b128 v[194:197], v135 offset:33792
	ds_read_b128 v[198:201], v156 offset:32768
	ds_read_b128 v[202:205], v156 offset:33792
	ds_read_b128 v[206:209], v157 offset:32768
	ds_read_b128 v[210:213], v157 offset:33792
	ds_read_b128 v[214:217], v158 offset:32768
	ds_read_b128 v[218:221], v158 offset:33792
	s_add_u32 m0, s32, 0x4000
	s_add_u32 s98, s22, 0xb0100
	s_addc_u32 s99, s23, 0
	global_load_lds_dwordx4 v253, s[98:99]
	s_add_u32 m0, s32, 0x6000
	s_nop 0
	global_load_lds_dwordx4 v252, s[98:99]
	s_waitcnt lgkmcnt(8)
	s_barrier
	s_waitcnt lgkmcnt(0)
	s_setprio 1
	v_mfma_f32_16x16x32_bf16 v[124:127], v[190:193], v[162:165], v[124:127]
	v_mfma_f32_16x16x32_bf16 v[120:123], v[190:193], v[182:185], v[120:123]
	v_mfma_f32_16x16x32_bf16 v[116:119], v[198:201], v[162:165], v[116:119]
	v_mfma_f32_16x16x32_bf16 v[112:115], v[198:201], v[182:185], v[112:115]
	v_mfma_f32_16x16x32_bf16 v[108:111], v[206:209], v[162:165], v[108:111]
	v_mfma_f32_16x16x32_bf16 v[104:107], v[206:209], v[182:185], v[104:107]
	v_mfma_f32_16x16x32_bf16 v[100:103], v[214:217], v[162:165], v[100:103]
	v_mfma_f32_16x16x32_bf16 v[96:99], v[214:217], v[182:185], v[96:99]
	v_mfma_f32_16x16x32_bf16 v[124:127], v[194:197], v[178:181], v[124:127]
	v_mfma_f32_16x16x32_bf16 v[120:123], v[194:197], v[186:189], v[120:123]
	v_mfma_f32_16x16x32_bf16 v[116:119], v[202:205], v[178:181], v[116:119]
	v_mfma_f32_16x16x32_bf16 v[112:115], v[202:205], v[186:189], v[112:115]
	v_mfma_f32_16x16x32_bf16 v[108:111], v[210:213], v[178:181], v[108:111]
	v_mfma_f32_16x16x32_bf16 v[104:107], v[210:213], v[186:189], v[104:107]
	v_mfma_f32_16x16x32_bf16 v[100:103], v[218:221], v[178:181], v[100:103]
	v_mfma_f32_16x16x32_bf16 v[96:99], v[218:221], v[186:189], v[96:99]
	s_setprio 0
	s_barrier
	ds_read_b128 v[222:225], v137
	ds_read_b128 v[226:229], v137 offset:1024
	ds_read_b128 v[230:233], v137 offset:2048
	ds_read_b128 v[234:237], v137 offset:3072
	s_add_u32 m0, s32, 0x18000
	s_add_u32 s98, s30, 0x180
	s_addc_u32 s99, s31, 0
	global_load_lds_dwordx4 v253, s[98:99]
	s_add_u32 m0, s32, 0x1a000
	s_nop 0
	global_load_lds_dwordx4 v252, s[98:99]
	s_barrier
	s_waitcnt lgkmcnt(0)
	s_setprio 1
	v_mfma_f32_16x16x32_bf16 v[92:95], v[190:193], v[222:225], v[92:95]
	v_mfma_f32_16x16x32_bf16 v[88:91], v[190:193], v[230:233], v[88:91]
	v_mfma_f32_16x16x32_bf16 v[84:87], v[198:201], v[222:225], v[84:87]
	v_mfma_f32_16x16x32_bf16 v[80:83], v[198:201], v[230:233], v[80:83]
	v_mfma_f32_16x16x32_bf16 v[76:79], v[206:209], v[222:225], v[76:79]
	v_mfma_f32_16x16x32_bf16 v[72:75], v[206:209], v[230:233], v[72:75]
	v_mfma_f32_16x16x32_bf16 v[68:71], v[214:217], v[222:225], v[68:71]
	v_mfma_f32_16x16x32_bf16 v[64:67], v[214:217], v[230:233], v[64:67]
	v_mfma_f32_16x16x32_bf16 v[92:95], v[194:197], v[226:229], v[92:95]
	v_mfma_f32_16x16x32_bf16 v[88:91], v[194:197], v[234:237], v[88:91]
	v_mfma_f32_16x16x32_bf16 v[84:87], v[202:205], v[226:229], v[84:87]
	v_mfma_f32_16x16x32_bf16 v[80:83], v[202:205], v[234:237], v[80:83]
	v_mfma_f32_16x16x32_bf16 v[76:79], v[210:213], v[226:229], v[76:79]
	v_mfma_f32_16x16x32_bf16 v[72:75], v[210:213], v[234:237], v[72:75]
	v_mfma_f32_16x16x32_bf16 v[68:71], v[218:221], v[226:229], v[68:71]
	v_mfma_f32_16x16x32_bf16 v[64:67], v[218:221], v[234:237], v[64:67]
	s_setprio 0
	s_barrier
	ds_read_b128 v[190:193], v135 offset:49152
	ds_read_b128 v[194:197], v135 offset:50176
	ds_read_b128 v[198:201], v156 offset:49152
	ds_read_b128 v[202:205], v156 offset:50176
	ds_read_b128 v[206:209], v157 offset:49152
	ds_read_b128 v[210:213], v157 offset:50176
	ds_read_b128 v[214:217], v158 offset:49152
	ds_read_b128 v[218:221], v158 offset:50176
	s_add_u32 m0, s32, 0x8000
	s_add_u32 s98, s22, 0x180
	s_addc_u32 s99, s23, 0
	global_load_lds_dwordx4 v253, s[98:99]
	s_nop 0
	s_add_u32 m0, s32, 0xa000
	s_nop 0
	global_load_lds_dwordx4 v252, s[98:99]
	s_barrier
; #define LDA(dst, b, h)                                                                                    \
;   _Pragma("unroll") for (int m = 0; m < 4; ++m) _Pragma("unroll") for (int k = 0; k < 2; ++k)             \
;       dst[m][k] = *reinterpret_cast<const bf16x8*>((char*)SA(b, h) + lds_byte(wr * 64 + m * 16 + fr, k * 32 + fq * 8))
; #define LDB(dst, b, h)                                                                                    \
;   _Pragma("unroll") for (int n = 0; n < 2; ++n) _Pragma("unroll") for (int k = 0; k < 2; ++k)             \
;       dst[n][k] = *reinterpret_cast<const bf16x8*>((char*)SB(b, h) + lds_byte(wc * 32 + n * 16 + fr, k * 32 + fq * 8))
; #define WAIT_V(n) asm volatile("s_waitcnt vmcnt(" #n ")" ::: "memory")
; #define WAIT_L(n) asm volatile("s_waitcnt lgkmcnt(" #n ")" ::: "memory")
; #define BAR __builtin_amdgcn_s_barrier()
; #define SCHED __builtin_amdgcn_sched_barrier(0)
; template <int EPI> ...
;     ...
;     BAR; WAIT_L(0); MMA(1, 0, At, B0); BAR; SCHED;
;     STAGE(SB(1, 1), Bt, bcol + HALF, t + 3);
;     WAIT_V(6); BAR; MMA(1, 1, At, B1); BAR;
;   }
;   {
;     LDB(B0, 0, 0); LDA(At, 0, 0); STAGE(SA(1, 1), A, brow + HALF, nt - 1);
;     BAR; WAIT_L(0); MMA(0, 0, At, B0); BAR;
;     LDB(B1, 0, 1); BAR; WAIT_L(0); MMA(0, 1, At, B1); BAR;
	s_waitcnt lgkmcnt(0)
	s_setprio 1
	v_mfma_f32_16x16x32_bf16 v[60:63], v[190:193], v[162:165], v[60:63]
	v_mfma_f32_16x16x32_bf16 v[56:59], v[190:193], v[182:185], v[56:59]
	v_mfma_f32_16x16x32_bf16 v[52:55], v[198:201], v[162:165], v[52:55]
	v_mfma_f32_16x16x32_bf16 v[48:51], v[198:201], v[182:185], v[48:51]
	v_mfma_f32_16x16x32_bf16 v[44:47], v[206:209], v[162:165], v[44:47]
	v_mfma_f32_16x16x32_bf16 v[40:43], v[206:209], v[182:185], v[40:43]
	v_mfma_f32_16x16x32_bf16 v[36:39], v[214:217], v[162:165], v[36:39]
	v_mfma_f32_16x16x32_bf16 v[32:35], v[214:217], v[182:185], v[32:35]
	v_mfma_f32_16x16x32_bf16 v[60:63], v[194:197], v[178:181], v[60:63]
	v_mfma_f32_16x16x32_bf16 v[56:59], v[194:197], v[186:189], v[56:59]
	v_mfma_f32_16x16x32_bf16 v[52:55], v[202:205], v[178:181], v[52:55]
	v_mfma_f32_16x16x32_bf16 v[48:51], v[202:205], v[186:189], v[48:51]
	v_mfma_f32_16x16x32_bf16 v[44:47], v[210:213], v[178:181], v[44:47]
	v_mfma_f32_16x16x32_bf16 v[40:43], v[210:213], v[186:189], v[40:43]
	v_mfma_f32_16x16x32_bf16 v[36:39], v[218:221], v[178:181], v[36:39]
	v_mfma_f32_16x16x32_bf16 v[32:35], v[218:221], v[186:189], v[32:35]
	s_setprio 0
	s_barrier
	s_add_u32 m0, s32, 0x1c000
	s_add_u32 s98, s30, 0xb0180
	s_addc_u32 s99, s31, 0
	global_load_lds_dwordx4 v253, s[98:99]
	s_add_u32 m0, s32, 0x1e000
	s_nop 0
	global_load_lds_dwordx4 v252, s[98:99]
	s_waitcnt vmcnt(6)
	s_barrier
	s_setprio 1
	v_mfma_f32_16x16x32_bf16 v[28:31], v[190:193], v[222:225], v[28:31]
	v_mfma_f32_16x16x32_bf16 v[24:27], v[190:193], v[230:233], v[24:27]
	v_mfma_f32_16x16x32_bf16 v[20:23], v[198:201], v[222:225], v[20:23]
	v_mfma_f32_16x16x32_bf16 v[16:19], v[198:201], v[230:233], v[16:19]
	v_mfma_f32_16x16x32_bf16 v[12:15], v[206:209], v[222:225], v[12:15]
	v_mfma_f32_16x16x32_bf16 v[8:11], v[206:209], v[230:233], v[8:11]
	v_mfma_f32_16x16x32_bf16 v[4:7], v[214:217], v[222:225], v[4:7]
	v_mfma_f32_16x16x32_bf16 v[0:3], v[214:217], v[230:233], v[0:3]
	v_mfma_f32_16x16x32_bf16 v[28:31], v[194:197], v[226:229], v[28:31]
	v_mfma_f32_16x16x32_bf16 v[24:27], v[194:197], v[234:237], v[24:27]
	v_mfma_f32_16x16x32_bf16 v[20:23], v[202:205], v[226:229], v[20:23]
	v_mfma_f32_16x16x32_bf16 v[16:19], v[202:205], v[234:237], v[16:19]
	v_mfma_f32_16x16x32_bf16 v[12:15], v[210:213], v[226:229], v[12:15]
	v_mfma_f32_16x16x32_bf16 v[8:11], v[210:213], v[234:237], v[8:11]
	v_mfma_f32_16x16x32_bf16 v[4:7], v[218:221], v[226:229], v[4:7]
	v_mfma_f32_16x16x32_bf16 v[0:3], v[218:221], v[234:237], v[0:3]
	s_setprio 0
	s_add_i32 s70, s70, 2
	s_add_u32 s20, s20, 0x100
	s_addc_u32 s21, s21, 0
	s_cmp_lt_u32 s70, 40
	s_barrier
	s_cbranch_scc1 .LBB0_166
	s_add_u32 s0, s18, 0x1580
	ds_read_b128 v[142:145], v155
	ds_read_b128 v[162:165], v155 offset:1024
	ds_read_b128 v[178:181], v155 offset:2048
	ds_read_b128 v[182:185], v155 offset:3072
	ds_read_b128 v[186:189], v135
	ds_read_b128 v[190:193], v135 offset:1024
	ds_read_b128 v[194:197], v156
	ds_read_b128 v[198:201], v156 offset:1024
	ds_read_b128 v[202:205], v157
	ds_read_b128 v[206:209], v157 offset:1024
	ds_read_b128 v[210:213], v158
	ds_read_b128 v[214:217], v158 offset:1024
	s_addc_u32 s1, s19, 0
	v_mov_b32_e32 v129, v149
	v_readfirstlane_b32 s4, v159
	v_lshl_add_u64 v[128:129], v[128:129], 1, s[0:1]
	s_mov_b32 m0, s4
	v_mov_b32_e32 v131, v149
	global_load_lds_dwordx4 v[128:129], off
	s_nop 0
	v_lshl_add_u64 v[128:129], v[130:131], 1, s[0:1]
	v_readfirstlane_b32 s0, v160
	s_mov_b32 m0, s0
	s_nop 0
	global_load_lds_dwordx4 v[128:129], off
	s_barrier
	s_waitcnt lgkmcnt(0)
	s_setprio 1
	v_mfma_f32_16x16x32_bf16 v[124:127], v[186:189], v[142:145], v[124:127]
	v_mfma_f32_16x16x32_bf16 v[120:123], v[186:189], v[178:181], v[120:123]
	v_mfma_f32_16x16x32_bf16 v[116:119], v[194:197], v[142:145], v[116:119]
	v_mfma_f32_16x16x32_bf16 v[112:115], v[194:197], v[178:181], v[112:115]
	v_mfma_f32_16x16x32_bf16 v[108:111], v[202:205], v[142:145], v[108:111]
	v_mfma_f32_16x16x32_bf16 v[104:107], v[202:205], v[178:181], v[104:107]
	v_mfma_f32_16x16x32_bf16 v[96:99], v[210:213], v[178:181], v[96:99]
	v_mfma_f32_16x16x32_bf16 v[124:127], v[190:193], v[162:165], v[124:127]
	v_mfma_f32_16x16x32_bf16 v[120:123], v[190:193], v[182:185], v[120:123]
	v_mfma_f32_16x16x32_bf16 v[116:119], v[198:201], v[162:165], v[116:119]
	v_mfma_f32_16x16x32_bf16 v[112:115], v[198:201], v[182:185], v[112:115]
	v_mfma_f32_16x16x32_bf16 v[108:111], v[206:209], v[162:165], v[108:111]
	v_mfma_f32_16x16x32_bf16 v[104:107], v[206:209], v[182:185], v[104:107]
	v_mfma_f32_16x16x32_bf16 v[100:103], v[210:213], v[142:145], v[100:103]
	v_mfma_f32_16x16x32_bf16 v[96:99], v[214:217], v[182:185], v[96:99]
	v_mfma_f32_16x16x32_bf16 v[128:131], v[214:217], v[162:165], v[100:103]
	s_setprio 0
	s_barrier
	s_nop 3
	ds_read_b128 v[100:103], v152
	ds_read_b128 v[218:221], v152 offset:1024
	ds_read_b128 v[222:225], v152 offset:2048
	ds_read_b128 v[152:155], v152 offset:3072
	s_barrier
	s_waitcnt lgkmcnt(0)
	s_setprio 1
	v_mfma_f32_16x16x32_bf16 v[88:91], v[186:189], v[222:225], v[88:91]
	v_mfma_f32_16x16x32_bf16 v[92:95], v[186:189], v[100:103], v[92:95]
	v_mfma_f32_16x16x32_bf16 v[88:91], v[190:193], v[152:155], v[88:91]
	v_mfma_f32_16x16x32_bf16 v[84:87], v[194:197], v[100:103], v[84:87]
	v_mfma_f32_16x16x32_bf16 v[80:83], v[194:197], v[222:225], v[80:83]
	v_mfma_f32_16x16x32_bf16 v[76:79], v[202:205], v[100:103], v[76:79]
	v_mfma_f32_16x16x32_bf16 v[72:75], v[202:205], v[222:225], v[72:75]
	v_mfma_f32_16x16x32_bf16 v[68:71], v[210:213], v[100:103], v[68:71]
	v_mfma_f32_16x16x32_bf16 v[64:67], v[210:213], v[222:225], v[64:67]
	v_mfma_f32_16x16x32_bf16 v[226:229], v[190:193], v[218:221], v[92:95]
	v_mfma_f32_16x16x32_bf16 v[186:189], v[198:201], v[218:221], v[84:87]
	v_mfma_f32_16x16x32_bf16 v[190:193], v[198:201], v[152:155], v[80:83]
	v_mfma_f32_16x16x32_bf16 v[194:197], v[206:209], v[218:221], v[76:79]
	v_mfma_f32_16x16x32_bf16 v[198:201], v[206:209], v[152:155], v[72:75]
	v_mfma_f32_16x16x32_bf16 v[202:205], v[214:217], v[218:221], v[68:71]
	v_mfma_f32_16x16x32_bf16 v[206:209], v[214:217], v[152:155], v[64:67]
	s_setprio 0
	s_barrier
; #define LDA(dst, b, h)                                                                                    \
;   _Pragma("unroll") for (int m = 0; m < 4; ++m) _Pragma("unroll") for (int k = 0; k < 2; ++k)             \
;       dst[m][k] = *reinterpret_cast<const bf16x8*>((char*)SA(b, h) + lds_byte(wr * 64 + m * 16 + fr, k * 32 + fq * 8))
; #define LDB(dst, b, h)                                                                                    \
;   _Pragma("unroll") for (int n = 0; n < 2; ++n) _Pragma("unroll") for (int k = 0; k < 2; ++k)             \
;       dst[n][k] = *reinterpret_cast<const bf16x8*>((char*)SB(b, h) + lds_byte(wc * 32 + n * 16 + fr, k * 32 + fq * 8))
; #define WAIT_V(n) asm volatile("s_waitcnt vmcnt(" #n ")" ::: "memory")
; #define WAIT_L(n) asm volatile("s_waitcnt lgkmcnt(" #n ")" ::: "memory")
; #define BAR __builtin_amdgcn_s_barrier()
; template <int EPI> ...
;     ...
;     LDA(At, 0, 1); WAIT_V(4); BAR; WAIT_L(0); MMA(1, 0, At, B0); MMA(1, 1, At, B1); BAR;
;   }
;   {
;     LDB(B0, 1, 0); LDA(At, 1, 0); WAIT_V(2); BAR; WAIT_L(0); MMA(0, 0, At, B0); BAR;
	s_nop 0
	ds_read_b128 v[64:67], v135 offset:16384
	ds_read_b128 v[68:71], v135 offset:17408
	ds_read_b128 v[72:75], v156 offset:16384
	ds_read_b128 v[76:79], v156 offset:17408
	ds_read_b128 v[80:83], v157 offset:16384
	ds_read_b128 v[84:87], v157 offset:17408
	ds_read_b128 v[92:95], v158 offset:16384
	ds_read_b128 v[210:213], v158 offset:17408
	s_waitcnt vmcnt(4)
	s_barrier
	s_waitcnt lgkmcnt(0)
	s_setprio 1
	v_mfma_f32_16x16x32_bf16 v[60:63], v[64:67], v[142:145], v[60:63]
	v_mfma_f32_16x16x32_bf16 v[56:59], v[64:67], v[178:181], v[56:59]
	v_mfma_f32_16x16x32_bf16 v[52:55], v[72:75], v[142:145], v[52:55]
	v_mfma_f32_16x16x32_bf16 v[48:51], v[72:75], v[178:181], v[48:51]
	v_mfma_f32_16x16x32_bf16 v[44:47], v[80:83], v[142:145], v[44:47]
	v_mfma_f32_16x16x32_bf16 v[40:43], v[80:83], v[178:181], v[40:43]
	v_mfma_f32_16x16x32_bf16 v[36:39], v[92:95], v[142:145], v[36:39]
	v_mfma_f32_16x16x32_bf16 v[32:35], v[92:95], v[178:181], v[32:35]
	v_mfma_f32_16x16x32_bf16 v[60:63], v[68:71], v[162:165], v[60:63]
	v_mfma_f32_16x16x32_bf16 v[56:59], v[68:71], v[182:185], v[56:59]
	v_mfma_f32_16x16x32_bf16 v[52:55], v[76:79], v[162:165], v[52:55]
	v_mfma_f32_16x16x32_bf16 v[48:51], v[76:79], v[182:185], v[48:51]
	v_mfma_f32_16x16x32_bf16 v[44:47], v[84:87], v[162:165], v[44:47]
	v_mfma_f32_16x16x32_bf16 v[40:43], v[84:87], v[182:185], v[40:43]
	v_mfma_f32_16x16x32_bf16 v[36:39], v[210:213], v[162:165], v[36:39]
	v_mfma_f32_16x16x32_bf16 v[32:35], v[210:213], v[182:185], v[32:35]
	s_setprio 0
	s_setprio 1
	v_mfma_f32_16x16x32_bf16 v[28:31], v[64:67], v[100:103], v[28:31]
	v_mfma_f32_16x16x32_bf16 v[24:27], v[64:67], v[222:225], v[24:27]
	v_mfma_f32_16x16x32_bf16 v[20:23], v[72:75], v[100:103], v[20:23]
	v_mfma_f32_16x16x32_bf16 v[16:19], v[72:75], v[222:225], v[16:19]
	v_mfma_f32_16x16x32_bf16 v[12:15], v[80:83], v[100:103], v[12:15]
	v_mfma_f32_16x16x32_bf16 v[8:11], v[80:83], v[222:225], v[8:11]
	v_mfma_f32_16x16x32_bf16 v[4:7], v[92:95], v[100:103], v[4:7]
	v_mfma_f32_16x16x32_bf16 v[0:3], v[92:95], v[222:225], v[0:3]
	v_mfma_f32_16x16x32_bf16 v[142:145], v[68:71], v[218:221], v[28:31]
	v_mfma_f32_16x16x32_bf16 v[160:163], v[68:71], v[152:155], v[24:27]
	v_mfma_f32_16x16x32_bf16 v[164:167], v[76:79], v[218:221], v[20:23]
	v_mfma_f32_16x16x32_bf16 v[178:181], v[76:79], v[152:155], v[16:19]
	v_mfma_f32_16x16x32_bf16 v[182:185], v[84:87], v[218:221], v[12:15]
	v_mfma_f32_16x16x32_bf16 v[214:217], v[84:87], v[152:155], v[8:11]
	v_mfma_f32_16x16x32_bf16 v[218:221], v[210:213], v[218:221], v[4:7]
	v_mfma_f32_16x16x32_bf16 v[152:155], v[210:213], v[152:155], v[0:3]
	s_setprio 0
	s_barrier
	s_nop 0
	ds_read_b128 v[0:3], v140
	ds_read_b128 v[4:7], v140 offset:1024
	ds_read_b128 v[210:213], v140 offset:2048
	ds_read_b128 v[138:141], v140 offset:3072
	ds_read_b128 v[8:11], v135 offset:32768
	ds_read_b128 v[12:15], v135 offset:33792
	ds_read_b128 v[16:19], v156 offset:32768
	ds_read_b128 v[20:23], v156 offset:33792
	ds_read_b128 v[24:27], v157 offset:32768
	ds_read_b128 v[28:31], v157 offset:33792
	ds_read_b128 v[222:225], v158 offset:32768
	ds_read_b128 v[230:233], v158 offset:33792
	s_waitcnt vmcnt(2)
	s_barrier
	s_waitcnt lgkmcnt(0)
	s_setprio 1
	v_mfma_f32_16x16x32_bf16 v[64:67], v[8:11], v[0:3], v[124:127]
	v_mfma_f32_16x16x32_bf16 v[92:95], v[12:15], v[4:7], v[64:67]
	v_mfma_f32_16x16x32_bf16 v[64:67], v[8:11], v[210:213], v[120:123]
	v_mfma_f32_16x16x32_bf16 v[100:103], v[12:15], v[138:141], v[64:67]
	v_mfma_f32_16x16x32_bf16 v[64:67], v[16:19], v[0:3], v[116:119]
	v_mfma_f32_16x16x32_bf16 v[80:83], v[20:23], v[4:7], v[64:67]
	v_mfma_f32_16x16x32_bf16 v[64:67], v[16:19], v[210:213], v[112:115]
	v_mfma_f32_16x16x32_bf16 v[84:87], v[20:23], v[138:141], v[64:67]
	v_mfma_f32_16x16x32_bf16 v[64:67], v[24:27], v[0:3], v[108:111]
	v_mfma_f32_16x16x32_bf16 v[72:75], v[28:31], v[4:7], v[64:67]
	v_mfma_f32_16x16x32_bf16 v[64:67], v[24:27], v[210:213], v[104:107]
	v_mfma_f32_16x16x32_bf16 v[76:79], v[28:31], v[138:141], v[64:67]
	v_mfma_f32_16x16x32_bf16 v[64:67], v[222:225], v[0:3], v[128:131]
	v_mfma_f32_16x16x32_bf16 v[68:71], v[222:225], v[210:213], v[96:99]
	v_mfma_f32_16x16x32_bf16 v[64:67], v[230:233], v[4:7], v[64:67]
	v_mfma_f32_16x16x32_bf16 v[68:71], v[230:233], v[138:141], v[68:71]
	s_setprio 0
	s_barrier
; #define LDA(dst, b, h)                                                                                    \
;   _Pragma("unroll") for (int m = 0; m < 4; ++m) _Pragma("unroll") for (int k = 0; k < 2; ++k)             \
;       dst[m][k] = *reinterpret_cast<const bf16x8*>((char*)SA(b, h) + lds_byte(wr * 64 + m * 16 + fr, k * 32 + fq * 8))
; #define LDB(dst, b, h)                                                                                    \
;   _Pragma("unroll") for (int n = 0; n < 2; ++n) _Pragma("unroll") for (int k = 0; k < 2; ++k)             \
;       dst[n][k] = *reinterpret_cast<const bf16x8*>((char*)SB(b, h) + lds_byte(wc * 32 + n * 16 + fr, k * 32 + fq * 8))
; #define WAIT_V(n) asm volatile("s_waitcnt vmcnt(" #n ")" ::: "memory")
; #define WAIT_L(n) asm volatile("s_waitcnt lgkmcnt(" #n ")" ::: "memory")
; #define BAR __builtin_amdgcn_s_barrier()
; template <int EPI> ...
;     ...
;     LDB(B1, 1, 1); WAIT_V(0); BAR; WAIT_L(0); MMA(0, 1, At, B1); BAR;
;     LDA(At, 1, 1); BAR; WAIT_L(0); MMA(1, 0, At, B0); MMA(1, 1, At, B1); BAR;
;   }
;   if (wr == 0) BAR;
	ds_read_b128 v[128:131], v137
	ds_read_b128 v[234:237], v137 offset:1024
	ds_read_b128 v[238:241], v137 offset:2048
	ds_read_b128 v[242:245], v137 offset:3072
	s_waitcnt vmcnt(0)
	s_barrier
	s_waitcnt lgkmcnt(0)
	s_setprio 1
	v_mfma_f32_16x16x32_bf16 v[96:99], v[8:11], v[128:131], v[226:229]
	v_mfma_f32_16x16x32_bf16 v[8:11], v[8:11], v[238:241], v[88:91]
	v_mfma_f32_16x16x32_bf16 v[124:127], v[12:15], v[242:245], v[8:11]
	v_mfma_f32_16x16x32_bf16 v[8:11], v[16:19], v[128:131], v[186:189]
	v_mfma_f32_16x16x32_bf16 v[112:115], v[20:23], v[234:237], v[8:11]
	v_mfma_f32_16x16x32_bf16 v[8:11], v[16:19], v[238:241], v[190:193]
	v_mfma_f32_16x16x32_bf16 v[116:119], v[20:23], v[242:245], v[8:11]
	v_mfma_f32_16x16x32_bf16 v[8:11], v[24:27], v[128:131], v[194:197]
	v_mfma_f32_16x16x32_bf16 v[104:107], v[28:31], v[234:237], v[8:11]
	v_mfma_f32_16x16x32_bf16 v[8:11], v[24:27], v[238:241], v[198:201]
	v_mfma_f32_16x16x32_bf16 v[108:111], v[28:31], v[242:245], v[8:11]
	v_mfma_f32_16x16x32_bf16 v[8:11], v[222:225], v[128:131], v[202:205]
	v_mfma_f32_16x16x32_bf16 v[88:91], v[230:233], v[234:237], v[8:11]
	v_mfma_f32_16x16x32_bf16 v[8:11], v[222:225], v[238:241], v[206:209]
	v_mfma_f32_16x16x32_bf16 v[120:123], v[12:15], v[234:237], v[96:99]
	v_mfma_f32_16x16x32_bf16 v[96:99], v[230:233], v[242:245], v[8:11]
	s_setprio 0
	s_barrier
	ds_read_b128 v[186:189], v135 offset:49152
	ds_read_b128 v[134:137], v135 offset:50176
	ds_read_b128 v[190:193], v156 offset:49152
	ds_read_b128 v[194:197], v156 offset:50176
	ds_read_b128 v[198:201], v157 offset:49152
	ds_read_b128 v[202:205], v157 offset:50176
	ds_read_b128 v[206:209], v158 offset:49152
	ds_read_b128 v[156:159], v158 offset:50176
	s_barrier
	s_waitcnt lgkmcnt(0)
	s_setprio 1
	v_mfma_f32_16x16x32_bf16 v[8:11], v[186:189], v[0:3], v[60:63]
	v_mfma_f32_16x16x32_bf16 v[24:27], v[134:137], v[4:7], v[8:11]
	v_mfma_f32_16x16x32_bf16 v[8:11], v[186:189], v[210:213], v[56:59]
	v_mfma_f32_16x16x32_bf16 v[28:31], v[134:137], v[138:141], v[8:11]
	v_mfma_f32_16x16x32_bf16 v[8:11], v[190:193], v[0:3], v[52:55]
	v_mfma_f32_16x16x32_bf16 v[16:19], v[194:197], v[4:7], v[8:11]
	v_mfma_f32_16x16x32_bf16 v[8:11], v[190:193], v[210:213], v[48:51]
	v_mfma_f32_16x16x32_bf16 v[20:23], v[194:197], v[138:141], v[8:11]
	v_mfma_f32_16x16x32_bf16 v[8:11], v[198:201], v[0:3], v[44:47]
	v_mfma_f32_16x16x32_bf16 v[0:3], v[206:209], v[0:3], v[36:39]
	v_mfma_f32_16x16x32_bf16 v[8:11], v[202:205], v[4:7], v[8:11]
	v_mfma_f32_16x16x32_bf16 v[12:15], v[198:201], v[210:213], v[40:43]
	v_mfma_f32_16x16x32_bf16 v[0:3], v[156:159], v[4:7], v[0:3]
	v_mfma_f32_16x16x32_bf16 v[4:7], v[206:209], v[210:213], v[32:35]
	v_mfma_f32_16x16x32_bf16 v[12:15], v[202:205], v[138:141], v[12:15]
	v_mfma_f32_16x16x32_bf16 v[4:7], v[156:159], v[138:141], v[4:7]
	s_setprio 0
	s_setprio 1
	v_mfma_f32_16x16x32_bf16 v[32:35], v[186:189], v[128:131], v[142:145]
	v_mfma_f32_16x16x32_bf16 v[56:59], v[134:137], v[234:237], v[32:35]
	v_mfma_f32_16x16x32_bf16 v[32:35], v[186:189], v[238:241], v[160:163]
	v_mfma_f32_16x16x32_bf16 v[60:63], v[134:137], v[242:245], v[32:35]
	v_mfma_f32_16x16x32_bf16 v[32:35], v[190:193], v[128:131], v[164:167]
	v_mfma_f32_16x16x32_bf16 v[48:51], v[194:197], v[234:237], v[32:35]
	v_mfma_f32_16x16x32_bf16 v[32:35], v[190:193], v[238:241], v[178:181]
	v_mfma_f32_16x16x32_bf16 v[52:55], v[194:197], v[242:245], v[32:35]
	v_mfma_f32_16x16x32_bf16 v[32:35], v[198:201], v[128:131], v[182:185]
	v_mfma_f32_16x16x32_bf16 v[40:43], v[202:205], v[234:237], v[32:35]
	v_mfma_f32_16x16x32_bf16 v[32:35], v[198:201], v[238:241], v[214:217]
	v_mfma_f32_16x16x32_bf16 v[44:47], v[202:205], v[242:245], v[32:35]
	v_mfma_f32_16x16x32_bf16 v[32:35], v[206:209], v[128:131], v[218:221]
	v_mfma_f32_16x16x32_bf16 v[36:39], v[206:209], v[238:241], v[152:155]
	v_mfma_f32_16x16x32_bf16 v[32:35], v[156:159], v[234:237], v[32:35]
	v_mfma_f32_16x16x32_bf16 v[36:39], v[156:159], v[242:245], v[36:39]
	s_setprio 0
	s_cmpk_gt_u32 s62, 0xff
	s_barrier
	s_cbranch_scc1 .LBB0_169
	s_barrier

; #define LDA(dst, b, h)                                                                                    \
;   _Pragma("unroll") for (int m = 0; m < 4; ++m) _Pragma("unroll") for (int k = 0; k < 2; ++k)             \
;       dst[m][k] = *reinterpret_cast<const bf16x8*>((char*)SA(b, h) + lds_byte(wr * 64 + m * 16 + fr, k * 32 + fq * 8))
; #define LDB(dst, b, h)                                                                                    \
;   _Pragma("unroll") for (int n = 0; n < 2; ++n) _Pragma("unroll") for (int k = 0; k < 2; ++k)             \
;       dst[n][k] = *reinterpret_cast<const bf16x8*>((char*)SB(b, h) + lds_byte(wc * 32 + n * 16 + fr, k * 32 + fq * 8))
; #define WAIT_V(n) asm volatile("s_waitcnt vmcnt(" #n ")" ::: "memory")
; #define WAIT_L(n) asm volatile("s_waitcnt lgkmcnt(" #n ")" ::: "memory")
; #define BAR __builtin_amdgcn_s_barrier()
; #define SCHED __builtin_amdgcn_sched_barrier(0)
; template <int EPI> ...
;     ...
;     LDB(B0, 0, 0); SCHED; LDA(At, 0, 0); STAGE(SA(1, 1), A, brow + HALF, t + 1);
;     WAIT_L(8); BAR; WAIT_L(0); MMA(0, 0, At, B0); BAR; SCHED;
;     LDB(B1, 0, 1); STAGE(SB(0, 0), Bt, bcol, t + 2);
;     BAR; WAIT_L(0); MMA(0, 1, At, B1); BAR;
;     LDA(At, 0, 1); STAGE(SA(0, 0), A, brow, t + 2);
;     BAR; WAIT_L(0); MMA(1, 0, At, B0); BAR; SCHED;
;     STAGE(SB(0, 1), Bt, bcol + HALF, t + 2);
;     WAIT_V(6); BAR; MMA(1, 1, At, B1); BAR;
.LBB0_416:
	ds_read_b128 v[162:165], v155
	ds_read_b128 v[178:181], v155 offset:1024
	ds_read_b128 v[182:185], v155 offset:2048
	ds_read_b128 v[186:189], v155 offset:3072
	s_add_u32 s14, s8, s12
	v_add_u32_e32 v156, s64, v154
	v_add_u32_e32 v157, s65, v154
	v_add_u32_e32 v158, s66, v154
	s_addc_u32 s15, s9, s13
	ds_read_b128 v[190:193], v135
	ds_read_b128 v[194:197], v135 offset:1024
	ds_read_b128 v[198:201], v156
	ds_read_b128 v[202:205], v156 offset:1024
	ds_read_b128 v[206:209], v157
	ds_read_b128 v[210:213], v157 offset:1024
	ds_read_b128 v[214:217], v158
	ds_read_b128 v[218:221], v158 offset:1024
	v_add_u32_e32 v159, 0xe000, v129
	v_add_u32_e32 v160, 0xc000, v129
	s_add_u32 m0, s32, 0xc000
	s_add_u32 s98, s14, 0x40080
	s_addc_u32 s99, s15, 0
	global_load_lds_dwordx4 v253, s[98:99]
	s_add_u32 m0, s32, 0xe000
	s_nop 0
	global_load_lds_dwordx4 v252, s[98:99]
	s_waitcnt lgkmcnt(8)
	s_barrier
	s_waitcnt lgkmcnt(0)
	s_setprio 1
	v_mfma_f32_16x16x32_bf16 v[124:127], v[190:193], v[162:165], v[124:127]
	v_mfma_f32_16x16x32_bf16 v[120:123], v[190:193], v[182:185], v[120:123]
	v_mfma_f32_16x16x32_bf16 v[116:119], v[198:201], v[162:165], v[116:119]
	v_mfma_f32_16x16x32_bf16 v[112:115], v[198:201], v[182:185], v[112:115]
	v_mfma_f32_16x16x32_bf16 v[108:111], v[206:209], v[162:165], v[108:111]
	v_mfma_f32_16x16x32_bf16 v[104:107], v[206:209], v[182:185], v[104:107]
	v_mfma_f32_16x16x32_bf16 v[100:103], v[214:217], v[162:165], v[100:103]
	v_mfma_f32_16x16x32_bf16 v[96:99], v[214:217], v[182:185], v[96:99]
	v_mfma_f32_16x16x32_bf16 v[124:127], v[194:197], v[178:181], v[124:127]
	v_mfma_f32_16x16x32_bf16 v[120:123], v[194:197], v[186:189], v[120:123]
	v_mfma_f32_16x16x32_bf16 v[116:119], v[202:205], v[178:181], v[116:119]
	v_mfma_f32_16x16x32_bf16 v[112:115], v[202:205], v[186:189], v[112:115]
	v_mfma_f32_16x16x32_bf16 v[108:111], v[210:213], v[178:181], v[108:111]
	v_mfma_f32_16x16x32_bf16 v[104:107], v[210:213], v[186:189], v[104:107]
	v_mfma_f32_16x16x32_bf16 v[100:103], v[218:221], v[178:181], v[100:103]
	v_mfma_f32_16x16x32_bf16 v[96:99], v[218:221], v[186:189], v[96:99]
	s_setprio 0
	s_barrier
	s_add_u32 s34, s6, s12
	s_addc_u32 s35, s7, s13
	ds_read_b128 v[222:225], v152
	ds_read_b128 v[226:229], v152 offset:1024
	ds_read_b128 v[230:233], v152 offset:2048
	ds_read_b128 v[234:237], v152 offset:3072
	s_add_u32 m0, s32, 0x10000
	s_add_u32 s98, s34, 0x100
	s_addc_u32 s99, s35, 0
	global_load_lds_dwordx4 v253, s[98:99]
	s_add_u32 m0, s32, 0x12000
	s_nop 0
	global_load_lds_dwordx4 v252, s[98:99]
	s_barrier
	s_waitcnt lgkmcnt(0)
	s_setprio 1
	v_mfma_f32_16x16x32_bf16 v[92:95], v[190:193], v[222:225], v[92:95]
	v_mfma_f32_16x16x32_bf16 v[88:91], v[190:193], v[230:233], v[88:91]
	v_mfma_f32_16x16x32_bf16 v[84:87], v[198:201], v[222:225], v[84:87]
	v_mfma_f32_16x16x32_bf16 v[80:83], v[198:201], v[230:233], v[80:83]
	v_mfma_f32_16x16x32_bf16 v[76:79], v[206:209], v[222:225], v[76:79]
	v_mfma_f32_16x16x32_bf16 v[72:75], v[206:209], v[230:233], v[72:75]
	v_mfma_f32_16x16x32_bf16 v[68:71], v[214:217], v[222:225], v[68:71]
	v_mfma_f32_16x16x32_bf16 v[64:67], v[214:217], v[230:233], v[64:67]
	v_mfma_f32_16x16x32_bf16 v[92:95], v[194:197], v[226:229], v[92:95]
	v_mfma_f32_16x16x32_bf16 v[88:91], v[194:197], v[234:237], v[88:91]
	v_mfma_f32_16x16x32_bf16 v[84:87], v[202:205], v[226:229], v[84:87]
	v_mfma_f32_16x16x32_bf16 v[80:83], v[202:205], v[234:237], v[80:83]
	v_mfma_f32_16x16x32_bf16 v[76:79], v[210:213], v[226:229], v[76:79]
	v_mfma_f32_16x16x32_bf16 v[72:75], v[210:213], v[234:237], v[72:75]
	v_mfma_f32_16x16x32_bf16 v[68:71], v[218:221], v[226:229], v[68:71]
	v_mfma_f32_16x16x32_bf16 v[64:67], v[218:221], v[234:237], v[64:67]
	s_setprio 0
	s_barrier
	ds_read_b128 v[190:193], v135 offset:16384
	ds_read_b128 v[194:197], v135 offset:17408
	ds_read_b128 v[198:201], v156 offset:16384
	ds_read_b128 v[202:205], v156 offset:17408
	ds_read_b128 v[206:209], v157 offset:16384
	ds_read_b128 v[210:213], v157 offset:17408
	ds_read_b128 v[214:217], v158 offset:16384
	ds_read_b128 v[218:221], v158 offset:17408
	s_mov_b32 m0, s32
	s_add_u32 s98, s14, 0x100
	s_addc_u32 s99, s15, 0
	global_load_lds_dwordx4 v253, s[98:99]
	s_add_u32 m0, s32, 0x2000
	s_nop 0
	global_load_lds_dwordx4 v252, s[98:99]
	s_barrier
	s_waitcnt lgkmcnt(0)
	s_setprio 1
	v_mfma_f32_16x16x32_bf16 v[60:63], v[190:193], v[162:165], v[60:63]
	v_mfma_f32_16x16x32_bf16 v[56:59], v[190:193], v[182:185], v[56:59]
	v_mfma_f32_16x16x32_bf16 v[52:55], v[198:201], v[162:165], v[52:55]
	v_mfma_f32_16x16x32_bf16 v[48:51], v[198:201], v[182:185], v[48:51]
	v_mfma_f32_16x16x32_bf16 v[44:47], v[206:209], v[162:165], v[44:47]
	v_mfma_f32_16x16x32_bf16 v[40:43], v[206:209], v[182:185], v[40:43]
	v_mfma_f32_16x16x32_bf16 v[36:39], v[214:217], v[162:165], v[36:39]
	v_mfma_f32_16x16x32_bf16 v[32:35], v[214:217], v[182:185], v[32:35]
	v_mfma_f32_16x16x32_bf16 v[60:63], v[194:197], v[178:181], v[60:63]
	v_mfma_f32_16x16x32_bf16 v[56:59], v[194:197], v[186:189], v[56:59]
	v_mfma_f32_16x16x32_bf16 v[52:55], v[202:205], v[178:181], v[52:55]
	v_mfma_f32_16x16x32_bf16 v[48:51], v[202:205], v[186:189], v[48:51]
	v_mfma_f32_16x16x32_bf16 v[44:47], v[210:213], v[178:181], v[44:47]
	v_mfma_f32_16x16x32_bf16 v[40:43], v[210:213], v[186:189], v[40:43]
	v_mfma_f32_16x16x32_bf16 v[36:39], v[218:221], v[178:181], v[36:39]
	v_mfma_f32_16x16x32_bf16 v[32:35], v[218:221], v[186:189], v[32:35]
	s_setprio 0
	s_barrier
	s_add_u32 m0, s32, 0x14000
	s_add_u32 s98, s34, 0x40100
	s_addc_u32 s99, s35, 0
	global_load_lds_dwordx4 v253, s[98:99]
	s_add_u32 m0, s32, 0x16000
	s_nop 0
	global_load_lds_dwordx4 v252, s[98:99]
	s_waitcnt vmcnt(6)
	s_barrier
; #define LDA(dst, b, h)                                                                                    \
;   _Pragma("unroll") for (int m = 0; m < 4; ++m) _Pragma("unroll") for (int k = 0; k < 2; ++k)             \
;       dst[m][k] = *reinterpret_cast<const bf16x8*>((char*)SA(b, h) + lds_byte(wr * 64 + m * 16 + fr, k * 32 + fq * 8))
; #define LDB(dst, b, h)                                                                                    \
;   _Pragma("unroll") for (int n = 0; n < 2; ++n) _Pragma("unroll") for (int k = 0; k < 2; ++k)             \
;       dst[n][k] = *reinterpret_cast<const bf16x8*>((char*)SB(b, h) + lds_byte(wc * 32 + n * 16 + fr, k * 32 + fq * 8))
; #define WAIT_V(n) asm volatile("s_waitcnt vmcnt(" #n ")" ::: "memory")
; #define WAIT_L(n) asm volatile("s_waitcnt lgkmcnt(" #n ")" ::: "memory")
; #define BAR __builtin_amdgcn_s_barrier()
; #define SCHED __builtin_amdgcn_sched_barrier(0)
; template <int EPI> ...
;     ...
;     WAIT_V(6); BAR; MMA(1, 1, At, B1); BAR;
;     LDB(B0, 1, 0); SCHED; LDA(At, 1, 0); STAGE(SA(0, 1), A, brow + HALF, t + 2);
;     WAIT_L(8); BAR; WAIT_L(0); MMA(0, 0, At, B0); BAR; SCHED;
;     LDB(B1, 1, 1); STAGE(SB(1, 0), Bt, bcol, t + 3);
;     BAR; WAIT_L(0); MMA(0, 1, At, B1); BAR;
;     LDA(At, 1, 1); STAGE(SA(1, 0), A, brow, t + 3);
;     BAR; WAIT_L(0); MMA(1, 0, At, B0); BAR; SCHED;
	s_setprio 1
	v_mfma_f32_16x16x32_bf16 v[28:31], v[190:193], v[222:225], v[28:31]
	v_mfma_f32_16x16x32_bf16 v[24:27], v[190:193], v[230:233], v[24:27]
	v_mfma_f32_16x16x32_bf16 v[20:23], v[198:201], v[222:225], v[20:23]
	v_mfma_f32_16x16x32_bf16 v[16:19], v[198:201], v[230:233], v[16:19]
	v_mfma_f32_16x16x32_bf16 v[12:15], v[206:209], v[222:225], v[12:15]
	v_mfma_f32_16x16x32_bf16 v[8:11], v[206:209], v[230:233], v[8:11]
	v_mfma_f32_16x16x32_bf16 v[4:7], v[214:217], v[222:225], v[4:7]
	v_mfma_f32_16x16x32_bf16 v[0:3], v[214:217], v[230:233], v[0:3]
	v_mfma_f32_16x16x32_bf16 v[28:31], v[194:197], v[226:229], v[28:31]
	v_mfma_f32_16x16x32_bf16 v[24:27], v[194:197], v[234:237], v[24:27]
	v_mfma_f32_16x16x32_bf16 v[20:23], v[202:205], v[226:229], v[20:23]
	v_mfma_f32_16x16x32_bf16 v[16:19], v[202:205], v[234:237], v[16:19]
	v_mfma_f32_16x16x32_bf16 v[12:15], v[210:213], v[226:229], v[12:15]
	v_mfma_f32_16x16x32_bf16 v[8:11], v[210:213], v[234:237], v[8:11]
	v_mfma_f32_16x16x32_bf16 v[4:7], v[218:221], v[226:229], v[4:7]
	v_mfma_f32_16x16x32_bf16 v[0:3], v[218:221], v[234:237], v[0:3]
	s_setprio 0
	s_barrier
	ds_read_b128 v[162:165], v140
	ds_read_b128 v[178:181], v140 offset:1024
	ds_read_b128 v[182:185], v140 offset:2048
	ds_read_b128 v[186:189], v140 offset:3072
	ds_read_b128 v[190:193], v135 offset:32768
	ds_read_b128 v[194:197], v135 offset:33792
	ds_read_b128 v[198:201], v156 offset:32768
	ds_read_b128 v[202:205], v156 offset:33792
	ds_read_b128 v[206:209], v157 offset:32768
	ds_read_b128 v[210:213], v157 offset:33792
	ds_read_b128 v[214:217], v158 offset:32768
	ds_read_b128 v[218:221], v158 offset:33792
	s_add_u32 m0, s32, 0x4000
	s_add_u32 s98, s14, 0x40100
	s_addc_u32 s99, s15, 0
	global_load_lds_dwordx4 v253, s[98:99]
	s_add_u32 m0, s32, 0x6000
	s_nop 0
	global_load_lds_dwordx4 v252, s[98:99]
	s_waitcnt lgkmcnt(8)
	s_barrier
	s_waitcnt lgkmcnt(0)
	s_setprio 1
	v_mfma_f32_16x16x32_bf16 v[124:127], v[190:193], v[162:165], v[124:127]
	v_mfma_f32_16x16x32_bf16 v[120:123], v[190:193], v[182:185], v[120:123]
	v_mfma_f32_16x16x32_bf16 v[116:119], v[198:201], v[162:165], v[116:119]
	v_mfma_f32_16x16x32_bf16 v[112:115], v[198:201], v[182:185], v[112:115]
	v_mfma_f32_16x16x32_bf16 v[108:111], v[206:209], v[162:165], v[108:111]
	v_mfma_f32_16x16x32_bf16 v[104:107], v[206:209], v[182:185], v[104:107]
	v_mfma_f32_16x16x32_bf16 v[100:103], v[214:217], v[162:165], v[100:103]
	v_mfma_f32_16x16x32_bf16 v[96:99], v[214:217], v[182:185], v[96:99]
	v_mfma_f32_16x16x32_bf16 v[124:127], v[194:197], v[178:181], v[124:127]
	v_mfma_f32_16x16x32_bf16 v[120:123], v[194:197], v[186:189], v[120:123]
	v_mfma_f32_16x16x32_bf16 v[116:119], v[202:205], v[178:181], v[116:119]
	v_mfma_f32_16x16x32_bf16 v[112:115], v[202:205], v[186:189], v[112:115]
	v_mfma_f32_16x16x32_bf16 v[108:111], v[210:213], v[178:181], v[108:111]
	v_mfma_f32_16x16x32_bf16 v[104:107], v[210:213], v[186:189], v[104:107]
	v_mfma_f32_16x16x32_bf16 v[100:103], v[218:221], v[178:181], v[100:103]
	v_mfma_f32_16x16x32_bf16 v[96:99], v[218:221], v[186:189], v[96:99]
	s_setprio 0
	s_barrier
	ds_read_b128 v[222:225], v137
	ds_read_b128 v[226:229], v137 offset:1024
	ds_read_b128 v[230:233], v137 offset:2048
	ds_read_b128 v[234:237], v137 offset:3072
	s_add_u32 m0, s32, 0x18000
	s_add_u32 s98, s34, 0x180
	s_addc_u32 s99, s35, 0
	global_load_lds_dwordx4 v253, s[98:99]
	s_add_u32 m0, s32, 0x1a000
	s_nop 0
	global_load_lds_dwordx4 v252, s[98:99]
	s_barrier
	s_waitcnt lgkmcnt(0)
	s_setprio 1
	v_mfma_f32_16x16x32_bf16 v[92:95], v[190:193], v[222:225], v[92:95]
	v_mfma_f32_16x16x32_bf16 v[88:91], v[190:193], v[230:233], v[88:91]
	v_mfma_f32_16x16x32_bf16 v[84:87], v[198:201], v[222:225], v[84:87]
	v_mfma_f32_16x16x32_bf16 v[80:83], v[198:201], v[230:233], v[80:83]
	v_mfma_f32_16x16x32_bf16 v[76:79], v[206:209], v[222:225], v[76:79]
	v_mfma_f32_16x16x32_bf16 v[72:75], v[206:209], v[230:233], v[72:75]
	v_mfma_f32_16x16x32_bf16 v[68:71], v[214:217], v[222:225], v[68:71]
	v_mfma_f32_16x16x32_bf16 v[64:67], v[214:217], v[230:233], v[64:67]
	v_mfma_f32_16x16x32_bf16 v[92:95], v[194:197], v[226:229], v[92:95]
	v_mfma_f32_16x16x32_bf16 v[88:91], v[194:197], v[234:237], v[88:91]
	v_mfma_f32_16x16x32_bf16 v[84:87], v[202:205], v[226:229], v[84:87]
	v_mfma_f32_16x16x32_bf16 v[80:83], v[202:205], v[234:237], v[80:83]
	v_mfma_f32_16x16x32_bf16 v[76:79], v[210:213], v[226:229], v[76:79]
	v_mfma_f32_16x16x32_bf16 v[72:75], v[210:213], v[234:237], v[72:75]
	v_mfma_f32_16x16x32_bf16 v[68:71], v[218:221], v[226:229], v[68:71]
	v_mfma_f32_16x16x32_bf16 v[64:67], v[218:221], v[234:237], v[64:67]
	s_setprio 0
	s_barrier
	ds_read_b128 v[190:193], v135 offset:49152
	ds_read_b128 v[194:197], v135 offset:50176
	ds_read_b128 v[198:201], v156 offset:49152
	ds_read_b128 v[202:205], v156 offset:50176
	ds_read_b128 v[206:209], v157 offset:49152
	ds_read_b128 v[210:213], v157 offset:50176
	ds_read_b128 v[214:217], v158 offset:49152
	ds_read_b128 v[218:221], v158 offset:50176
	s_add_u32 m0, s32, 0x8000
	s_add_u32 s98, s14, 0x180
	s_addc_u32 s99, s15, 0
	global_load_lds_dwordx4 v253, s[98:99]
	s_nop 0
	s_add_u32 m0, s32, 0xa000
	s_nop 0
	global_load_lds_dwordx4 v252, s[98:99]
	s_barrier
; #define LDA(dst, b, h)                                                                                    \
;   _Pragma("unroll") for (int m = 0; m < 4; ++m) _Pragma("unroll") for (int k = 0; k < 2; ++k)             \
;       dst[m][k] = *reinterpret_cast<const bf16x8*>((char*)SA(b, h) + lds_byte(wr * 64 + m * 16 + fr, k * 32 + fq * 8))
; #define LDB(dst, b, h)                                                                                    \
;   _Pragma("unroll") for (int n = 0; n < 2; ++n) _Pragma("unroll") for (int k = 0; k < 2; ++k)             \
;       dst[n][k] = *reinterpret_cast<const bf16x8*>((char*)SB(b, h) + lds_byte(wc * 32 + n * 16 + fr, k * 32 + fq * 8))
; #define WAIT_V(n) asm volatile("s_waitcnt vmcnt(" #n ")" ::: "memory")
; #define WAIT_L(n) asm volatile("s_waitcnt lgkmcnt(" #n ")" ::: "memory")
; #define BAR __builtin_amdgcn_s_barrier()
; #define SCHED __builtin_amdgcn_sched_barrier(0)
; template <int EPI> ...
;     ...
;     BAR; WAIT_L(0); MMA(1, 0, At, B0); BAR; SCHED;
;     STAGE(SB(1, 1), Bt, bcol + HALF, t + 3);
;     WAIT_V(6); BAR; MMA(1, 1, At, B1); BAR;
;   }
;   {
;     LDB(B0, 0, 0); LDA(At, 0, 0); STAGE(SA(1, 1), A, brow + HALF, nt - 1);
;     BAR; WAIT_L(0); MMA(0, 0, At, B0); BAR;
;     LDB(B1, 0, 1); BAR; WAIT_L(0); MMA(0, 1, At, B1); BAR;
	s_waitcnt lgkmcnt(0)
	s_setprio 1
	v_mfma_f32_16x16x32_bf16 v[60:63], v[190:193], v[162:165], v[60:63]
	v_mfma_f32_16x16x32_bf16 v[56:59], v[190:193], v[182:185], v[56:59]
	v_mfma_f32_16x16x32_bf16 v[52:55], v[198:201], v[162:165], v[52:55]
	v_mfma_f32_16x16x32_bf16 v[48:51], v[198:201], v[182:185], v[48:51]
	v_mfma_f32_16x16x32_bf16 v[44:47], v[206:209], v[162:165], v[44:47]
	v_mfma_f32_16x16x32_bf16 v[40:43], v[206:209], v[182:185], v[40:43]
	v_mfma_f32_16x16x32_bf16 v[36:39], v[214:217], v[162:165], v[36:39]
	v_mfma_f32_16x16x32_bf16 v[32:35], v[214:217], v[182:185], v[32:35]
	v_mfma_f32_16x16x32_bf16 v[60:63], v[194:197], v[178:181], v[60:63]
	v_mfma_f32_16x16x32_bf16 v[56:59], v[194:197], v[186:189], v[56:59]
	v_mfma_f32_16x16x32_bf16 v[52:55], v[202:205], v[178:181], v[52:55]
	v_mfma_f32_16x16x32_bf16 v[48:51], v[202:205], v[186:189], v[48:51]
	v_mfma_f32_16x16x32_bf16 v[44:47], v[210:213], v[178:181], v[44:47]
	v_mfma_f32_16x16x32_bf16 v[40:43], v[210:213], v[186:189], v[40:43]
	v_mfma_f32_16x16x32_bf16 v[36:39], v[218:221], v[178:181], v[36:39]
	v_mfma_f32_16x16x32_bf16 v[32:35], v[218:221], v[186:189], v[32:35]
	s_setprio 0
	s_barrier
	s_add_u32 m0, s32, 0x1c000
	s_add_u32 s98, s34, 0x40180
	s_addc_u32 s99, s35, 0
	global_load_lds_dwordx4 v253, s[98:99]
	s_add_u32 m0, s32, 0x1e000
	s_nop 0
	global_load_lds_dwordx4 v252, s[98:99]
	s_waitcnt vmcnt(6)
	s_barrier
	s_setprio 1
	v_mfma_f32_16x16x32_bf16 v[28:31], v[190:193], v[222:225], v[28:31]
	v_mfma_f32_16x16x32_bf16 v[24:27], v[190:193], v[230:233], v[24:27]
	v_mfma_f32_16x16x32_bf16 v[20:23], v[198:201], v[222:225], v[20:23]
	v_mfma_f32_16x16x32_bf16 v[16:19], v[198:201], v[230:233], v[16:19]
	v_mfma_f32_16x16x32_bf16 v[12:15], v[206:209], v[222:225], v[12:15]
	v_mfma_f32_16x16x32_bf16 v[8:11], v[206:209], v[230:233], v[8:11]
	v_mfma_f32_16x16x32_bf16 v[4:7], v[214:217], v[222:225], v[4:7]
	v_mfma_f32_16x16x32_bf16 v[0:3], v[214:217], v[230:233], v[0:3]
	v_mfma_f32_16x16x32_bf16 v[28:31], v[194:197], v[226:229], v[28:31]
	v_mfma_f32_16x16x32_bf16 v[24:27], v[194:197], v[234:237], v[24:27]
	v_mfma_f32_16x16x32_bf16 v[20:23], v[202:205], v[226:229], v[20:23]
	v_mfma_f32_16x16x32_bf16 v[16:19], v[202:205], v[234:237], v[16:19]
	v_mfma_f32_16x16x32_bf16 v[12:15], v[210:213], v[226:229], v[12:15]
	v_mfma_f32_16x16x32_bf16 v[8:11], v[210:213], v[234:237], v[8:11]
	v_mfma_f32_16x16x32_bf16 v[4:7], v[218:221], v[226:229], v[4:7]
	v_mfma_f32_16x16x32_bf16 v[0:3], v[218:221], v[234:237], v[0:3]
	s_setprio 0
	s_add_i32 s67, s67, 2
	s_add_u32 s12, s12, 0x100
	s_addc_u32 s13, s13, 0
	s_cmp_lt_u32 s67, 12
	s_barrier
	s_cbranch_scc1 .LBB0_416
	ds_read_b128 v[142:145], v155
	ds_read_b128 v[162:165], v155 offset:1024
	ds_read_b128 v[178:181], v155 offset:2048
	ds_read_b128 v[182:185], v155 offset:3072
	ds_read_b128 v[186:189], v135
	ds_read_b128 v[190:193], v135 offset:1024
	ds_read_b128 v[194:197], v156
	ds_read_b128 v[198:201], v156 offset:1024
	ds_read_b128 v[202:205], v157
	ds_read_b128 v[206:209], v157 offset:1024
	ds_read_b128 v[210:213], v158
	ds_read_b128 v[214:217], v158 offset:1024
	v_mov_b32_e32 v129, v149
	v_lshl_add_u64 v[128:129], v[128:129], 1, s[10:11]
	s_mov_b64 s[8:9], 0x780
	v_readfirstlane_b32 s6, v160
	v_lshl_add_u64 v[128:129], v[128:129], 0, s[8:9]
	s_mov_b32 m0, s6
	v_mov_b32_e32 v131, v149
	global_load_lds_dwordx4 v[128:129], off
	v_readfirstlane_b32 s6, v159
	v_lshl_add_u64 v[128:129], v[130:131], 1, s[10:11]
	v_lshl_add_u64 v[128:129], v[128:129], 0, s[8:9]
	s_mov_b32 m0, s6
	s_nop 0
	global_load_lds_dwordx4 v[128:129], off
	s_barrier
	s_waitcnt lgkmcnt(0)
	s_setprio 1
	v_mfma_f32_16x16x32_bf16 v[124:127], v[186:189], v[142:145], v[124:127]
	v_mfma_f32_16x16x32_bf16 v[120:123], v[186:189], v[178:181], v[120:123]
	v_mfma_f32_16x16x32_bf16 v[116:119], v[194:197], v[142:145], v[116:119]
	v_mfma_f32_16x16x32_bf16 v[112:115], v[194:197], v[178:181], v[112:115]
	v_mfma_f32_16x16x32_bf16 v[108:111], v[202:205], v[142:145], v[108:111]
	v_mfma_f32_16x16x32_bf16 v[104:107], v[202:205], v[178:181], v[104:107]
	v_mfma_f32_16x16x32_bf16 v[96:99], v[210:213], v[178:181], v[96:99]
	v_mfma_f32_16x16x32_bf16 v[124:127], v[190:193], v[162:165], v[124:127]
	v_mfma_f32_16x16x32_bf16 v[120:123], v[190:193], v[182:185], v[120:123]
	v_mfma_f32_16x16x32_bf16 v[116:119], v[198:201], v[162:165], v[116:119]
	v_mfma_f32_16x16x32_bf16 v[112:115], v[198:201], v[182:185], v[112:115]
	v_mfma_f32_16x16x32_bf16 v[108:111], v[206:209], v[162:165], v[108:111]
	v_mfma_f32_16x16x32_bf16 v[104:107], v[206:209], v[182:185], v[104:107]
	v_mfma_f32_16x16x32_bf16 v[100:103], v[210:213], v[142:145], v[100:103]
	v_mfma_f32_16x16x32_bf16 v[96:99], v[214:217], v[182:185], v[96:99]
	v_mfma_f32_16x16x32_bf16 v[128:131], v[214:217], v[162:165], v[100:103]
	s_setprio 0
	s_barrier
	s_nop 3
	ds_read_b128 v[100:103], v152
	ds_read_b128 v[218:221], v152 offset:1024
	ds_read_b128 v[222:225], v152 offset:2048
	ds_read_b128 v[152:155], v152 offset:3072
	s_barrier
	s_waitcnt lgkmcnt(0)
	s_setprio 1
	v_mfma_f32_16x16x32_bf16 v[88:91], v[186:189], v[222:225], v[88:91]
	v_mfma_f32_16x16x32_bf16 v[92:95], v[186:189], v[100:103], v[92:95]
	v_mfma_f32_16x16x32_bf16 v[88:91], v[190:193], v[152:155], v[88:91]
	v_mfma_f32_16x16x32_bf16 v[84:87], v[194:197], v[100:103], v[84:87]
	v_mfma_f32_16x16x32_bf16 v[80:83], v[194:197], v[222:225], v[80:83]
	v_mfma_f32_16x16x32_bf16 v[76:79], v[202:205], v[100:103], v[76:79]
	v_mfma_f32_16x16x32_bf16 v[72:75], v[202:205], v[222:225], v[72:75]
	v_mfma_f32_16x16x32_bf16 v[68:71], v[210:213], v[100:103], v[68:71]
	v_mfma_f32_16x16x32_bf16 v[64:67], v[210:213], v[222:225], v[64:67]
	v_mfma_f32_16x16x32_bf16 v[226:229], v[190:193], v[218:221], v[92:95]
	v_mfma_f32_16x16x32_bf16 v[186:189], v[198:201], v[218:221], v[84:87]
	v_mfma_f32_16x16x32_bf16 v[190:193], v[198:201], v[152:155], v[80:83]
	v_mfma_f32_16x16x32_bf16 v[194:197], v[206:209], v[218:221], v[76:79]
	v_mfma_f32_16x16x32_bf16 v[198:201], v[206:209], v[152:155], v[72:75]
	v_mfma_f32_16x16x32_bf16 v[202:205], v[214:217], v[218:221], v[68:71]
	v_mfma_f32_16x16x32_bf16 v[206:209], v[214:217], v[152:155], v[64:67]
	s_setprio 0
	s_barrier
; #define LDA(dst, b, h)                                                                                    \
;   _Pragma("unroll") for (int m = 0; m < 4; ++m) _Pragma("unroll") for (int k = 0; k < 2; ++k)             \
;       dst[m][k] = *reinterpret_cast<const bf16x8*>((char*)SA(b, h) + lds_byte(wr * 64 + m * 16 + fr, k * 32 + fq * 8))
; #define LDB(dst, b, h)                                                                                    \
;   _Pragma("unroll") for (int n = 0; n < 2; ++n) _Pragma("unroll") for (int k = 0; k < 2; ++k)             \
;       dst[n][k] = *reinterpret_cast<const bf16x8*>((char*)SB(b, h) + lds_byte(wc * 32 + n * 16 + fr, k * 32 + fq * 8))
; #define WAIT_V(n) asm volatile("s_waitcnt vmcnt(" #n ")" ::: "memory")
; #define WAIT_L(n) asm volatile("s_waitcnt lgkmcnt(" #n ")" ::: "memory")
; #define BAR __builtin_amdgcn_s_barrier()
; template <int EPI> ...
;     ...
;     LDA(At, 0, 1); WAIT_V(4); BAR; WAIT_L(0); MMA(1, 0, At, B0); MMA(1, 1, At, B1); BAR;
;   }
;   {
;     LDB(B0, 1, 0); LDA(At, 1, 0); WAIT_V(2); BAR; WAIT_L(0); MMA(0, 0, At, B0); BAR;
	s_nop 0
	ds_read_b128 v[64:67], v135 offset:16384
	ds_read_b128 v[68:71], v135 offset:17408
	ds_read_b128 v[72:75], v156 offset:16384
	ds_read_b128 v[76:79], v156 offset:17408
	ds_read_b128 v[80:83], v157 offset:16384
	ds_read_b128 v[84:87], v157 offset:17408
	ds_read_b128 v[92:95], v158 offset:16384
	ds_read_b128 v[210:213], v158 offset:17408
	s_waitcnt vmcnt(4)
	s_barrier
	s_waitcnt lgkmcnt(0)
	s_setprio 1
	v_mfma_f32_16x16x32_bf16 v[60:63], v[64:67], v[142:145], v[60:63]
	v_mfma_f32_16x16x32_bf16 v[56:59], v[64:67], v[178:181], v[56:59]
	v_mfma_f32_16x16x32_bf16 v[52:55], v[72:75], v[142:145], v[52:55]
	v_mfma_f32_16x16x32_bf16 v[48:51], v[72:75], v[178:181], v[48:51]
	v_mfma_f32_16x16x32_bf16 v[44:47], v[80:83], v[142:145], v[44:47]
	v_mfma_f32_16x16x32_bf16 v[40:43], v[80:83], v[178:181], v[40:43]
	v_mfma_f32_16x16x32_bf16 v[36:39], v[92:95], v[142:145], v[36:39]
	v_mfma_f32_16x16x32_bf16 v[32:35], v[92:95], v[178:181], v[32:35]
	v_mfma_f32_16x16x32_bf16 v[60:63], v[68:71], v[162:165], v[60:63]
	v_mfma_f32_16x16x32_bf16 v[56:59], v[68:71], v[182:185], v[56:59]
	v_mfma_f32_16x16x32_bf16 v[52:55], v[76:79], v[162:165], v[52:55]
	v_mfma_f32_16x16x32_bf16 v[48:51], v[76:79], v[182:185], v[48:51]
	v_mfma_f32_16x16x32_bf16 v[44:47], v[84:87], v[162:165], v[44:47]
	v_mfma_f32_16x16x32_bf16 v[40:43], v[84:87], v[182:185], v[40:43]
	v_mfma_f32_16x16x32_bf16 v[36:39], v[210:213], v[162:165], v[36:39]
	v_mfma_f32_16x16x32_bf16 v[32:35], v[210:213], v[182:185], v[32:35]
	s_setprio 0
	s_setprio 1
	v_mfma_f32_16x16x32_bf16 v[28:31], v[64:67], v[100:103], v[28:31]
	v_mfma_f32_16x16x32_bf16 v[24:27], v[64:67], v[222:225], v[24:27]
	v_mfma_f32_16x16x32_bf16 v[20:23], v[72:75], v[100:103], v[20:23]
	v_mfma_f32_16x16x32_bf16 v[16:19], v[72:75], v[222:225], v[16:19]
	v_mfma_f32_16x16x32_bf16 v[12:15], v[80:83], v[100:103], v[12:15]
	v_mfma_f32_16x16x32_bf16 v[8:11], v[80:83], v[222:225], v[8:11]
	v_mfma_f32_16x16x32_bf16 v[4:7], v[92:95], v[100:103], v[4:7]
	v_mfma_f32_16x16x32_bf16 v[0:3], v[92:95], v[222:225], v[0:3]
	v_mfma_f32_16x16x32_bf16 v[142:145], v[68:71], v[218:221], v[28:31]
	v_mfma_f32_16x16x32_bf16 v[160:163], v[68:71], v[152:155], v[24:27]
	v_mfma_f32_16x16x32_bf16 v[164:167], v[76:79], v[218:221], v[20:23]
	v_mfma_f32_16x16x32_bf16 v[178:181], v[76:79], v[152:155], v[16:19]
	v_mfma_f32_16x16x32_bf16 v[182:185], v[84:87], v[218:221], v[12:15]
	v_mfma_f32_16x16x32_bf16 v[214:217], v[84:87], v[152:155], v[8:11]
	v_mfma_f32_16x16x32_bf16 v[218:221], v[210:213], v[218:221], v[4:7]
	v_mfma_f32_16x16x32_bf16 v[152:155], v[210:213], v[152:155], v[0:3]
	s_setprio 0
	s_barrier
	s_nop 0
	ds_read_b128 v[0:3], v140
	ds_read_b128 v[4:7], v140 offset:1024
	ds_read_b128 v[210:213], v140 offset:2048
	ds_read_b128 v[138:141], v140 offset:3072
	ds_read_b128 v[8:11], v135 offset:32768
	ds_read_b128 v[12:15], v135 offset:33792
	ds_read_b128 v[16:19], v156 offset:32768
	ds_read_b128 v[20:23], v156 offset:33792
	ds_read_b128 v[24:27], v157 offset:32768
	ds_read_b128 v[28:31], v157 offset:33792
	ds_read_b128 v[222:225], v158 offset:32768
	ds_read_b128 v[230:233], v158 offset:33792
	s_waitcnt vmcnt(2)
	s_barrier
	s_waitcnt lgkmcnt(0)
	s_setprio 1
	v_mfma_f32_16x16x32_bf16 v[64:67], v[8:11], v[0:3], v[124:127]
	v_mfma_f32_16x16x32_bf16 v[92:95], v[12:15], v[4:7], v[64:67]
	v_mfma_f32_16x16x32_bf16 v[64:67], v[8:11], v[210:213], v[120:123]
	v_mfma_f32_16x16x32_bf16 v[100:103], v[12:15], v[138:141], v[64:67]
	v_mfma_f32_16x16x32_bf16 v[64:67], v[16:19], v[0:3], v[116:119]
	v_mfma_f32_16x16x32_bf16 v[80:83], v[20:23], v[4:7], v[64:67]
	v_mfma_f32_16x16x32_bf16 v[64:67], v[16:19], v[210:213], v[112:115]
	v_mfma_f32_16x16x32_bf16 v[84:87], v[20:23], v[138:141], v[64:67]
	v_mfma_f32_16x16x32_bf16 v[64:67], v[24:27], v[0:3], v[108:111]
	v_mfma_f32_16x16x32_bf16 v[72:75], v[28:31], v[4:7], v[64:67]
	v_mfma_f32_16x16x32_bf16 v[64:67], v[24:27], v[210:213], v[104:107]
	v_mfma_f32_16x16x32_bf16 v[76:79], v[28:31], v[138:141], v[64:67]
	v_mfma_f32_16x16x32_bf16 v[64:67], v[222:225], v[0:3], v[128:131]
	v_mfma_f32_16x16x32_bf16 v[68:71], v[222:225], v[210:213], v[96:99]
	v_mfma_f32_16x16x32_bf16 v[64:67], v[230:233], v[4:7], v[64:67]
	v_mfma_f32_16x16x32_bf16 v[68:71], v[230:233], v[138:141], v[68:71]
	s_setprio 0
	s_barrier
; #define LDA(dst, b, h)                                                                                    \
;   _Pragma("unroll") for (int m = 0; m < 4; ++m) _Pragma("unroll") for (int k = 0; k < 2; ++k)             \
;       dst[m][k] = *reinterpret_cast<const bf16x8*>((char*)SA(b, h) + lds_byte(wr * 64 + m * 16 + fr, k * 32 + fq * 8))
; #define LDB(dst, b, h)                                                                                    \
;   _Pragma("unroll") for (int n = 0; n < 2; ++n) _Pragma("unroll") for (int k = 0; k < 2; ++k)             \
;       dst[n][k] = *reinterpret_cast<const bf16x8*>((char*)SB(b, h) + lds_byte(wc * 32 + n * 16 + fr, k * 32 + fq * 8))
; #define WAIT_V(n) asm volatile("s_waitcnt vmcnt(" #n ")" ::: "memory")
; #define WAIT_L(n) asm volatile("s_waitcnt lgkmcnt(" #n ")" ::: "memory")
; #define BAR __builtin_amdgcn_s_barrier()
; template <int EPI> ...
;     ...
;     LDB(B1, 1, 1); WAIT_V(0); BAR; WAIT_L(0); MMA(0, 1, At, B1); BAR;
;     LDA(At, 1, 1); BAR; WAIT_L(0); MMA(1, 0, At, B0); MMA(1, 1, At, B1); BAR;
;   }
;   if (wr == 0) BAR;
	ds_read_b128 v[128:131], v137
	ds_read_b128 v[234:237], v137 offset:1024
	ds_read_b128 v[238:241], v137 offset:2048
	ds_read_b128 v[242:245], v137 offset:3072
	s_waitcnt vmcnt(0)
	s_barrier
	s_waitcnt lgkmcnt(0)
	s_setprio 1
	v_mfma_f32_16x16x32_bf16 v[96:99], v[8:11], v[128:131], v[226:229]
	v_mfma_f32_16x16x32_bf16 v[8:11], v[8:11], v[238:241], v[88:91]
	v_mfma_f32_16x16x32_bf16 v[124:127], v[12:15], v[242:245], v[8:11]
	v_mfma_f32_16x16x32_bf16 v[8:11], v[16:19], v[128:131], v[186:189]
	v_mfma_f32_16x16x32_bf16 v[112:115], v[20:23], v[234:237], v[8:11]
	v_mfma_f32_16x16x32_bf16 v[8:11], v[16:19], v[238:241], v[190:193]
	v_mfma_f32_16x16x32_bf16 v[116:119], v[20:23], v[242:245], v[8:11]
	v_mfma_f32_16x16x32_bf16 v[8:11], v[24:27], v[128:131], v[194:197]
	v_mfma_f32_16x16x32_bf16 v[104:107], v[28:31], v[234:237], v[8:11]
	v_mfma_f32_16x16x32_bf16 v[8:11], v[24:27], v[238:241], v[198:201]
	v_mfma_f32_16x16x32_bf16 v[108:111], v[28:31], v[242:245], v[8:11]
	v_mfma_f32_16x16x32_bf16 v[8:11], v[222:225], v[128:131], v[202:205]
	v_mfma_f32_16x16x32_bf16 v[88:91], v[230:233], v[234:237], v[8:11]
	v_mfma_f32_16x16x32_bf16 v[8:11], v[222:225], v[238:241], v[206:209]
	v_mfma_f32_16x16x32_bf16 v[120:123], v[12:15], v[234:237], v[96:99]
	v_mfma_f32_16x16x32_bf16 v[96:99], v[230:233], v[242:245], v[8:11]
	s_setprio 0
	s_barrier
	ds_read_b128 v[186:189], v135 offset:49152
	ds_read_b128 v[134:137], v135 offset:50176
	ds_read_b128 v[190:193], v156 offset:49152
	ds_read_b128 v[194:197], v156 offset:50176
	ds_read_b128 v[198:201], v157 offset:49152
	ds_read_b128 v[202:205], v157 offset:50176
	ds_read_b128 v[206:209], v158 offset:49152
	ds_read_b128 v[156:159], v158 offset:50176
	s_barrier
	s_waitcnt lgkmcnt(0)
	s_setprio 1
	v_mfma_f32_16x16x32_bf16 v[8:11], v[186:189], v[0:3], v[60:63]
	v_mfma_f32_16x16x32_bf16 v[24:27], v[134:137], v[4:7], v[8:11]
	v_mfma_f32_16x16x32_bf16 v[8:11], v[186:189], v[210:213], v[56:59]
	v_mfma_f32_16x16x32_bf16 v[28:31], v[134:137], v[138:141], v[8:11]
	v_mfma_f32_16x16x32_bf16 v[8:11], v[190:193], v[0:3], v[52:55]
	v_mfma_f32_16x16x32_bf16 v[16:19], v[194:197], v[4:7], v[8:11]
	v_mfma_f32_16x16x32_bf16 v[8:11], v[190:193], v[210:213], v[48:51]
	v_mfma_f32_16x16x32_bf16 v[20:23], v[194:197], v[138:141], v[8:11]
	v_mfma_f32_16x16x32_bf16 v[8:11], v[198:201], v[0:3], v[44:47]
	v_mfma_f32_16x16x32_bf16 v[0:3], v[206:209], v[0:3], v[36:39]
	v_mfma_f32_16x16x32_bf16 v[8:11], v[202:205], v[4:7], v[8:11]
	v_mfma_f32_16x16x32_bf16 v[12:15], v[198:201], v[210:213], v[40:43]
	v_mfma_f32_16x16x32_bf16 v[0:3], v[156:159], v[4:7], v[0:3]
	v_mfma_f32_16x16x32_bf16 v[4:7], v[206:209], v[210:213], v[32:35]
	v_mfma_f32_16x16x32_bf16 v[12:15], v[202:205], v[138:141], v[12:15]
	v_mfma_f32_16x16x32_bf16 v[4:7], v[156:159], v[138:141], v[4:7]
	s_setprio 0
	s_setprio 1
	v_mfma_f32_16x16x32_bf16 v[32:35], v[186:189], v[128:131], v[142:145]
	v_mfma_f32_16x16x32_bf16 v[56:59], v[134:137], v[234:237], v[32:35]
	v_mfma_f32_16x16x32_bf16 v[32:35], v[186:189], v[238:241], v[160:163]
	v_mfma_f32_16x16x32_bf16 v[60:63], v[134:137], v[242:245], v[32:35]
	v_mfma_f32_16x16x32_bf16 v[32:35], v[190:193], v[128:131], v[164:167]
	v_mfma_f32_16x16x32_bf16 v[48:51], v[194:197], v[234:237], v[32:35]
	v_mfma_f32_16x16x32_bf16 v[32:35], v[190:193], v[238:241], v[178:181]
	v_mfma_f32_16x16x32_bf16 v[52:55], v[194:197], v[242:245], v[32:35]
	v_mfma_f32_16x16x32_bf16 v[32:35], v[198:201], v[128:131], v[182:185]
	v_mfma_f32_16x16x32_bf16 v[40:43], v[202:205], v[234:237], v[32:35]
	v_mfma_f32_16x16x32_bf16 v[32:35], v[198:201], v[238:241], v[214:217]
	v_mfma_f32_16x16x32_bf16 v[44:47], v[202:205], v[242:245], v[32:35]
	v_mfma_f32_16x16x32_bf16 v[32:35], v[206:209], v[128:131], v[218:221]
	v_mfma_f32_16x16x32_bf16 v[36:39], v[206:209], v[238:241], v[152:155]
	v_mfma_f32_16x16x32_bf16 v[32:35], v[156:159], v[234:237], v[32:35]
	v_mfma_f32_16x16x32_bf16 v[36:39], v[156:159], v[242:245], v[36:39]
	s_setprio 0
	s_cmpk_gt_u32 s62, 0xff
	s_barrier
	s_cbranch_scc1 .LBB0_419
	s_barrier

; #define LDA(dst, b, h)                                                                                    \
;   _Pragma("unroll") for (int m = 0; m < 4; ++m) _Pragma("unroll") for (int k = 0; k < 2; ++k)             \
;       dst[m][k] = *reinterpret_cast<const bf16x8*>((char*)SA(b, h) + lds_byte(wr * 64 + m * 16 + fr, k * 32 + fq * 8))
; #define LDB(dst, b, h)                                                                                    \
;   _Pragma("unroll") for (int n = 0; n < 2; ++n) _Pragma("unroll") for (int k = 0; k < 2; ++k)             \
;       dst[n][k] = *reinterpret_cast<const bf16x8*>((char*)SB(b, h) + lds_byte(wc * 32 + n * 16 + fr, k * 32 + fq * 8))
; #define WAIT_V(n) asm volatile("s_waitcnt vmcnt(" #n ")" ::: "memory")
; #define WAIT_L(n) asm volatile("s_waitcnt lgkmcnt(" #n ")" ::: "memory")
; #define BAR __builtin_amdgcn_s_barrier()
; #define SCHED __builtin_amdgcn_sched_barrier(0)
; template <int EPI> ...
;     ...
;   if (wr == 1) BAR;
;   WAIT_V(10); BAR;
;   WAIT_V(6); BAR;
;   for (int t = 0; t < nt - 2; t += 2) {
;     LDB(B0, 0, 0); SCHED; LDA(At, 0, 0); STAGE(SA(1, 1), A, brow + HALF, t + 1);
;     WAIT_L(8); BAR; WAIT_L(0); MMA(0, 0, At, B0); BAR; SCHED;
;     LDB(B1, 0, 1); STAGE(SB(0, 0), Bt, bcol, t + 2);
;     BAR; WAIT_L(0); MMA(0, 1, At, B1); BAR;
;     LDA(At, 0, 1); STAGE(SA(0, 0), A, brow, t + 2);
.LBB0_704:
	s_ashr_i32 s30, s23, 6
	s_and_b32 s31, s30, 3
	v_and_b32_e32 v128, 15, v130
	v_and_b32_e32 v9, 48, v130
	v_lshlrev_b32_e32 v131, 2, v130
	s_lshl_b32 s44, s31, 12
	v_lshl_or_b32 v8, v128, 6, v9
	v_and_b32_e32 v12, 32, v131
	v_bitop3_b32 v129, s44, v8, v12 bitop3:0xf6
	v_or_b32_e32 v5, 0x10000, v129
	v_or_b32_e32 v10, 0x10800, v129
	s_waitcnt vmcnt(10)
	s_barrier
	s_waitcnt vmcnt(6)
	s_barrier
	v_or_b32_e32 v7, 0x10400, v129
	ds_read_b128 v[32:35], v5
	ds_read_b128 v[36:39], v7
	v_or_b32_e32 v11, 0x10c00, v129
	ds_read_b128 v[40:43], v10
	ds_read_b128 v[44:47], v11
	v_mov_b32_e32 v1, v0
	v_mov_b32_e32 v2, v0
	v_mov_b32_e32 v3, v0
	v_lshlrev_b32_e32 v13, 6, v130
	s_movk_i32 s64, 0x3c0
	s_lshl_b32 s44, s22, 13
	v_and_or_b32 v9, v13, s64, v9
	v_bitop3_b32 v8, s44, v8, v12 bitop3:0xf6
	v_bitop3_b32 v9, s44, v9, v12 bitop3:0xf6
	v_mov_b32_e32 v148, v4
	ds_read_b128 v[48:51], v8
	ds_read_b128 v[52:55], v8 offset:1024
	ds_read_b128 v[56:59], v9 offset:2048
	ds_read_b128 v[60:63], v9 offset:3072
	ds_read_b128 v[64:67], v9 offset:4096
	ds_read_b128 v[68:71], v9 offset:5120
	ds_read_b128 v[72:75], v9 offset:6144
	ds_read_b128 v[76:79], v9 offset:7168
	s_nop 0
	v_lshl_add_u64 v[12:13], v[148:149], 1, s[0:1]
	v_lshl_add_u64 v[14:15], v[12:13], 0, s[46:47]
	v_add_u32_e32 v12, 0xc000, v18
	v_mov_b32_e32 v148, v6
	v_readfirstlane_b32 s67, v12
	s_mov_b32 m0, s67
	v_add_u32_e32 v13, 0xe000, v18
	global_load_lds_dwordx4 v[14:15], off
	v_readfirstlane_b32 s44, v13
	v_lshl_add_u64 v[14:15], v[148:149], 1, s[0:1]
	v_lshl_add_u64 v[14:15], v[14:15], 0, s[46:47]
	s_mov_b32 m0, s44
	s_nop 0
	global_load_lds_dwordx4 v[14:15], off
	s_waitcnt lgkmcnt(8)
	s_barrier
	s_waitcnt lgkmcnt(0)
	s_setprio 1
	v_mfma_f32_16x16x32_bf16 v[14:17], v[48:51], v[32:35], v[0:3]
	v_mfma_f32_16x16x32_bf16 v[80:83], v[52:55], v[36:39], v[14:17]
	v_mfma_f32_16x16x32_bf16 v[14:17], v[48:51], v[40:43], v[0:3]
	v_mfma_f32_16x16x32_bf16 v[84:87], v[52:55], v[44:47], v[14:17]
	v_mfma_f32_16x16x32_bf16 v[14:17], v[56:59], v[32:35], v[0:3]
	v_mfma_f32_16x16x32_bf16 v[88:91], v[60:63], v[36:39], v[14:17]
	v_mfma_f32_16x16x32_bf16 v[14:17], v[56:59], v[40:43], v[0:3]
	v_mfma_f32_16x16x32_bf16 v[92:95], v[60:63], v[44:47], v[14:17]
	v_mfma_f32_16x16x32_bf16 v[14:17], v[64:67], v[32:35], v[0:3]
	v_mfma_f32_16x16x32_bf16 v[96:99], v[68:71], v[36:39], v[14:17]
	v_mfma_f32_16x16x32_bf16 v[14:17], v[64:67], v[40:43], v[0:3]
	v_mfma_f32_16x16x32_bf16 v[100:103], v[68:71], v[44:47], v[14:17]
	v_mfma_f32_16x16x32_bf16 v[14:17], v[72:75], v[32:35], v[0:3]
	v_mfma_f32_16x16x32_bf16 v[104:107], v[76:79], v[36:39], v[14:17]
	v_mfma_f32_16x16x32_bf16 v[14:17], v[72:75], v[40:43], v[0:3]
	v_mfma_f32_16x16x32_bf16 v[108:111], v[76:79], v[44:47], v[14:17]
	s_setprio 0
	s_barrier
	s_nop 4
	v_or_b32_e32 v14, 0x14000, v129
	v_or_b32_e32 v16, 0x14800, v129
	v_mov_b32_e32 v148, v4
	v_or_b32_e32 v15, 0x14400, v129
	ds_read_b128 v[112:115], v14
	ds_read_b128 v[116:119], v15
	v_or_b32_e32 v17, 0x14c00, v129
	ds_read_b128 v[120:123], v16
	ds_read_b128 v[124:127], v17
	v_readfirstlane_b32 s70, v30
	v_lshl_add_u64 v[132:133], v[148:149], 1, s[14:15]
	v_lshl_add_u64 v[132:133], v[132:133], 0, s[50:51]
	s_mov_b32 m0, s70
	v_mov_b32_e32 v148, v6
	global_load_lds_dwordx4 v[132:133], off
	v_readfirstlane_b32 s64, v31
	v_lshl_add_u64 v[132:133], v[148:149], 1, s[14:15]
	v_lshl_add_u64 v[132:133], v[132:133], 0, s[50:51]
	s_mov_b32 m0, s64
	s_nop 0
	global_load_lds_dwordx4 v[132:133], off
	s_barrier
	s_waitcnt lgkmcnt(0)
	s_setprio 1
	v_mfma_f32_16x16x32_bf16 v[132:135], v[48:51], v[112:115], v[0:3]
	v_mfma_f32_16x16x32_bf16 v[48:51], v[48:51], v[120:123], v[0:3]
	v_mfma_f32_16x16x32_bf16 v[132:135], v[52:55], v[116:119], v[132:135]
	v_mfma_f32_16x16x32_bf16 v[48:51], v[52:55], v[124:127], v[48:51]
	v_mfma_f32_16x16x32_bf16 v[52:55], v[56:59], v[112:115], v[0:3]
	v_mfma_f32_16x16x32_bf16 v[56:59], v[56:59], v[120:123], v[0:3]
	v_mfma_f32_16x16x32_bf16 v[52:55], v[60:63], v[116:119], v[52:55]
	v_mfma_f32_16x16x32_bf16 v[56:59], v[60:63], v[124:127], v[56:59]
	v_mfma_f32_16x16x32_bf16 v[60:63], v[64:67], v[112:115], v[0:3]
	v_mfma_f32_16x16x32_bf16 v[64:67], v[64:67], v[120:123], v[0:3]
	v_mfma_f32_16x16x32_bf16 v[60:63], v[68:71], v[116:119], v[60:63]
	v_mfma_f32_16x16x32_bf16 v[64:67], v[68:71], v[124:127], v[64:67]
	v_mfma_f32_16x16x32_bf16 v[68:71], v[72:75], v[112:115], v[0:3]
	v_mfma_f32_16x16x32_bf16 v[72:75], v[72:75], v[120:123], v[0:3]
	v_mfma_f32_16x16x32_bf16 v[68:71], v[76:79], v[116:119], v[68:71]
	v_mfma_f32_16x16x32_bf16 v[72:75], v[76:79], v[124:127], v[72:75]
	s_setprio 0
	v_mov_b32_e32 v148, v4
	s_barrier
	ds_read_b128 v[76:79], v8 offset:16384
	ds_read_b128 v[136:139], v8 offset:17408
	ds_read_b128 v[140:143], v9 offset:18432
	ds_read_b128 v[144:147], v9 offset:19456
	ds_read_b128 v[152:155], v9 offset:20480
	ds_read_b128 v[156:159], v9 offset:21504
	ds_read_b128 v[160:163], v9 offset:22528
	ds_read_b128 v[164:167], v9 offset:23552
	v_readfirstlane_b32 s73, v18
	v_lshl_add_u64 v[30:31], v[148:149], 1, s[12:13]
	v_lshl_add_u64 v[30:31], v[30:31], 0, s[50:51]
	s_mov_b32 m0, s73
	v_mov_b32_e32 v148, v6
	global_load_lds_dwordx4 v[30:31], off
	v_readfirstlane_b32 s65, v19
	v_lshl_add_u64 v[30:31], v[148:149], 1, s[12:13]
	v_lshl_add_u64 v[30:31], v[30:31], 0, s[50:51]
	s_mov_b32 m0, s65
	s_nop 0
	global_load_lds_dwordx4 v[30:31], off
	s_barrier
; #define LDA(dst, b, h)                                                                                    \
;   _Pragma("unroll") for (int m = 0; m < 4; ++m) _Pragma("unroll") for (int k = 0; k < 2; ++k)             \
;       dst[m][k] = *reinterpret_cast<const bf16x8*>((char*)SA(b, h) + lds_byte(wr * 64 + m * 16 + fr, k * 32 + fq * 8))
; #define LDB(dst, b, h)                                                                                    \
;   _Pragma("unroll") for (int n = 0; n < 2; ++n) _Pragma("unroll") for (int k = 0; k < 2; ++k)             \
;       dst[n][k] = *reinterpret_cast<const bf16x8*>((char*)SB(b, h) + lds_byte(wc * 32 + n * 16 + fr, k * 32 + fq * 8))
; #define WAIT_V(n) asm volatile("s_waitcnt vmcnt(" #n ")" ::: "memory")
; #define WAIT_L(n) asm volatile("s_waitcnt lgkmcnt(" #n ")" ::: "memory")
; #define BAR __builtin_amdgcn_s_barrier()
; #define SCHED __builtin_amdgcn_sched_barrier(0)
; template <int EPI> ...
;     ...
;     BAR; WAIT_L(0); MMA(1, 0, At, B0); BAR; SCHED;
;     STAGE(SB(0, 1), Bt, bcol + HALF, t + 2);
;     WAIT_V(6); BAR; MMA(1, 1, At, B1); BAR;
;     LDB(B0, 1, 0); SCHED; LDA(At, 1, 0); STAGE(SA(0, 1), A, brow + HALF, t + 2);
;     WAIT_L(8); BAR; WAIT_L(0); MMA(0, 0, At, B0); BAR; SCHED;
;     LDB(B1, 1, 1); STAGE(SB(1, 0), Bt, bcol, t + 3);
	s_waitcnt lgkmcnt(0)
	s_setprio 1
	v_mfma_f32_16x16x32_bf16 v[178:181], v[76:79], v[32:35], v[0:3]
	v_mfma_f32_16x16x32_bf16 v[186:189], v[140:143], v[32:35], v[0:3]
	v_mfma_f32_16x16x32_bf16 v[194:197], v[152:155], v[32:35], v[0:3]
	v_mfma_f32_16x16x32_bf16 v[30:33], v[160:163], v[32:35], v[0:3]
	v_mfma_f32_16x16x32_bf16 v[178:181], v[136:139], v[36:39], v[178:181]
	v_mfma_f32_16x16x32_bf16 v[186:189], v[144:147], v[36:39], v[186:189]
	v_mfma_f32_16x16x32_bf16 v[194:197], v[156:159], v[36:39], v[194:197]
	v_mfma_f32_16x16x32_bf16 v[30:33], v[164:167], v[36:39], v[30:33]
	v_mfma_f32_16x16x32_bf16 v[34:37], v[160:163], v[40:43], v[0:3]
	v_mfma_f32_16x16x32_bf16 v[182:185], v[76:79], v[40:43], v[0:3]
	v_mfma_f32_16x16x32_bf16 v[190:193], v[140:143], v[40:43], v[0:3]
	v_mfma_f32_16x16x32_bf16 v[198:201], v[152:155], v[40:43], v[0:3]
	v_mfma_f32_16x16x32_bf16 v[34:37], v[164:167], v[44:47], v[34:37]
	v_mfma_f32_16x16x32_bf16 v[182:185], v[136:139], v[44:47], v[182:185]
	v_mfma_f32_16x16x32_bf16 v[190:193], v[144:147], v[44:47], v[190:193]
	v_mfma_f32_16x16x32_bf16 v[198:201], v[156:159], v[44:47], v[198:201]
	s_setprio 0
	s_barrier
	v_mov_b32_e32 v148, v4
	v_readfirstlane_b32 s69, v28
	v_lshl_add_u64 v[18:19], v[148:149], 1, s[4:5]
	v_lshl_add_u64 v[18:19], v[18:19], 0, s[50:51]
	s_mov_b32 m0, s69
	v_mov_b32_e32 v148, v6
	global_load_lds_dwordx4 v[18:19], off
	v_readfirstlane_b32 s66, v29
	v_lshl_add_u64 v[18:19], v[148:149], 1, s[4:5]
	v_lshl_add_u64 v[18:19], v[18:19], 0, s[50:51]
	s_mov_b32 m0, s66
	s_nop 0
	global_load_lds_dwordx4 v[18:19], off
	s_waitcnt vmcnt(6)
	s_barrier
	s_setprio 1
	v_mfma_f32_16x16x32_bf16 v[38:41], v[76:79], v[112:115], v[0:3]
	v_mfma_f32_16x16x32_bf16 v[42:45], v[76:79], v[120:123], v[0:3]
	v_mfma_f32_16x16x32_bf16 v[38:41], v[136:139], v[116:119], v[38:41]
	v_mfma_f32_16x16x32_bf16 v[42:45], v[136:139], v[124:127], v[42:45]
	v_mfma_f32_16x16x32_bf16 v[76:79], v[140:143], v[112:115], v[0:3]
	v_mfma_f32_16x16x32_bf16 v[136:139], v[140:143], v[120:123], v[0:3]
	v_mfma_f32_16x16x32_bf16 v[76:79], v[144:147], v[116:119], v[76:79]
	v_mfma_f32_16x16x32_bf16 v[136:139], v[144:147], v[124:127], v[136:139]
	v_mfma_f32_16x16x32_bf16 v[140:143], v[152:155], v[112:115], v[0:3]
	v_mfma_f32_16x16x32_bf16 v[144:147], v[152:155], v[120:123], v[0:3]
	v_mfma_f32_16x16x32_bf16 v[112:115], v[160:163], v[112:115], v[0:3]
	v_mfma_f32_16x16x32_bf16 v[0:3], v[160:163], v[120:123], v[0:3]
	v_mfma_f32_16x16x32_bf16 v[140:143], v[156:159], v[116:119], v[140:143]
	v_mfma_f32_16x16x32_bf16 v[112:115], v[164:167], v[116:119], v[112:115]
	v_mfma_f32_16x16x32_bf16 v[116:119], v[164:167], v[124:127], v[0:3]
	v_mfma_f32_16x16x32_bf16 v[144:147], v[156:159], v[124:127], v[144:147]
	s_setprio 0
	s_nop 2
	v_or_b32_e32 v0, 0x18000, v129
	v_or_b32_e32 v2, 0x18800, v129
	s_barrier
	v_or_b32_e32 v1, 0x18400, v129
	ds_read_b128 v[120:123], v0
	ds_read_b128 v[124:127], v1
	v_or_b32_e32 v3, 0x18c00, v129
	ds_read_b128 v[152:155], v2
	ds_read_b128 v[156:159], v3
	v_mov_b32_e32 v148, v4
	ds_read_b128 v[160:163], v8 offset:32768
	ds_read_b128 v[164:167], v8 offset:33792
	ds_read_b128 v[202:205], v9 offset:34816
	ds_read_b128 v[206:209], v9 offset:35840
	ds_read_b128 v[210:213], v9 offset:36864
	ds_read_b128 v[214:217], v9 offset:37888
	ds_read_b128 v[218:221], v9 offset:38912
	ds_read_b128 v[222:225], v9 offset:39936
	v_readfirstlane_b32 s75, v20
	v_lshl_add_u64 v[18:19], v[148:149], 1, s[0:1]
	v_lshl_add_u64 v[18:19], v[18:19], 0, s[50:51]
	s_mov_b32 m0, s75
	v_mov_b32_e32 v148, v6
	global_load_lds_dwordx4 v[18:19], off
	v_readfirstlane_b32 s68, v21
	v_lshl_add_u64 v[18:19], v[148:149], 1, s[0:1]
	v_lshl_add_u64 v[18:19], v[18:19], 0, s[50:51]
	s_mov_b32 m0, s68
	s_nop 0
	global_load_lds_dwordx4 v[18:19], off
	s_waitcnt lgkmcnt(8)
	s_barrier
	s_waitcnt lgkmcnt(0)
	s_setprio 1
	v_mfma_f32_16x16x32_bf16 v[18:21], v[160:163], v[120:123], v[80:83]
	v_mfma_f32_16x16x32_bf16 v[80:83], v[164:167], v[124:127], v[18:21]
	v_mfma_f32_16x16x32_bf16 v[18:21], v[160:163], v[152:155], v[84:87]
	v_mfma_f32_16x16x32_bf16 v[84:87], v[164:167], v[156:159], v[18:21]
	v_mfma_f32_16x16x32_bf16 v[18:21], v[202:205], v[120:123], v[88:91]
	v_mfma_f32_16x16x32_bf16 v[88:91], v[206:209], v[124:127], v[18:21]
	v_mfma_f32_16x16x32_bf16 v[18:21], v[202:205], v[152:155], v[92:95]
	v_mfma_f32_16x16x32_bf16 v[92:95], v[206:209], v[156:159], v[18:21]
	v_mfma_f32_16x16x32_bf16 v[18:21], v[210:213], v[120:123], v[96:99]
	v_mfma_f32_16x16x32_bf16 v[96:99], v[214:217], v[124:127], v[18:21]
	v_mfma_f32_16x16x32_bf16 v[18:21], v[210:213], v[152:155], v[100:103]
	v_mfma_f32_16x16x32_bf16 v[100:103], v[214:217], v[156:159], v[18:21]
	v_mfma_f32_16x16x32_bf16 v[18:21], v[218:221], v[120:123], v[104:107]
	v_mfma_f32_16x16x32_bf16 v[104:107], v[222:225], v[124:127], v[18:21]
	v_mfma_f32_16x16x32_bf16 v[18:21], v[218:221], v[152:155], v[108:111]
	v_mfma_f32_16x16x32_bf16 v[108:111], v[222:225], v[156:159], v[18:21]
	s_setprio 0
	s_barrier
	s_nop 4
	v_or_b32_e32 v18, 0x1c000, v129
	v_or_b32_e32 v20, 0x1c800, v129
	v_mov_b32_e32 v148, v4
	v_or_b32_e32 v19, 0x1c400, v129
	ds_read_b128 v[226:229], v18
	ds_read_b128 v[230:233], v19
	v_or_b32_e32 v21, 0x1cc00, v129
	ds_read_b128 v[234:237], v20
	ds_read_b128 v[238:241], v21
	v_readfirstlane_b32 s77, v26
	v_lshl_add_u64 v[28:29], v[148:149], 1, s[14:15]
	v_lshl_add_u64 v[28:29], v[28:29], 0, s[54:55]
	s_mov_b32 m0, s77
	v_mov_b32_e32 v148, v6
	global_load_lds_dwordx4 v[28:29], off
	v_readfirstlane_b32 s71, v27
	v_lshl_add_u64 v[28:29], v[148:149], 1, s[14:15]
	v_lshl_add_u64 v[28:29], v[28:29], 0, s[54:55]
	s_mov_b32 m0, s71
	s_nop 0
	global_load_lds_dwordx4 v[28:29], off
	s_barrier
; #define LDA(dst, b, h)                                                                                    \
;   _Pragma("unroll") for (int m = 0; m < 4; ++m) _Pragma("unroll") for (int k = 0; k < 2; ++k)             \
;       dst[m][k] = *reinterpret_cast<const bf16x8*>((char*)SA(b, h) + lds_byte(wr * 64 + m * 16 + fr, k * 32 + fq * 8))
; #define LDB(dst, b, h)                                                                                    \
;   _Pragma("unroll") for (int n = 0; n < 2; ++n) _Pragma("unroll") for (int k = 0; k < 2; ++k)             \
;       dst[n][k] = *reinterpret_cast<const bf16x8*>((char*)SB(b, h) + lds_byte(wc * 32 + n * 16 + fr, k * 32 + fq * 8))
; #define WAIT_V(n) asm volatile("s_waitcnt vmcnt(" #n ")" ::: "memory")
; #define WAIT_L(n) asm volatile("s_waitcnt lgkmcnt(" #n ")" ::: "memory")
; #define BAR __builtin_amdgcn_s_barrier()
; #define SCHED __builtin_amdgcn_sched_barrier(0)
; template <int EPI> ...
;     ...
;     LDB(B0, 0, 0); SCHED; LDA(At, 0, 0); STAGE(SA(1, 1), A, brow + HALF, t + 1);
;     WAIT_L(8); BAR; WAIT_L(0); MMA(0, 0, At, B0); BAR; SCHED;
;     ...
;     BAR; WAIT_L(0); MMA(0, 1, At, B1); BAR;
;     LDA(At, 1, 1); STAGE(SA(1, 0), A, brow, t + 3);
;     BAR; WAIT_L(0); MMA(1, 0, At, B0); BAR; SCHED;
;     STAGE(SB(1, 1), Bt, bcol + HALF, t + 3);
;     WAIT_V(6); BAR; MMA(1, 1, At, B1); BAR;
;   }
	s_waitcnt lgkmcnt(0)
	s_setprio 1
	v_mfma_f32_16x16x32_bf16 v[26:29], v[160:163], v[226:229], v[132:135]
	v_mfma_f32_16x16x32_bf16 v[46:49], v[160:163], v[234:237], v[48:51]
	v_mfma_f32_16x16x32_bf16 v[50:53], v[202:205], v[226:229], v[52:55]
	v_mfma_f32_16x16x32_bf16 v[54:57], v[202:205], v[234:237], v[56:59]
	v_mfma_f32_16x16x32_bf16 v[58:61], v[210:213], v[226:229], v[60:63]
	v_mfma_f32_16x16x32_bf16 v[62:65], v[210:213], v[234:237], v[64:67]
	v_mfma_f32_16x16x32_bf16 v[66:69], v[218:221], v[226:229], v[68:71]
	v_mfma_f32_16x16x32_bf16 v[70:73], v[218:221], v[234:237], v[72:75]
	v_mfma_f32_16x16x32_bf16 v[26:29], v[164:167], v[230:233], v[26:29]
	v_mfma_f32_16x16x32_bf16 v[46:49], v[164:167], v[238:241], v[46:49]
	v_mfma_f32_16x16x32_bf16 v[50:53], v[206:209], v[230:233], v[50:53]
	v_mfma_f32_16x16x32_bf16 v[54:57], v[206:209], v[238:241], v[54:57]
	v_mfma_f32_16x16x32_bf16 v[58:61], v[214:217], v[230:233], v[58:61]
	v_mfma_f32_16x16x32_bf16 v[62:65], v[214:217], v[238:241], v[62:65]
	v_mfma_f32_16x16x32_bf16 v[66:69], v[222:225], v[230:233], v[66:69]
	v_mfma_f32_16x16x32_bf16 v[70:73], v[222:225], v[238:241], v[70:73]
	s_setprio 0
	v_mov_b32_e32 v148, v4
	s_barrier
	ds_read_b128 v[132:135], v8 offset:49152
	ds_read_b128 v[160:163], v8 offset:50176
	ds_read_b128 v[164:167], v9 offset:51200
	ds_read_b128 v[202:205], v9 offset:52224
	ds_read_b128 v[206:209], v9 offset:53248
	ds_read_b128 v[210:213], v9 offset:54272
	ds_read_b128 v[214:217], v9 offset:55296
	ds_read_b128 v[218:221], v9 offset:56320
	v_readfirstlane_b32 s78, v24
	v_lshl_add_u64 v[74:75], v[148:149], 1, s[12:13]
	v_lshl_add_u64 v[74:75], v[74:75], 0, s[54:55]
	s_mov_b32 m0, s78
	v_mov_b32_e32 v148, v6
	global_load_lds_dwordx4 v[74:75], off
	v_readfirstlane_b32 s72, v25
	v_lshl_add_u64 v[74:75], v[148:149], 1, s[12:13]
	v_lshl_add_u64 v[74:75], v[74:75], 0, s[54:55]
	s_mov_b32 m0, s72
	s_nop 0
	global_load_lds_dwordx4 v[74:75], off
	s_barrier
	s_waitcnt lgkmcnt(0)
	s_setprio 1
	v_mfma_f32_16x16x32_bf16 v[30:33], v[214:217], v[120:123], v[30:33]
	v_mfma_f32_16x16x32_bf16 v[34:37], v[214:217], v[152:155], v[34:37]
	v_mfma_f32_16x16x32_bf16 v[178:181], v[132:135], v[120:123], v[178:181]
	v_mfma_f32_16x16x32_bf16 v[182:185], v[132:135], v[152:155], v[182:185]
	v_mfma_f32_16x16x32_bf16 v[186:189], v[164:167], v[120:123], v[186:189]
	v_mfma_f32_16x16x32_bf16 v[190:193], v[164:167], v[152:155], v[190:193]
	v_mfma_f32_16x16x32_bf16 v[194:197], v[206:209], v[120:123], v[194:197]
	v_mfma_f32_16x16x32_bf16 v[198:201], v[206:209], v[152:155], v[198:201]
	v_mfma_f32_16x16x32_bf16 v[30:33], v[218:221], v[124:127], v[30:33]
	v_mfma_f32_16x16x32_bf16 v[34:37], v[218:221], v[156:159], v[34:37]
	v_mfma_f32_16x16x32_bf16 v[178:181], v[160:163], v[124:127], v[178:181]
	v_mfma_f32_16x16x32_bf16 v[182:185], v[160:163], v[156:159], v[182:185]
	v_mfma_f32_16x16x32_bf16 v[186:189], v[202:205], v[124:127], v[186:189]
	v_mfma_f32_16x16x32_bf16 v[190:193], v[202:205], v[156:159], v[190:193]
	v_mfma_f32_16x16x32_bf16 v[194:197], v[210:213], v[124:127], v[194:197]
	v_mfma_f32_16x16x32_bf16 v[198:201], v[210:213], v[156:159], v[198:201]
	s_setprio 0
	s_barrier
	v_mov_b32_e32 v148, v4
	v_readfirstlane_b32 s76, v22
	v_lshl_add_u64 v[24:25], v[148:149], 1, s[4:5]
	v_lshl_add_u64 v[24:25], v[24:25], 0, s[54:55]
	s_mov_b32 m0, s76
	v_mov_b32_e32 v148, v6
	global_load_lds_dwordx4 v[24:25], off
	v_readfirstlane_b32 s74, v23
	v_lshl_add_u64 v[24:25], v[148:149], 1, s[4:5]
	v_lshl_add_u64 v[24:25], v[24:25], 0, s[54:55]
	s_mov_b32 m0, s74
	s_nop 0
	global_load_lds_dwordx4 v[24:25], off
	s_waitcnt vmcnt(6)
	s_barrier
	s_setprio 1
	v_mfma_f32_16x16x32_bf16 v[22:25], v[132:135], v[226:229], v[38:41]
	v_mfma_f32_16x16x32_bf16 v[38:41], v[132:135], v[234:237], v[42:45]
	v_mfma_f32_16x16x32_bf16 v[42:45], v[164:167], v[226:229], v[76:79]
	v_mfma_f32_16x16x32_bf16 v[74:77], v[164:167], v[234:237], v[136:139]
	v_mfma_f32_16x16x32_bf16 v[120:123], v[206:209], v[226:229], v[140:143]
	v_mfma_f32_16x16x32_bf16 v[124:127], v[206:209], v[234:237], v[144:147]
	v_mfma_f32_16x16x32_bf16 v[112:115], v[214:217], v[226:229], v[112:115]
	v_mfma_f32_16x16x32_bf16 v[116:119], v[214:217], v[234:237], v[116:119]
	v_mfma_f32_16x16x32_bf16 v[22:25], v[160:163], v[230:233], v[22:25]
	v_mfma_f32_16x16x32_bf16 v[38:41], v[160:163], v[238:241], v[38:41]
	v_mfma_f32_16x16x32_bf16 v[42:45], v[202:205], v[230:233], v[42:45]
	v_mfma_f32_16x16x32_bf16 v[74:77], v[202:205], v[238:241], v[74:77]
	v_mfma_f32_16x16x32_bf16 v[120:123], v[210:213], v[230:233], v[120:123]
	v_mfma_f32_16x16x32_bf16 v[124:127], v[210:213], v[238:241], v[124:127]
	v_mfma_f32_16x16x32_bf16 v[112:115], v[218:221], v[230:233], v[112:115]
	v_mfma_f32_16x16x32_bf16 v[116:119], v[218:221], v[238:241], v[116:119]
	s_setprio 0
	s_barrier
	ds_read_b128 v[132:135], v5
	ds_read_b128 v[136:139], v7
	ds_read_b128 v[140:143], v10
	ds_read_b128 v[144:147], v11
	v_mov_b32_e32 v148, v4
	ds_read_b128 v[152:155], v8
	ds_read_b128 v[156:159], v8 offset:1024
	ds_read_b128 v[160:163], v9 offset:2048
	ds_read_b128 v[164:167], v9 offset:3072
	ds_read_b128 v[202:205], v9 offset:4096
	ds_read_b128 v[206:209], v9 offset:5120
	ds_read_b128 v[210:213], v9 offset:6144
	ds_read_b128 v[214:217], v9 offset:7168
	s_mov_b32 m0, s67
	v_lshl_add_u64 v[78:79], v[148:149], 1, s[0:1]
	v_lshl_add_u64 v[78:79], v[78:79], 0, s[54:55]
	v_mov_b32_e32 v148, v6
	global_load_lds_dwordx4 v[78:79], off
	s_mov_b32 m0, s44
	v_lshl_add_u64 v[78:79], v[148:149], 1, s[0:1]
	v_lshl_add_u64 v[78:79], v[78:79], 0, s[54:55]
	global_load_lds_dwordx4 v[78:79], off
	s_waitcnt lgkmcnt(8)
	s_barrier
; #define LDA(dst, b, h)                                                                                    \
;   _Pragma("unroll") for (int m = 0; m < 4; ++m) _Pragma("unroll") for (int k = 0; k < 2; ++k)             \
;       dst[m][k] = *reinterpret_cast<const bf16x8*>((char*)SA(b, h) + lds_byte(wr * 64 + m * 16 + fr, k * 32 + fq * 8))
; #define LDB(dst, b, h)                                                                                    \
;   _Pragma("unroll") for (int n = 0; n < 2; ++n) _Pragma("unroll") for (int k = 0; k < 2; ++k)             \
;       dst[n][k] = *reinterpret_cast<const bf16x8*>((char*)SB(b, h) + lds_byte(wc * 32 + n * 16 + fr, k * 32 + fq * 8))
; #define WAIT_V(n) asm volatile("s_waitcnt vmcnt(" #n ")" ::: "memory")
; #define WAIT_L(n) asm volatile("s_waitcnt lgkmcnt(" #n ")" ::: "memory")
; #define BAR __builtin_amdgcn_s_barrier()
; #define SCHED __builtin_amdgcn_sched_barrier(0)
; template <int EPI> ...
;     ...
;     WAIT_L(8); BAR; WAIT_L(0); MMA(0, 0, At, B0); BAR; SCHED;
;     LDB(B1, 0, 1); STAGE(SB(0, 0), Bt, bcol, t + 2);
;     BAR; WAIT_L(0); MMA(0, 1, At, B1); BAR;
;     LDA(At, 0, 1); STAGE(SA(0, 0), A, brow, t + 2);
;     BAR; WAIT_L(0); MMA(1, 0, At, B0); BAR; SCHED;
;     STAGE(SB(0, 1), Bt, bcol + HALF, t + 2);
;     WAIT_V(6); BAR; MMA(1, 1, At, B1); BAR;
	s_waitcnt lgkmcnt(0)
	s_setprio 1
	v_mfma_f32_16x16x32_bf16 v[78:81], v[152:155], v[132:135], v[80:83]
	v_mfma_f32_16x16x32_bf16 v[82:85], v[152:155], v[140:143], v[84:87]
	v_mfma_f32_16x16x32_bf16 v[86:89], v[160:163], v[132:135], v[88:91]
	v_mfma_f32_16x16x32_bf16 v[90:93], v[160:163], v[140:143], v[92:95]
	v_mfma_f32_16x16x32_bf16 v[94:97], v[202:205], v[132:135], v[96:99]
	v_mfma_f32_16x16x32_bf16 v[98:101], v[202:205], v[140:143], v[100:103]
	v_mfma_f32_16x16x32_bf16 v[102:105], v[210:213], v[132:135], v[104:107]
	v_mfma_f32_16x16x32_bf16 v[106:109], v[210:213], v[140:143], v[108:111]
	v_mfma_f32_16x16x32_bf16 v[78:81], v[156:159], v[136:139], v[78:81]
	v_mfma_f32_16x16x32_bf16 v[82:85], v[156:159], v[144:147], v[82:85]
	v_mfma_f32_16x16x32_bf16 v[86:89], v[164:167], v[136:139], v[86:89]
	v_mfma_f32_16x16x32_bf16 v[90:93], v[164:167], v[144:147], v[90:93]
	v_mfma_f32_16x16x32_bf16 v[94:97], v[206:209], v[136:139], v[94:97]
	v_mfma_f32_16x16x32_bf16 v[98:101], v[206:209], v[144:147], v[98:101]
	v_mfma_f32_16x16x32_bf16 v[102:105], v[214:217], v[136:139], v[102:105]
	v_mfma_f32_16x16x32_bf16 v[106:109], v[214:217], v[144:147], v[106:109]
	s_setprio 0
	s_barrier
	v_mov_b32_e32 v148, v4
	ds_read_b128 v[218:221], v14
	ds_read_b128 v[222:225], v15
	ds_read_b128 v[226:229], v16
	ds_read_b128 v[230:233], v17
	s_mov_b64 s[80:81], 0x200
	v_lshl_add_u64 v[110:111], v[148:149], 1, s[14:15]
	s_mov_b32 m0, s70
	v_lshl_add_u64 v[110:111], v[110:111], 0, s[80:81]
	v_mov_b32_e32 v148, v6
	global_load_lds_dwordx4 v[110:111], off
	s_mov_b32 m0, s64
	v_lshl_add_u64 v[110:111], v[148:149], 1, s[14:15]
	v_lshl_add_u64 v[110:111], v[110:111], 0, s[80:81]
	global_load_lds_dwordx4 v[110:111], off
	s_barrier
	s_waitcnt lgkmcnt(0)
	s_setprio 1
	v_mfma_f32_16x16x32_bf16 v[26:29], v[152:155], v[218:221], v[26:29]
	v_mfma_f32_16x16x32_bf16 v[46:49], v[152:155], v[226:229], v[46:49]
	v_mfma_f32_16x16x32_bf16 v[50:53], v[160:163], v[218:221], v[50:53]
	v_mfma_f32_16x16x32_bf16 v[54:57], v[160:163], v[226:229], v[54:57]
	v_mfma_f32_16x16x32_bf16 v[58:61], v[202:205], v[218:221], v[58:61]
	v_mfma_f32_16x16x32_bf16 v[62:65], v[202:205], v[226:229], v[62:65]
	v_mfma_f32_16x16x32_bf16 v[66:69], v[210:213], v[218:221], v[66:69]
	v_mfma_f32_16x16x32_bf16 v[70:73], v[210:213], v[226:229], v[70:73]
	v_mfma_f32_16x16x32_bf16 v[26:29], v[156:159], v[222:225], v[26:29]
	v_mfma_f32_16x16x32_bf16 v[46:49], v[156:159], v[230:233], v[46:49]
	v_mfma_f32_16x16x32_bf16 v[50:53], v[164:167], v[222:225], v[50:53]
	v_mfma_f32_16x16x32_bf16 v[54:57], v[164:167], v[230:233], v[54:57]
	v_mfma_f32_16x16x32_bf16 v[58:61], v[206:209], v[222:225], v[58:61]
	v_mfma_f32_16x16x32_bf16 v[62:65], v[206:209], v[230:233], v[62:65]
	v_mfma_f32_16x16x32_bf16 v[66:69], v[214:217], v[222:225], v[66:69]
	v_mfma_f32_16x16x32_bf16 v[70:73], v[214:217], v[230:233], v[70:73]
	s_setprio 0
	v_mov_b32_e32 v148, v4
	s_barrier
	ds_read_b128 v[152:155], v8 offset:16384
	ds_read_b128 v[156:159], v8 offset:17408
	ds_read_b128 v[160:163], v9 offset:18432
	ds_read_b128 v[164:167], v9 offset:19456
	ds_read_b128 v[202:205], v9 offset:20480
	ds_read_b128 v[206:209], v9 offset:21504
	ds_read_b128 v[210:213], v9 offset:22528
	ds_read_b128 v[214:217], v9 offset:23552
	s_mov_b32 m0, s73
	v_lshl_add_u64 v[110:111], v[148:149], 1, s[12:13]
	v_lshl_add_u64 v[110:111], v[110:111], 0, s[80:81]
	v_mov_b32_e32 v148, v6
	global_load_lds_dwordx4 v[110:111], off
	s_mov_b32 m0, s65
	v_lshl_add_u64 v[110:111], v[148:149], 1, s[12:13]
	v_lshl_add_u64 v[110:111], v[110:111], 0, s[80:81]
	global_load_lds_dwordx4 v[110:111], off
	s_barrier
	s_waitcnt lgkmcnt(0)
	s_setprio 1
	v_mfma_f32_16x16x32_bf16 v[30:33], v[210:213], v[132:135], v[30:33]
	v_mfma_f32_16x16x32_bf16 v[34:37], v[210:213], v[140:143], v[34:37]
	v_mfma_f32_16x16x32_bf16 v[178:181], v[152:155], v[132:135], v[178:181]
	v_mfma_f32_16x16x32_bf16 v[182:185], v[152:155], v[140:143], v[182:185]
	v_mfma_f32_16x16x32_bf16 v[186:189], v[160:163], v[132:135], v[186:189]
	v_mfma_f32_16x16x32_bf16 v[190:193], v[160:163], v[140:143], v[190:193]
	v_mfma_f32_16x16x32_bf16 v[194:197], v[202:205], v[132:135], v[194:197]
	v_mfma_f32_16x16x32_bf16 v[198:201], v[202:205], v[140:143], v[198:201]
	v_mfma_f32_16x16x32_bf16 v[30:33], v[214:217], v[136:139], v[30:33]
	v_mfma_f32_16x16x32_bf16 v[34:37], v[214:217], v[144:147], v[34:37]
	v_mfma_f32_16x16x32_bf16 v[178:181], v[156:159], v[136:139], v[178:181]
	v_mfma_f32_16x16x32_bf16 v[182:185], v[156:159], v[144:147], v[182:185]
	v_mfma_f32_16x16x32_bf16 v[186:189], v[164:167], v[136:139], v[186:189]
	v_mfma_f32_16x16x32_bf16 v[190:193], v[164:167], v[144:147], v[190:193]
	v_mfma_f32_16x16x32_bf16 v[194:197], v[206:209], v[136:139], v[194:197]
	v_mfma_f32_16x16x32_bf16 v[198:201], v[206:209], v[144:147], v[198:201]
	s_setprio 0
	s_barrier
	v_mov_b32_e32 v148, v4
	s_mov_b32 m0, s69
	v_lshl_add_u64 v[110:111], v[148:149], 1, s[4:5]
	v_lshl_add_u64 v[110:111], v[110:111], 0, s[80:81]
	v_mov_b32_e32 v148, v6
	global_load_lds_dwordx4 v[110:111], off
	s_mov_b32 m0, s66
	v_lshl_add_u64 v[110:111], v[148:149], 1, s[4:5]
	v_lshl_add_u64 v[110:111], v[110:111], 0, s[80:81]
	global_load_lds_dwordx4 v[110:111], off
	s_waitcnt vmcnt(6)
	s_barrier
; #define LDA(dst, b, h)                                                                                    \
;   _Pragma("unroll") for (int m = 0; m < 4; ++m) _Pragma("unroll") for (int k = 0; k < 2; ++k)             \
;       dst[m][k] = *reinterpret_cast<const bf16x8*>((char*)SA(b, h) + lds_byte(wr * 64 + m * 16 + fr, k * 32 + fq * 8))
; #define LDB(dst, b, h)                                                                                    \
;   _Pragma("unroll") for (int n = 0; n < 2; ++n) _Pragma("unroll") for (int k = 0; k < 2; ++k)             \
;       dst[n][k] = *reinterpret_cast<const bf16x8*>((char*)SB(b, h) + lds_byte(wc * 32 + n * 16 + fr, k * 32 + fq * 8))
; #define WAIT_V(n) asm volatile("s_waitcnt vmcnt(" #n ")" ::: "memory")
; #define WAIT_L(n) asm volatile("s_waitcnt lgkmcnt(" #n ")" ::: "memory")
; #define BAR __builtin_amdgcn_s_barrier()
; #define SCHED __builtin_amdgcn_sched_barrier(0)
; template <int EPI> ...
;     ...
;     WAIT_V(6); BAR; MMA(1, 1, At, B1); BAR;
;     LDB(B0, 1, 0); SCHED; LDA(At, 1, 0); STAGE(SA(0, 1), A, brow + HALF, t + 2);
;     WAIT_L(8); BAR; WAIT_L(0); MMA(0, 0, At, B0); BAR; SCHED;
;     LDB(B1, 1, 1); STAGE(SB(1, 0), Bt, bcol, t + 3);
;     BAR; WAIT_L(0); MMA(0, 1, At, B1); BAR;
;     LDA(At, 1, 1); STAGE(SA(1, 0), A, brow, t + 3);
	s_setprio 1
	v_mfma_f32_16x16x32_bf16 v[22:25], v[152:155], v[218:221], v[22:25]
	v_mfma_f32_16x16x32_bf16 v[38:41], v[152:155], v[226:229], v[38:41]
	v_mfma_f32_16x16x32_bf16 v[42:45], v[160:163], v[218:221], v[42:45]
	v_mfma_f32_16x16x32_bf16 v[74:77], v[160:163], v[226:229], v[74:77]
	v_mfma_f32_16x16x32_bf16 v[120:123], v[202:205], v[218:221], v[120:123]
	v_mfma_f32_16x16x32_bf16 v[124:127], v[202:205], v[226:229], v[124:127]
	v_mfma_f32_16x16x32_bf16 v[110:113], v[210:213], v[218:221], v[112:115]
	v_mfma_f32_16x16x32_bf16 v[114:117], v[210:213], v[226:229], v[116:119]
	v_mfma_f32_16x16x32_bf16 v[22:25], v[156:159], v[222:225], v[22:25]
	v_mfma_f32_16x16x32_bf16 v[38:41], v[156:159], v[230:233], v[38:41]
	v_mfma_f32_16x16x32_bf16 v[42:45], v[164:167], v[222:225], v[42:45]
	v_mfma_f32_16x16x32_bf16 v[74:77], v[164:167], v[230:233], v[74:77]
	v_mfma_f32_16x16x32_bf16 v[120:123], v[206:209], v[222:225], v[120:123]
	v_mfma_f32_16x16x32_bf16 v[124:127], v[206:209], v[230:233], v[124:127]
	v_mfma_f32_16x16x32_bf16 v[110:113], v[214:217], v[222:225], v[110:113]
	v_mfma_f32_16x16x32_bf16 v[114:117], v[214:217], v[230:233], v[114:117]
	s_setprio 0
	s_barrier
	ds_read_b128 v[132:135], v0
	ds_read_b128 v[136:139], v1
	ds_read_b128 v[140:143], v2
	ds_read_b128 v[144:147], v3
	v_mov_b32_e32 v148, v4
	ds_read_b128 v[152:155], v8 offset:32768
	ds_read_b128 v[156:159], v8 offset:33792
	ds_read_b128 v[160:163], v9 offset:34816
	ds_read_b128 v[164:167], v9 offset:35840
	ds_read_b128 v[202:205], v9 offset:36864
	ds_read_b128 v[206:209], v9 offset:37888
	ds_read_b128 v[210:213], v9 offset:38912
	ds_read_b128 v[214:217], v9 offset:39936
	s_mov_b32 m0, s75
	v_lshl_add_u64 v[118:119], v[148:149], 1, s[0:1]
	v_lshl_add_u64 v[118:119], v[118:119], 0, s[80:81]
	v_mov_b32_e32 v148, v6
	global_load_lds_dwordx4 v[118:119], off
	s_mov_b32 m0, s68
	v_lshl_add_u64 v[118:119], v[148:149], 1, s[0:1]
	v_lshl_add_u64 v[118:119], v[118:119], 0, s[80:81]
	global_load_lds_dwordx4 v[118:119], off
	s_waitcnt lgkmcnt(8)
	s_barrier
	s_waitcnt lgkmcnt(0)
	s_setprio 1
	v_mfma_f32_16x16x32_bf16 v[78:81], v[152:155], v[132:135], v[78:81]
	v_mfma_f32_16x16x32_bf16 v[82:85], v[152:155], v[140:143], v[82:85]
	v_mfma_f32_16x16x32_bf16 v[86:89], v[160:163], v[132:135], v[86:89]
	v_mfma_f32_16x16x32_bf16 v[90:93], v[160:163], v[140:143], v[90:93]
	v_mfma_f32_16x16x32_bf16 v[94:97], v[202:205], v[132:135], v[94:97]
	v_mfma_f32_16x16x32_bf16 v[98:101], v[202:205], v[140:143], v[98:101]
	v_mfma_f32_16x16x32_bf16 v[102:105], v[210:213], v[132:135], v[102:105]
	v_mfma_f32_16x16x32_bf16 v[106:109], v[210:213], v[140:143], v[106:109]
	v_mfma_f32_16x16x32_bf16 v[78:81], v[156:159], v[136:139], v[78:81]
	v_mfma_f32_16x16x32_bf16 v[82:85], v[156:159], v[144:147], v[82:85]
	v_mfma_f32_16x16x32_bf16 v[86:89], v[164:167], v[136:139], v[86:89]
	v_mfma_f32_16x16x32_bf16 v[90:93], v[164:167], v[144:147], v[90:93]
	v_mfma_f32_16x16x32_bf16 v[94:97], v[206:209], v[136:139], v[94:97]
	v_mfma_f32_16x16x32_bf16 v[98:101], v[206:209], v[144:147], v[98:101]
	v_mfma_f32_16x16x32_bf16 v[102:105], v[214:217], v[136:139], v[102:105]
	v_mfma_f32_16x16x32_bf16 v[106:109], v[214:217], v[144:147], v[106:109]
	s_setprio 0
	s_barrier
	v_mov_b32_e32 v148, v4
	ds_read_b128 v[218:221], v18
	ds_read_b128 v[222:225], v19
	ds_read_b128 v[226:229], v20
	ds_read_b128 v[230:233], v21
	s_mov_b64 s[64:65], 0x280
	v_lshl_add_u64 v[118:119], v[148:149], 1, s[14:15]
	s_mov_b32 m0, s77
	v_lshl_add_u64 v[118:119], v[118:119], 0, s[64:65]
	v_mov_b32_e32 v148, v6
	global_load_lds_dwordx4 v[118:119], off
	s_mov_b32 m0, s71
	v_lshl_add_u64 v[118:119], v[148:149], 1, s[14:15]
	v_lshl_add_u64 v[118:119], v[118:119], 0, s[64:65]
	global_load_lds_dwordx4 v[118:119], off
	s_barrier
	s_waitcnt lgkmcnt(0)
	s_setprio 1
	v_mfma_f32_16x16x32_bf16 v[26:29], v[152:155], v[218:221], v[26:29]
	v_mfma_f32_16x16x32_bf16 v[46:49], v[152:155], v[226:229], v[46:49]
	v_mfma_f32_16x16x32_bf16 v[50:53], v[160:163], v[218:221], v[50:53]
	v_mfma_f32_16x16x32_bf16 v[54:57], v[160:163], v[226:229], v[54:57]
	v_mfma_f32_16x16x32_bf16 v[58:61], v[202:205], v[218:221], v[58:61]
	v_mfma_f32_16x16x32_bf16 v[62:65], v[202:205], v[226:229], v[62:65]
	v_mfma_f32_16x16x32_bf16 v[66:69], v[210:213], v[218:221], v[66:69]
	v_mfma_f32_16x16x32_bf16 v[70:73], v[210:213], v[226:229], v[70:73]
	v_mfma_f32_16x16x32_bf16 v[26:29], v[156:159], v[222:225], v[26:29]
	v_mfma_f32_16x16x32_bf16 v[46:49], v[156:159], v[230:233], v[46:49]
	v_mfma_f32_16x16x32_bf16 v[50:53], v[164:167], v[222:225], v[50:53]
	v_mfma_f32_16x16x32_bf16 v[54:57], v[164:167], v[230:233], v[54:57]
	v_mfma_f32_16x16x32_bf16 v[58:61], v[206:209], v[222:225], v[58:61]
	v_mfma_f32_16x16x32_bf16 v[62:65], v[206:209], v[230:233], v[62:65]
	v_mfma_f32_16x16x32_bf16 v[66:69], v[214:217], v[222:225], v[66:69]
	v_mfma_f32_16x16x32_bf16 v[70:73], v[214:217], v[230:233], v[70:73]
	s_setprio 0
	v_mov_b32_e32 v148, v4
	s_barrier
	ds_read_b128 v[152:155], v8 offset:49152
	ds_read_b128 v[156:159], v8 offset:50176
	ds_read_b128 v[160:163], v9 offset:51200
	ds_read_b128 v[164:167], v9 offset:52224
	ds_read_b128 v[202:205], v9 offset:53248
	ds_read_b128 v[206:209], v9 offset:54272
	ds_read_b128 v[210:213], v9 offset:55296
	ds_read_b128 v[214:217], v9 offset:56320
	s_mov_b32 m0, s78
	v_lshl_add_u64 v[118:119], v[148:149], 1, s[12:13]
	v_lshl_add_u64 v[118:119], v[118:119], 0, s[64:65]
	v_mov_b32_e32 v148, v6
	global_load_lds_dwordx4 v[118:119], off
	s_mov_b32 m0, s72
	v_lshl_add_u64 v[118:119], v[148:149], 1, s[12:13]
	v_lshl_add_u64 v[118:119], v[118:119], 0, s[64:65]
	global_load_lds_dwordx4 v[118:119], off
	s_barrier
; #define LDA(dst, b, h)                                                                                    \
;   _Pragma("unroll") for (int m = 0; m < 4; ++m) _Pragma("unroll") for (int k = 0; k < 2; ++k)             \
;       dst[m][k] = *reinterpret_cast<const bf16x8*>((char*)SA(b, h) + lds_byte(wr * 64 + m * 16 + fr, k * 32 + fq * 8))
; #define LDB(dst, b, h)                                                                                    \
;   _Pragma("unroll") for (int n = 0; n < 2; ++n) _Pragma("unroll") for (int k = 0; k < 2; ++k)             \
;       dst[n][k] = *reinterpret_cast<const bf16x8*>((char*)SB(b, h) + lds_byte(wc * 32 + n * 16 + fr, k * 32 + fq * 8))
; #define WAIT_V(n) asm volatile("s_waitcnt vmcnt(" #n ")" ::: "memory")
; #define WAIT_L(n) asm volatile("s_waitcnt lgkmcnt(" #n ")" ::: "memory")
; #define BAR __builtin_amdgcn_s_barrier()
; #define SCHED __builtin_amdgcn_sched_barrier(0)
; template <int EPI> ...
;     ...
;     BAR; WAIT_L(0); MMA(1, 0, At, B0); BAR; SCHED;
;     STAGE(SB(1, 1), Bt, bcol + HALF, t + 3);
;     WAIT_V(6); BAR; MMA(1, 1, At, B1); BAR;
;   }
;   {
;     LDB(B0, 0, 0); LDA(At, 0, 0); STAGE(SA(1, 1), A, brow + HALF, nt - 1);
;     BAR; WAIT_L(0); MMA(0, 0, At, B0); BAR;
;     LDB(B1, 0, 1); BAR; WAIT_L(0); MMA(0, 1, At, B1); BAR;
	s_waitcnt lgkmcnt(0)
	s_setprio 1
	v_mfma_f32_16x16x32_bf16 v[30:33], v[210:213], v[132:135], v[30:33]
	v_mfma_f32_16x16x32_bf16 v[34:37], v[210:213], v[140:143], v[34:37]
	v_mfma_f32_16x16x32_bf16 v[178:181], v[152:155], v[132:135], v[178:181]
	v_mfma_f32_16x16x32_bf16 v[182:185], v[152:155], v[140:143], v[182:185]
	v_mfma_f32_16x16x32_bf16 v[186:189], v[160:163], v[132:135], v[186:189]
	v_mfma_f32_16x16x32_bf16 v[190:193], v[160:163], v[140:143], v[190:193]
	v_mfma_f32_16x16x32_bf16 v[194:197], v[202:205], v[132:135], v[194:197]
	v_mfma_f32_16x16x32_bf16 v[198:201], v[202:205], v[140:143], v[198:201]
	v_mfma_f32_16x16x32_bf16 v[30:33], v[214:217], v[136:139], v[30:33]
	v_mfma_f32_16x16x32_bf16 v[34:37], v[214:217], v[144:147], v[34:37]
	v_mfma_f32_16x16x32_bf16 v[178:181], v[156:159], v[136:139], v[178:181]
	v_mfma_f32_16x16x32_bf16 v[182:185], v[156:159], v[144:147], v[182:185]
	v_mfma_f32_16x16x32_bf16 v[186:189], v[164:167], v[136:139], v[186:189]
	v_mfma_f32_16x16x32_bf16 v[190:193], v[164:167], v[144:147], v[190:193]
	v_mfma_f32_16x16x32_bf16 v[194:197], v[206:209], v[136:139], v[194:197]
	v_mfma_f32_16x16x32_bf16 v[198:201], v[206:209], v[144:147], v[198:201]
	s_setprio 0
	s_barrier
	v_mov_b32_e32 v148, v4
	s_mov_b32 m0, s76
	v_lshl_add_u64 v[118:119], v[148:149], 1, s[4:5]
	v_lshl_add_u64 v[118:119], v[118:119], 0, s[64:65]
	v_mov_b32_e32 v148, v6
	global_load_lds_dwordx4 v[118:119], off
	s_mov_b32 m0, s74
	v_lshl_add_u64 v[118:119], v[148:149], 1, s[4:5]
	v_lshl_add_u64 v[118:119], v[118:119], 0, s[64:65]
	global_load_lds_dwordx4 v[118:119], off
	s_waitcnt vmcnt(6)
	s_barrier
	s_setprio 1
	v_mfma_f32_16x16x32_bf16 v[22:25], v[152:155], v[218:221], v[22:25]
	v_mfma_f32_16x16x32_bf16 v[38:41], v[152:155], v[226:229], v[38:41]
	v_mfma_f32_16x16x32_bf16 v[42:45], v[160:163], v[218:221], v[42:45]
	v_mfma_f32_16x16x32_bf16 v[74:77], v[160:163], v[226:229], v[74:77]
	v_mfma_f32_16x16x32_bf16 v[118:121], v[202:205], v[218:221], v[120:123]
	v_mfma_f32_16x16x32_bf16 v[122:125], v[202:205], v[226:229], v[124:127]
	v_mfma_f32_16x16x32_bf16 v[110:113], v[210:213], v[218:221], v[110:113]
	v_mfma_f32_16x16x32_bf16 v[114:117], v[210:213], v[226:229], v[114:117]
	v_mfma_f32_16x16x32_bf16 v[22:25], v[156:159], v[222:225], v[22:25]
	v_mfma_f32_16x16x32_bf16 v[38:41], v[156:159], v[230:233], v[38:41]
	v_mfma_f32_16x16x32_bf16 v[42:45], v[164:167], v[222:225], v[42:45]
	v_mfma_f32_16x16x32_bf16 v[74:77], v[164:167], v[230:233], v[74:77]
	v_mfma_f32_16x16x32_bf16 v[118:121], v[206:209], v[222:225], v[118:121]
	v_mfma_f32_16x16x32_bf16 v[122:125], v[206:209], v[230:233], v[122:125]
	v_mfma_f32_16x16x32_bf16 v[110:113], v[214:217], v[222:225], v[110:113]
	v_mfma_f32_16x16x32_bf16 v[114:117], v[214:217], v[230:233], v[114:117]
	s_setprio 0
	s_barrier
	ds_read_b128 v[132:135], v5
	ds_read_b128 v[136:139], v7
	ds_read_b128 v[140:143], v10
	ds_read_b128 v[144:147], v11
	ds_read_b128 v[152:155], v8
	ds_read_b128 v[156:159], v8 offset:1024
	ds_read_b128 v[160:163], v9 offset:2048
	ds_read_b128 v[164:167], v9 offset:3072
	ds_read_b128 v[202:205], v9 offset:4096
	ds_read_b128 v[206:209], v9 offset:5120
	ds_read_b128 v[210:213], v9 offset:6144
	ds_read_b128 v[214:217], v9 offset:7168
	v_mov_b32_e32 v5, v149
	v_lshl_add_u64 v[4:5], v[4:5], 1, s[0:1]
	v_readfirstlane_b32 s4, v12
	v_lshl_add_u64 v[4:5], v[4:5], 0, s[64:65]
	s_mov_b32 m0, s4
	v_mov_b32_e32 v7, v149
	global_load_lds_dwordx4 v[4:5], off
	s_nop 0
	v_lshl_add_u64 v[4:5], v[6:7], 1, s[0:1]
	v_readfirstlane_b32 s0, v13
	v_lshl_add_u64 v[4:5], v[4:5], 0, s[64:65]
	s_mov_b32 m0, s0
	s_nop 0
	global_load_lds_dwordx4 v[4:5], off
	s_barrier
	s_waitcnt lgkmcnt(0)
	s_setprio 1
	v_mfma_f32_16x16x32_bf16 v[4:7], v[152:155], v[132:135], v[78:81]
	v_mfma_f32_16x16x32_bf16 v[10:13], v[152:155], v[140:143], v[82:85]
	v_mfma_f32_16x16x32_bf16 v[78:81], v[160:163], v[132:135], v[86:89]
	v_mfma_f32_16x16x32_bf16 v[82:85], v[160:163], v[140:143], v[90:93]
	v_mfma_f32_16x16x32_bf16 v[88:91], v[202:205], v[132:135], v[94:97]
	v_mfma_f32_16x16x32_bf16 v[92:95], v[202:205], v[140:143], v[98:101]
	v_mfma_f32_16x16x32_bf16 v[96:99], v[206:209], v[144:147], v[92:95]
	v_mfma_f32_16x16x32_bf16 v[92:95], v[210:213], v[132:135], v[102:105]
	v_mfma_f32_16x16x32_bf16 v[218:221], v[214:217], v[136:139], v[92:95]
	v_mfma_f32_16x16x32_bf16 v[92:95], v[210:213], v[140:143], v[106:109]
	v_mfma_f32_16x16x32_bf16 v[4:7], v[156:159], v[136:139], v[4:7]
	v_mfma_f32_16x16x32_bf16 v[10:13], v[156:159], v[144:147], v[10:13]
	v_mfma_f32_16x16x32_bf16 v[78:81], v[164:167], v[136:139], v[78:81]
	v_mfma_f32_16x16x32_bf16 v[84:87], v[164:167], v[144:147], v[82:85]
	v_mfma_f32_16x16x32_bf16 v[88:91], v[206:209], v[136:139], v[88:91]
	v_mfma_f32_16x16x32_bf16 v[104:107], v[214:217], v[144:147], v[92:95]
	s_setprio 0
	s_barrier
	s_nop 0
	ds_read_b128 v[92:95], v14
	ds_read_b128 v[100:103], v15
	ds_read_b128 v[222:225], v16
	ds_read_b128 v[14:17], v17
	s_barrier
	s_waitcnt lgkmcnt(0)
	s_setprio 1
	v_mfma_f32_16x16x32_bf16 v[62:65], v[202:205], v[222:225], v[62:65]
	v_mfma_f32_16x16x32_bf16 v[26:29], v[152:155], v[92:95], v[26:29]
	v_mfma_f32_16x16x32_bf16 v[46:49], v[152:155], v[222:225], v[46:49]
	v_mfma_f32_16x16x32_bf16 v[50:53], v[160:163], v[92:95], v[50:53]
	v_mfma_f32_16x16x32_bf16 v[54:57], v[160:163], v[222:225], v[54:57]
	v_mfma_f32_16x16x32_bf16 v[58:61], v[202:205], v[92:95], v[58:61]
	v_mfma_f32_16x16x32_bf16 v[152:155], v[206:209], v[14:17], v[62:65]
	v_mfma_f32_16x16x32_bf16 v[62:65], v[210:213], v[92:95], v[66:69]
	v_mfma_f32_16x16x32_bf16 v[26:29], v[156:159], v[100:103], v[26:29]
	v_mfma_f32_16x16x32_bf16 v[46:49], v[156:159], v[14:17], v[46:49]
	v_mfma_f32_16x16x32_bf16 v[50:53], v[164:167], v[100:103], v[50:53]
	v_mfma_f32_16x16x32_bf16 v[54:57], v[164:167], v[14:17], v[54:57]
	v_mfma_f32_16x16x32_bf16 v[58:61], v[206:209], v[100:103], v[58:61]
	v_mfma_f32_16x16x32_bf16 v[156:159], v[214:217], v[100:103], v[62:65]
	v_mfma_f32_16x16x32_bf16 v[62:65], v[210:213], v[222:225], v[70:73]
	v_mfma_f32_16x16x32_bf16 v[160:163], v[214:217], v[14:17], v[62:65]
	s_setprio 0
	s_barrier
; #define LDA(dst, b, h)                                                                                    \
;   _Pragma("unroll") for (int m = 0; m < 4; ++m) _Pragma("unroll") for (int k = 0; k < 2; ++k)             \
;       dst[m][k] = *reinterpret_cast<const bf16x8*>((char*)SA(b, h) + lds_byte(wr * 64 + m * 16 + fr, k * 32 + fq * 8))
; #define LDB(dst, b, h)                                                                                    \
;   _Pragma("unroll") for (int n = 0; n < 2; ++n) _Pragma("unroll") for (int k = 0; k < 2; ++k)             \
;       dst[n][k] = *reinterpret_cast<const bf16x8*>((char*)SB(b, h) + lds_byte(wc * 32 + n * 16 + fr, k * 32 + fq * 8))
; #define WAIT_V(n) asm volatile("s_waitcnt vmcnt(" #n ")" ::: "memory")
; #define WAIT_L(n) asm volatile("s_waitcnt lgkmcnt(" #n ")" ::: "memory")
; #define BAR __builtin_amdgcn_s_barrier()
; template <int EPI> ...
;     ...
;     LDA(At, 0, 1); WAIT_V(4); BAR; WAIT_L(0); MMA(1, 0, At, B0); MMA(1, 1, At, B1); BAR;
;   }
;   {
;     LDB(B0, 1, 0); LDA(At, 1, 0); WAIT_V(2); BAR; WAIT_L(0); MMA(0, 0, At, B0); BAR;
	s_nop 4
	ds_read_b128 v[62:65], v8 offset:16384
	ds_read_b128 v[66:69], v8 offset:17408
	ds_read_b128 v[70:73], v9 offset:18432
	ds_read_b128 v[164:167], v9 offset:19456
	ds_read_b128 v[202:205], v9 offset:20480
	ds_read_b128 v[206:209], v9 offset:21504
	ds_read_b128 v[210:213], v9 offset:22528
	ds_read_b128 v[214:217], v9 offset:23552
	s_waitcnt vmcnt(4)
	s_barrier
	s_waitcnt lgkmcnt(0)
	s_setprio 1
	v_mfma_f32_16x16x32_bf16 v[30:33], v[210:213], v[132:135], v[30:33]
	v_mfma_f32_16x16x32_bf16 v[178:181], v[62:65], v[132:135], v[178:181]
	v_mfma_f32_16x16x32_bf16 v[186:189], v[70:73], v[132:135], v[186:189]
	v_mfma_f32_16x16x32_bf16 v[194:197], v[202:205], v[132:135], v[194:197]
	v_mfma_f32_16x16x32_bf16 v[132:135], v[214:217], v[136:139], v[30:33]
	v_mfma_f32_16x16x32_bf16 v[30:33], v[210:213], v[140:143], v[34:37]
	v_mfma_f32_16x16x32_bf16 v[182:185], v[62:65], v[140:143], v[182:185]
	v_mfma_f32_16x16x32_bf16 v[190:193], v[70:73], v[140:143], v[190:193]
	v_mfma_f32_16x16x32_bf16 v[198:201], v[202:205], v[140:143], v[198:201]
	v_mfma_f32_16x16x32_bf16 v[32:35], v[214:217], v[144:147], v[30:33]
	v_mfma_f32_16x16x32_bf16 v[178:181], v[66:69], v[136:139], v[178:181]
	v_mfma_f32_16x16x32_bf16 v[182:185], v[66:69], v[144:147], v[182:185]
	v_mfma_f32_16x16x32_bf16 v[186:189], v[164:167], v[136:139], v[186:189]
	v_mfma_f32_16x16x32_bf16 v[190:193], v[164:167], v[144:147], v[190:193]
	v_mfma_f32_16x16x32_bf16 v[194:197], v[206:209], v[136:139], v[194:197]
	v_mfma_f32_16x16x32_bf16 v[198:201], v[206:209], v[144:147], v[198:201]
	s_setprio 0
	s_setprio 1
	v_mfma_f32_16x16x32_bf16 v[22:25], v[62:65], v[92:95], v[22:25]
	v_mfma_f32_16x16x32_bf16 v[136:139], v[66:69], v[100:103], v[22:25]
	v_mfma_f32_16x16x32_bf16 v[22:25], v[62:65], v[222:225], v[38:41]
	v_mfma_f32_16x16x32_bf16 v[36:39], v[66:69], v[14:17], v[22:25]
	v_mfma_f32_16x16x32_bf16 v[22:25], v[70:73], v[92:95], v[42:45]
	v_mfma_f32_16x16x32_bf16 v[40:43], v[164:167], v[100:103], v[22:25]
	v_mfma_f32_16x16x32_bf16 v[22:25], v[70:73], v[222:225], v[74:77]
	v_mfma_f32_16x16x32_bf16 v[140:143], v[164:167], v[14:17], v[22:25]
	v_mfma_f32_16x16x32_bf16 v[22:25], v[202:205], v[92:95], v[118:121]
	v_mfma_f32_16x16x32_bf16 v[144:147], v[206:209], v[100:103], v[22:25]
	v_mfma_f32_16x16x32_bf16 v[22:25], v[202:205], v[222:225], v[122:125]
	v_mfma_f32_16x16x32_bf16 v[164:167], v[206:209], v[14:17], v[22:25]
	v_mfma_f32_16x16x32_bf16 v[22:25], v[210:213], v[92:95], v[110:113]
	v_mfma_f32_16x16x32_bf16 v[202:205], v[214:217], v[100:103], v[22:25]
	v_mfma_f32_16x16x32_bf16 v[22:25], v[210:213], v[222:225], v[114:117]
	v_mfma_f32_16x16x32_bf16 v[206:209], v[214:217], v[14:17], v[22:25]
	s_setprio 0
	s_barrier
	ds_read_b128 v[210:213], v0
	ds_read_b128 v[214:217], v1
	ds_read_b128 v[222:225], v2
	ds_read_b128 v[226:229], v3
	ds_read_b128 v[0:3], v8 offset:32768
	ds_read_b128 v[14:17], v8 offset:33792
	ds_read_b128 v[22:25], v9 offset:34816
	ds_read_b128 v[108:111], v9 offset:35840
	ds_read_b128 v[230:233], v9 offset:36864
	ds_read_b128 v[234:237], v9 offset:37888
	ds_read_b128 v[238:241], v9 offset:38912
	ds_read_b128 v[242:245], v9 offset:39936
	s_waitcnt vmcnt(2)
	s_barrier
	s_waitcnt lgkmcnt(0)
	s_setprio 1
	v_mfma_f32_16x16x32_bf16 v[4:7], v[0:3], v[210:213], v[4:7]
	v_mfma_f32_16x16x32_bf16 v[92:95], v[14:17], v[214:217], v[4:7]
	v_mfma_f32_16x16x32_bf16 v[4:7], v[0:3], v[222:225], v[10:13]
	v_mfma_f32_16x16x32_bf16 v[100:103], v[14:17], v[226:229], v[4:7]
	v_mfma_f32_16x16x32_bf16 v[4:7], v[22:25], v[210:213], v[78:81]
	v_mfma_f32_16x16x32_bf16 v[80:83], v[108:111], v[214:217], v[4:7]
	v_mfma_f32_16x16x32_bf16 v[4:7], v[22:25], v[222:225], v[84:87]
	v_mfma_f32_16x16x32_bf16 v[84:87], v[108:111], v[226:229], v[4:7]
	v_mfma_f32_16x16x32_bf16 v[4:7], v[230:233], v[210:213], v[88:91]
	v_mfma_f32_16x16x32_bf16 v[72:75], v[234:237], v[214:217], v[4:7]
	v_mfma_f32_16x16x32_bf16 v[4:7], v[230:233], v[222:225], v[96:99]
	v_mfma_f32_16x16x32_bf16 v[76:79], v[234:237], v[226:229], v[4:7]
	v_mfma_f32_16x16x32_bf16 v[4:7], v[238:241], v[210:213], v[218:221]
	v_mfma_f32_16x16x32_bf16 v[64:67], v[242:245], v[214:217], v[4:7]
	v_mfma_f32_16x16x32_bf16 v[4:7], v[238:241], v[222:225], v[104:107]
	v_mfma_f32_16x16x32_bf16 v[68:71], v[242:245], v[226:229], v[4:7]
	s_setprio 0
	s_barrier
; #define LDA(dst, b, h)                                                                                    \
;   _Pragma("unroll") for (int m = 0; m < 4; ++m) _Pragma("unroll") for (int k = 0; k < 2; ++k)             \
;       dst[m][k] = *reinterpret_cast<const bf16x8*>((char*)SA(b, h) + lds_byte(wr * 64 + m * 16 + fr, k * 32 + fq * 8))
; #define LDB(dst, b, h)                                                                                    \
;   _Pragma("unroll") for (int n = 0; n < 2; ++n) _Pragma("unroll") for (int k = 0; k < 2; ++k)             \
;       dst[n][k] = *reinterpret_cast<const bf16x8*>((char*)SB(b, h) + lds_byte(wc * 32 + n * 16 + fr, k * 32 + fq * 8))
; #define WAIT_V(n) asm volatile("s_waitcnt vmcnt(" #n ")" ::: "memory")
; #define WAIT_L(n) asm volatile("s_waitcnt lgkmcnt(" #n ")" ::: "memory")
; #define BAR __builtin_amdgcn_s_barrier()
; template <int EPI> ...
;     ...
;     LDB(B1, 1, 1); WAIT_V(0); BAR; WAIT_L(0); MMA(0, 1, At, B1); BAR;
;     LDA(At, 1, 1); BAR; WAIT_L(0); MMA(1, 0, At, B0); MMA(1, 1, At, B1); BAR;
;   }
;   if (wr == 0) BAR;
	ds_read_b128 v[218:221], v18
	ds_read_b128 v[246:249], v19
	ds_read_b128 v[250:253], v20
	ds_read_b128 v[174:177], v21
	s_waitcnt vmcnt(0)
	s_barrier
	s_waitcnt lgkmcnt(0)
	s_setprio 1
	v_mfma_f32_16x16x32_bf16 v[4:7], v[0:3], v[218:221], v[26:29]
	v_mfma_f32_16x16x32_bf16 v[0:3], v[0:3], v[250:253], v[46:49]
	v_mfma_f32_16x16x32_bf16 v[124:127], v[14:17], v[174:177], v[0:3]
	v_mfma_f32_16x16x32_bf16 v[0:3], v[22:25], v[218:221], v[50:53]
	v_mfma_f32_16x16x32_bf16 v[112:115], v[108:111], v[246:249], v[0:3]
	v_mfma_f32_16x16x32_bf16 v[0:3], v[22:25], v[250:253], v[54:57]
	v_mfma_f32_16x16x32_bf16 v[116:119], v[108:111], v[174:177], v[0:3]
	v_mfma_f32_16x16x32_bf16 v[0:3], v[230:233], v[218:221], v[58:61]
	v_mfma_f32_16x16x32_bf16 v[104:107], v[234:237], v[246:249], v[0:3]
	v_mfma_f32_16x16x32_bf16 v[0:3], v[230:233], v[250:253], v[152:155]
	v_mfma_f32_16x16x32_bf16 v[108:111], v[234:237], v[174:177], v[0:3]
	v_mfma_f32_16x16x32_bf16 v[0:3], v[238:241], v[218:221], v[156:159]
	v_mfma_f32_16x16x32_bf16 v[88:91], v[242:245], v[246:249], v[0:3]
	v_mfma_f32_16x16x32_bf16 v[0:3], v[238:241], v[250:253], v[160:163]
	v_mfma_f32_16x16x32_bf16 v[120:123], v[14:17], v[246:249], v[4:7]
	v_mfma_f32_16x16x32_bf16 v[96:99], v[242:245], v[174:177], v[0:3]
	s_setprio 0
	s_barrier
	ds_read_b128 v[44:47], v8 offset:49152
	ds_read_b128 v[48:51], v8 offset:50176
	ds_read_b128 v[52:55], v9 offset:51200
	ds_read_b128 v[152:155], v9 offset:52224
	ds_read_b128 v[156:159], v9 offset:53248
	ds_read_b128 v[160:163], v9 offset:54272
	ds_read_b128 v[230:233], v9 offset:55296
	ds_read_b128 v[234:237], v9 offset:56320
	s_barrier
	s_waitcnt lgkmcnt(0)
	s_setprio 1
	v_mfma_f32_16x16x32_bf16 v[0:3], v[44:47], v[210:213], v[178:181]
	v_mfma_f32_16x16x32_bf16 v[24:27], v[48:51], v[214:217], v[0:3]
	v_mfma_f32_16x16x32_bf16 v[0:3], v[44:47], v[222:225], v[182:185]
	v_mfma_f32_16x16x32_bf16 v[28:31], v[48:51], v[226:229], v[0:3]
	v_mfma_f32_16x16x32_bf16 v[0:3], v[52:55], v[210:213], v[186:189]
	v_mfma_f32_16x16x32_bf16 v[16:19], v[152:155], v[214:217], v[0:3]
	v_mfma_f32_16x16x32_bf16 v[0:3], v[52:55], v[222:225], v[190:193]
	v_mfma_f32_16x16x32_bf16 v[20:23], v[152:155], v[226:229], v[0:3]
	v_mfma_f32_16x16x32_bf16 v[0:3], v[156:159], v[210:213], v[194:197]
	v_mfma_f32_16x16x32_bf16 v[8:11], v[160:163], v[214:217], v[0:3]
	v_mfma_f32_16x16x32_bf16 v[0:3], v[156:159], v[222:225], v[198:201]
	v_mfma_f32_16x16x32_bf16 v[12:15], v[160:163], v[226:229], v[0:3]
	v_mfma_f32_16x16x32_bf16 v[0:3], v[230:233], v[210:213], v[132:135]
	v_mfma_f32_16x16x32_bf16 v[4:7], v[230:233], v[222:225], v[32:35]
	v_mfma_f32_16x16x32_bf16 v[0:3], v[234:237], v[214:217], v[0:3]
	v_mfma_f32_16x16x32_bf16 v[4:7], v[234:237], v[226:229], v[4:7]
	s_setprio 0
	s_setprio 1
	v_mfma_f32_16x16x32_bf16 v[32:35], v[44:47], v[218:221], v[136:139]
	v_mfma_f32_16x16x32_bf16 v[56:59], v[48:51], v[246:249], v[32:35]
	v_mfma_f32_16x16x32_bf16 v[32:35], v[44:47], v[250:253], v[36:39]
	v_mfma_f32_16x16x32_bf16 v[60:63], v[48:51], v[174:177], v[32:35]
	v_mfma_f32_16x16x32_bf16 v[32:35], v[52:55], v[218:221], v[40:43]
	v_mfma_f32_16x16x32_bf16 v[48:51], v[152:155], v[246:249], v[32:35]
	v_mfma_f32_16x16x32_bf16 v[32:35], v[52:55], v[250:253], v[140:143]
	v_mfma_f32_16x16x32_bf16 v[52:55], v[152:155], v[174:177], v[32:35]
	v_mfma_f32_16x16x32_bf16 v[32:35], v[156:159], v[218:221], v[144:147]
	v_mfma_f32_16x16x32_bf16 v[40:43], v[160:163], v[246:249], v[32:35]
	v_mfma_f32_16x16x32_bf16 v[32:35], v[156:159], v[250:253], v[164:167]
	v_mfma_f32_16x16x32_bf16 v[44:47], v[160:163], v[174:177], v[32:35]
	v_mfma_f32_16x16x32_bf16 v[32:35], v[230:233], v[218:221], v[202:205]
	v_mfma_f32_16x16x32_bf16 v[36:39], v[230:233], v[250:253], v[206:209]
	v_mfma_f32_16x16x32_bf16 v[32:35], v[234:237], v[246:249], v[32:35]
	v_mfma_f32_16x16x32_bf16 v[36:39], v[234:237], v[174:177], v[36:39]
	s_setprio 0
	s_cmpk_gt_u32 s23, 0xff
	s_barrier
	s_cbranch_scc1 .LBB0_706
	s_barrier

; #define LDA(dst, b, h)                                                                                    \
;   _Pragma("unroll") for (int m = 0; m < 4; ++m) _Pragma("unroll") for (int k = 0; k < 2; ++k)             \
;       dst[m][k] = *reinterpret_cast<const bf16x8*>((char*)SA(b, h) + lds_byte(wr * 64 + m * 16 + fr, k * 32 + fq * 8))
; #define LDB(dst, b, h)                                                                                    \
;   _Pragma("unroll") for (int n = 0; n < 2; ++n) _Pragma("unroll") for (int k = 0; k < 2; ++k)             \
;       dst[n][k] = *reinterpret_cast<const bf16x8*>((char*)SB(b, h) + lds_byte(wc * 32 + n * 16 + fr, k * 32 + fq * 8))
; #define WAIT_V(n) asm volatile("s_waitcnt vmcnt(" #n ")" ::: "memory")
; #define WAIT_L(n) asm volatile("s_waitcnt lgkmcnt(" #n ")" ::: "memory")
; #define BAR __builtin_amdgcn_s_barrier()
; #define SCHED __builtin_amdgcn_sched_barrier(0)
; template <int EPI> ...
;     ...
;   if (wr == 1) BAR;
;   WAIT_V(10); BAR;
;   WAIT_V(6); BAR;
;   for (int t = 0; t < nt - 2; t += 2) {
;     LDB(B0, 0, 0); SCHED; LDA(At, 0, 0); STAGE(SA(1, 1), A, brow + HALF, t + 1);
;     WAIT_L(8); BAR; WAIT_L(0); MMA(0, 0, At, B0); BAR; SCHED;
;     LDB(B1, 0, 1); STAGE(SB(0, 0), Bt, bcol, t + 2);
;     BAR; WAIT_L(0); MMA(0, 1, At, B1); BAR;
;     LDA(At, 0, 1); STAGE(SA(0, 0), A, brow, t + 2);
.LBB0_909:
	s_ashr_i32 s13, s64, 6
	v_and_b32_e32 v130, 15, v128
	s_and_b32 s15, s13, 3
	v_and_b32_e32 v9, 48, v128
	v_lshlrev_b32_e32 v1, 2, v128
	s_lshl_b32 s65, s15, 12
	v_lshl_or_b32 v8, v130, 6, v9
	v_and_b32_e32 v46, 32, v1
	v_bitop3_b32 v126, s65, v8, v46 bitop3:0xf6
	v_or_b32_e32 v127, 0x10000, v126
	v_or_b32_e32 v131, 0x10800, v126
	s_waitcnt vmcnt(10)
	s_barrier
	s_waitcnt vmcnt(6)
	s_barrier
	v_or_b32_e32 v129, 0x10400, v126
	ds_read_b128 v[22:25], v127
	ds_read_b128 v[26:29], v129
	v_or_b32_e32 v222, 0x10c00, v126
	ds_read_b128 v[30:33], v131
	ds_read_b128 v[34:37], v222
	v_mov_b32_e32 v1, v0
	v_mov_b32_e32 v2, v0
	v_mov_b32_e32 v3, v0
	v_lshlrev_b32_e32 v47, 6, v128
	s_movk_i32 s66, 0x3c0
	s_lshl_b32 s65, s63, 13
	v_and_or_b32 v9, v47, s66, v9
	v_bitop3_b32 v8, s65, v8, v46 bitop3:0xf6
	v_bitop3_b32 v9, s65, v9, v46 bitop3:0xf6
	v_mov_b32_e32 v148, v4
	v_add_u32_e32 v72, 0xc000, v12
	ds_read_b128 v[38:41], v8
	ds_read_b128 v[42:45], v8 offset:1024
	ds_read_b128 v[46:49], v9 offset:2048
	ds_read_b128 v[50:53], v9 offset:3072
	ds_read_b128 v[54:57], v9 offset:4096
	ds_read_b128 v[58:61], v9 offset:5120
	ds_read_b128 v[62:65], v9 offset:6144
	ds_read_b128 v[66:69], v9 offset:7168
	v_readfirstlane_b32 s66, v72
	v_lshl_add_u64 v[70:71], v[148:149], 1, s[2:3]
	v_lshl_add_u64 v[70:71], v[70:71], 0, s[46:47]
	s_mov_b32 m0, s66
	v_mov_b32_e32 v148, v6
	v_add_u32_e32 v72, 0xe000, v12
	global_load_lds_dwordx4 v[70:71], off
	v_readfirstlane_b32 s65, v72
	v_lshl_add_u64 v[70:71], v[148:149], 1, s[2:3]
	v_lshl_add_u64 v[70:71], v[70:71], 0, s[46:47]
	s_mov_b32 m0, s65
	s_nop 0
	global_load_lds_dwordx4 v[70:71], off
	s_waitcnt lgkmcnt(8)
	s_barrier
	s_waitcnt lgkmcnt(0)
	s_setprio 1
	v_mfma_f32_16x16x32_bf16 v[70:73], v[38:41], v[22:25], v[0:3]
	v_mfma_f32_16x16x32_bf16 v[74:77], v[38:41], v[30:33], v[0:3]
	v_mfma_f32_16x16x32_bf16 v[78:81], v[46:49], v[22:25], v[0:3]
	v_mfma_f32_16x16x32_bf16 v[82:85], v[46:49], v[30:33], v[0:3]
	v_mfma_f32_16x16x32_bf16 v[86:89], v[54:57], v[22:25], v[0:3]
	v_mfma_f32_16x16x32_bf16 v[90:93], v[54:57], v[30:33], v[0:3]
	v_mfma_f32_16x16x32_bf16 v[94:97], v[62:65], v[22:25], v[0:3]
	v_mfma_f32_16x16x32_bf16 v[98:101], v[62:65], v[30:33], v[0:3]
	v_mfma_f32_16x16x32_bf16 v[70:73], v[42:45], v[26:29], v[70:73]
	v_mfma_f32_16x16x32_bf16 v[74:77], v[42:45], v[34:37], v[74:77]
	v_mfma_f32_16x16x32_bf16 v[78:81], v[50:53], v[26:29], v[78:81]
	v_mfma_f32_16x16x32_bf16 v[82:85], v[50:53], v[34:37], v[82:85]
	v_mfma_f32_16x16x32_bf16 v[86:89], v[58:61], v[26:29], v[86:89]
	v_mfma_f32_16x16x32_bf16 v[90:93], v[58:61], v[34:37], v[90:93]
	v_mfma_f32_16x16x32_bf16 v[94:97], v[66:69], v[26:29], v[94:97]
	v_mfma_f32_16x16x32_bf16 v[98:101], v[66:69], v[34:37], v[98:101]
	s_setprio 0
	s_barrier
	v_or_b32_e32 v223, 0x14000, v126
	v_or_b32_e32 v225, 0x14800, v126
	v_mov_b32_e32 v148, v4
	v_or_b32_e32 v224, 0x14400, v126
	ds_read_b128 v[102:105], v223
	ds_read_b128 v[106:109], v224
	v_or_b32_e32 v226, 0x14c00, v126
	ds_read_b128 v[110:113], v225
	ds_read_b128 v[114:117], v226
	v_readfirstlane_b32 s67, v20
	v_lshl_add_u64 v[118:119], v[148:149], 1, s[22:23]
	v_lshl_add_u64 v[118:119], v[118:119], 0, s[50:51]
	s_mov_b32 m0, s67
	v_mov_b32_e32 v148, v6
	global_load_lds_dwordx4 v[118:119], off
	v_readfirstlane_b32 s67, v21
	v_lshl_add_u64 v[118:119], v[148:149], 1, s[22:23]
	v_lshl_add_u64 v[118:119], v[118:119], 0, s[50:51]
	s_mov_b32 m0, s67
	s_nop 0
	global_load_lds_dwordx4 v[118:119], off
	s_barrier
	s_waitcnt lgkmcnt(0)
	s_setprio 1
	v_mfma_f32_16x16x32_bf16 v[118:121], v[38:41], v[102:105], v[0:3]
	v_mfma_f32_16x16x32_bf16 v[38:41], v[38:41], v[110:113], v[0:3]
	v_mfma_f32_16x16x32_bf16 v[118:121], v[42:45], v[106:109], v[118:121]
	v_mfma_f32_16x16x32_bf16 v[38:41], v[42:45], v[114:117], v[38:41]
	v_mfma_f32_16x16x32_bf16 v[42:45], v[46:49], v[102:105], v[0:3]
	v_mfma_f32_16x16x32_bf16 v[46:49], v[46:49], v[110:113], v[0:3]
	v_mfma_f32_16x16x32_bf16 v[42:45], v[50:53], v[106:109], v[42:45]
	v_mfma_f32_16x16x32_bf16 v[46:49], v[50:53], v[114:117], v[46:49]
	v_mfma_f32_16x16x32_bf16 v[50:53], v[54:57], v[102:105], v[0:3]
	v_mfma_f32_16x16x32_bf16 v[54:57], v[54:57], v[110:113], v[0:3]
	v_mfma_f32_16x16x32_bf16 v[50:53], v[58:61], v[106:109], v[50:53]
	v_mfma_f32_16x16x32_bf16 v[54:57], v[58:61], v[114:117], v[54:57]
	v_mfma_f32_16x16x32_bf16 v[58:61], v[62:65], v[102:105], v[0:3]
	v_mfma_f32_16x16x32_bf16 v[62:65], v[62:65], v[110:113], v[0:3]
	v_mfma_f32_16x16x32_bf16 v[58:61], v[66:69], v[106:109], v[58:61]
	v_mfma_f32_16x16x32_bf16 v[62:65], v[66:69], v[114:117], v[62:65]
	s_setprio 0
	v_mov_b32_e32 v148, v4
	s_barrier
	ds_read_b128 v[66:69], v8 offset:16384
	ds_read_b128 v[122:125], v8 offset:17408
	ds_read_b128 v[132:135], v9 offset:18432
	ds_read_b128 v[136:139], v9 offset:19456
	ds_read_b128 v[140:143], v9 offset:20480
	ds_read_b128 v[144:147], v9 offset:21504
	ds_read_b128 v[152:155], v9 offset:22528
	ds_read_b128 v[156:159], v9 offset:23552
	v_readfirstlane_b32 s67, v12
	v_lshl_add_u64 v[20:21], v[148:149], 1, s[20:21]
	v_lshl_add_u64 v[20:21], v[20:21], 0, s[50:51]
	s_mov_b32 m0, s67
	v_mov_b32_e32 v148, v6
	global_load_lds_dwordx4 v[20:21], off
	v_readfirstlane_b32 s67, v15
	v_lshl_add_u64 v[20:21], v[148:149], 1, s[20:21]
	v_lshl_add_u64 v[20:21], v[20:21], 0, s[50:51]
	s_mov_b32 m0, s67
	s_nop 0
	global_load_lds_dwordx4 v[20:21], off
	s_barrier
; #define LDA(dst, b, h)                                                                                    \
;   _Pragma("unroll") for (int m = 0; m < 4; ++m) _Pragma("unroll") for (int k = 0; k < 2; ++k)             \
;       dst[m][k] = *reinterpret_cast<const bf16x8*>((char*)SA(b, h) + lds_byte(wr * 64 + m * 16 + fr, k * 32 + fq * 8))
; #define LDB(dst, b, h)                                                                                    \
;   _Pragma("unroll") for (int n = 0; n < 2; ++n) _Pragma("unroll") for (int k = 0; k < 2; ++k)             \
;       dst[n][k] = *reinterpret_cast<const bf16x8*>((char*)SB(b, h) + lds_byte(wc * 32 + n * 16 + fr, k * 32 + fq * 8))
; #define WAIT_V(n) asm volatile("s_waitcnt vmcnt(" #n ")" ::: "memory")
; #define WAIT_L(n) asm volatile("s_waitcnt lgkmcnt(" #n ")" ::: "memory")
; #define BAR __builtin_amdgcn_s_barrier()
; #define SCHED __builtin_amdgcn_sched_barrier(0)
; template <int EPI> ...
;     ...
;     BAR; WAIT_L(0); MMA(1, 0, At, B0); BAR; SCHED;
;     STAGE(SB(0, 1), Bt, bcol + HALF, t + 2);
;     WAIT_V(6); BAR; MMA(1, 1, At, B1); BAR;
;     LDB(B0, 1, 0); SCHED; LDA(At, 1, 0); STAGE(SA(0, 1), A, brow + HALF, t + 2);
;     WAIT_L(8); BAR; WAIT_L(0); MMA(0, 0, At, B0); BAR; SCHED;
;     LDB(B1, 1, 1); STAGE(SB(1, 0), Bt, bcol, t + 3);
	s_waitcnt lgkmcnt(0)
	s_setprio 1
	v_mfma_f32_16x16x32_bf16 v[160:163], v[66:69], v[22:25], v[0:3]
	v_mfma_f32_16x16x32_bf16 v[174:177], v[132:135], v[22:25], v[0:3]
	v_mfma_f32_16x16x32_bf16 v[182:185], v[140:143], v[22:25], v[0:3]
	v_mfma_f32_16x16x32_bf16 v[20:23], v[152:155], v[22:25], v[0:3]
	v_mfma_f32_16x16x32_bf16 v[160:163], v[122:125], v[26:29], v[160:163]
	v_mfma_f32_16x16x32_bf16 v[174:177], v[136:139], v[26:29], v[174:177]
	v_mfma_f32_16x16x32_bf16 v[182:185], v[144:147], v[26:29], v[182:185]
	v_mfma_f32_16x16x32_bf16 v[20:23], v[156:159], v[26:29], v[20:23]
	v_mfma_f32_16x16x32_bf16 v[24:27], v[152:155], v[30:33], v[0:3]
	v_mfma_f32_16x16x32_bf16 v[164:167], v[66:69], v[30:33], v[0:3]
	v_mfma_f32_16x16x32_bf16 v[178:181], v[132:135], v[30:33], v[0:3]
	v_mfma_f32_16x16x32_bf16 v[186:189], v[140:143], v[30:33], v[0:3]
	v_mfma_f32_16x16x32_bf16 v[24:27], v[156:159], v[34:37], v[24:27]
	v_mfma_f32_16x16x32_bf16 v[164:167], v[122:125], v[34:37], v[164:167]
	v_mfma_f32_16x16x32_bf16 v[178:181], v[136:139], v[34:37], v[178:181]
	v_mfma_f32_16x16x32_bf16 v[186:189], v[144:147], v[34:37], v[186:189]
	s_setprio 0
	s_barrier
	v_mov_b32_e32 v148, v4
	v_readfirstlane_b32 s67, v18
	v_lshl_add_u64 v[28:29], v[148:149], 1, s[18:19]
	v_lshl_add_u64 v[28:29], v[28:29], 0, s[50:51]
	s_mov_b32 m0, s67
	v_mov_b32_e32 v148, v6
	global_load_lds_dwordx4 v[28:29], off
	v_readfirstlane_b32 s67, v19
	v_lshl_add_u64 v[28:29], v[148:149], 1, s[18:19]
	v_lshl_add_u64 v[28:29], v[28:29], 0, s[50:51]
	s_mov_b32 m0, s67
	s_nop 0
	global_load_lds_dwordx4 v[28:29], off
	s_waitcnt vmcnt(6)
	s_barrier
	s_setprio 1
	v_mfma_f32_16x16x32_bf16 v[28:31], v[66:69], v[102:105], v[0:3]
	v_mfma_f32_16x16x32_bf16 v[32:35], v[66:69], v[110:113], v[0:3]
	v_mfma_f32_16x16x32_bf16 v[28:31], v[122:125], v[106:109], v[28:31]
	v_mfma_f32_16x16x32_bf16 v[32:35], v[122:125], v[114:117], v[32:35]
	v_mfma_f32_16x16x32_bf16 v[66:69], v[132:135], v[102:105], v[0:3]
	v_mfma_f32_16x16x32_bf16 v[122:125], v[132:135], v[110:113], v[0:3]
	v_mfma_f32_16x16x32_bf16 v[66:69], v[136:139], v[106:109], v[66:69]
	v_mfma_f32_16x16x32_bf16 v[122:125], v[136:139], v[114:117], v[122:125]
	v_mfma_f32_16x16x32_bf16 v[132:135], v[140:143], v[102:105], v[0:3]
	v_mfma_f32_16x16x32_bf16 v[136:139], v[140:143], v[110:113], v[0:3]
	v_mfma_f32_16x16x32_bf16 v[102:105], v[152:155], v[102:105], v[0:3]
	v_mfma_f32_16x16x32_bf16 v[0:3], v[152:155], v[110:113], v[0:3]
	v_mfma_f32_16x16x32_bf16 v[102:105], v[156:159], v[106:109], v[102:105]
	v_mfma_f32_16x16x32_bf16 v[0:3], v[156:159], v[114:117], v[0:3]
	v_mfma_f32_16x16x32_bf16 v[132:135], v[144:147], v[106:109], v[132:135]
	v_mfma_f32_16x16x32_bf16 v[136:139], v[144:147], v[114:117], v[136:139]
	s_setprio 0
	v_or_b32_e32 v227, 0x18000, v126
	v_or_b32_e32 v229, 0x18800, v126
	s_barrier
	v_or_b32_e32 v228, 0x18400, v126
	ds_read_b128 v[106:109], v227
	ds_read_b128 v[110:113], v228
	v_or_b32_e32 v230, 0x18c00, v126
	ds_read_b128 v[114:117], v229
	ds_read_b128 v[140:143], v230
	v_mov_b32_e32 v148, v4
	ds_read_b128 v[144:147], v8 offset:32768
	ds_read_b128 v[152:155], v8 offset:33792
	ds_read_b128 v[156:159], v9 offset:34816
	ds_read_b128 v[190:193], v9 offset:35840
	ds_read_b128 v[194:197], v9 offset:36864
	ds_read_b128 v[198:201], v9 offset:37888
	ds_read_b128 v[202:205], v9 offset:38912
	ds_read_b128 v[206:209], v9 offset:39936
	v_readfirstlane_b32 s67, v16
	v_lshl_add_u64 v[18:19], v[148:149], 1, s[2:3]
	v_lshl_add_u64 v[18:19], v[18:19], 0, s[50:51]
	s_mov_b32 m0, s67
	v_mov_b32_e32 v148, v6
	global_load_lds_dwordx4 v[18:19], off
	v_readfirstlane_b32 s67, v17
	v_lshl_add_u64 v[18:19], v[148:149], 1, s[2:3]
	v_lshl_add_u64 v[18:19], v[18:19], 0, s[50:51]
	s_mov_b32 m0, s67
	s_nop 0
	global_load_lds_dwordx4 v[18:19], off
	s_waitcnt lgkmcnt(8)
	s_barrier
	s_waitcnt lgkmcnt(0)
	s_setprio 1
	v_mfma_f32_16x16x32_bf16 v[16:19], v[144:147], v[106:109], v[70:73]
	v_mfma_f32_16x16x32_bf16 v[70:73], v[144:147], v[114:117], v[74:77]
	v_mfma_f32_16x16x32_bf16 v[74:77], v[156:159], v[106:109], v[78:81]
	v_mfma_f32_16x16x32_bf16 v[78:81], v[156:159], v[114:117], v[82:85]
	v_mfma_f32_16x16x32_bf16 v[82:85], v[194:197], v[106:109], v[86:89]
	v_mfma_f32_16x16x32_bf16 v[86:89], v[194:197], v[114:117], v[90:93]
	v_mfma_f32_16x16x32_bf16 v[90:93], v[202:205], v[106:109], v[94:97]
	v_mfma_f32_16x16x32_bf16 v[94:97], v[202:205], v[114:117], v[98:101]
	v_mfma_f32_16x16x32_bf16 v[16:19], v[152:155], v[110:113], v[16:19]
	v_mfma_f32_16x16x32_bf16 v[70:73], v[152:155], v[140:143], v[70:73]
	v_mfma_f32_16x16x32_bf16 v[74:77], v[190:193], v[110:113], v[74:77]
	v_mfma_f32_16x16x32_bf16 v[78:81], v[190:193], v[140:143], v[78:81]
	v_mfma_f32_16x16x32_bf16 v[82:85], v[198:201], v[110:113], v[82:85]
	v_mfma_f32_16x16x32_bf16 v[86:89], v[198:201], v[140:143], v[86:89]
	v_mfma_f32_16x16x32_bf16 v[90:93], v[206:209], v[110:113], v[90:93]
	v_mfma_f32_16x16x32_bf16 v[94:97], v[206:209], v[140:143], v[94:97]
	s_setprio 0
	s_barrier
	v_or_b32_e32 v234, 0x1c000, v126
	v_or_b32_e32 v236, 0x1c800, v126
	v_mov_b32_e32 v148, v4
	v_or_b32_e32 v235, 0x1c400, v126
	ds_read_b128 v[98:101], v234
	ds_read_b128 v[210:213], v235
	v_or_b32_e32 v126, 0x1cc00, v126
	ds_read_b128 v[214:217], v236
	ds_read_b128 v[218:221], v126
	v_readfirstlane_b32 s67, v13
	v_lshl_add_u64 v[36:37], v[148:149], 1, s[22:23]
	v_lshl_add_u64 v[36:37], v[36:37], 0, s[54:55]
	s_mov_b32 m0, s67
	v_mov_b32_e32 v148, v6
	global_load_lds_dwordx4 v[36:37], off
	s_nop 0
	v_lshl_add_u64 v[12:13], v[148:149], 1, s[22:23]
	v_readfirstlane_b32 s22, v14
	v_lshl_add_u64 v[12:13], v[12:13], 0, s[54:55]
	s_mov_b32 m0, s22
	s_nop 0
	global_load_lds_dwordx4 v[12:13], off
	s_barrier
; #define LDA(dst, b, h)                                                                                    \
;   _Pragma("unroll") for (int m = 0; m < 4; ++m) _Pragma("unroll") for (int k = 0; k < 2; ++k)             \
;       dst[m][k] = *reinterpret_cast<const bf16x8*>((char*)SA(b, h) + lds_byte(wr * 64 + m * 16 + fr, k * 32 + fq * 8))
; #define LDB(dst, b, h)                                                                                    \
;   _Pragma("unroll") for (int n = 0; n < 2; ++n) _Pragma("unroll") for (int k = 0; k < 2; ++k)             \
;       dst[n][k] = *reinterpret_cast<const bf16x8*>((char*)SB(b, h) + lds_byte(wc * 32 + n * 16 + fr, k * 32 + fq * 8))
; #define WAIT_V(n) asm volatile("s_waitcnt vmcnt(" #n ")" ::: "memory")
; #define WAIT_L(n) asm volatile("s_waitcnt lgkmcnt(" #n ")" ::: "memory")
; #define BAR __builtin_amdgcn_s_barrier()
; #define SCHED __builtin_amdgcn_sched_barrier(0)
; template <int EPI> ...
;     ...
;     BAR; WAIT_L(0); MMA(0, 1, At, B1); BAR;
;     LDA(At, 1, 1); STAGE(SA(1, 0), A, brow, t + 3);
;     BAR; WAIT_L(0); MMA(1, 0, At, B0); BAR; SCHED;
;     STAGE(SB(1, 1), Bt, bcol + HALF, t + 3);
;     WAIT_V(6); BAR; MMA(1, 1, At, B1); BAR;
;   }
;   {
;     LDB(B0, 0, 0); LDA(At, 0, 0); STAGE(SA(1, 1), A, brow + HALF, nt - 1);
	s_waitcnt lgkmcnt(0)
	s_setprio 1
	v_mfma_f32_16x16x32_bf16 v[12:15], v[144:147], v[98:101], v[118:121]
	v_mfma_f32_16x16x32_bf16 v[36:39], v[144:147], v[214:217], v[38:41]
	v_mfma_f32_16x16x32_bf16 v[40:43], v[156:159], v[98:101], v[42:45]
	v_mfma_f32_16x16x32_bf16 v[44:47], v[156:159], v[214:217], v[46:49]
	v_mfma_f32_16x16x32_bf16 v[48:51], v[194:197], v[98:101], v[50:53]
	v_mfma_f32_16x16x32_bf16 v[52:55], v[194:197], v[214:217], v[54:57]
	v_mfma_f32_16x16x32_bf16 v[56:59], v[202:205], v[98:101], v[58:61]
	v_mfma_f32_16x16x32_bf16 v[60:63], v[202:205], v[214:217], v[62:65]
	v_mfma_f32_16x16x32_bf16 v[12:15], v[152:155], v[210:213], v[12:15]
	v_mfma_f32_16x16x32_bf16 v[36:39], v[152:155], v[218:221], v[36:39]
	v_mfma_f32_16x16x32_bf16 v[40:43], v[190:193], v[210:213], v[40:43]
	v_mfma_f32_16x16x32_bf16 v[44:47], v[190:193], v[218:221], v[44:47]
	v_mfma_f32_16x16x32_bf16 v[48:51], v[198:201], v[210:213], v[48:51]
	v_mfma_f32_16x16x32_bf16 v[52:55], v[198:201], v[218:221], v[52:55]
	v_mfma_f32_16x16x32_bf16 v[56:59], v[206:209], v[210:213], v[56:59]
	v_mfma_f32_16x16x32_bf16 v[60:63], v[206:209], v[218:221], v[60:63]
	s_setprio 0
	v_mov_b32_e32 v148, v4
	s_barrier
	ds_read_b128 v[118:121], v8 offset:49152
	ds_read_b128 v[144:147], v8 offset:50176
	ds_read_b128 v[152:155], v9 offset:51200
	ds_read_b128 v[156:159], v9 offset:52224
	ds_read_b128 v[190:193], v9 offset:53248
	ds_read_b128 v[194:197], v9 offset:54272
	ds_read_b128 v[198:201], v9 offset:55296
	ds_read_b128 v[202:205], v9 offset:56320
	v_readfirstlane_b32 s22, v10
	v_lshl_add_u64 v[64:65], v[148:149], 1, s[20:21]
	v_lshl_add_u64 v[64:65], v[64:65], 0, s[54:55]
	s_mov_b32 m0, s22
	v_mov_b32_e32 v148, v6
	global_load_lds_dwordx4 v[64:65], off
	s_nop 0
	v_lshl_add_u64 v[64:65], v[148:149], 1, s[20:21]
	v_readfirstlane_b32 s20, v11
	v_lshl_add_u64 v[64:65], v[64:65], 0, s[54:55]
	s_mov_b32 m0, s20
	s_nop 0
	global_load_lds_dwordx4 v[64:65], off
	s_barrier
	s_waitcnt lgkmcnt(0)
	s_setprio 1
	v_mfma_f32_16x16x32_bf16 v[20:23], v[198:201], v[106:109], v[20:23]
	v_mfma_f32_16x16x32_bf16 v[24:27], v[198:201], v[114:117], v[24:27]
	v_mfma_f32_16x16x32_bf16 v[160:163], v[118:121], v[106:109], v[160:163]
	v_mfma_f32_16x16x32_bf16 v[164:167], v[118:121], v[114:117], v[164:167]
	v_mfma_f32_16x16x32_bf16 v[174:177], v[152:155], v[106:109], v[174:177]
	v_mfma_f32_16x16x32_bf16 v[178:181], v[152:155], v[114:117], v[178:181]
	v_mfma_f32_16x16x32_bf16 v[182:185], v[190:193], v[106:109], v[182:185]
	v_mfma_f32_16x16x32_bf16 v[186:189], v[190:193], v[114:117], v[186:189]
	v_mfma_f32_16x16x32_bf16 v[20:23], v[202:205], v[110:113], v[20:23]
	v_mfma_f32_16x16x32_bf16 v[24:27], v[202:205], v[140:143], v[24:27]
	v_mfma_f32_16x16x32_bf16 v[160:163], v[144:147], v[110:113], v[160:163]
	v_mfma_f32_16x16x32_bf16 v[164:167], v[144:147], v[140:143], v[164:167]
	v_mfma_f32_16x16x32_bf16 v[174:177], v[156:159], v[110:113], v[174:177]
	v_mfma_f32_16x16x32_bf16 v[178:181], v[156:159], v[140:143], v[178:181]
	v_mfma_f32_16x16x32_bf16 v[182:185], v[194:197], v[110:113], v[182:185]
	v_mfma_f32_16x16x32_bf16 v[186:189], v[194:197], v[140:143], v[186:189]
	s_setprio 0
	s_barrier
	v_mov_b32_e32 v148, v4
	v_readfirstlane_b32 s20, v5
	v_lshl_add_u64 v[10:11], v[148:149], 1, s[18:19]
	v_lshl_add_u64 v[10:11], v[10:11], 0, s[54:55]
	s_mov_b32 m0, s20
	v_mov_b32_e32 v148, v6
	global_load_lds_dwordx4 v[10:11], off
	s_nop 0
	v_lshl_add_u64 v[10:11], v[148:149], 1, s[18:19]
	v_readfirstlane_b32 s18, v7
	v_lshl_add_u64 v[10:11], v[10:11], 0, s[54:55]
	s_mov_b32 m0, s18
	s_nop 0
	global_load_lds_dwordx4 v[10:11], off
	s_waitcnt vmcnt(6)
	s_barrier
	s_setprio 1
	v_mfma_f32_16x16x32_bf16 v[28:31], v[118:121], v[98:101], v[28:31]
	v_mfma_f32_16x16x32_bf16 v[32:35], v[118:121], v[214:217], v[32:35]
	v_mfma_f32_16x16x32_bf16 v[64:67], v[152:155], v[98:101], v[66:69]
	v_mfma_f32_16x16x32_bf16 v[106:109], v[152:155], v[214:217], v[122:125]
	v_mfma_f32_16x16x32_bf16 v[110:113], v[190:193], v[98:101], v[132:135]
	v_mfma_f32_16x16x32_bf16 v[114:117], v[190:193], v[214:217], v[136:139]
	v_mfma_f32_16x16x32_bf16 v[98:101], v[198:201], v[98:101], v[102:105]
	v_mfma_f32_16x16x32_bf16 v[0:3], v[198:201], v[214:217], v[0:3]
	v_mfma_f32_16x16x32_bf16 v[28:31], v[144:147], v[210:213], v[28:31]
	v_mfma_f32_16x16x32_bf16 v[32:35], v[144:147], v[218:221], v[32:35]
	v_mfma_f32_16x16x32_bf16 v[64:67], v[156:159], v[210:213], v[64:67]
	v_mfma_f32_16x16x32_bf16 v[106:109], v[156:159], v[218:221], v[106:109]
	v_mfma_f32_16x16x32_bf16 v[110:113], v[194:197], v[210:213], v[110:113]
	v_mfma_f32_16x16x32_bf16 v[114:117], v[194:197], v[218:221], v[114:117]
	v_mfma_f32_16x16x32_bf16 v[98:101], v[202:205], v[210:213], v[98:101]
	v_mfma_f32_16x16x32_bf16 v[0:3], v[202:205], v[218:221], v[0:3]
	s_setprio 0
	s_barrier
	ds_read_b128 v[102:105], v127
	ds_read_b128 v[118:121], v129
	ds_read_b128 v[122:125], v131
	ds_read_b128 v[132:135], v222
	ds_read_b128 v[136:139], v8
	ds_read_b128 v[140:143], v8 offset:1024
	ds_read_b128 v[144:147], v9 offset:2048
	ds_read_b128 v[152:155], v9 offset:3072
	ds_read_b128 v[156:159], v9 offset:4096
	ds_read_b128 v[190:193], v9 offset:5120
	ds_read_b128 v[194:197], v9 offset:6144
	ds_read_b128 v[198:201], v9 offset:7168
	v_mov_b32_e32 v5, v149
	v_lshl_add_u64 v[4:5], v[4:5], 1, s[2:3]
	s_mov_b32 m0, s66
	v_lshl_add_u64 v[4:5], v[4:5], 0, s[54:55]
	v_mov_b32_e32 v7, v149
	global_load_lds_dwordx4 v[4:5], off
	s_mov_b32 m0, s65
	v_lshl_add_u64 v[4:5], v[6:7], 1, s[2:3]
	v_lshl_add_u64 v[4:5], v[4:5], 0, s[54:55]
	global_load_lds_dwordx4 v[4:5], off
	s_barrier
; #define LDA(dst, b, h)                                                                                    \
;   _Pragma("unroll") for (int m = 0; m < 4; ++m) _Pragma("unroll") for (int k = 0; k < 2; ++k)             \
;       dst[m][k] = *reinterpret_cast<const bf16x8*>((char*)SA(b, h) + lds_byte(wr * 64 + m * 16 + fr, k * 32 + fq * 8))
; #define LDB(dst, b, h)                                                                                    \
;   _Pragma("unroll") for (int n = 0; n < 2; ++n) _Pragma("unroll") for (int k = 0; k < 2; ++k)             \
;       dst[n][k] = *reinterpret_cast<const bf16x8*>((char*)SB(b, h) + lds_byte(wc * 32 + n * 16 + fr, k * 32 + fq * 8))
; #define WAIT_V(n) asm volatile("s_waitcnt vmcnt(" #n ")" ::: "memory")
; #define WAIT_L(n) asm volatile("s_waitcnt lgkmcnt(" #n ")" ::: "memory")
; #define BAR __builtin_amdgcn_s_barrier()
; template <int EPI> ...
;     ...
;     BAR; WAIT_L(0); MMA(0, 0, At, B0); BAR;
;     LDB(B1, 0, 1); BAR; WAIT_L(0); MMA(0, 1, At, B1); BAR;
;     LDA(At, 0, 1); WAIT_V(4); BAR; WAIT_L(0); MMA(1, 0, At, B0); MMA(1, 1, At, B1); BAR;
	s_waitcnt lgkmcnt(0)
	s_setprio 1
	v_mfma_f32_16x16x32_bf16 v[4:7], v[136:139], v[102:105], v[16:19]
	v_mfma_f32_16x16x32_bf16 v[16:19], v[136:139], v[122:125], v[70:73]
	v_mfma_f32_16x16x32_bf16 v[68:71], v[144:147], v[102:105], v[74:77]
	v_mfma_f32_16x16x32_bf16 v[72:75], v[144:147], v[122:125], v[78:81]
	v_mfma_f32_16x16x32_bf16 v[76:79], v[156:159], v[102:105], v[82:85]
	v_mfma_f32_16x16x32_bf16 v[80:83], v[156:159], v[122:125], v[86:89]
	v_mfma_f32_16x16x32_bf16 v[202:205], v[190:193], v[132:135], v[80:83]
	v_mfma_f32_16x16x32_bf16 v[80:83], v[194:197], v[102:105], v[90:93]
	v_mfma_f32_16x16x32_bf16 v[206:209], v[198:201], v[118:121], v[80:83]
	v_mfma_f32_16x16x32_bf16 v[80:83], v[194:197], v[122:125], v[94:97]
	v_mfma_f32_16x16x32_bf16 v[4:7], v[140:143], v[118:121], v[4:7]
	v_mfma_f32_16x16x32_bf16 v[16:19], v[140:143], v[132:135], v[16:19]
	v_mfma_f32_16x16x32_bf16 v[68:71], v[152:155], v[118:121], v[68:71]
	v_mfma_f32_16x16x32_bf16 v[72:75], v[152:155], v[132:135], v[72:75]
	v_mfma_f32_16x16x32_bf16 v[76:79], v[190:193], v[118:121], v[76:79]
	v_mfma_f32_16x16x32_bf16 v[92:95], v[198:201], v[132:135], v[80:83]
	s_setprio 0
	s_barrier
	s_nop 0
	ds_read_b128 v[80:83], v223
	ds_read_b128 v[84:87], v224
	ds_read_b128 v[88:91], v225
	ds_read_b128 v[210:213], v226
	s_barrier
	s_waitcnt lgkmcnt(0)
	s_setprio 1
	v_mfma_f32_16x16x32_bf16 v[10:13], v[136:139], v[80:83], v[12:15]
	v_mfma_f32_16x16x32_bf16 v[36:39], v[136:139], v[88:91], v[36:39]
	v_mfma_f32_16x16x32_bf16 v[40:43], v[144:147], v[80:83], v[40:43]
	v_mfma_f32_16x16x32_bf16 v[44:47], v[144:147], v[88:91], v[44:47]
	v_mfma_f32_16x16x32_bf16 v[48:51], v[156:159], v[80:83], v[48:51]
	v_mfma_f32_16x16x32_bf16 v[52:55], v[156:159], v[88:91], v[52:55]
	v_mfma_f32_16x16x32_bf16 v[56:59], v[194:197], v[80:83], v[56:59]
	v_mfma_f32_16x16x32_bf16 v[60:63], v[194:197], v[88:91], v[60:63]
	v_mfma_f32_16x16x32_bf16 v[10:13], v[140:143], v[84:87], v[10:13]
	v_mfma_f32_16x16x32_bf16 v[36:39], v[140:143], v[210:213], v[36:39]
	v_mfma_f32_16x16x32_bf16 v[40:43], v[152:155], v[84:87], v[40:43]
	v_mfma_f32_16x16x32_bf16 v[44:47], v[152:155], v[210:213], v[44:47]
	v_mfma_f32_16x16x32_bf16 v[48:51], v[190:193], v[84:87], v[48:51]
	v_mfma_f32_16x16x32_bf16 v[52:55], v[190:193], v[210:213], v[52:55]
	v_mfma_f32_16x16x32_bf16 v[56:59], v[198:201], v[84:87], v[56:59]
	v_mfma_f32_16x16x32_bf16 v[60:63], v[198:201], v[210:213], v[60:63]
	s_setprio 0
	s_barrier
	ds_read_b128 v[136:139], v8 offset:16384
	ds_read_b128 v[140:143], v8 offset:17408
	ds_read_b128 v[144:147], v9 offset:18432
	ds_read_b128 v[152:155], v9 offset:19456
	ds_read_b128 v[156:159], v9 offset:20480
	ds_read_b128 v[190:193], v9 offset:21504
	ds_read_b128 v[194:197], v9 offset:22528
	ds_read_b128 v[198:201], v9 offset:23552
	s_waitcnt vmcnt(4)
	s_barrier
	s_waitcnt lgkmcnt(0)
	s_setprio 1
	v_mfma_f32_16x16x32_bf16 v[20:23], v[194:197], v[102:105], v[20:23]
	v_mfma_f32_16x16x32_bf16 v[160:163], v[136:139], v[102:105], v[160:163]
	v_mfma_f32_16x16x32_bf16 v[164:167], v[136:139], v[122:125], v[164:167]
	v_mfma_f32_16x16x32_bf16 v[174:177], v[144:147], v[102:105], v[174:177]
	v_mfma_f32_16x16x32_bf16 v[178:181], v[144:147], v[122:125], v[178:181]
	v_mfma_f32_16x16x32_bf16 v[182:185], v[156:159], v[102:105], v[182:185]
	v_mfma_f32_16x16x32_bf16 v[186:189], v[156:159], v[122:125], v[186:189]
	v_mfma_f32_16x16x32_bf16 v[214:217], v[198:201], v[118:121], v[20:23]
	v_mfma_f32_16x16x32_bf16 v[20:23], v[194:197], v[122:125], v[24:27]
	v_mfma_f32_16x16x32_bf16 v[160:163], v[140:143], v[118:121], v[160:163]
	v_mfma_f32_16x16x32_bf16 v[164:167], v[140:143], v[132:135], v[164:167]
	v_mfma_f32_16x16x32_bf16 v[174:177], v[152:155], v[118:121], v[174:177]
	v_mfma_f32_16x16x32_bf16 v[178:181], v[152:155], v[132:135], v[178:181]
	v_mfma_f32_16x16x32_bf16 v[182:185], v[190:193], v[118:121], v[182:185]
	v_mfma_f32_16x16x32_bf16 v[186:189], v[190:193], v[132:135], v[186:189]
	v_mfma_f32_16x16x32_bf16 v[132:135], v[198:201], v[132:135], v[20:23]
	s_setprio 0
	s_setprio 1
	v_mfma_f32_16x16x32_bf16 v[20:23], v[136:139], v[80:83], v[28:31]
	v_mfma_f32_16x16x32_bf16 v[218:221], v[140:143], v[84:87], v[20:23]
	v_mfma_f32_16x16x32_bf16 v[20:23], v[136:139], v[88:91], v[32:35]
	v_mfma_f32_16x16x32_bf16 v[32:35], v[140:143], v[210:213], v[20:23]
	v_mfma_f32_16x16x32_bf16 v[20:23], v[144:147], v[80:83], v[64:67]
	v_mfma_f32_16x16x32_bf16 v[136:139], v[152:155], v[84:87], v[20:23]
	v_mfma_f32_16x16x32_bf16 v[20:23], v[144:147], v[88:91], v[106:109]
	v_mfma_f32_16x16x32_bf16 v[140:143], v[152:155], v[210:213], v[20:23]
	v_mfma_f32_16x16x32_bf16 v[20:23], v[156:159], v[80:83], v[110:113]
	v_mfma_f32_16x16x32_bf16 v[144:147], v[190:193], v[84:87], v[20:23]
	v_mfma_f32_16x16x32_bf16 v[20:23], v[156:159], v[88:91], v[114:117]
	v_mfma_f32_16x16x32_bf16 v[152:155], v[190:193], v[210:213], v[20:23]
	v_mfma_f32_16x16x32_bf16 v[20:23], v[194:197], v[80:83], v[98:101]
	v_mfma_f32_16x16x32_bf16 v[0:3], v[194:197], v[88:91], v[0:3]
	v_mfma_f32_16x16x32_bf16 v[156:159], v[198:201], v[84:87], v[20:23]
	v_mfma_f32_16x16x32_bf16 v[190:193], v[198:201], v[210:213], v[0:3]
	s_setprio 0
	s_barrier
; #define LDA(dst, b, h)                                                                                    \
;   _Pragma("unroll") for (int m = 0; m < 4; ++m) _Pragma("unroll") for (int k = 0; k < 2; ++k)             \
;       dst[m][k] = *reinterpret_cast<const bf16x8*>((char*)SA(b, h) + lds_byte(wr * 64 + m * 16 + fr, k * 32 + fq * 8))
; #define LDB(dst, b, h)                                                                                    \
;   _Pragma("unroll") for (int n = 0; n < 2; ++n) _Pragma("unroll") for (int k = 0; k < 2; ++k)             \
;       dst[n][k] = *reinterpret_cast<const bf16x8*>((char*)SB(b, h) + lds_byte(wc * 32 + n * 16 + fr, k * 32 + fq * 8))
; #define WAIT_V(n) asm volatile("s_waitcnt vmcnt(" #n ")" ::: "memory")
; #define WAIT_L(n) asm volatile("s_waitcnt lgkmcnt(" #n ")" ::: "memory")
; #define BAR __builtin_amdgcn_s_barrier()
; template <int EPI> ...
;     ...
;     LDB(B0, 1, 0); LDA(At, 1, 0); WAIT_V(2); BAR; WAIT_L(0); MMA(0, 0, At, B0); BAR;
;     LDB(B1, 1, 1); WAIT_V(0); BAR; WAIT_L(0); MMA(0, 1, At, B1); BAR;
;     LDA(At, 1, 1); BAR; WAIT_L(0); MMA(1, 0, At, B0); MMA(1, 1, At, B1); BAR;
;   }
;   if (wr == 0) BAR;
	s_nop 3
	ds_read_b128 v[0:3], v227
	ds_read_b128 v[194:197], v228
	ds_read_b128 v[198:201], v229
	ds_read_b128 v[210:213], v230
	ds_read_b128 v[20:23], v8 offset:32768
	ds_read_b128 v[24:27], v8 offset:33792
	ds_read_b128 v[28:31], v9 offset:34816
	ds_read_b128 v[100:103], v9 offset:35840
	ds_read_b128 v[108:111], v9 offset:36864
	ds_read_b128 v[222:225], v9 offset:37888
	ds_read_b128 v[226:229], v9 offset:38912
	ds_read_b128 v[230:233], v9 offset:39936
	s_waitcnt vmcnt(2)
	s_barrier
	s_waitcnt lgkmcnt(0)
	s_setprio 1
	v_mfma_f32_16x16x32_bf16 v[4:7], v[20:23], v[0:3], v[4:7]
	v_mfma_f32_16x16x32_bf16 v[88:91], v[24:27], v[194:197], v[4:7]
	v_mfma_f32_16x16x32_bf16 v[4:7], v[20:23], v[198:201], v[16:19]
	v_mfma_f32_16x16x32_bf16 v[96:99], v[24:27], v[210:213], v[4:7]
	v_mfma_f32_16x16x32_bf16 v[4:7], v[28:31], v[0:3], v[68:71]
	v_mfma_f32_16x16x32_bf16 v[80:83], v[100:103], v[194:197], v[4:7]
	v_mfma_f32_16x16x32_bf16 v[4:7], v[28:31], v[198:201], v[72:75]
	v_mfma_f32_16x16x32_bf16 v[84:87], v[100:103], v[210:213], v[4:7]
	v_mfma_f32_16x16x32_bf16 v[4:7], v[108:111], v[0:3], v[76:79]
	v_mfma_f32_16x16x32_bf16 v[72:75], v[222:225], v[194:197], v[4:7]
	v_mfma_f32_16x16x32_bf16 v[4:7], v[108:111], v[198:201], v[202:205]
	v_mfma_f32_16x16x32_bf16 v[76:79], v[222:225], v[210:213], v[4:7]
	v_mfma_f32_16x16x32_bf16 v[4:7], v[226:229], v[0:3], v[206:209]
	v_mfma_f32_16x16x32_bf16 v[64:67], v[230:233], v[194:197], v[4:7]
	v_mfma_f32_16x16x32_bf16 v[4:7], v[226:229], v[198:201], v[92:95]
	v_mfma_f32_16x16x32_bf16 v[68:71], v[230:233], v[210:213], v[4:7]
	s_setprio 0
	s_barrier
	ds_read_b128 v[202:205], v234
	ds_read_b128 v[206:209], v235
	ds_read_b128 v[234:237], v236
	ds_read_b128 v[238:241], v126
	s_waitcnt vmcnt(0)
	s_barrier
	s_waitcnt lgkmcnt(0)
	s_setprio 1
	v_mfma_f32_16x16x32_bf16 v[4:7], v[20:23], v[202:205], v[10:13]
	v_mfma_f32_16x16x32_bf16 v[120:123], v[24:27], v[206:209], v[4:7]
	v_mfma_f32_16x16x32_bf16 v[4:7], v[20:23], v[234:237], v[36:39]
	v_mfma_f32_16x16x32_bf16 v[124:127], v[24:27], v[238:241], v[4:7]
	v_mfma_f32_16x16x32_bf16 v[4:7], v[28:31], v[202:205], v[40:43]
	v_mfma_f32_16x16x32_bf16 v[112:115], v[100:103], v[206:209], v[4:7]
	v_mfma_f32_16x16x32_bf16 v[4:7], v[28:31], v[234:237], v[44:47]
	v_mfma_f32_16x16x32_bf16 v[116:119], v[100:103], v[238:241], v[4:7]
	v_mfma_f32_16x16x32_bf16 v[4:7], v[108:111], v[202:205], v[48:51]
	v_mfma_f32_16x16x32_bf16 v[104:107], v[222:225], v[206:209], v[4:7]
	v_mfma_f32_16x16x32_bf16 v[4:7], v[108:111], v[234:237], v[52:55]
	v_mfma_f32_16x16x32_bf16 v[108:111], v[222:225], v[238:241], v[4:7]
	v_mfma_f32_16x16x32_bf16 v[4:7], v[226:229], v[202:205], v[56:59]
	v_mfma_f32_16x16x32_bf16 v[92:95], v[230:233], v[206:209], v[4:7]
	v_mfma_f32_16x16x32_bf16 v[4:7], v[226:229], v[234:237], v[60:63]
	v_mfma_f32_16x16x32_bf16 v[100:103], v[230:233], v[238:241], v[4:7]
	s_setprio 0
	s_barrier
	ds_read_b128 v[36:39], v8 offset:49152
	ds_read_b128 v[40:43], v8 offset:50176
	ds_read_b128 v[44:47], v9 offset:51200
	ds_read_b128 v[52:55], v9 offset:52224
	ds_read_b128 v[222:225], v9 offset:53248
	ds_read_b128 v[226:229], v9 offset:54272
	ds_read_b128 v[230:233], v9 offset:55296
	ds_read_b128 v[242:245], v9 offset:56320
	s_barrier
	s_waitcnt lgkmcnt(0)
	s_setprio 1
	v_mfma_f32_16x16x32_bf16 v[4:7], v[36:39], v[0:3], v[160:163]
	v_mfma_f32_16x16x32_bf16 v[24:27], v[40:43], v[194:197], v[4:7]
	v_mfma_f32_16x16x32_bf16 v[4:7], v[36:39], v[198:201], v[164:167]
	v_mfma_f32_16x16x32_bf16 v[28:31], v[40:43], v[210:213], v[4:7]
	v_mfma_f32_16x16x32_bf16 v[4:7], v[44:47], v[0:3], v[174:177]
	v_mfma_f32_16x16x32_bf16 v[16:19], v[52:55], v[194:197], v[4:7]
	v_mfma_f32_16x16x32_bf16 v[4:7], v[44:47], v[198:201], v[178:181]
	v_mfma_f32_16x16x32_bf16 v[20:23], v[52:55], v[210:213], v[4:7]
	v_mfma_f32_16x16x32_bf16 v[4:7], v[222:225], v[0:3], v[182:185]
	v_mfma_f32_16x16x32_bf16 v[8:11], v[226:229], v[194:197], v[4:7]
	v_mfma_f32_16x16x32_bf16 v[4:7], v[222:225], v[198:201], v[186:189]
	v_mfma_f32_16x16x32_bf16 v[12:15], v[226:229], v[210:213], v[4:7]
	v_mfma_f32_16x16x32_bf16 v[0:3], v[230:233], v[0:3], v[214:217]
	v_mfma_f32_16x16x32_bf16 v[4:7], v[230:233], v[198:201], v[132:135]
	v_mfma_f32_16x16x32_bf16 v[0:3], v[242:245], v[194:197], v[0:3]
	v_mfma_f32_16x16x32_bf16 v[4:7], v[242:245], v[210:213], v[4:7]
	s_setprio 0
	s_setprio 1
	v_mfma_f32_16x16x32_bf16 v[32:35], v[36:39], v[234:237], v[32:35]
	v_mfma_f32_16x16x32_bf16 v[48:51], v[36:39], v[202:205], v[218:221]
	v_mfma_f32_16x16x32_bf16 v[60:63], v[40:43], v[238:241], v[32:35]
	v_mfma_f32_16x16x32_bf16 v[32:35], v[44:47], v[202:205], v[136:139]
	v_mfma_f32_16x16x32_bf16 v[56:59], v[40:43], v[206:209], v[48:51]
	v_mfma_f32_16x16x32_bf16 v[48:51], v[52:55], v[206:209], v[32:35]
	v_mfma_f32_16x16x32_bf16 v[32:35], v[44:47], v[234:237], v[140:143]
	v_mfma_f32_16x16x32_bf16 v[52:55], v[52:55], v[238:241], v[32:35]
	v_mfma_f32_16x16x32_bf16 v[32:35], v[222:225], v[202:205], v[144:147]
	v_mfma_f32_16x16x32_bf16 v[40:43], v[226:229], v[206:209], v[32:35]
	v_mfma_f32_16x16x32_bf16 v[32:35], v[222:225], v[234:237], v[152:155]
	v_mfma_f32_16x16x32_bf16 v[44:47], v[226:229], v[238:241], v[32:35]
	v_mfma_f32_16x16x32_bf16 v[32:35], v[230:233], v[202:205], v[156:159]
	v_mfma_f32_16x16x32_bf16 v[36:39], v[230:233], v[234:237], v[190:193]
	v_mfma_f32_16x16x32_bf16 v[32:35], v[242:245], v[206:209], v[32:35]
	v_mfma_f32_16x16x32_bf16 v[36:39], v[242:245], v[238:241], v[36:39]
	s_setprio 0
	s_cmpk_gt_u32 s64, 0xff
	s_barrier
	s_cbranch_scc1 .LBB0_911
	s_barrier

; #define LDA(dst, b, h)                                                                                    \
;   _Pragma("unroll") for (int m = 0; m < 4; ++m) _Pragma("unroll") for (int k = 0; k < 2; ++k)             \
;       dst[m][k] = *reinterpret_cast<const bf16x8*>((char*)SA(b, h) + lds_byte(wr * 64 + m * 16 + fr, k * 32 + fq * 8))
; #define LDB(dst, b, h)                                                                                    \
;   _Pragma("unroll") for (int n = 0; n < 2; ++n) _Pragma("unroll") for (int k = 0; k < 2; ++k)             \
;       dst[n][k] = *reinterpret_cast<const bf16x8*>((char*)SB(b, h) + lds_byte(wc * 32 + n * 16 + fr, k * 32 + fq * 8))
; #define WAIT_V(n) asm volatile("s_waitcnt vmcnt(" #n ")" ::: "memory")
; #define WAIT_L(n) asm volatile("s_waitcnt lgkmcnt(" #n ")" ::: "memory")
; #define BAR __builtin_amdgcn_s_barrier()
; #define SCHED __builtin_amdgcn_sched_barrier(0)
; template <int EPI> ...
;     ...
;     LDB(B0, 0, 0); SCHED; LDA(At, 0, 0); STAGE(SA(1, 1), A, brow + HALF, t + 1);
;     WAIT_L(8); BAR; WAIT_L(0); MMA(0, 0, At, B0); BAR; SCHED;
;     LDB(B1, 0, 1); STAGE(SB(0, 0), Bt, bcol, t + 2);
;     BAR; WAIT_L(0); MMA(0, 1, At, B1); BAR;
;     LDA(At, 0, 1); STAGE(SA(0, 0), A, brow, t + 2);
;     BAR; WAIT_L(0); MMA(1, 0, At, B0); BAR; SCHED;
;     STAGE(SB(0, 1), Bt, bcol + HALF, t + 2);
;     WAIT_V(6); BAR; MMA(1, 1, At, B1); BAR;
.LBB0_1016:
	ds_read_b128 v[162:165], v155
	ds_read_b128 v[174:177], v155 offset:1024
	ds_read_b128 v[178:181], v155 offset:2048
	ds_read_b128 v[182:185], v155 offset:3072
	s_add_u32 s22, s14, s20
	v_add_u32_e32 v156, s63, v154
	v_add_u32_e32 v157, s69, v154
	v_add_u32_e32 v158, s70, v154
	s_addc_u32 s23, s15, s21
	ds_read_b128 v[186:189], v135
	ds_read_b128 v[190:193], v135 offset:1024
	ds_read_b128 v[194:197], v156
	ds_read_b128 v[198:201], v156 offset:1024
	ds_read_b128 v[202:205], v157
	ds_read_b128 v[206:209], v157 offset:1024
	ds_read_b128 v[210:213], v158
	ds_read_b128 v[214:217], v158 offset:1024
	v_add_u32_e32 v159, 0xe000, v129
	v_add_u32_e32 v160, 0xc000, v129
	s_add_u32 m0, s32, 0xc000
	s_add_u32 s98, s22, 0x40080
	s_addc_u32 s99, s23, 0
	global_load_lds_dwordx4 v253, s[98:99]
	s_add_u32 m0, s32, 0xe000
	s_nop 0
	global_load_lds_dwordx4 v252, s[98:99]
	s_waitcnt lgkmcnt(8)
	s_barrier
	s_waitcnt lgkmcnt(0)
	s_setprio 1
	v_mfma_f32_16x16x32_bf16 v[124:127], v[186:189], v[162:165], v[124:127]
	v_mfma_f32_16x16x32_bf16 v[120:123], v[186:189], v[178:181], v[120:123]
	v_mfma_f32_16x16x32_bf16 v[116:119], v[194:197], v[162:165], v[116:119]
	v_mfma_f32_16x16x32_bf16 v[112:115], v[194:197], v[178:181], v[112:115]
	v_mfma_f32_16x16x32_bf16 v[108:111], v[202:205], v[162:165], v[108:111]
	v_mfma_f32_16x16x32_bf16 v[104:107], v[202:205], v[178:181], v[104:107]
	v_mfma_f32_16x16x32_bf16 v[100:103], v[210:213], v[162:165], v[100:103]
	v_mfma_f32_16x16x32_bf16 v[96:99], v[210:213], v[178:181], v[96:99]
	v_mfma_f32_16x16x32_bf16 v[124:127], v[190:193], v[174:177], v[124:127]
	v_mfma_f32_16x16x32_bf16 v[120:123], v[190:193], v[182:185], v[120:123]
	v_mfma_f32_16x16x32_bf16 v[116:119], v[198:201], v[174:177], v[116:119]
	v_mfma_f32_16x16x32_bf16 v[112:115], v[198:201], v[182:185], v[112:115]
	v_mfma_f32_16x16x32_bf16 v[108:111], v[206:209], v[174:177], v[108:111]
	v_mfma_f32_16x16x32_bf16 v[104:107], v[206:209], v[182:185], v[104:107]
	v_mfma_f32_16x16x32_bf16 v[100:103], v[214:217], v[174:177], v[100:103]
	v_mfma_f32_16x16x32_bf16 v[96:99], v[214:217], v[182:185], v[96:99]
	s_setprio 0
	s_barrier
	s_add_u32 s30, s12, s20
	s_addc_u32 s31, s13, s21
	ds_read_b128 v[218:221], v152
	ds_read_b128 v[222:225], v152 offset:1024
	ds_read_b128 v[226:229], v152 offset:2048
	ds_read_b128 v[230:233], v152 offset:3072
	s_add_u32 m0, s32, 0x10000
	s_add_u32 s98, s30, 0x100
	s_addc_u32 s99, s31, 0
	global_load_lds_dwordx4 v253, s[98:99]
	s_add_u32 m0, s32, 0x12000
	s_nop 0
	global_load_lds_dwordx4 v252, s[98:99]
	s_barrier
	s_waitcnt lgkmcnt(0)
	s_setprio 1
	v_mfma_f32_16x16x32_bf16 v[92:95], v[186:189], v[218:221], v[92:95]
	v_mfma_f32_16x16x32_bf16 v[88:91], v[186:189], v[226:229], v[88:91]
	v_mfma_f32_16x16x32_bf16 v[84:87], v[194:197], v[218:221], v[84:87]
	v_mfma_f32_16x16x32_bf16 v[80:83], v[194:197], v[226:229], v[80:83]
	v_mfma_f32_16x16x32_bf16 v[76:79], v[202:205], v[218:221], v[76:79]
	v_mfma_f32_16x16x32_bf16 v[72:75], v[202:205], v[226:229], v[72:75]
	v_mfma_f32_16x16x32_bf16 v[68:71], v[210:213], v[218:221], v[68:71]
	v_mfma_f32_16x16x32_bf16 v[64:67], v[210:213], v[226:229], v[64:67]
	v_mfma_f32_16x16x32_bf16 v[92:95], v[190:193], v[222:225], v[92:95]
	v_mfma_f32_16x16x32_bf16 v[88:91], v[190:193], v[230:233], v[88:91]
	v_mfma_f32_16x16x32_bf16 v[84:87], v[198:201], v[222:225], v[84:87]
	v_mfma_f32_16x16x32_bf16 v[80:83], v[198:201], v[230:233], v[80:83]
	v_mfma_f32_16x16x32_bf16 v[76:79], v[206:209], v[222:225], v[76:79]
	v_mfma_f32_16x16x32_bf16 v[72:75], v[206:209], v[230:233], v[72:75]
	v_mfma_f32_16x16x32_bf16 v[68:71], v[214:217], v[222:225], v[68:71]
	v_mfma_f32_16x16x32_bf16 v[64:67], v[214:217], v[230:233], v[64:67]
	s_setprio 0
	s_barrier
	ds_read_b128 v[186:189], v135 offset:16384
	ds_read_b128 v[190:193], v135 offset:17408
	ds_read_b128 v[194:197], v156 offset:16384
	ds_read_b128 v[198:201], v156 offset:17408
	ds_read_b128 v[202:205], v157 offset:16384
	ds_read_b128 v[206:209], v157 offset:17408
	ds_read_b128 v[210:213], v158 offset:16384
	ds_read_b128 v[214:217], v158 offset:17408
	s_mov_b32 m0, s32
	s_add_u32 s98, s22, 0x100
	s_addc_u32 s99, s23, 0
	global_load_lds_dwordx4 v253, s[98:99]
	s_add_u32 m0, s32, 0x2000
	s_nop 0
	global_load_lds_dwordx4 v252, s[98:99]
	s_barrier
	s_waitcnt lgkmcnt(0)
	s_setprio 1
	v_mfma_f32_16x16x32_bf16 v[60:63], v[186:189], v[162:165], v[60:63]
	v_mfma_f32_16x16x32_bf16 v[56:59], v[186:189], v[178:181], v[56:59]
	v_mfma_f32_16x16x32_bf16 v[52:55], v[194:197], v[162:165], v[52:55]
	v_mfma_f32_16x16x32_bf16 v[48:51], v[194:197], v[178:181], v[48:51]
	v_mfma_f32_16x16x32_bf16 v[44:47], v[202:205], v[162:165], v[44:47]
	v_mfma_f32_16x16x32_bf16 v[40:43], v[202:205], v[178:181], v[40:43]
	v_mfma_f32_16x16x32_bf16 v[36:39], v[210:213], v[162:165], v[36:39]
	v_mfma_f32_16x16x32_bf16 v[32:35], v[210:213], v[178:181], v[32:35]
	v_mfma_f32_16x16x32_bf16 v[60:63], v[190:193], v[174:177], v[60:63]
	v_mfma_f32_16x16x32_bf16 v[56:59], v[190:193], v[182:185], v[56:59]
	v_mfma_f32_16x16x32_bf16 v[52:55], v[198:201], v[174:177], v[52:55]
	v_mfma_f32_16x16x32_bf16 v[48:51], v[198:201], v[182:185], v[48:51]
	v_mfma_f32_16x16x32_bf16 v[44:47], v[206:209], v[174:177], v[44:47]
	v_mfma_f32_16x16x32_bf16 v[40:43], v[206:209], v[182:185], v[40:43]
	v_mfma_f32_16x16x32_bf16 v[36:39], v[214:217], v[174:177], v[36:39]
	v_mfma_f32_16x16x32_bf16 v[32:35], v[214:217], v[182:185], v[32:35]
	s_setprio 0
	s_barrier
	s_add_u32 m0, s32, 0x14000
	s_add_u32 s98, s30, 0x40100
	s_addc_u32 s99, s31, 0
	global_load_lds_dwordx4 v253, s[98:99]
	s_add_u32 m0, s32, 0x16000
	s_nop 0
	global_load_lds_dwordx4 v252, s[98:99]
	s_waitcnt vmcnt(6)
	s_barrier
; #define LDA(dst, b, h)                                                                                    \
;   _Pragma("unroll") for (int m = 0; m < 4; ++m) _Pragma("unroll") for (int k = 0; k < 2; ++k)             \
;       dst[m][k] = *reinterpret_cast<const bf16x8*>((char*)SA(b, h) + lds_byte(wr * 64 + m * 16 + fr, k * 32 + fq * 8))
; #define LDB(dst, b, h)                                                                                    \
;   _Pragma("unroll") for (int n = 0; n < 2; ++n) _Pragma("unroll") for (int k = 0; k < 2; ++k)             \
;       dst[n][k] = *reinterpret_cast<const bf16x8*>((char*)SB(b, h) + lds_byte(wc * 32 + n * 16 + fr, k * 32 + fq * 8))
; #define WAIT_V(n) asm volatile("s_waitcnt vmcnt(" #n ")" ::: "memory")
; #define WAIT_L(n) asm volatile("s_waitcnt lgkmcnt(" #n ")" ::: "memory")
; #define BAR __builtin_amdgcn_s_barrier()
; #define SCHED __builtin_amdgcn_sched_barrier(0)
; template <int EPI> ...
;     ...
;     WAIT_V(6); BAR; MMA(1, 1, At, B1); BAR;
;     LDB(B0, 1, 0); SCHED; LDA(At, 1, 0); STAGE(SA(0, 1), A, brow + HALF, t + 2);
;     WAIT_L(8); BAR; WAIT_L(0); MMA(0, 0, At, B0); BAR; SCHED;
;     LDB(B1, 1, 1); STAGE(SB(1, 0), Bt, bcol, t + 3);
;     BAR; WAIT_L(0); MMA(0, 1, At, B1); BAR;
;     LDA(At, 1, 1); STAGE(SA(1, 0), A, brow, t + 3);
;     BAR; WAIT_L(0); MMA(1, 0, At, B0); BAR; SCHED;
	s_setprio 1
	v_mfma_f32_16x16x32_bf16 v[28:31], v[186:189], v[218:221], v[28:31]
	v_mfma_f32_16x16x32_bf16 v[24:27], v[186:189], v[226:229], v[24:27]
	v_mfma_f32_16x16x32_bf16 v[20:23], v[194:197], v[218:221], v[20:23]
	v_mfma_f32_16x16x32_bf16 v[16:19], v[194:197], v[226:229], v[16:19]
	v_mfma_f32_16x16x32_bf16 v[12:15], v[202:205], v[218:221], v[12:15]
	v_mfma_f32_16x16x32_bf16 v[8:11], v[202:205], v[226:229], v[8:11]
	v_mfma_f32_16x16x32_bf16 v[4:7], v[210:213], v[218:221], v[4:7]
	v_mfma_f32_16x16x32_bf16 v[0:3], v[210:213], v[226:229], v[0:3]
	v_mfma_f32_16x16x32_bf16 v[28:31], v[190:193], v[222:225], v[28:31]
	v_mfma_f32_16x16x32_bf16 v[24:27], v[190:193], v[230:233], v[24:27]
	v_mfma_f32_16x16x32_bf16 v[20:23], v[198:201], v[222:225], v[20:23]
	v_mfma_f32_16x16x32_bf16 v[16:19], v[198:201], v[230:233], v[16:19]
	v_mfma_f32_16x16x32_bf16 v[12:15], v[206:209], v[222:225], v[12:15]
	v_mfma_f32_16x16x32_bf16 v[8:11], v[206:209], v[230:233], v[8:11]
	v_mfma_f32_16x16x32_bf16 v[4:7], v[214:217], v[222:225], v[4:7]
	v_mfma_f32_16x16x32_bf16 v[0:3], v[214:217], v[230:233], v[0:3]
	s_setprio 0
	s_barrier
	ds_read_b128 v[162:165], v140
	ds_read_b128 v[174:177], v140 offset:1024
	ds_read_b128 v[178:181], v140 offset:2048
	ds_read_b128 v[182:185], v140 offset:3072
	ds_read_b128 v[186:189], v135 offset:32768
	ds_read_b128 v[190:193], v135 offset:33792
	ds_read_b128 v[194:197], v156 offset:32768
	ds_read_b128 v[198:201], v156 offset:33792
	ds_read_b128 v[202:205], v157 offset:32768
	ds_read_b128 v[206:209], v157 offset:33792
	ds_read_b128 v[210:213], v158 offset:32768
	ds_read_b128 v[214:217], v158 offset:33792
	s_add_u32 m0, s32, 0x4000
	s_add_u32 s98, s22, 0x40100
	s_addc_u32 s99, s23, 0
	global_load_lds_dwordx4 v253, s[98:99]
	s_add_u32 m0, s32, 0x6000
	s_nop 0
	global_load_lds_dwordx4 v252, s[98:99]
	s_waitcnt lgkmcnt(8)
	s_barrier
	s_waitcnt lgkmcnt(0)
	s_setprio 1
	v_mfma_f32_16x16x32_bf16 v[124:127], v[186:189], v[162:165], v[124:127]
	v_mfma_f32_16x16x32_bf16 v[120:123], v[186:189], v[178:181], v[120:123]
	v_mfma_f32_16x16x32_bf16 v[116:119], v[194:197], v[162:165], v[116:119]
	v_mfma_f32_16x16x32_bf16 v[112:115], v[194:197], v[178:181], v[112:115]
	v_mfma_f32_16x16x32_bf16 v[108:111], v[202:205], v[162:165], v[108:111]
	v_mfma_f32_16x16x32_bf16 v[104:107], v[202:205], v[178:181], v[104:107]
	v_mfma_f32_16x16x32_bf16 v[100:103], v[210:213], v[162:165], v[100:103]
	v_mfma_f32_16x16x32_bf16 v[96:99], v[210:213], v[178:181], v[96:99]
	v_mfma_f32_16x16x32_bf16 v[124:127], v[190:193], v[174:177], v[124:127]
	v_mfma_f32_16x16x32_bf16 v[120:123], v[190:193], v[182:185], v[120:123]
	v_mfma_f32_16x16x32_bf16 v[116:119], v[198:201], v[174:177], v[116:119]
	v_mfma_f32_16x16x32_bf16 v[112:115], v[198:201], v[182:185], v[112:115]
	v_mfma_f32_16x16x32_bf16 v[108:111], v[206:209], v[174:177], v[108:111]
	v_mfma_f32_16x16x32_bf16 v[104:107], v[206:209], v[182:185], v[104:107]
	v_mfma_f32_16x16x32_bf16 v[100:103], v[214:217], v[174:177], v[100:103]
	v_mfma_f32_16x16x32_bf16 v[96:99], v[214:217], v[182:185], v[96:99]
	s_setprio 0
	s_barrier
	ds_read_b128 v[218:221], v137
	ds_read_b128 v[222:225], v137 offset:1024
	ds_read_b128 v[226:229], v137 offset:2048
	ds_read_b128 v[230:233], v137 offset:3072
	s_add_u32 m0, s32, 0x18000
	s_add_u32 s98, s30, 0x180
	s_addc_u32 s99, s31, 0
	global_load_lds_dwordx4 v253, s[98:99]
	s_add_u32 m0, s32, 0x1a000
	s_nop 0
	global_load_lds_dwordx4 v252, s[98:99]
	s_barrier
	s_waitcnt lgkmcnt(0)
	s_setprio 1
	v_mfma_f32_16x16x32_bf16 v[92:95], v[186:189], v[218:221], v[92:95]
	v_mfma_f32_16x16x32_bf16 v[88:91], v[186:189], v[226:229], v[88:91]
	v_mfma_f32_16x16x32_bf16 v[84:87], v[194:197], v[218:221], v[84:87]
	v_mfma_f32_16x16x32_bf16 v[80:83], v[194:197], v[226:229], v[80:83]
	v_mfma_f32_16x16x32_bf16 v[76:79], v[202:205], v[218:221], v[76:79]
	v_mfma_f32_16x16x32_bf16 v[72:75], v[202:205], v[226:229], v[72:75]
	v_mfma_f32_16x16x32_bf16 v[68:71], v[210:213], v[218:221], v[68:71]
	v_mfma_f32_16x16x32_bf16 v[64:67], v[210:213], v[226:229], v[64:67]
	v_mfma_f32_16x16x32_bf16 v[92:95], v[190:193], v[222:225], v[92:95]
	v_mfma_f32_16x16x32_bf16 v[88:91], v[190:193], v[230:233], v[88:91]
	v_mfma_f32_16x16x32_bf16 v[84:87], v[198:201], v[222:225], v[84:87]
	v_mfma_f32_16x16x32_bf16 v[80:83], v[198:201], v[230:233], v[80:83]
	v_mfma_f32_16x16x32_bf16 v[76:79], v[206:209], v[222:225], v[76:79]
	v_mfma_f32_16x16x32_bf16 v[72:75], v[206:209], v[230:233], v[72:75]
	v_mfma_f32_16x16x32_bf16 v[68:71], v[214:217], v[222:225], v[68:71]
	v_mfma_f32_16x16x32_bf16 v[64:67], v[214:217], v[230:233], v[64:67]
	s_setprio 0
	s_barrier
	ds_read_b128 v[186:189], v135 offset:49152
	ds_read_b128 v[190:193], v135 offset:50176
	ds_read_b128 v[194:197], v156 offset:49152
	ds_read_b128 v[198:201], v156 offset:50176
	ds_read_b128 v[202:205], v157 offset:49152
	ds_read_b128 v[206:209], v157 offset:50176
	ds_read_b128 v[210:213], v158 offset:49152
	ds_read_b128 v[214:217], v158 offset:50176
	s_add_u32 m0, s32, 0x8000
	s_add_u32 s98, s22, 0x180
	s_addc_u32 s99, s23, 0
	global_load_lds_dwordx4 v253, s[98:99]
	s_nop 0
	s_add_u32 m0, s32, 0xa000
	s_nop 0
	global_load_lds_dwordx4 v252, s[98:99]
	s_barrier
; #define LDA(dst, b, h)                                                                                    \
;   _Pragma("unroll") for (int m = 0; m < 4; ++m) _Pragma("unroll") for (int k = 0; k < 2; ++k)             \
;       dst[m][k] = *reinterpret_cast<const bf16x8*>((char*)SA(b, h) + lds_byte(wr * 64 + m * 16 + fr, k * 32 + fq * 8))
; #define LDB(dst, b, h)                                                                                    \
;   _Pragma("unroll") for (int n = 0; n < 2; ++n) _Pragma("unroll") for (int k = 0; k < 2; ++k)             \
;       dst[n][k] = *reinterpret_cast<const bf16x8*>((char*)SB(b, h) + lds_byte(wc * 32 + n * 16 + fr, k * 32 + fq * 8))
; #define WAIT_V(n) asm volatile("s_waitcnt vmcnt(" #n ")" ::: "memory")
; #define WAIT_L(n) asm volatile("s_waitcnt lgkmcnt(" #n ")" ::: "memory")
; #define BAR __builtin_amdgcn_s_barrier()
; #define SCHED __builtin_amdgcn_sched_barrier(0)
; template <int EPI> ...
;     ...
;     LDA(At, 1, 1); STAGE(SA(1, 0), A, brow, t + 3);
;     BAR; WAIT_L(0); MMA(1, 0, At, B0); BAR; SCHED;
;     STAGE(SB(1, 1), Bt, bcol + HALF, t + 3);
;     WAIT_V(6); BAR; MMA(1, 1, At, B1); BAR;
;   }
;   {
;     LDB(B0, 0, 0); LDA(At, 0, 0); STAGE(SA(1, 1), A, brow + HALF, nt - 1);
;     BAR; WAIT_L(0); MMA(0, 0, At, B0); BAR;
;     LDB(B1, 0, 1); BAR; WAIT_L(0); MMA(0, 1, At, B1); BAR;
	s_waitcnt lgkmcnt(0)
	s_setprio 1
	v_mfma_f32_16x16x32_bf16 v[60:63], v[186:189], v[162:165], v[60:63]
	v_mfma_f32_16x16x32_bf16 v[56:59], v[186:189], v[178:181], v[56:59]
	v_mfma_f32_16x16x32_bf16 v[52:55], v[194:197], v[162:165], v[52:55]
	v_mfma_f32_16x16x32_bf16 v[48:51], v[194:197], v[178:181], v[48:51]
	v_mfma_f32_16x16x32_bf16 v[44:47], v[202:205], v[162:165], v[44:47]
	v_mfma_f32_16x16x32_bf16 v[40:43], v[202:205], v[178:181], v[40:43]
	v_mfma_f32_16x16x32_bf16 v[36:39], v[210:213], v[162:165], v[36:39]
	v_mfma_f32_16x16x32_bf16 v[32:35], v[210:213], v[178:181], v[32:35]
	v_mfma_f32_16x16x32_bf16 v[60:63], v[190:193], v[174:177], v[60:63]
	v_mfma_f32_16x16x32_bf16 v[56:59], v[190:193], v[182:185], v[56:59]
	v_mfma_f32_16x16x32_bf16 v[52:55], v[198:201], v[174:177], v[52:55]
	v_mfma_f32_16x16x32_bf16 v[48:51], v[198:201], v[182:185], v[48:51]
	v_mfma_f32_16x16x32_bf16 v[44:47], v[206:209], v[174:177], v[44:47]
	v_mfma_f32_16x16x32_bf16 v[40:43], v[206:209], v[182:185], v[40:43]
	v_mfma_f32_16x16x32_bf16 v[36:39], v[214:217], v[174:177], v[36:39]
	v_mfma_f32_16x16x32_bf16 v[32:35], v[214:217], v[182:185], v[32:35]
	s_setprio 0
	s_barrier
	s_add_u32 m0, s32, 0x1c000
	s_add_u32 s98, s30, 0x40180
	s_addc_u32 s99, s31, 0
	global_load_lds_dwordx4 v253, s[98:99]
	s_add_u32 m0, s32, 0x1e000
	s_nop 0
	global_load_lds_dwordx4 v252, s[98:99]
	s_waitcnt vmcnt(6)
	s_barrier
	s_setprio 1
	v_mfma_f32_16x16x32_bf16 v[28:31], v[186:189], v[218:221], v[28:31]
	v_mfma_f32_16x16x32_bf16 v[24:27], v[186:189], v[226:229], v[24:27]
	v_mfma_f32_16x16x32_bf16 v[20:23], v[194:197], v[218:221], v[20:23]
	v_mfma_f32_16x16x32_bf16 v[16:19], v[194:197], v[226:229], v[16:19]
	v_mfma_f32_16x16x32_bf16 v[12:15], v[202:205], v[218:221], v[12:15]
	v_mfma_f32_16x16x32_bf16 v[8:11], v[202:205], v[226:229], v[8:11]
	v_mfma_f32_16x16x32_bf16 v[4:7], v[210:213], v[218:221], v[4:7]
	v_mfma_f32_16x16x32_bf16 v[0:3], v[210:213], v[226:229], v[0:3]
	v_mfma_f32_16x16x32_bf16 v[28:31], v[190:193], v[222:225], v[28:31]
	v_mfma_f32_16x16x32_bf16 v[24:27], v[190:193], v[230:233], v[24:27]
	v_mfma_f32_16x16x32_bf16 v[20:23], v[198:201], v[222:225], v[20:23]
	v_mfma_f32_16x16x32_bf16 v[16:19], v[198:201], v[230:233], v[16:19]
	v_mfma_f32_16x16x32_bf16 v[12:15], v[206:209], v[222:225], v[12:15]
	v_mfma_f32_16x16x32_bf16 v[8:11], v[206:209], v[230:233], v[8:11]
	v_mfma_f32_16x16x32_bf16 v[4:7], v[214:217], v[222:225], v[4:7]
	v_mfma_f32_16x16x32_bf16 v[0:3], v[214:217], v[230:233], v[0:3]
	s_setprio 0
	s_add_i32 s71, s71, 2
	s_add_u32 s20, s20, 0x100
	s_addc_u32 s21, s21, 0
	s_cmp_lt_u32 s71, 12
	s_barrier
	s_cbranch_scc1 .LBB0_1016
	ds_read_b128 v[142:145], v155
	ds_read_b128 v[162:165], v155 offset:1024
	ds_read_b128 v[174:177], v155 offset:2048
	ds_read_b128 v[178:181], v155 offset:3072
	ds_read_b128 v[182:185], v135
	ds_read_b128 v[186:189], v135 offset:1024
	ds_read_b128 v[190:193], v156
	ds_read_b128 v[194:197], v156 offset:1024
	ds_read_b128 v[198:201], v157
	ds_read_b128 v[202:205], v157 offset:1024
	ds_read_b128 v[206:209], v158
	ds_read_b128 v[210:213], v158 offset:1024
	v_mov_b32_e32 v129, v149
	v_lshl_add_u64 v[128:129], v[128:129], 1, s[18:19]
	s_mov_b64 s[14:15], 0x780
	v_readfirstlane_b32 s12, v160
	v_lshl_add_u64 v[128:129], v[128:129], 0, s[14:15]
	s_mov_b32 m0, s12
	v_mov_b32_e32 v131, v149
	global_load_lds_dwordx4 v[128:129], off
	v_readfirstlane_b32 s12, v159
	v_lshl_add_u64 v[128:129], v[130:131], 1, s[18:19]
	v_lshl_add_u64 v[128:129], v[128:129], 0, s[14:15]
	s_mov_b32 m0, s12
	s_nop 0
	global_load_lds_dwordx4 v[128:129], off
	s_barrier
	s_waitcnt lgkmcnt(0)
	s_setprio 1
	v_mfma_f32_16x16x32_bf16 v[124:127], v[182:185], v[142:145], v[124:127]
	v_mfma_f32_16x16x32_bf16 v[120:123], v[182:185], v[174:177], v[120:123]
	v_mfma_f32_16x16x32_bf16 v[116:119], v[190:193], v[142:145], v[116:119]
	v_mfma_f32_16x16x32_bf16 v[112:115], v[190:193], v[174:177], v[112:115]
	v_mfma_f32_16x16x32_bf16 v[108:111], v[198:201], v[142:145], v[108:111]
	v_mfma_f32_16x16x32_bf16 v[104:107], v[198:201], v[174:177], v[104:107]
	v_mfma_f32_16x16x32_bf16 v[96:99], v[206:209], v[174:177], v[96:99]
	v_mfma_f32_16x16x32_bf16 v[124:127], v[186:189], v[162:165], v[124:127]
	v_mfma_f32_16x16x32_bf16 v[120:123], v[186:189], v[178:181], v[120:123]
	v_mfma_f32_16x16x32_bf16 v[116:119], v[194:197], v[162:165], v[116:119]
	v_mfma_f32_16x16x32_bf16 v[112:115], v[194:197], v[178:181], v[112:115]
	v_mfma_f32_16x16x32_bf16 v[108:111], v[202:205], v[162:165], v[108:111]
	v_mfma_f32_16x16x32_bf16 v[104:107], v[202:205], v[178:181], v[104:107]
	v_mfma_f32_16x16x32_bf16 v[100:103], v[206:209], v[142:145], v[100:103]
	v_mfma_f32_16x16x32_bf16 v[96:99], v[210:213], v[178:181], v[96:99]
	v_mfma_f32_16x16x32_bf16 v[128:131], v[210:213], v[162:165], v[100:103]
	s_setprio 0
	s_barrier
	s_nop 3
	ds_read_b128 v[100:103], v152
	ds_read_b128 v[214:217], v152 offset:1024
	ds_read_b128 v[218:221], v152 offset:2048
	ds_read_b128 v[152:155], v152 offset:3072
	s_barrier
	s_waitcnt lgkmcnt(0)
	s_setprio 1
	v_mfma_f32_16x16x32_bf16 v[88:91], v[182:185], v[218:221], v[88:91]
	v_mfma_f32_16x16x32_bf16 v[92:95], v[182:185], v[100:103], v[92:95]
	v_mfma_f32_16x16x32_bf16 v[88:91], v[186:189], v[152:155], v[88:91]
	v_mfma_f32_16x16x32_bf16 v[84:87], v[190:193], v[100:103], v[84:87]
	v_mfma_f32_16x16x32_bf16 v[80:83], v[190:193], v[218:221], v[80:83]
	v_mfma_f32_16x16x32_bf16 v[76:79], v[198:201], v[100:103], v[76:79]
	v_mfma_f32_16x16x32_bf16 v[72:75], v[198:201], v[218:221], v[72:75]
	v_mfma_f32_16x16x32_bf16 v[68:71], v[206:209], v[100:103], v[68:71]
	v_mfma_f32_16x16x32_bf16 v[64:67], v[206:209], v[218:221], v[64:67]
	v_mfma_f32_16x16x32_bf16 v[222:225], v[186:189], v[214:217], v[92:95]
	v_mfma_f32_16x16x32_bf16 v[182:185], v[194:197], v[214:217], v[84:87]
	v_mfma_f32_16x16x32_bf16 v[186:189], v[194:197], v[152:155], v[80:83]
	v_mfma_f32_16x16x32_bf16 v[190:193], v[202:205], v[214:217], v[76:79]
	v_mfma_f32_16x16x32_bf16 v[194:197], v[202:205], v[152:155], v[72:75]
	v_mfma_f32_16x16x32_bf16 v[198:201], v[210:213], v[214:217], v[68:71]
	v_mfma_f32_16x16x32_bf16 v[202:205], v[210:213], v[152:155], v[64:67]
	s_setprio 0
	s_barrier
; #define LDA(dst, b, h)                                                                                    \
;   _Pragma("unroll") for (int m = 0; m < 4; ++m) _Pragma("unroll") for (int k = 0; k < 2; ++k)             \
;       dst[m][k] = *reinterpret_cast<const bf16x8*>((char*)SA(b, h) + lds_byte(wr * 64 + m * 16 + fr, k * 32 + fq * 8))
; #define LDB(dst, b, h)                                                                                    \
;   _Pragma("unroll") for (int n = 0; n < 2; ++n) _Pragma("unroll") for (int k = 0; k < 2; ++k)             \
;       dst[n][k] = *reinterpret_cast<const bf16x8*>((char*)SB(b, h) + lds_byte(wc * 32 + n * 16 + fr, k * 32 + fq * 8))
; #define WAIT_V(n) asm volatile("s_waitcnt vmcnt(" #n ")" ::: "memory")
; #define WAIT_L(n) asm volatile("s_waitcnt lgkmcnt(" #n ")" ::: "memory")
; #define BAR __builtin_amdgcn_s_barrier()
; template <int EPI> ...
;     ...
;     LDA(At, 0, 1); WAIT_V(4); BAR; WAIT_L(0); MMA(1, 0, At, B0); MMA(1, 1, At, B1); BAR;
;   }
;   {
;     LDB(B0, 1, 0); LDA(At, 1, 0); WAIT_V(2); BAR; WAIT_L(0); MMA(0, 0, At, B0); BAR;
	s_nop 0
	ds_read_b128 v[64:67], v135 offset:16384
	ds_read_b128 v[68:71], v135 offset:17408
	ds_read_b128 v[72:75], v156 offset:16384
	ds_read_b128 v[76:79], v156 offset:17408
	ds_read_b128 v[80:83], v157 offset:16384
	ds_read_b128 v[84:87], v157 offset:17408
	ds_read_b128 v[92:95], v158 offset:16384
	ds_read_b128 v[206:209], v158 offset:17408
	s_waitcnt vmcnt(4)
	s_barrier
	s_waitcnt lgkmcnt(0)
	s_setprio 1
	v_mfma_f32_16x16x32_bf16 v[60:63], v[64:67], v[142:145], v[60:63]
	v_mfma_f32_16x16x32_bf16 v[56:59], v[64:67], v[174:177], v[56:59]
	v_mfma_f32_16x16x32_bf16 v[52:55], v[72:75], v[142:145], v[52:55]
	v_mfma_f32_16x16x32_bf16 v[48:51], v[72:75], v[174:177], v[48:51]
	v_mfma_f32_16x16x32_bf16 v[44:47], v[80:83], v[142:145], v[44:47]
	v_mfma_f32_16x16x32_bf16 v[40:43], v[80:83], v[174:177], v[40:43]
	v_mfma_f32_16x16x32_bf16 v[36:39], v[92:95], v[142:145], v[36:39]
	v_mfma_f32_16x16x32_bf16 v[32:35], v[92:95], v[174:177], v[32:35]
	v_mfma_f32_16x16x32_bf16 v[60:63], v[68:71], v[162:165], v[60:63]
	v_mfma_f32_16x16x32_bf16 v[56:59], v[68:71], v[178:181], v[56:59]
	v_mfma_f32_16x16x32_bf16 v[52:55], v[76:79], v[162:165], v[52:55]
	v_mfma_f32_16x16x32_bf16 v[48:51], v[76:79], v[178:181], v[48:51]
	v_mfma_f32_16x16x32_bf16 v[44:47], v[84:87], v[162:165], v[44:47]
	v_mfma_f32_16x16x32_bf16 v[40:43], v[84:87], v[178:181], v[40:43]
	v_mfma_f32_16x16x32_bf16 v[36:39], v[206:209], v[162:165], v[36:39]
	v_mfma_f32_16x16x32_bf16 v[32:35], v[206:209], v[178:181], v[32:35]
	s_setprio 0
	s_setprio 1
	v_mfma_f32_16x16x32_bf16 v[28:31], v[64:67], v[100:103], v[28:31]
	v_mfma_f32_16x16x32_bf16 v[24:27], v[64:67], v[218:221], v[24:27]
	v_mfma_f32_16x16x32_bf16 v[20:23], v[72:75], v[100:103], v[20:23]
	v_mfma_f32_16x16x32_bf16 v[16:19], v[72:75], v[218:221], v[16:19]
	v_mfma_f32_16x16x32_bf16 v[12:15], v[80:83], v[100:103], v[12:15]
	v_mfma_f32_16x16x32_bf16 v[8:11], v[80:83], v[218:221], v[8:11]
	v_mfma_f32_16x16x32_bf16 v[4:7], v[92:95], v[100:103], v[4:7]
	v_mfma_f32_16x16x32_bf16 v[0:3], v[92:95], v[218:221], v[0:3]
	v_mfma_f32_16x16x32_bf16 v[142:145], v[68:71], v[214:217], v[28:31]
	v_mfma_f32_16x16x32_bf16 v[160:163], v[68:71], v[152:155], v[24:27]
	v_mfma_f32_16x16x32_bf16 v[164:167], v[76:79], v[214:217], v[20:23]
	v_mfma_f32_16x16x32_bf16 v[174:177], v[76:79], v[152:155], v[16:19]
	v_mfma_f32_16x16x32_bf16 v[178:181], v[84:87], v[214:217], v[12:15]
	v_mfma_f32_16x16x32_bf16 v[210:213], v[84:87], v[152:155], v[8:11]
	v_mfma_f32_16x16x32_bf16 v[214:217], v[206:209], v[214:217], v[4:7]
	v_mfma_f32_16x16x32_bf16 v[152:155], v[206:209], v[152:155], v[0:3]
	s_setprio 0
	s_barrier
	s_nop 0
	ds_read_b128 v[0:3], v140
	ds_read_b128 v[4:7], v140 offset:1024
	ds_read_b128 v[206:209], v140 offset:2048
	ds_read_b128 v[138:141], v140 offset:3072
	ds_read_b128 v[8:11], v135 offset:32768
	ds_read_b128 v[12:15], v135 offset:33792
	ds_read_b128 v[16:19], v156 offset:32768
	ds_read_b128 v[20:23], v156 offset:33792
	ds_read_b128 v[24:27], v157 offset:32768
	ds_read_b128 v[28:31], v157 offset:33792
	ds_read_b128 v[218:221], v158 offset:32768
	ds_read_b128 v[226:229], v158 offset:33792
	s_waitcnt vmcnt(2)
	s_barrier
	s_waitcnt lgkmcnt(0)
	s_setprio 1
	v_mfma_f32_16x16x32_bf16 v[64:67], v[8:11], v[0:3], v[124:127]
	v_mfma_f32_16x16x32_bf16 v[92:95], v[12:15], v[4:7], v[64:67]
	v_mfma_f32_16x16x32_bf16 v[64:67], v[8:11], v[206:209], v[120:123]
	v_mfma_f32_16x16x32_bf16 v[100:103], v[12:15], v[138:141], v[64:67]
	v_mfma_f32_16x16x32_bf16 v[64:67], v[16:19], v[0:3], v[116:119]
	v_mfma_f32_16x16x32_bf16 v[80:83], v[20:23], v[4:7], v[64:67]
	v_mfma_f32_16x16x32_bf16 v[64:67], v[16:19], v[206:209], v[112:115]
	v_mfma_f32_16x16x32_bf16 v[84:87], v[20:23], v[138:141], v[64:67]
	v_mfma_f32_16x16x32_bf16 v[64:67], v[24:27], v[0:3], v[108:111]
	v_mfma_f32_16x16x32_bf16 v[72:75], v[28:31], v[4:7], v[64:67]
	v_mfma_f32_16x16x32_bf16 v[64:67], v[24:27], v[206:209], v[104:107]
	v_mfma_f32_16x16x32_bf16 v[76:79], v[28:31], v[138:141], v[64:67]
	v_mfma_f32_16x16x32_bf16 v[64:67], v[218:221], v[0:3], v[128:131]
	v_mfma_f32_16x16x32_bf16 v[68:71], v[218:221], v[206:209], v[96:99]
	v_mfma_f32_16x16x32_bf16 v[64:67], v[226:229], v[4:7], v[64:67]
	v_mfma_f32_16x16x32_bf16 v[68:71], v[226:229], v[138:141], v[68:71]
	s_setprio 0
	s_barrier
; #define LDA(dst, b, h)                                                                                    \
;   _Pragma("unroll") for (int m = 0; m < 4; ++m) _Pragma("unroll") for (int k = 0; k < 2; ++k)             \
;       dst[m][k] = *reinterpret_cast<const bf16x8*>((char*)SA(b, h) + lds_byte(wr * 64 + m * 16 + fr, k * 32 + fq * 8))
; #define LDB(dst, b, h)                                                                                    \
;   _Pragma("unroll") for (int n = 0; n < 2; ++n) _Pragma("unroll") for (int k = 0; k < 2; ++k)             \
;       dst[n][k] = *reinterpret_cast<const bf16x8*>((char*)SB(b, h) + lds_byte(wc * 32 + n * 16 + fr, k * 32 + fq * 8))
; #define WAIT_V(n) asm volatile("s_waitcnt vmcnt(" #n ")" ::: "memory")
; #define WAIT_L(n) asm volatile("s_waitcnt lgkmcnt(" #n ")" ::: "memory")
; #define BAR __builtin_amdgcn_s_barrier()
; template <int EPI> ...
;     ...
;     LDB(B1, 1, 1); WAIT_V(0); BAR; WAIT_L(0); MMA(0, 1, At, B1); BAR;
;     LDA(At, 1, 1); BAR; WAIT_L(0); MMA(1, 0, At, B0); MMA(1, 1, At, B1); BAR;
;   }
;   if (wr == 0) BAR;
	ds_read_b128 v[128:131], v137
	ds_read_b128 v[230:233], v137 offset:1024
	ds_read_b128 v[234:237], v137 offset:2048
	ds_read_b128 v[238:241], v137 offset:3072
	s_waitcnt vmcnt(0)
	s_barrier
	s_waitcnt lgkmcnt(0)
	s_setprio 1
	v_mfma_f32_16x16x32_bf16 v[96:99], v[8:11], v[128:131], v[222:225]
	v_mfma_f32_16x16x32_bf16 v[8:11], v[8:11], v[234:237], v[88:91]
	v_mfma_f32_16x16x32_bf16 v[124:127], v[12:15], v[238:241], v[8:11]
	v_mfma_f32_16x16x32_bf16 v[8:11], v[16:19], v[128:131], v[182:185]
	v_mfma_f32_16x16x32_bf16 v[112:115], v[20:23], v[230:233], v[8:11]
	v_mfma_f32_16x16x32_bf16 v[8:11], v[16:19], v[234:237], v[186:189]
	v_mfma_f32_16x16x32_bf16 v[116:119], v[20:23], v[238:241], v[8:11]
	v_mfma_f32_16x16x32_bf16 v[8:11], v[24:27], v[128:131], v[190:193]
	v_mfma_f32_16x16x32_bf16 v[104:107], v[28:31], v[230:233], v[8:11]
	v_mfma_f32_16x16x32_bf16 v[8:11], v[24:27], v[234:237], v[194:197]
	v_mfma_f32_16x16x32_bf16 v[108:111], v[28:31], v[238:241], v[8:11]
	v_mfma_f32_16x16x32_bf16 v[8:11], v[218:221], v[128:131], v[198:201]
	v_mfma_f32_16x16x32_bf16 v[88:91], v[226:229], v[230:233], v[8:11]
	v_mfma_f32_16x16x32_bf16 v[8:11], v[218:221], v[234:237], v[202:205]
	v_mfma_f32_16x16x32_bf16 v[120:123], v[12:15], v[230:233], v[96:99]
	v_mfma_f32_16x16x32_bf16 v[96:99], v[226:229], v[238:241], v[8:11]
	s_setprio 0
	s_barrier
	ds_read_b128 v[182:185], v135 offset:49152
	ds_read_b128 v[134:137], v135 offset:50176
	ds_read_b128 v[186:189], v156 offset:49152
	ds_read_b128 v[190:193], v156 offset:50176
	ds_read_b128 v[194:197], v157 offset:49152
	ds_read_b128 v[198:201], v157 offset:50176
	ds_read_b128 v[202:205], v158 offset:49152
	ds_read_b128 v[156:159], v158 offset:50176
	s_barrier
	s_waitcnt lgkmcnt(0)
	s_setprio 1
	v_mfma_f32_16x16x32_bf16 v[8:11], v[182:185], v[0:3], v[60:63]
	v_mfma_f32_16x16x32_bf16 v[24:27], v[134:137], v[4:7], v[8:11]
	v_mfma_f32_16x16x32_bf16 v[8:11], v[182:185], v[206:209], v[56:59]
	v_mfma_f32_16x16x32_bf16 v[28:31], v[134:137], v[138:141], v[8:11]
	v_mfma_f32_16x16x32_bf16 v[8:11], v[186:189], v[0:3], v[52:55]
	v_mfma_f32_16x16x32_bf16 v[16:19], v[190:193], v[4:7], v[8:11]
	v_mfma_f32_16x16x32_bf16 v[8:11], v[186:189], v[206:209], v[48:51]
	v_mfma_f32_16x16x32_bf16 v[20:23], v[190:193], v[138:141], v[8:11]
	v_mfma_f32_16x16x32_bf16 v[8:11], v[194:197], v[0:3], v[44:47]
	v_mfma_f32_16x16x32_bf16 v[0:3], v[202:205], v[0:3], v[36:39]
	v_mfma_f32_16x16x32_bf16 v[8:11], v[198:201], v[4:7], v[8:11]
	v_mfma_f32_16x16x32_bf16 v[12:15], v[194:197], v[206:209], v[40:43]
	v_mfma_f32_16x16x32_bf16 v[0:3], v[156:159], v[4:7], v[0:3]
	v_mfma_f32_16x16x32_bf16 v[4:7], v[202:205], v[206:209], v[32:35]
	v_mfma_f32_16x16x32_bf16 v[12:15], v[198:201], v[138:141], v[12:15]
	v_mfma_f32_16x16x32_bf16 v[4:7], v[156:159], v[138:141], v[4:7]
	s_setprio 0
	s_setprio 1
	v_mfma_f32_16x16x32_bf16 v[32:35], v[182:185], v[128:131], v[142:145]
	v_mfma_f32_16x16x32_bf16 v[56:59], v[134:137], v[230:233], v[32:35]
	v_mfma_f32_16x16x32_bf16 v[32:35], v[182:185], v[234:237], v[160:163]
	v_mfma_f32_16x16x32_bf16 v[60:63], v[134:137], v[238:241], v[32:35]
	v_mfma_f32_16x16x32_bf16 v[32:35], v[186:189], v[128:131], v[164:167]
	v_mfma_f32_16x16x32_bf16 v[48:51], v[190:193], v[230:233], v[32:35]
	v_mfma_f32_16x16x32_bf16 v[32:35], v[186:189], v[234:237], v[174:177]
	v_mfma_f32_16x16x32_bf16 v[52:55], v[190:193], v[238:241], v[32:35]
	v_mfma_f32_16x16x32_bf16 v[32:35], v[194:197], v[128:131], v[178:181]
	v_mfma_f32_16x16x32_bf16 v[40:43], v[198:201], v[230:233], v[32:35]
	v_mfma_f32_16x16x32_bf16 v[32:35], v[194:197], v[234:237], v[210:213]
	v_mfma_f32_16x16x32_bf16 v[44:47], v[198:201], v[238:241], v[32:35]
	v_mfma_f32_16x16x32_bf16 v[32:35], v[202:205], v[128:131], v[214:217]
	v_mfma_f32_16x16x32_bf16 v[36:39], v[202:205], v[234:237], v[152:155]
	v_mfma_f32_16x16x32_bf16 v[32:35], v[156:159], v[230:233], v[32:35]
	v_mfma_f32_16x16x32_bf16 v[36:39], v[156:159], v[238:241], v[36:39]
	s_setprio 0
	s_cmpk_gt_u32 s34, 0xff
	s_barrier
	s_cbranch_scc1 .LBB0_1019
	s_barrier

; #define LDA(dst, b, h)                                                                                    \
;   _Pragma("unroll") for (int m = 0; m < 4; ++m) _Pragma("unroll") for (int k = 0; k < 2; ++k)             \
;       dst[m][k] = *reinterpret_cast<const bf16x8*>((char*)SA(b, h) + lds_byte(wr * 64 + m * 16 + fr, k * 32 + fq * 8))
; #define LDB(dst, b, h)                                                                                    \
;   _Pragma("unroll") for (int n = 0; n < 2; ++n) _Pragma("unroll") for (int k = 0; k < 2; ++k)             \
;       dst[n][k] = *reinterpret_cast<const bf16x8*>((char*)SB(b, h) + lds_byte(wc * 32 + n * 16 + fr, k * 32 + fq * 8))
; #define WAIT_V(n) asm volatile("s_waitcnt vmcnt(" #n ")" ::: "memory")
; #define WAIT_L(n) asm volatile("s_waitcnt lgkmcnt(" #n ")" ::: "memory")
; #define BAR __builtin_amdgcn_s_barrier()
; #define SCHED __builtin_amdgcn_sched_barrier(0)
; template <int EPI> ...
;     ...
;     LDB(B0, 0, 0); SCHED; LDA(At, 0, 0); STAGE(SA(1, 1), A, brow + HALF, t + 1);
;     WAIT_L(8); BAR; WAIT_L(0); MMA(0, 0, At, B0); BAR; SCHED;
;     LDB(B1, 0, 1); STAGE(SB(0, 0), Bt, bcol, t + 2);
;     BAR; WAIT_L(0); MMA(0, 1, At, B1); BAR;
;     LDA(At, 0, 1); STAGE(SA(0, 0), A, brow, t + 2);
;     BAR; WAIT_L(0); MMA(1, 0, At, B0); BAR; SCHED;
;     STAGE(SB(0, 1), Bt, bcol + HALF, t + 2);
;     WAIT_V(6); BAR; MMA(1, 1, At, B1); BAR;
.LBB0_1117:
	ds_read_b128 v[162:165], v155
	ds_read_b128 v[178:181], v155 offset:1024
	ds_read_b128 v[182:185], v155 offset:2048
	ds_read_b128 v[186:189], v155 offset:3072
	s_add_u32 s22, s4, s8
	v_add_u32_e32 v156, s66, v154
	v_add_u32_e32 v157, s67, v154
	v_add_u32_e32 v158, s68, v154
	v_mov_b32_e32 v148, v128
	s_addc_u32 s23, s5, s9
	ds_read_b128 v[190:193], v134
	ds_read_b128 v[194:197], v134 offset:1024
	ds_read_b128 v[198:201], v156
	ds_read_b128 v[202:205], v156 offset:1024
	ds_read_b128 v[206:209], v157
	ds_read_b128 v[210:213], v157 offset:1024
	ds_read_b128 v[214:217], v158
	ds_read_b128 v[218:221], v158 offset:1024
	v_add_u32_e32 v159, 0xe000, v129
	v_lshl_add_u64 v[160:161], v[148:149], 1, s[22:23]
	v_lshl_add_u64 v[166:167], v[160:161], 0, s[48:49]
	v_add_u32_e32 v160, 0xc000, v129
	v_mov_b32_e32 v148, v130
	v_readfirstlane_b32 s30, v160
	s_mov_b32 m0, s30
	v_readfirstlane_b32 s30, v159
	global_load_lds_dwordx4 v[166:167], off
	s_mov_b32 m0, s30
	v_lshl_add_u64 v[166:167], v[148:149], 1, s[22:23]
	v_lshl_add_u64 v[166:167], v[166:167], 0, s[48:49]
	global_load_lds_dwordx4 v[166:167], off
	s_waitcnt lgkmcnt(8)
	s_barrier
	s_waitcnt lgkmcnt(0)
	s_setprio 1
	v_mfma_f32_16x16x32_bf16 v[124:127], v[190:193], v[162:165], v[124:127]
	v_mfma_f32_16x16x32_bf16 v[120:123], v[190:193], v[182:185], v[120:123]
	v_mfma_f32_16x16x32_bf16 v[116:119], v[198:201], v[162:165], v[116:119]
	v_mfma_f32_16x16x32_bf16 v[112:115], v[198:201], v[182:185], v[112:115]
	v_mfma_f32_16x16x32_bf16 v[108:111], v[206:209], v[162:165], v[108:111]
	v_mfma_f32_16x16x32_bf16 v[104:107], v[206:209], v[182:185], v[104:107]
	v_mfma_f32_16x16x32_bf16 v[100:103], v[214:217], v[162:165], v[100:103]
	v_mfma_f32_16x16x32_bf16 v[96:99], v[214:217], v[182:185], v[96:99]
	v_mfma_f32_16x16x32_bf16 v[124:127], v[194:197], v[178:181], v[124:127]
	v_mfma_f32_16x16x32_bf16 v[120:123], v[194:197], v[186:189], v[120:123]
	v_mfma_f32_16x16x32_bf16 v[116:119], v[202:205], v[178:181], v[116:119]
	v_mfma_f32_16x16x32_bf16 v[112:115], v[202:205], v[186:189], v[112:115]
	v_mfma_f32_16x16x32_bf16 v[108:111], v[210:213], v[178:181], v[108:111]
	v_mfma_f32_16x16x32_bf16 v[104:107], v[210:213], v[186:189], v[104:107]
	v_mfma_f32_16x16x32_bf16 v[100:103], v[218:221], v[178:181], v[100:103]
	v_mfma_f32_16x16x32_bf16 v[96:99], v[218:221], v[186:189], v[96:99]
	s_setprio 0
	s_barrier
	s_add_u32 s30, s0, s8
	v_mov_b32_e32 v148, v128
	s_addc_u32 s31, s1, s9
	ds_read_b128 v[222:225], v152
	ds_read_b128 v[226:229], v152 offset:1024
	ds_read_b128 v[230:233], v152 offset:2048
	ds_read_b128 v[234:237], v152 offset:3072
	v_readfirstlane_b32 s70, v133
	v_lshl_add_u64 v[166:167], v[148:149], 1, s[30:31]
	v_lshl_add_u64 v[166:167], v[166:167], 0, s[50:51]
	s_mov_b32 m0, s70
	v_mov_b32_e32 v148, v130
	global_load_lds_dwordx4 v[166:167], off
	v_readfirstlane_b32 s70, v135
	v_lshl_add_u64 v[166:167], v[148:149], 1, s[30:31]
	v_lshl_add_u64 v[166:167], v[166:167], 0, s[50:51]
	s_mov_b32 m0, s70
	s_nop 0
	global_load_lds_dwordx4 v[166:167], off
	s_barrier
	s_waitcnt lgkmcnt(0)
	s_setprio 1
	v_mfma_f32_16x16x32_bf16 v[92:95], v[190:193], v[222:225], v[92:95]
	v_mfma_f32_16x16x32_bf16 v[88:91], v[190:193], v[230:233], v[88:91]
	v_mfma_f32_16x16x32_bf16 v[84:87], v[198:201], v[222:225], v[84:87]
	v_mfma_f32_16x16x32_bf16 v[80:83], v[198:201], v[230:233], v[80:83]
	v_mfma_f32_16x16x32_bf16 v[76:79], v[206:209], v[222:225], v[76:79]
	v_mfma_f32_16x16x32_bf16 v[72:75], v[206:209], v[230:233], v[72:75]
	v_mfma_f32_16x16x32_bf16 v[68:71], v[214:217], v[222:225], v[68:71]
	v_mfma_f32_16x16x32_bf16 v[64:67], v[214:217], v[230:233], v[64:67]
	v_mfma_f32_16x16x32_bf16 v[92:95], v[194:197], v[226:229], v[92:95]
	v_mfma_f32_16x16x32_bf16 v[88:91], v[194:197], v[234:237], v[88:91]
	v_mfma_f32_16x16x32_bf16 v[84:87], v[202:205], v[226:229], v[84:87]
	v_mfma_f32_16x16x32_bf16 v[80:83], v[202:205], v[234:237], v[80:83]
	v_mfma_f32_16x16x32_bf16 v[76:79], v[210:213], v[226:229], v[76:79]
	v_mfma_f32_16x16x32_bf16 v[72:75], v[210:213], v[234:237], v[72:75]
	v_mfma_f32_16x16x32_bf16 v[68:71], v[218:221], v[226:229], v[68:71]
	v_mfma_f32_16x16x32_bf16 v[64:67], v[218:221], v[234:237], v[64:67]
	s_setprio 0
	v_mov_b32_e32 v148, v128
	s_barrier
	ds_read_b128 v[190:193], v134 offset:16384
	ds_read_b128 v[194:197], v134 offset:17408
	ds_read_b128 v[198:201], v156 offset:16384
	ds_read_b128 v[202:205], v156 offset:17408
	ds_read_b128 v[206:209], v157 offset:16384
	ds_read_b128 v[210:213], v157 offset:17408
	ds_read_b128 v[214:217], v158 offset:16384
	ds_read_b128 v[218:221], v158 offset:17408
	v_readfirstlane_b32 s70, v129
	v_lshl_add_u64 v[166:167], v[148:149], 1, s[22:23]
	v_lshl_add_u64 v[166:167], v[166:167], 0, s[50:51]
	s_mov_b32 m0, s70
	v_mov_b32_e32 v148, v130
	global_load_lds_dwordx4 v[166:167], off
	v_readfirstlane_b32 s70, v131
	v_lshl_add_u64 v[166:167], v[148:149], 1, s[22:23]
	v_lshl_add_u64 v[166:167], v[166:167], 0, s[50:51]
	s_mov_b32 m0, s70
	s_nop 0
	global_load_lds_dwordx4 v[166:167], off
	s_barrier
	s_waitcnt lgkmcnt(0)
	s_setprio 1
	v_mfma_f32_16x16x32_bf16 v[60:63], v[190:193], v[162:165], v[60:63]
	v_mfma_f32_16x16x32_bf16 v[56:59], v[190:193], v[182:185], v[56:59]
	v_mfma_f32_16x16x32_bf16 v[52:55], v[198:201], v[162:165], v[52:55]
	v_mfma_f32_16x16x32_bf16 v[48:51], v[198:201], v[182:185], v[48:51]
	v_mfma_f32_16x16x32_bf16 v[44:47], v[206:209], v[162:165], v[44:47]
	v_mfma_f32_16x16x32_bf16 v[40:43], v[206:209], v[182:185], v[40:43]
	v_mfma_f32_16x16x32_bf16 v[36:39], v[214:217], v[162:165], v[36:39]
	v_mfma_f32_16x16x32_bf16 v[32:35], v[214:217], v[182:185], v[32:35]
	v_mfma_f32_16x16x32_bf16 v[60:63], v[194:197], v[178:181], v[60:63]
	v_mfma_f32_16x16x32_bf16 v[56:59], v[194:197], v[186:189], v[56:59]
	v_mfma_f32_16x16x32_bf16 v[52:55], v[202:205], v[178:181], v[52:55]
	v_mfma_f32_16x16x32_bf16 v[48:51], v[202:205], v[186:189], v[48:51]
	v_mfma_f32_16x16x32_bf16 v[44:47], v[210:213], v[178:181], v[44:47]
	v_mfma_f32_16x16x32_bf16 v[40:43], v[210:213], v[186:189], v[40:43]
	v_mfma_f32_16x16x32_bf16 v[36:39], v[218:221], v[178:181], v[36:39]
	v_mfma_f32_16x16x32_bf16 v[32:35], v[218:221], v[186:189], v[32:35]
	s_setprio 0
	s_barrier
; #define LDA(dst, b, h)                                                                                    \
;   _Pragma("unroll") for (int m = 0; m < 4; ++m) _Pragma("unroll") for (int k = 0; k < 2; ++k)             \
;       dst[m][k] = *reinterpret_cast<const bf16x8*>((char*)SA(b, h) + lds_byte(wr * 64 + m * 16 + fr, k * 32 + fq * 8))
; #define LDB(dst, b, h)                                                                                    \
;   _Pragma("unroll") for (int n = 0; n < 2; ++n) _Pragma("unroll") for (int k = 0; k < 2; ++k)             \
;       dst[n][k] = *reinterpret_cast<const bf16x8*>((char*)SB(b, h) + lds_byte(wc * 32 + n * 16 + fr, k * 32 + fq * 8))
; #define WAIT_V(n) asm volatile("s_waitcnt vmcnt(" #n ")" ::: "memory")
; #define WAIT_L(n) asm volatile("s_waitcnt lgkmcnt(" #n ")" ::: "memory")
; #define BAR __builtin_amdgcn_s_barrier()
; #define SCHED __builtin_amdgcn_sched_barrier(0)
; template <int EPI> ...
;     ...
;     WAIT_V(6); BAR; MMA(1, 1, At, B1); BAR;
;     LDB(B0, 1, 0); SCHED; LDA(At, 1, 0); STAGE(SA(0, 1), A, brow + HALF, t + 2);
;     WAIT_L(8); BAR; WAIT_L(0); MMA(0, 0, At, B0); BAR; SCHED;
;     LDB(B1, 1, 1); STAGE(SB(1, 0), Bt, bcol, t + 3);
;     BAR; WAIT_L(0); MMA(0, 1, At, B1); BAR;
;     LDA(At, 1, 1); STAGE(SA(1, 0), A, brow, t + 3);
;     BAR; WAIT_L(0); MMA(1, 0, At, B0); BAR; SCHED;
	v_mov_b32_e32 v148, v128
	v_readfirstlane_b32 s70, v138
	v_lshl_add_u64 v[162:163], v[148:149], 1, s[30:31]
	v_lshl_add_u64 v[162:163], v[162:163], 0, s[52:53]
	s_mov_b32 m0, s70
	v_mov_b32_e32 v148, v130
	global_load_lds_dwordx4 v[162:163], off
	v_readfirstlane_b32 s70, v139
	v_lshl_add_u64 v[162:163], v[148:149], 1, s[30:31]
	v_lshl_add_u64 v[162:163], v[162:163], 0, s[52:53]
	s_mov_b32 m0, s70
	s_nop 0
	global_load_lds_dwordx4 v[162:163], off
	s_waitcnt vmcnt(6)
	s_barrier
	s_setprio 1
	v_mfma_f32_16x16x32_bf16 v[28:31], v[190:193], v[222:225], v[28:31]
	v_mfma_f32_16x16x32_bf16 v[24:27], v[190:193], v[230:233], v[24:27]
	v_mfma_f32_16x16x32_bf16 v[20:23], v[198:201], v[222:225], v[20:23]
	v_mfma_f32_16x16x32_bf16 v[16:19], v[198:201], v[230:233], v[16:19]
	v_mfma_f32_16x16x32_bf16 v[12:15], v[206:209], v[222:225], v[12:15]
	v_mfma_f32_16x16x32_bf16 v[8:11], v[206:209], v[230:233], v[8:11]
	v_mfma_f32_16x16x32_bf16 v[4:7], v[214:217], v[222:225], v[4:7]
	v_mfma_f32_16x16x32_bf16 v[0:3], v[214:217], v[230:233], v[0:3]
	v_mfma_f32_16x16x32_bf16 v[28:31], v[194:197], v[226:229], v[28:31]
	v_mfma_f32_16x16x32_bf16 v[24:27], v[194:197], v[234:237], v[24:27]
	v_mfma_f32_16x16x32_bf16 v[20:23], v[202:205], v[226:229], v[20:23]
	v_mfma_f32_16x16x32_bf16 v[16:19], v[202:205], v[234:237], v[16:19]
	v_mfma_f32_16x16x32_bf16 v[12:15], v[210:213], v[226:229], v[12:15]
	v_mfma_f32_16x16x32_bf16 v[8:11], v[210:213], v[234:237], v[8:11]
	v_mfma_f32_16x16x32_bf16 v[4:7], v[218:221], v[226:229], v[4:7]
	v_mfma_f32_16x16x32_bf16 v[0:3], v[218:221], v[234:237], v[0:3]
	s_setprio 0
	s_barrier
	ds_read_b128 v[162:165], v140
	ds_read_b128 v[178:181], v140 offset:1024
	ds_read_b128 v[182:185], v140 offset:2048
	ds_read_b128 v[186:189], v140 offset:3072
	v_mov_b32_e32 v148, v128
	ds_read_b128 v[190:193], v134 offset:32768
	ds_read_b128 v[194:197], v134 offset:33792
	ds_read_b128 v[198:201], v156 offset:32768
	ds_read_b128 v[202:205], v156 offset:33792
	ds_read_b128 v[206:209], v157 offset:32768
	ds_read_b128 v[210:213], v157 offset:33792
	ds_read_b128 v[214:217], v158 offset:32768
	ds_read_b128 v[218:221], v158 offset:33792
	v_readfirstlane_b32 s70, v141
	v_lshl_add_u64 v[166:167], v[148:149], 1, s[22:23]
	v_lshl_add_u64 v[166:167], v[166:167], 0, s[52:53]
	s_mov_b32 m0, s70
	v_mov_b32_e32 v148, v130
	global_load_lds_dwordx4 v[166:167], off
	v_readfirstlane_b32 s70, v142
	v_lshl_add_u64 v[166:167], v[148:149], 1, s[22:23]
	v_lshl_add_u64 v[166:167], v[166:167], 0, s[52:53]
	s_mov_b32 m0, s70
	s_nop 0
	global_load_lds_dwordx4 v[166:167], off
	s_waitcnt lgkmcnt(8)
	s_barrier
	s_waitcnt lgkmcnt(0)
	s_setprio 1
	v_mfma_f32_16x16x32_bf16 v[124:127], v[190:193], v[162:165], v[124:127]
	v_mfma_f32_16x16x32_bf16 v[120:123], v[190:193], v[182:185], v[120:123]
	v_mfma_f32_16x16x32_bf16 v[116:119], v[198:201], v[162:165], v[116:119]
	v_mfma_f32_16x16x32_bf16 v[112:115], v[198:201], v[182:185], v[112:115]
	v_mfma_f32_16x16x32_bf16 v[108:111], v[206:209], v[162:165], v[108:111]
	v_mfma_f32_16x16x32_bf16 v[104:107], v[206:209], v[182:185], v[104:107]
	v_mfma_f32_16x16x32_bf16 v[100:103], v[214:217], v[162:165], v[100:103]
	v_mfma_f32_16x16x32_bf16 v[96:99], v[214:217], v[182:185], v[96:99]
	v_mfma_f32_16x16x32_bf16 v[124:127], v[194:197], v[178:181], v[124:127]
	v_mfma_f32_16x16x32_bf16 v[120:123], v[194:197], v[186:189], v[120:123]
	v_mfma_f32_16x16x32_bf16 v[116:119], v[202:205], v[178:181], v[116:119]
	v_mfma_f32_16x16x32_bf16 v[112:115], v[202:205], v[186:189], v[112:115]
	v_mfma_f32_16x16x32_bf16 v[108:111], v[210:213], v[178:181], v[108:111]
	v_mfma_f32_16x16x32_bf16 v[104:107], v[210:213], v[186:189], v[104:107]
	v_mfma_f32_16x16x32_bf16 v[100:103], v[218:221], v[178:181], v[100:103]
	v_mfma_f32_16x16x32_bf16 v[96:99], v[218:221], v[186:189], v[96:99]
	s_setprio 0
	s_barrier
	v_mov_b32_e32 v148, v128
	ds_read_b128 v[222:225], v137
	ds_read_b128 v[226:229], v137 offset:1024
	ds_read_b128 v[230:233], v137 offset:2048
	ds_read_b128 v[234:237], v137 offset:3072
	v_readfirstlane_b32 s70, v143
	v_lshl_add_u64 v[166:167], v[148:149], 1, s[30:31]
	v_lshl_add_u64 v[166:167], v[166:167], 0, s[54:55]
	s_mov_b32 m0, s70
	v_mov_b32_e32 v148, v130
	global_load_lds_dwordx4 v[166:167], off
	v_readfirstlane_b32 s70, v144
	v_lshl_add_u64 v[166:167], v[148:149], 1, s[30:31]
	v_lshl_add_u64 v[166:167], v[166:167], 0, s[54:55]
	s_mov_b32 m0, s70
	s_nop 0
	global_load_lds_dwordx4 v[166:167], off
	s_barrier
	s_waitcnt lgkmcnt(0)
	s_setprio 1
	v_mfma_f32_16x16x32_bf16 v[92:95], v[190:193], v[222:225], v[92:95]
	v_mfma_f32_16x16x32_bf16 v[88:91], v[190:193], v[230:233], v[88:91]
	v_mfma_f32_16x16x32_bf16 v[84:87], v[198:201], v[222:225], v[84:87]
	v_mfma_f32_16x16x32_bf16 v[80:83], v[198:201], v[230:233], v[80:83]
	v_mfma_f32_16x16x32_bf16 v[76:79], v[206:209], v[222:225], v[76:79]
	v_mfma_f32_16x16x32_bf16 v[72:75], v[206:209], v[230:233], v[72:75]
	v_mfma_f32_16x16x32_bf16 v[68:71], v[214:217], v[222:225], v[68:71]
	v_mfma_f32_16x16x32_bf16 v[64:67], v[214:217], v[230:233], v[64:67]
	v_mfma_f32_16x16x32_bf16 v[92:95], v[194:197], v[226:229], v[92:95]
	v_mfma_f32_16x16x32_bf16 v[88:91], v[194:197], v[234:237], v[88:91]
	v_mfma_f32_16x16x32_bf16 v[84:87], v[202:205], v[226:229], v[84:87]
	v_mfma_f32_16x16x32_bf16 v[80:83], v[202:205], v[234:237], v[80:83]
	v_mfma_f32_16x16x32_bf16 v[76:79], v[210:213], v[226:229], v[76:79]
	v_mfma_f32_16x16x32_bf16 v[72:75], v[210:213], v[234:237], v[72:75]
	v_mfma_f32_16x16x32_bf16 v[68:71], v[218:221], v[226:229], v[68:71]
	v_mfma_f32_16x16x32_bf16 v[64:67], v[218:221], v[234:237], v[64:67]
	s_setprio 0
	v_mov_b32_e32 v148, v128
	s_barrier
; #define LDA(dst, b, h)                                                                                    \
;   _Pragma("unroll") for (int m = 0; m < 4; ++m) _Pragma("unroll") for (int k = 0; k < 2; ++k)             \
;       dst[m][k] = *reinterpret_cast<const bf16x8*>((char*)SA(b, h) + lds_byte(wr * 64 + m * 16 + fr, k * 32 + fq * 8))
; #define LDB(dst, b, h)                                                                                    \
;   _Pragma("unroll") for (int n = 0; n < 2; ++n) _Pragma("unroll") for (int k = 0; k < 2; ++k)             \
;       dst[n][k] = *reinterpret_cast<const bf16x8*>((char*)SB(b, h) + lds_byte(wc * 32 + n * 16 + fr, k * 32 + fq * 8))
; #define WAIT_V(n) asm volatile("s_waitcnt vmcnt(" #n ")" ::: "memory")
; #define WAIT_L(n) asm volatile("s_waitcnt lgkmcnt(" #n ")" ::: "memory")
; #define BAR __builtin_amdgcn_s_barrier()
; #define SCHED __builtin_amdgcn_sched_barrier(0)
; template <int EPI> ...
;     ...
;     LDA(At, 1, 1); STAGE(SA(1, 0), A, brow, t + 3);
;     BAR; WAIT_L(0); MMA(1, 0, At, B0); BAR; SCHED;
;     STAGE(SB(1, 1), Bt, bcol + HALF, t + 3);
;     WAIT_V(6); BAR; MMA(1, 1, At, B1); BAR;
;   }
;   {
;     LDB(B0, 0, 0); LDA(At, 0, 0); STAGE(SA(1, 1), A, brow + HALF, nt - 1);
;     BAR; WAIT_L(0); MMA(0, 0, At, B0); BAR;
;     LDB(B1, 0, 1); BAR; WAIT_L(0); MMA(0, 1, At, B1); BAR;
	ds_read_b128 v[190:193], v134 offset:49152
	ds_read_b128 v[194:197], v134 offset:50176
	ds_read_b128 v[198:201], v156 offset:49152
	ds_read_b128 v[202:205], v156 offset:50176
	ds_read_b128 v[206:209], v157 offset:49152
	ds_read_b128 v[210:213], v157 offset:50176
	ds_read_b128 v[214:217], v158 offset:49152
	ds_read_b128 v[218:221], v158 offset:50176
	v_readfirstlane_b32 s70, v145
	v_lshl_add_u64 v[166:167], v[148:149], 1, s[22:23]
	v_lshl_add_u64 v[166:167], v[166:167], 0, s[54:55]
	s_mov_b32 m0, s70
	v_mov_b32_e32 v148, v130
	global_load_lds_dwordx4 v[166:167], off
	s_nop 0
	v_lshl_add_u64 v[166:167], v[148:149], 1, s[22:23]
	v_readfirstlane_b32 s22, v146
	v_lshl_add_u64 v[166:167], v[166:167], 0, s[54:55]
	s_mov_b32 m0, s22
	s_nop 0
	global_load_lds_dwordx4 v[166:167], off
	s_barrier
	s_waitcnt lgkmcnt(0)
	s_setprio 1
	v_mfma_f32_16x16x32_bf16 v[60:63], v[190:193], v[162:165], v[60:63]
	v_mfma_f32_16x16x32_bf16 v[56:59], v[190:193], v[182:185], v[56:59]
	v_mfma_f32_16x16x32_bf16 v[52:55], v[198:201], v[162:165], v[52:55]
	v_mfma_f32_16x16x32_bf16 v[48:51], v[198:201], v[182:185], v[48:51]
	v_mfma_f32_16x16x32_bf16 v[44:47], v[206:209], v[162:165], v[44:47]
	v_mfma_f32_16x16x32_bf16 v[40:43], v[206:209], v[182:185], v[40:43]
	v_mfma_f32_16x16x32_bf16 v[36:39], v[214:217], v[162:165], v[36:39]
	v_mfma_f32_16x16x32_bf16 v[32:35], v[214:217], v[182:185], v[32:35]
	v_mfma_f32_16x16x32_bf16 v[60:63], v[194:197], v[178:181], v[60:63]
	v_mfma_f32_16x16x32_bf16 v[56:59], v[194:197], v[186:189], v[56:59]
	v_mfma_f32_16x16x32_bf16 v[52:55], v[202:205], v[178:181], v[52:55]
	v_mfma_f32_16x16x32_bf16 v[48:51], v[202:205], v[186:189], v[48:51]
	v_mfma_f32_16x16x32_bf16 v[44:47], v[210:213], v[178:181], v[44:47]
	v_mfma_f32_16x16x32_bf16 v[40:43], v[210:213], v[186:189], v[40:43]
	v_mfma_f32_16x16x32_bf16 v[36:39], v[218:221], v[178:181], v[36:39]
	v_mfma_f32_16x16x32_bf16 v[32:35], v[218:221], v[186:189], v[32:35]
	s_setprio 0
	s_barrier
	v_mov_b32_e32 v148, v128
	v_readfirstlane_b32 s22, v147
	v_lshl_add_u64 v[162:163], v[148:149], 1, s[30:31]
	v_lshl_add_u64 v[162:163], v[162:163], 0, s[56:57]
	s_mov_b32 m0, s22
	v_mov_b32_e32 v148, v130
	global_load_lds_dwordx4 v[162:163], off
	v_readfirstlane_b32 s22, v153
	v_lshl_add_u64 v[162:163], v[148:149], 1, s[30:31]
	v_lshl_add_u64 v[162:163], v[162:163], 0, s[56:57]
	s_mov_b32 m0, s22
	s_nop 0
	global_load_lds_dwordx4 v[162:163], off
	s_waitcnt vmcnt(6)
	s_barrier
	s_setprio 1
	v_mfma_f32_16x16x32_bf16 v[28:31], v[190:193], v[222:225], v[28:31]
	v_mfma_f32_16x16x32_bf16 v[24:27], v[190:193], v[230:233], v[24:27]
	v_mfma_f32_16x16x32_bf16 v[20:23], v[198:201], v[222:225], v[20:23]
	v_mfma_f32_16x16x32_bf16 v[16:19], v[198:201], v[230:233], v[16:19]
	v_mfma_f32_16x16x32_bf16 v[12:15], v[206:209], v[222:225], v[12:15]
	v_mfma_f32_16x16x32_bf16 v[8:11], v[206:209], v[230:233], v[8:11]
	v_mfma_f32_16x16x32_bf16 v[4:7], v[214:217], v[222:225], v[4:7]
	v_mfma_f32_16x16x32_bf16 v[0:3], v[214:217], v[230:233], v[0:3]
	v_mfma_f32_16x16x32_bf16 v[28:31], v[194:197], v[226:229], v[28:31]
	v_mfma_f32_16x16x32_bf16 v[24:27], v[194:197], v[234:237], v[24:27]
	v_mfma_f32_16x16x32_bf16 v[20:23], v[202:205], v[226:229], v[20:23]
	v_mfma_f32_16x16x32_bf16 v[16:19], v[202:205], v[234:237], v[16:19]
	v_mfma_f32_16x16x32_bf16 v[12:15], v[210:213], v[226:229], v[12:15]
	v_mfma_f32_16x16x32_bf16 v[8:11], v[210:213], v[234:237], v[8:11]
	v_mfma_f32_16x16x32_bf16 v[4:7], v[218:221], v[226:229], v[4:7]
	v_mfma_f32_16x16x32_bf16 v[0:3], v[218:221], v[234:237], v[0:3]
	s_setprio 0
	s_add_i32 s69, s69, 2
	s_add_u32 s8, s8, 0x100
	s_addc_u32 s9, s9, 0
	s_cmp_lt_u32 s69, 12
	s_barrier
	s_cbranch_scc1 .LBB0_1117
	ds_read_b128 v[142:145], v155
	ds_read_b128 v[162:165], v155 offset:1024
	ds_read_b128 v[178:181], v155 offset:2048
	ds_read_b128 v[182:185], v155 offset:3072
	ds_read_b128 v[186:189], v134
	ds_read_b128 v[190:193], v134 offset:1024
	ds_read_b128 v[194:197], v156
	ds_read_b128 v[198:201], v156 offset:1024
	ds_read_b128 v[202:205], v157
	ds_read_b128 v[206:209], v157 offset:1024
	ds_read_b128 v[210:213], v158
	ds_read_b128 v[214:217], v158 offset:1024
	v_mov_b32_e32 v129, v149
	v_lshl_add_u64 v[128:129], v[128:129], 1, s[6:7]
	s_mov_b64 s[4:5], 0x780
	v_readfirstlane_b32 s0, v160
	v_lshl_add_u64 v[128:129], v[128:129], 0, s[4:5]
	s_mov_b32 m0, s0
	v_mov_b32_e32 v131, v149
	global_load_lds_dwordx4 v[128:129], off
	v_readfirstlane_b32 s0, v159
	v_lshl_add_u64 v[128:129], v[130:131], 1, s[6:7]
	v_lshl_add_u64 v[128:129], v[128:129], 0, s[4:5]
	s_mov_b32 m0, s0
	s_nop 0
	global_load_lds_dwordx4 v[128:129], off
	s_barrier
	s_waitcnt lgkmcnt(0)
	s_setprio 1
	v_mfma_f32_16x16x32_bf16 v[124:127], v[186:189], v[142:145], v[124:127]
	v_mfma_f32_16x16x32_bf16 v[120:123], v[186:189], v[178:181], v[120:123]
	v_mfma_f32_16x16x32_bf16 v[116:119], v[194:197], v[142:145], v[116:119]
	v_mfma_f32_16x16x32_bf16 v[112:115], v[194:197], v[178:181], v[112:115]
	v_mfma_f32_16x16x32_bf16 v[108:111], v[202:205], v[142:145], v[108:111]
	v_mfma_f32_16x16x32_bf16 v[104:107], v[202:205], v[178:181], v[104:107]
	v_mfma_f32_16x16x32_bf16 v[100:103], v[210:213], v[142:145], v[100:103]
	v_mfma_f32_16x16x32_bf16 v[124:127], v[190:193], v[162:165], v[124:127]
	v_mfma_f32_16x16x32_bf16 v[120:123], v[190:193], v[182:185], v[120:123]
	v_mfma_f32_16x16x32_bf16 v[116:119], v[198:201], v[162:165], v[116:119]
	v_mfma_f32_16x16x32_bf16 v[112:115], v[198:201], v[182:185], v[112:115]
	v_mfma_f32_16x16x32_bf16 v[108:111], v[206:209], v[162:165], v[108:111]
	v_mfma_f32_16x16x32_bf16 v[104:107], v[206:209], v[182:185], v[104:107]
	v_mfma_f32_16x16x32_bf16 v[100:103], v[214:217], v[162:165], v[100:103]
	v_mfma_f32_16x16x32_bf16 v[96:99], v[210:213], v[178:181], v[96:99]
	v_mfma_f32_16x16x32_bf16 v[128:131], v[214:217], v[182:185], v[96:99]
	s_setprio 0
	s_barrier
; #define LDA(dst, b, h)                                                                                    \
;   _Pragma("unroll") for (int m = 0; m < 4; ++m) _Pragma("unroll") for (int k = 0; k < 2; ++k)             \
;       dst[m][k] = *reinterpret_cast<const bf16x8*>((char*)SA(b, h) + lds_byte(wr * 64 + m * 16 + fr, k * 32 + fq * 8))
; #define LDB(dst, b, h)                                                                                    \
;   _Pragma("unroll") for (int n = 0; n < 2; ++n) _Pragma("unroll") for (int k = 0; k < 2; ++k)             \
;       dst[n][k] = *reinterpret_cast<const bf16x8*>((char*)SB(b, h) + lds_byte(wc * 32 + n * 16 + fr, k * 32 + fq * 8))
; #define WAIT_V(n) asm volatile("s_waitcnt vmcnt(" #n ")" ::: "memory")
; #define WAIT_L(n) asm volatile("s_waitcnt lgkmcnt(" #n ")" ::: "memory")
; #define BAR __builtin_amdgcn_s_barrier()
; template <int EPI> ...
;     ...
;     LDB(B1, 0, 1); BAR; WAIT_L(0); MMA(0, 1, At, B1); BAR;
;     LDA(At, 0, 1); WAIT_V(4); BAR; WAIT_L(0); MMA(1, 0, At, B0); MMA(1, 1, At, B1); BAR;
;   }
;   {
;     LDB(B0, 1, 0); LDA(At, 1, 0); WAIT_V(2); BAR; WAIT_L(0); MMA(0, 0, At, B0); BAR;
	s_nop 4
	ds_read_b128 v[96:99], v152
	ds_read_b128 v[218:221], v152 offset:1024
	ds_read_b128 v[222:225], v152 offset:2048
	ds_read_b128 v[152:155], v152 offset:3072
	s_barrier
	s_waitcnt lgkmcnt(0)
	s_setprio 1
	v_mfma_f32_16x16x32_bf16 v[92:95], v[186:189], v[96:99], v[92:95]
	v_mfma_f32_16x16x32_bf16 v[92:95], v[190:193], v[218:221], v[92:95]
	v_mfma_f32_16x16x32_bf16 v[88:91], v[186:189], v[222:225], v[88:91]
	v_mfma_f32_16x16x32_bf16 v[84:87], v[194:197], v[96:99], v[84:87]
	v_mfma_f32_16x16x32_bf16 v[80:83], v[194:197], v[222:225], v[80:83]
	v_mfma_f32_16x16x32_bf16 v[76:79], v[202:205], v[96:99], v[76:79]
	v_mfma_f32_16x16x32_bf16 v[72:75], v[202:205], v[222:225], v[72:75]
	v_mfma_f32_16x16x32_bf16 v[68:71], v[210:213], v[96:99], v[68:71]
	v_mfma_f32_16x16x32_bf16 v[64:67], v[210:213], v[222:225], v[64:67]
	v_mfma_f32_16x16x32_bf16 v[186:189], v[190:193], v[152:155], v[88:91]
	v_mfma_f32_16x16x32_bf16 v[190:193], v[198:201], v[218:221], v[84:87]
	v_mfma_f32_16x16x32_bf16 v[194:197], v[198:201], v[152:155], v[80:83]
	v_mfma_f32_16x16x32_bf16 v[198:201], v[206:209], v[218:221], v[76:79]
	v_mfma_f32_16x16x32_bf16 v[202:205], v[206:209], v[152:155], v[72:75]
	v_mfma_f32_16x16x32_bf16 v[206:209], v[214:217], v[218:221], v[68:71]
	v_mfma_f32_16x16x32_bf16 v[210:213], v[214:217], v[152:155], v[64:67]
	s_setprio 0
	s_barrier
	s_nop 0
	ds_read_b128 v[64:67], v134 offset:16384
	ds_read_b128 v[68:71], v134 offset:17408
	ds_read_b128 v[72:75], v156 offset:16384
	ds_read_b128 v[76:79], v156 offset:17408
	ds_read_b128 v[80:83], v157 offset:16384
	ds_read_b128 v[84:87], v157 offset:17408
	ds_read_b128 v[88:91], v158 offset:16384
	ds_read_b128 v[214:217], v158 offset:17408
	s_waitcnt vmcnt(4)
	s_barrier
	s_waitcnt lgkmcnt(0)
	s_setprio 1
	v_mfma_f32_16x16x32_bf16 v[60:63], v[64:67], v[142:145], v[60:63]
	v_mfma_f32_16x16x32_bf16 v[56:59], v[64:67], v[178:181], v[56:59]
	v_mfma_f32_16x16x32_bf16 v[52:55], v[72:75], v[142:145], v[52:55]
	v_mfma_f32_16x16x32_bf16 v[48:51], v[72:75], v[178:181], v[48:51]
	v_mfma_f32_16x16x32_bf16 v[44:47], v[80:83], v[142:145], v[44:47]
	v_mfma_f32_16x16x32_bf16 v[40:43], v[80:83], v[178:181], v[40:43]
	v_mfma_f32_16x16x32_bf16 v[36:39], v[88:91], v[142:145], v[36:39]
	v_mfma_f32_16x16x32_bf16 v[32:35], v[88:91], v[178:181], v[32:35]
	v_mfma_f32_16x16x32_bf16 v[60:63], v[68:71], v[162:165], v[60:63]
	v_mfma_f32_16x16x32_bf16 v[56:59], v[68:71], v[182:185], v[56:59]
	v_mfma_f32_16x16x32_bf16 v[52:55], v[76:79], v[162:165], v[52:55]
	v_mfma_f32_16x16x32_bf16 v[48:51], v[76:79], v[182:185], v[48:51]
	v_mfma_f32_16x16x32_bf16 v[44:47], v[84:87], v[162:165], v[44:47]
	v_mfma_f32_16x16x32_bf16 v[40:43], v[84:87], v[182:185], v[40:43]
	v_mfma_f32_16x16x32_bf16 v[36:39], v[214:217], v[162:165], v[36:39]
	v_mfma_f32_16x16x32_bf16 v[32:35], v[214:217], v[182:185], v[32:35]
	s_setprio 0
	s_setprio 1
	v_mfma_f32_16x16x32_bf16 v[28:31], v[64:67], v[96:99], v[28:31]
	v_mfma_f32_16x16x32_bf16 v[24:27], v[64:67], v[222:225], v[24:27]
	v_mfma_f32_16x16x32_bf16 v[20:23], v[72:75], v[96:99], v[20:23]
	v_mfma_f32_16x16x32_bf16 v[16:19], v[72:75], v[222:225], v[16:19]
	v_mfma_f32_16x16x32_bf16 v[12:15], v[80:83], v[96:99], v[12:15]
	v_mfma_f32_16x16x32_bf16 v[8:11], v[80:83], v[222:225], v[8:11]
	v_mfma_f32_16x16x32_bf16 v[4:7], v[88:91], v[96:99], v[4:7]
	v_mfma_f32_16x16x32_bf16 v[0:3], v[88:91], v[222:225], v[0:3]
	v_mfma_f32_16x16x32_bf16 v[142:145], v[68:71], v[218:221], v[28:31]
	v_mfma_f32_16x16x32_bf16 v[160:163], v[68:71], v[152:155], v[24:27]
	v_mfma_f32_16x16x32_bf16 v[164:167], v[76:79], v[218:221], v[20:23]
	v_mfma_f32_16x16x32_bf16 v[178:181], v[76:79], v[152:155], v[16:19]
	v_mfma_f32_16x16x32_bf16 v[182:185], v[84:87], v[218:221], v[12:15]
	v_mfma_f32_16x16x32_bf16 v[226:229], v[84:87], v[152:155], v[8:11]
	v_mfma_f32_16x16x32_bf16 v[218:221], v[214:217], v[218:221], v[4:7]
	v_mfma_f32_16x16x32_bf16 v[152:155], v[214:217], v[152:155], v[0:3]
	s_setprio 0
	s_barrier
	s_nop 0
	ds_read_b128 v[0:3], v140
	ds_read_b128 v[4:7], v140 offset:1024
	ds_read_b128 v[214:217], v140 offset:2048
	ds_read_b128 v[138:141], v140 offset:3072
	ds_read_b128 v[8:11], v134 offset:32768
	ds_read_b128 v[12:15], v134 offset:33792
	ds_read_b128 v[16:19], v156 offset:32768
	ds_read_b128 v[20:23], v156 offset:33792
	ds_read_b128 v[24:27], v157 offset:32768
	ds_read_b128 v[28:31], v157 offset:33792
	ds_read_b128 v[222:225], v158 offset:32768
	ds_read_b128 v[230:233], v158 offset:33792
	s_waitcnt vmcnt(2)
	s_barrier
; #define LDA(dst, b, h)                                                                                    \
;   _Pragma("unroll") for (int m = 0; m < 4; ++m) _Pragma("unroll") for (int k = 0; k < 2; ++k)             \
;       dst[m][k] = *reinterpret_cast<const bf16x8*>((char*)SA(b, h) + lds_byte(wr * 64 + m * 16 + fr, k * 32 + fq * 8))
; #define LDB(dst, b, h)                                                                                    \
;   _Pragma("unroll") for (int n = 0; n < 2; ++n) _Pragma("unroll") for (int k = 0; k < 2; ++k)             \
;       dst[n][k] = *reinterpret_cast<const bf16x8*>((char*)SB(b, h) + lds_byte(wc * 32 + n * 16 + fr, k * 32 + fq * 8))
; #define WAIT_V(n) asm volatile("s_waitcnt vmcnt(" #n ")" ::: "memory")
; #define WAIT_L(n) asm volatile("s_waitcnt lgkmcnt(" #n ")" ::: "memory")
; #define BAR __builtin_amdgcn_s_barrier()
; template <int EPI> ...
;     ...
;     LDB(B0, 1, 0); LDA(At, 1, 0); WAIT_V(2); BAR; WAIT_L(0); MMA(0, 0, At, B0); BAR;
;     LDB(B1, 1, 1); WAIT_V(0); BAR; WAIT_L(0); MMA(0, 1, At, B1); BAR;
;     LDA(At, 1, 1); BAR; WAIT_L(0); MMA(1, 0, At, B0); MMA(1, 1, At, B1); BAR;
;   }
;   if (wr == 0) BAR;
	s_waitcnt lgkmcnt(0)
	s_setprio 1
	v_mfma_f32_16x16x32_bf16 v[64:67], v[8:11], v[0:3], v[124:127]
	v_mfma_f32_16x16x32_bf16 v[88:91], v[12:15], v[4:7], v[64:67]
	v_mfma_f32_16x16x32_bf16 v[64:67], v[8:11], v[214:217], v[120:123]
	v_mfma_f32_16x16x32_bf16 v[96:99], v[12:15], v[138:141], v[64:67]
	v_mfma_f32_16x16x32_bf16 v[64:67], v[16:19], v[0:3], v[116:119]
	v_mfma_f32_16x16x32_bf16 v[80:83], v[20:23], v[4:7], v[64:67]
	v_mfma_f32_16x16x32_bf16 v[64:67], v[16:19], v[214:217], v[112:115]
	v_mfma_f32_16x16x32_bf16 v[84:87], v[20:23], v[138:141], v[64:67]
	v_mfma_f32_16x16x32_bf16 v[64:67], v[24:27], v[0:3], v[108:111]
	v_mfma_f32_16x16x32_bf16 v[72:75], v[28:31], v[4:7], v[64:67]
	v_mfma_f32_16x16x32_bf16 v[64:67], v[24:27], v[214:217], v[104:107]
	v_mfma_f32_16x16x32_bf16 v[76:79], v[28:31], v[138:141], v[64:67]
	v_mfma_f32_16x16x32_bf16 v[64:67], v[222:225], v[0:3], v[100:103]
	v_mfma_f32_16x16x32_bf16 v[68:71], v[222:225], v[214:217], v[128:131]
	v_mfma_f32_16x16x32_bf16 v[64:67], v[230:233], v[4:7], v[64:67]
	v_mfma_f32_16x16x32_bf16 v[68:71], v[230:233], v[138:141], v[68:71]
	s_setprio 0
	s_barrier
	ds_read_b128 v[128:131], v137
	ds_read_b128 v[234:237], v137 offset:1024
	ds_read_b128 v[238:241], v137 offset:2048
	ds_read_b128 v[242:245], v137 offset:3072
	s_waitcnt vmcnt(0)
	s_barrier
	s_waitcnt lgkmcnt(0)
	s_setprio 1
	v_mfma_f32_16x16x32_bf16 v[92:95], v[8:11], v[128:131], v[92:95]
	v_mfma_f32_16x16x32_bf16 v[8:11], v[8:11], v[238:241], v[186:189]
	v_mfma_f32_16x16x32_bf16 v[124:127], v[12:15], v[242:245], v[8:11]
	v_mfma_f32_16x16x32_bf16 v[8:11], v[16:19], v[128:131], v[190:193]
	v_mfma_f32_16x16x32_bf16 v[112:115], v[20:23], v[234:237], v[8:11]
	v_mfma_f32_16x16x32_bf16 v[8:11], v[16:19], v[238:241], v[194:197]
	v_mfma_f32_16x16x32_bf16 v[116:119], v[20:23], v[242:245], v[8:11]
	v_mfma_f32_16x16x32_bf16 v[8:11], v[24:27], v[128:131], v[198:201]
	v_mfma_f32_16x16x32_bf16 v[104:107], v[28:31], v[234:237], v[8:11]
	v_mfma_f32_16x16x32_bf16 v[8:11], v[24:27], v[238:241], v[202:205]
	v_mfma_f32_16x16x32_bf16 v[108:111], v[28:31], v[242:245], v[8:11]
	v_mfma_f32_16x16x32_bf16 v[8:11], v[222:225], v[128:131], v[206:209]
	v_mfma_f32_16x16x32_bf16 v[120:123], v[12:15], v[234:237], v[92:95]
	v_mfma_f32_16x16x32_bf16 v[92:95], v[230:233], v[234:237], v[8:11]
	v_mfma_f32_16x16x32_bf16 v[8:11], v[222:225], v[238:241], v[210:213]
	v_mfma_f32_16x16x32_bf16 v[100:103], v[230:233], v[242:245], v[8:11]
	s_setprio 0
	s_barrier
	ds_read_b128 v[186:189], v134 offset:49152
	ds_read_b128 v[190:193], v134 offset:50176
	ds_read_b128 v[194:197], v156 offset:49152
	ds_read_b128 v[198:201], v156 offset:50176
	ds_read_b128 v[202:205], v157 offset:49152
	ds_read_b128 v[206:209], v157 offset:50176
	ds_read_b128 v[210:213], v158 offset:49152
	ds_read_b128 v[156:159], v158 offset:50176
	s_barrier
	s_waitcnt lgkmcnt(0)
	s_setprio 1
	v_mfma_f32_16x16x32_bf16 v[8:11], v[186:189], v[0:3], v[60:63]
	v_mfma_f32_16x16x32_bf16 v[24:27], v[190:193], v[4:7], v[8:11]
	v_mfma_f32_16x16x32_bf16 v[8:11], v[186:189], v[214:217], v[56:59]
	v_mfma_f32_16x16x32_bf16 v[28:31], v[190:193], v[138:141], v[8:11]
	v_mfma_f32_16x16x32_bf16 v[8:11], v[194:197], v[0:3], v[52:55]
	v_mfma_f32_16x16x32_bf16 v[16:19], v[198:201], v[4:7], v[8:11]
	v_mfma_f32_16x16x32_bf16 v[8:11], v[194:197], v[214:217], v[48:51]
	v_mfma_f32_16x16x32_bf16 v[20:23], v[198:201], v[138:141], v[8:11]
	v_mfma_f32_16x16x32_bf16 v[8:11], v[202:205], v[0:3], v[44:47]
	v_mfma_f32_16x16x32_bf16 v[0:3], v[210:213], v[0:3], v[36:39]
	v_mfma_f32_16x16x32_bf16 v[8:11], v[206:209], v[4:7], v[8:11]
	v_mfma_f32_16x16x32_bf16 v[12:15], v[202:205], v[214:217], v[40:43]
	v_mfma_f32_16x16x32_bf16 v[0:3], v[156:159], v[4:7], v[0:3]
	v_mfma_f32_16x16x32_bf16 v[4:7], v[210:213], v[214:217], v[32:35]
	v_mfma_f32_16x16x32_bf16 v[12:15], v[206:209], v[138:141], v[12:15]
	v_mfma_f32_16x16x32_bf16 v[4:7], v[156:159], v[138:141], v[4:7]
	s_setprio 0
	s_setprio 1
	v_mfma_f32_16x16x32_bf16 v[32:35], v[186:189], v[128:131], v[142:145]
	v_mfma_f32_16x16x32_bf16 v[56:59], v[190:193], v[234:237], v[32:35]
	v_mfma_f32_16x16x32_bf16 v[32:35], v[186:189], v[238:241], v[160:163]
	v_mfma_f32_16x16x32_bf16 v[60:63], v[190:193], v[242:245], v[32:35]
	v_mfma_f32_16x16x32_bf16 v[32:35], v[194:197], v[128:131], v[164:167]
	v_mfma_f32_16x16x32_bf16 v[48:51], v[198:201], v[234:237], v[32:35]
	v_mfma_f32_16x16x32_bf16 v[32:35], v[194:197], v[238:241], v[178:181]
	v_mfma_f32_16x16x32_bf16 v[52:55], v[198:201], v[242:245], v[32:35]
	v_mfma_f32_16x16x32_bf16 v[32:35], v[202:205], v[128:131], v[182:185]
	v_mfma_f32_16x16x32_bf16 v[40:43], v[206:209], v[234:237], v[32:35]
	v_mfma_f32_16x16x32_bf16 v[32:35], v[202:205], v[238:241], v[226:229]
	v_mfma_f32_16x16x32_bf16 v[44:47], v[206:209], v[242:245], v[32:35]
	v_mfma_f32_16x16x32_bf16 v[32:35], v[210:213], v[128:131], v[218:221]
	v_mfma_f32_16x16x32_bf16 v[36:39], v[210:213], v[238:241], v[152:155]
	v_mfma_f32_16x16x32_bf16 v[32:35], v[156:159], v[234:237], v[32:35]
	v_mfma_f32_16x16x32_bf16 v[36:39], v[156:159], v[242:245], v[36:39]
	s_setprio 0
	s_cmpk_gt_u32 s35, 0xff
	s_barrier
	s_cbranch_scc1 .LBB0_1120
	s_barrier

; #define LDA(dst, b, h)                                                                                    \
;   _Pragma("unroll") for (int m = 0; m < 4; ++m) _Pragma("unroll") for (int k = 0; k < 2; ++k)             \
;       dst[m][k] = *reinterpret_cast<const bf16x8*>((char*)SA(b, h) + lds_byte(wr * 64 + m * 16 + fr, k * 32 + fq * 8))
; #define LDB(dst, b, h)                                                                                    \
;   _Pragma("unroll") for (int n = 0; n < 2; ++n) _Pragma("unroll") for (int k = 0; k < 2; ++k)             \
;       dst[n][k] = *reinterpret_cast<const bf16x8*>((char*)SB(b, h) + lds_byte(wc * 32 + n * 16 + fr, k * 32 + fq * 8))
; #define WAIT_V(n) asm volatile("s_waitcnt vmcnt(" #n ")" ::: "memory")
; #define WAIT_L(n) asm volatile("s_waitcnt lgkmcnt(" #n ")" ::: "memory")
; #define BAR __builtin_amdgcn_s_barrier()
; #define SCHED __builtin_amdgcn_sched_barrier(0)
; template <int EPI> ...
;     ...
;     LDB(B0, 0, 0); SCHED; LDA(At, 0, 0); STAGE(SA(1, 1), A, brow + HALF, t + 1);
;     WAIT_L(8); BAR; WAIT_L(0); MMA(0, 0, At, B0); BAR; SCHED;
;     LDB(B1, 0, 1); STAGE(SB(0, 0), Bt, bcol, t + 2);
;     BAR; WAIT_L(0); MMA(0, 1, At, B1); BAR;
;     LDA(At, 0, 1); STAGE(SA(0, 0), A, brow, t + 2);
;     BAR; WAIT_L(0); MMA(1, 0, At, B0); BAR; SCHED;
;     STAGE(SB(0, 1), Bt, bcol + HALF, t + 2);
;     WAIT_V(6); BAR; MMA(1, 1, At, B1); BAR;
.LBB0_1666:
	ds_read_b128 v[162:165], v155
	ds_read_b128 v[178:181], v155 offset:1024
	ds_read_b128 v[182:185], v155 offset:2048
	ds_read_b128 v[186:189], v155 offset:3072
	s_add_u32 s20, s14, s18
	v_add_u32_e32 v156, s35, v154
	v_add_u32_e32 v157, s67, v154
	v_add_u32_e32 v158, s68, v154
	s_addc_u32 s21, s15, s19
	ds_read_b128 v[190:193], v135
	ds_read_b128 v[194:197], v135 offset:1024
	ds_read_b128 v[198:201], v156
	ds_read_b128 v[202:205], v156 offset:1024
	ds_read_b128 v[206:209], v157
	ds_read_b128 v[210:213], v157 offset:1024
	ds_read_b128 v[214:217], v158
	ds_read_b128 v[218:221], v158 offset:1024
	v_add_u32_e32 v159, 0xe000, v129
	v_add_u32_e32 v160, 0xc000, v129
	s_add_u32 m0, s32, 0xc000
	s_add_u32 s98, s20, 0x40080
	s_addc_u32 s99, s21, 0
	global_load_lds_dwordx4 v253, s[98:99]
	s_add_u32 m0, s32, 0xe000
	s_nop 0
	global_load_lds_dwordx4 v252, s[98:99]
	s_waitcnt lgkmcnt(8)
	s_barrier
	s_waitcnt lgkmcnt(0)
	s_setprio 1
	v_mfma_f32_16x16x32_bf16 v[124:127], v[190:193], v[162:165], v[124:127]
	v_mfma_f32_16x16x32_bf16 v[120:123], v[190:193], v[182:185], v[120:123]
	v_mfma_f32_16x16x32_bf16 v[116:119], v[198:201], v[162:165], v[116:119]
	v_mfma_f32_16x16x32_bf16 v[112:115], v[198:201], v[182:185], v[112:115]
	v_mfma_f32_16x16x32_bf16 v[108:111], v[206:209], v[162:165], v[108:111]
	v_mfma_f32_16x16x32_bf16 v[104:107], v[206:209], v[182:185], v[104:107]
	v_mfma_f32_16x16x32_bf16 v[100:103], v[214:217], v[162:165], v[100:103]
	v_mfma_f32_16x16x32_bf16 v[96:99], v[214:217], v[182:185], v[96:99]
	v_mfma_f32_16x16x32_bf16 v[124:127], v[194:197], v[178:181], v[124:127]
	v_mfma_f32_16x16x32_bf16 v[120:123], v[194:197], v[186:189], v[120:123]
	v_mfma_f32_16x16x32_bf16 v[116:119], v[202:205], v[178:181], v[116:119]
	v_mfma_f32_16x16x32_bf16 v[112:115], v[202:205], v[186:189], v[112:115]
	v_mfma_f32_16x16x32_bf16 v[108:111], v[210:213], v[178:181], v[108:111]
	v_mfma_f32_16x16x32_bf16 v[104:107], v[210:213], v[186:189], v[104:107]
	v_mfma_f32_16x16x32_bf16 v[100:103], v[218:221], v[178:181], v[100:103]
	v_mfma_f32_16x16x32_bf16 v[96:99], v[218:221], v[186:189], v[96:99]
	s_setprio 0
	s_barrier
	s_add_u32 s22, s12, s18
	s_addc_u32 s23, s13, s19
	ds_read_b128 v[222:225], v152
	ds_read_b128 v[226:229], v152 offset:1024
	ds_read_b128 v[230:233], v152 offset:2048
	ds_read_b128 v[234:237], v152 offset:3072
	s_add_u32 m0, s32, 0x10000
	s_add_u32 s98, s22, 0x100
	s_addc_u32 s99, s23, 0
	global_load_lds_dwordx4 v253, s[98:99]
	s_add_u32 m0, s32, 0x12000
	s_nop 0
	global_load_lds_dwordx4 v252, s[98:99]
	s_barrier
	s_waitcnt lgkmcnt(0)
	s_setprio 1
	v_mfma_f32_16x16x32_bf16 v[92:95], v[190:193], v[222:225], v[92:95]
	v_mfma_f32_16x16x32_bf16 v[88:91], v[190:193], v[230:233], v[88:91]
	v_mfma_f32_16x16x32_bf16 v[84:87], v[198:201], v[222:225], v[84:87]
	v_mfma_f32_16x16x32_bf16 v[80:83], v[198:201], v[230:233], v[80:83]
	v_mfma_f32_16x16x32_bf16 v[76:79], v[206:209], v[222:225], v[76:79]
	v_mfma_f32_16x16x32_bf16 v[72:75], v[206:209], v[230:233], v[72:75]
	v_mfma_f32_16x16x32_bf16 v[68:71], v[214:217], v[222:225], v[68:71]
	v_mfma_f32_16x16x32_bf16 v[64:67], v[214:217], v[230:233], v[64:67]
	v_mfma_f32_16x16x32_bf16 v[92:95], v[194:197], v[226:229], v[92:95]
	v_mfma_f32_16x16x32_bf16 v[88:91], v[194:197], v[234:237], v[88:91]
	v_mfma_f32_16x16x32_bf16 v[84:87], v[202:205], v[226:229], v[84:87]
	v_mfma_f32_16x16x32_bf16 v[80:83], v[202:205], v[234:237], v[80:83]
	v_mfma_f32_16x16x32_bf16 v[76:79], v[210:213], v[226:229], v[76:79]
	v_mfma_f32_16x16x32_bf16 v[72:75], v[210:213], v[234:237], v[72:75]
	v_mfma_f32_16x16x32_bf16 v[68:71], v[218:221], v[226:229], v[68:71]
	v_mfma_f32_16x16x32_bf16 v[64:67], v[218:221], v[234:237], v[64:67]
	s_setprio 0
	s_barrier
	ds_read_b128 v[190:193], v135 offset:16384
	ds_read_b128 v[194:197], v135 offset:17408
	ds_read_b128 v[198:201], v156 offset:16384
	ds_read_b128 v[202:205], v156 offset:17408
	ds_read_b128 v[206:209], v157 offset:16384
	ds_read_b128 v[210:213], v157 offset:17408
	ds_read_b128 v[214:217], v158 offset:16384
	ds_read_b128 v[218:221], v158 offset:17408
	s_mov_b32 m0, s32
	s_add_u32 s98, s20, 0x100
	s_addc_u32 s99, s21, 0
	global_load_lds_dwordx4 v253, s[98:99]
	s_add_u32 m0, s32, 0x2000
	s_nop 0
	global_load_lds_dwordx4 v252, s[98:99]
	s_barrier
	s_waitcnt lgkmcnt(0)
	s_setprio 1
	v_mfma_f32_16x16x32_bf16 v[60:63], v[190:193], v[162:165], v[60:63]
	v_mfma_f32_16x16x32_bf16 v[56:59], v[190:193], v[182:185], v[56:59]
	v_mfma_f32_16x16x32_bf16 v[52:55], v[198:201], v[162:165], v[52:55]
	v_mfma_f32_16x16x32_bf16 v[48:51], v[198:201], v[182:185], v[48:51]
	v_mfma_f32_16x16x32_bf16 v[44:47], v[206:209], v[162:165], v[44:47]
	v_mfma_f32_16x16x32_bf16 v[40:43], v[206:209], v[182:185], v[40:43]
	v_mfma_f32_16x16x32_bf16 v[36:39], v[214:217], v[162:165], v[36:39]
	v_mfma_f32_16x16x32_bf16 v[32:35], v[214:217], v[182:185], v[32:35]
	v_mfma_f32_16x16x32_bf16 v[60:63], v[194:197], v[178:181], v[60:63]
	v_mfma_f32_16x16x32_bf16 v[56:59], v[194:197], v[186:189], v[56:59]
	v_mfma_f32_16x16x32_bf16 v[52:55], v[202:205], v[178:181], v[52:55]
	v_mfma_f32_16x16x32_bf16 v[48:51], v[202:205], v[186:189], v[48:51]
	v_mfma_f32_16x16x32_bf16 v[44:47], v[210:213], v[178:181], v[44:47]
	v_mfma_f32_16x16x32_bf16 v[40:43], v[210:213], v[186:189], v[40:43]
	v_mfma_f32_16x16x32_bf16 v[36:39], v[218:221], v[178:181], v[36:39]
	v_mfma_f32_16x16x32_bf16 v[32:35], v[218:221], v[186:189], v[32:35]
	s_setprio 0
	s_barrier
	s_add_u32 m0, s32, 0x14000
	s_add_u32 s98, s22, 0x40100
	s_addc_u32 s99, s23, 0
	global_load_lds_dwordx4 v253, s[98:99]
	s_add_u32 m0, s32, 0x16000
	s_nop 0
	global_load_lds_dwordx4 v252, s[98:99]
	s_waitcnt vmcnt(6)
	s_barrier
; #define LDA(dst, b, h)                                                                                    \
;   _Pragma("unroll") for (int m = 0; m < 4; ++m) _Pragma("unroll") for (int k = 0; k < 2; ++k)             \
;       dst[m][k] = *reinterpret_cast<const bf16x8*>((char*)SA(b, h) + lds_byte(wr * 64 + m * 16 + fr, k * 32 + fq * 8))
; #define LDB(dst, b, h)                                                                                    \
;   _Pragma("unroll") for (int n = 0; n < 2; ++n) _Pragma("unroll") for (int k = 0; k < 2; ++k)             \
;       dst[n][k] = *reinterpret_cast<const bf16x8*>((char*)SB(b, h) + lds_byte(wc * 32 + n * 16 + fr, k * 32 + fq * 8))
; #define WAIT_V(n) asm volatile("s_waitcnt vmcnt(" #n ")" ::: "memory")
; #define WAIT_L(n) asm volatile("s_waitcnt lgkmcnt(" #n ")" ::: "memory")
; #define BAR __builtin_amdgcn_s_barrier()
; #define SCHED __builtin_amdgcn_sched_barrier(0)
; template <int EPI> ...
;     ...
;     WAIT_V(6); BAR; MMA(1, 1, At, B1); BAR;
;     LDB(B0, 1, 0); SCHED; LDA(At, 1, 0); STAGE(SA(0, 1), A, brow + HALF, t + 2);
;     WAIT_L(8); BAR; WAIT_L(0); MMA(0, 0, At, B0); BAR; SCHED;
;     LDB(B1, 1, 1); STAGE(SB(1, 0), Bt, bcol, t + 3);
;     BAR; WAIT_L(0); MMA(0, 1, At, B1); BAR;
;     LDA(At, 1, 1); STAGE(SA(1, 0), A, brow, t + 3);
;     BAR; WAIT_L(0); MMA(1, 0, At, B0); BAR; SCHED;
	s_setprio 1
	v_mfma_f32_16x16x32_bf16 v[28:31], v[190:193], v[222:225], v[28:31]
	v_mfma_f32_16x16x32_bf16 v[24:27], v[190:193], v[230:233], v[24:27]
	v_mfma_f32_16x16x32_bf16 v[20:23], v[198:201], v[222:225], v[20:23]
	v_mfma_f32_16x16x32_bf16 v[16:19], v[198:201], v[230:233], v[16:19]
	v_mfma_f32_16x16x32_bf16 v[12:15], v[206:209], v[222:225], v[12:15]
	v_mfma_f32_16x16x32_bf16 v[8:11], v[206:209], v[230:233], v[8:11]
	v_mfma_f32_16x16x32_bf16 v[4:7], v[214:217], v[222:225], v[4:7]
	v_mfma_f32_16x16x32_bf16 v[0:3], v[214:217], v[230:233], v[0:3]
	v_mfma_f32_16x16x32_bf16 v[28:31], v[194:197], v[226:229], v[28:31]
	v_mfma_f32_16x16x32_bf16 v[24:27], v[194:197], v[234:237], v[24:27]
	v_mfma_f32_16x16x32_bf16 v[20:23], v[202:205], v[226:229], v[20:23]
	v_mfma_f32_16x16x32_bf16 v[16:19], v[202:205], v[234:237], v[16:19]
	v_mfma_f32_16x16x32_bf16 v[12:15], v[210:213], v[226:229], v[12:15]
	v_mfma_f32_16x16x32_bf16 v[8:11], v[210:213], v[234:237], v[8:11]
	v_mfma_f32_16x16x32_bf16 v[4:7], v[218:221], v[226:229], v[4:7]
	v_mfma_f32_16x16x32_bf16 v[0:3], v[218:221], v[234:237], v[0:3]
	s_setprio 0
	s_barrier
	ds_read_b128 v[162:165], v140
	ds_read_b128 v[178:181], v140 offset:1024
	ds_read_b128 v[182:185], v140 offset:2048
	ds_read_b128 v[186:189], v140 offset:3072
	ds_read_b128 v[190:193], v135 offset:32768
	ds_read_b128 v[194:197], v135 offset:33792
	ds_read_b128 v[198:201], v156 offset:32768
	ds_read_b128 v[202:205], v156 offset:33792
	ds_read_b128 v[206:209], v157 offset:32768
	ds_read_b128 v[210:213], v157 offset:33792
	ds_read_b128 v[214:217], v158 offset:32768
	ds_read_b128 v[218:221], v158 offset:33792
	s_add_u32 m0, s32, 0x4000
	s_add_u32 s98, s20, 0x40100
	s_addc_u32 s99, s21, 0
	global_load_lds_dwordx4 v253, s[98:99]
	s_add_u32 m0, s32, 0x6000
	s_nop 0
	global_load_lds_dwordx4 v252, s[98:99]
	s_waitcnt lgkmcnt(8)
	s_barrier
	s_waitcnt lgkmcnt(0)
	s_setprio 1
	v_mfma_f32_16x16x32_bf16 v[124:127], v[190:193], v[162:165], v[124:127]
	v_mfma_f32_16x16x32_bf16 v[120:123], v[190:193], v[182:185], v[120:123]
	v_mfma_f32_16x16x32_bf16 v[116:119], v[198:201], v[162:165], v[116:119]
	v_mfma_f32_16x16x32_bf16 v[112:115], v[198:201], v[182:185], v[112:115]
	v_mfma_f32_16x16x32_bf16 v[108:111], v[206:209], v[162:165], v[108:111]
	v_mfma_f32_16x16x32_bf16 v[104:107], v[206:209], v[182:185], v[104:107]
	v_mfma_f32_16x16x32_bf16 v[100:103], v[214:217], v[162:165], v[100:103]
	v_mfma_f32_16x16x32_bf16 v[96:99], v[214:217], v[182:185], v[96:99]
	v_mfma_f32_16x16x32_bf16 v[124:127], v[194:197], v[178:181], v[124:127]
	v_mfma_f32_16x16x32_bf16 v[120:123], v[194:197], v[186:189], v[120:123]
	v_mfma_f32_16x16x32_bf16 v[116:119], v[202:205], v[178:181], v[116:119]
	v_mfma_f32_16x16x32_bf16 v[112:115], v[202:205], v[186:189], v[112:115]
	v_mfma_f32_16x16x32_bf16 v[108:111], v[210:213], v[178:181], v[108:111]
	v_mfma_f32_16x16x32_bf16 v[104:107], v[210:213], v[186:189], v[104:107]
	v_mfma_f32_16x16x32_bf16 v[100:103], v[218:221], v[178:181], v[100:103]
	v_mfma_f32_16x16x32_bf16 v[96:99], v[218:221], v[186:189], v[96:99]
	s_setprio 0
	s_barrier
	ds_read_b128 v[222:225], v137
	ds_read_b128 v[226:229], v137 offset:1024
	ds_read_b128 v[230:233], v137 offset:2048
	ds_read_b128 v[234:237], v137 offset:3072
	s_add_u32 m0, s32, 0x18000
	s_add_u32 s98, s22, 0x180
	s_addc_u32 s99, s23, 0
	global_load_lds_dwordx4 v253, s[98:99]
	s_add_u32 m0, s32, 0x1a000
	s_nop 0
	global_load_lds_dwordx4 v252, s[98:99]
	s_barrier
	s_waitcnt lgkmcnt(0)
	s_setprio 1
	v_mfma_f32_16x16x32_bf16 v[92:95], v[190:193], v[222:225], v[92:95]
	v_mfma_f32_16x16x32_bf16 v[88:91], v[190:193], v[230:233], v[88:91]
	v_mfma_f32_16x16x32_bf16 v[84:87], v[198:201], v[222:225], v[84:87]
	v_mfma_f32_16x16x32_bf16 v[80:83], v[198:201], v[230:233], v[80:83]
	v_mfma_f32_16x16x32_bf16 v[76:79], v[206:209], v[222:225], v[76:79]
	v_mfma_f32_16x16x32_bf16 v[72:75], v[206:209], v[230:233], v[72:75]
	v_mfma_f32_16x16x32_bf16 v[68:71], v[214:217], v[222:225], v[68:71]
	v_mfma_f32_16x16x32_bf16 v[64:67], v[214:217], v[230:233], v[64:67]
	v_mfma_f32_16x16x32_bf16 v[92:95], v[194:197], v[226:229], v[92:95]
	v_mfma_f32_16x16x32_bf16 v[88:91], v[194:197], v[234:237], v[88:91]
	v_mfma_f32_16x16x32_bf16 v[84:87], v[202:205], v[226:229], v[84:87]
	v_mfma_f32_16x16x32_bf16 v[80:83], v[202:205], v[234:237], v[80:83]
	v_mfma_f32_16x16x32_bf16 v[76:79], v[210:213], v[226:229], v[76:79]
	v_mfma_f32_16x16x32_bf16 v[72:75], v[210:213], v[234:237], v[72:75]
	v_mfma_f32_16x16x32_bf16 v[68:71], v[218:221], v[226:229], v[68:71]
	v_mfma_f32_16x16x32_bf16 v[64:67], v[218:221], v[234:237], v[64:67]
	s_setprio 0
	s_barrier
	ds_read_b128 v[190:193], v135 offset:49152
	ds_read_b128 v[194:197], v135 offset:50176
	ds_read_b128 v[198:201], v156 offset:49152
	ds_read_b128 v[202:205], v156 offset:50176
	ds_read_b128 v[206:209], v157 offset:49152
	ds_read_b128 v[210:213], v157 offset:50176
	ds_read_b128 v[214:217], v158 offset:49152
	ds_read_b128 v[218:221], v158 offset:50176
	s_add_u32 m0, s32, 0x8000
	s_add_u32 s98, s20, 0x180
	s_addc_u32 s99, s21, 0
	global_load_lds_dwordx4 v253, s[98:99]
	s_nop 0
	s_add_u32 m0, s32, 0xa000
	s_nop 0
	global_load_lds_dwordx4 v252, s[98:99]
	s_barrier
; #define LDA(dst, b, h)                                                                                    \
;   _Pragma("unroll") for (int m = 0; m < 4; ++m) _Pragma("unroll") for (int k = 0; k < 2; ++k)             \
;       dst[m][k] = *reinterpret_cast<const bf16x8*>((char*)SA(b, h) + lds_byte(wr * 64 + m * 16 + fr, k * 32 + fq * 8))
; #define LDB(dst, b, h)                                                                                    \
;   _Pragma("unroll") for (int n = 0; n < 2; ++n) _Pragma("unroll") for (int k = 0; k < 2; ++k)             \
;       dst[n][k] = *reinterpret_cast<const bf16x8*>((char*)SB(b, h) + lds_byte(wc * 32 + n * 16 + fr, k * 32 + fq * 8))
; #define WAIT_V(n) asm volatile("s_waitcnt vmcnt(" #n ")" ::: "memory")
; #define WAIT_L(n) asm volatile("s_waitcnt lgkmcnt(" #n ")" ::: "memory")
; #define BAR __builtin_amdgcn_s_barrier()
; #define SCHED __builtin_amdgcn_sched_barrier(0)
; template <int EPI> ...
;     ...
;     LDA(At, 1, 1); STAGE(SA(1, 0), A, brow, t + 3);
;     BAR; WAIT_L(0); MMA(1, 0, At, B0); BAR; SCHED;
;     STAGE(SB(1, 1), Bt, bcol + HALF, t + 3);
;     WAIT_V(6); BAR; MMA(1, 1, At, B1); BAR;
;   }
;   {
;     LDB(B0, 0, 0); LDA(At, 0, 0); STAGE(SA(1, 1), A, brow + HALF, nt - 1);
;     BAR; WAIT_L(0); MMA(0, 0, At, B0); BAR;
;     LDB(B1, 0, 1); BAR; WAIT_L(0); MMA(0, 1, At, B1); BAR;
	s_waitcnt lgkmcnt(0)
	s_setprio 1
	v_mfma_f32_16x16x32_bf16 v[60:63], v[190:193], v[162:165], v[60:63]
	v_mfma_f32_16x16x32_bf16 v[56:59], v[190:193], v[182:185], v[56:59]
	v_mfma_f32_16x16x32_bf16 v[52:55], v[198:201], v[162:165], v[52:55]
	v_mfma_f32_16x16x32_bf16 v[48:51], v[198:201], v[182:185], v[48:51]
	v_mfma_f32_16x16x32_bf16 v[44:47], v[206:209], v[162:165], v[44:47]
	v_mfma_f32_16x16x32_bf16 v[40:43], v[206:209], v[182:185], v[40:43]
	v_mfma_f32_16x16x32_bf16 v[36:39], v[214:217], v[162:165], v[36:39]
	v_mfma_f32_16x16x32_bf16 v[32:35], v[214:217], v[182:185], v[32:35]
	v_mfma_f32_16x16x32_bf16 v[60:63], v[194:197], v[178:181], v[60:63]
	v_mfma_f32_16x16x32_bf16 v[56:59], v[194:197], v[186:189], v[56:59]
	v_mfma_f32_16x16x32_bf16 v[52:55], v[202:205], v[178:181], v[52:55]
	v_mfma_f32_16x16x32_bf16 v[48:51], v[202:205], v[186:189], v[48:51]
	v_mfma_f32_16x16x32_bf16 v[44:47], v[210:213], v[178:181], v[44:47]
	v_mfma_f32_16x16x32_bf16 v[40:43], v[210:213], v[186:189], v[40:43]
	v_mfma_f32_16x16x32_bf16 v[36:39], v[218:221], v[178:181], v[36:39]
	v_mfma_f32_16x16x32_bf16 v[32:35], v[218:221], v[186:189], v[32:35]
	s_setprio 0
	s_barrier
	s_add_u32 m0, s32, 0x1c000
	s_add_u32 s98, s22, 0x40180
	s_addc_u32 s99, s23, 0
	global_load_lds_dwordx4 v253, s[98:99]
	s_add_u32 m0, s32, 0x1e000
	s_nop 0
	global_load_lds_dwordx4 v252, s[98:99]
	s_waitcnt vmcnt(6)
	s_barrier
	s_setprio 1
	v_mfma_f32_16x16x32_bf16 v[28:31], v[190:193], v[222:225], v[28:31]
	v_mfma_f32_16x16x32_bf16 v[24:27], v[190:193], v[230:233], v[24:27]
	v_mfma_f32_16x16x32_bf16 v[20:23], v[198:201], v[222:225], v[20:23]
	v_mfma_f32_16x16x32_bf16 v[16:19], v[198:201], v[230:233], v[16:19]
	v_mfma_f32_16x16x32_bf16 v[12:15], v[206:209], v[222:225], v[12:15]
	v_mfma_f32_16x16x32_bf16 v[8:11], v[206:209], v[230:233], v[8:11]
	v_mfma_f32_16x16x32_bf16 v[4:7], v[214:217], v[222:225], v[4:7]
	v_mfma_f32_16x16x32_bf16 v[0:3], v[214:217], v[230:233], v[0:3]
	v_mfma_f32_16x16x32_bf16 v[28:31], v[194:197], v[226:229], v[28:31]
	v_mfma_f32_16x16x32_bf16 v[24:27], v[194:197], v[234:237], v[24:27]
	v_mfma_f32_16x16x32_bf16 v[20:23], v[202:205], v[226:229], v[20:23]
	v_mfma_f32_16x16x32_bf16 v[16:19], v[202:205], v[234:237], v[16:19]
	v_mfma_f32_16x16x32_bf16 v[12:15], v[210:213], v[226:229], v[12:15]
	v_mfma_f32_16x16x32_bf16 v[8:11], v[210:213], v[234:237], v[8:11]
	v_mfma_f32_16x16x32_bf16 v[4:7], v[218:221], v[226:229], v[4:7]
	v_mfma_f32_16x16x32_bf16 v[0:3], v[218:221], v[234:237], v[0:3]
	s_setprio 0
	s_add_i32 s69, s69, 2
	s_add_u32 s18, s18, 0x100
	s_addc_u32 s19, s19, 0
	s_cmp_lt_u32 s69, 12
	s_barrier
	s_cbranch_scc1 .LBB0_1666
	ds_read_b128 v[142:145], v155
	ds_read_b128 v[162:165], v155 offset:1024
	ds_read_b128 v[178:181], v155 offset:2048
	ds_read_b128 v[182:185], v155 offset:3072
	ds_read_b128 v[186:189], v135
	ds_read_b128 v[190:193], v135 offset:1024
	ds_read_b128 v[194:197], v156
	ds_read_b128 v[198:201], v156 offset:1024
	ds_read_b128 v[202:205], v157
	ds_read_b128 v[206:209], v157 offset:1024
	ds_read_b128 v[210:213], v158
	ds_read_b128 v[214:217], v158 offset:1024
	v_mov_b32_e32 v129, v149
	v_lshl_add_u64 v[128:129], v[128:129], 1, s[16:17]
	s_mov_b64 s[14:15], 0x780
	v_readfirstlane_b32 s12, v160
	v_lshl_add_u64 v[128:129], v[128:129], 0, s[14:15]
	s_mov_b32 m0, s12
	v_mov_b32_e32 v131, v149
	global_load_lds_dwordx4 v[128:129], off
	v_readfirstlane_b32 s12, v159
	v_lshl_add_u64 v[128:129], v[130:131], 1, s[16:17]
	v_lshl_add_u64 v[128:129], v[128:129], 0, s[14:15]
	s_mov_b32 m0, s12
	s_nop 0
	global_load_lds_dwordx4 v[128:129], off
	s_barrier
	s_waitcnt lgkmcnt(0)
	s_setprio 1
	v_mfma_f32_16x16x32_bf16 v[124:127], v[186:189], v[142:145], v[124:127]
	v_mfma_f32_16x16x32_bf16 v[120:123], v[186:189], v[178:181], v[120:123]
	v_mfma_f32_16x16x32_bf16 v[116:119], v[194:197], v[142:145], v[116:119]
	v_mfma_f32_16x16x32_bf16 v[112:115], v[194:197], v[178:181], v[112:115]
	v_mfma_f32_16x16x32_bf16 v[108:111], v[202:205], v[142:145], v[108:111]
	v_mfma_f32_16x16x32_bf16 v[104:107], v[202:205], v[178:181], v[104:107]
	v_mfma_f32_16x16x32_bf16 v[96:99], v[210:213], v[178:181], v[96:99]
	v_mfma_f32_16x16x32_bf16 v[124:127], v[190:193], v[162:165], v[124:127]
	v_mfma_f32_16x16x32_bf16 v[120:123], v[190:193], v[182:185], v[120:123]
	v_mfma_f32_16x16x32_bf16 v[116:119], v[198:201], v[162:165], v[116:119]
	v_mfma_f32_16x16x32_bf16 v[112:115], v[198:201], v[182:185], v[112:115]
	v_mfma_f32_16x16x32_bf16 v[108:111], v[206:209], v[162:165], v[108:111]
	v_mfma_f32_16x16x32_bf16 v[104:107], v[206:209], v[182:185], v[104:107]
	v_mfma_f32_16x16x32_bf16 v[100:103], v[210:213], v[142:145], v[100:103]
	v_mfma_f32_16x16x32_bf16 v[96:99], v[214:217], v[182:185], v[96:99]
	v_mfma_f32_16x16x32_bf16 v[128:131], v[214:217], v[162:165], v[100:103]
	s_setprio 0
	s_barrier
	s_nop 3
	ds_read_b128 v[100:103], v152
	ds_read_b128 v[218:221], v152 offset:1024
	ds_read_b128 v[222:225], v152 offset:2048
	ds_read_b128 v[152:155], v152 offset:3072
	s_barrier
	s_waitcnt lgkmcnt(0)
	s_setprio 1
	v_mfma_f32_16x16x32_bf16 v[88:91], v[186:189], v[222:225], v[88:91]
	v_mfma_f32_16x16x32_bf16 v[92:95], v[186:189], v[100:103], v[92:95]
	v_mfma_f32_16x16x32_bf16 v[88:91], v[190:193], v[152:155], v[88:91]
	v_mfma_f32_16x16x32_bf16 v[84:87], v[194:197], v[100:103], v[84:87]
	v_mfma_f32_16x16x32_bf16 v[80:83], v[194:197], v[222:225], v[80:83]
	v_mfma_f32_16x16x32_bf16 v[76:79], v[202:205], v[100:103], v[76:79]
	v_mfma_f32_16x16x32_bf16 v[72:75], v[202:205], v[222:225], v[72:75]
	v_mfma_f32_16x16x32_bf16 v[68:71], v[210:213], v[100:103], v[68:71]
	v_mfma_f32_16x16x32_bf16 v[64:67], v[210:213], v[222:225], v[64:67]
	v_mfma_f32_16x16x32_bf16 v[226:229], v[190:193], v[218:221], v[92:95]
	v_mfma_f32_16x16x32_bf16 v[186:189], v[198:201], v[218:221], v[84:87]
	v_mfma_f32_16x16x32_bf16 v[190:193], v[198:201], v[152:155], v[80:83]
	v_mfma_f32_16x16x32_bf16 v[194:197], v[206:209], v[218:221], v[76:79]
	v_mfma_f32_16x16x32_bf16 v[198:201], v[206:209], v[152:155], v[72:75]
	v_mfma_f32_16x16x32_bf16 v[202:205], v[214:217], v[218:221], v[68:71]
	v_mfma_f32_16x16x32_bf16 v[206:209], v[214:217], v[152:155], v[64:67]
	s_setprio 0
	s_barrier
; #define LDA(dst, b, h)                                                                                    \
;   _Pragma("unroll") for (int m = 0; m < 4; ++m) _Pragma("unroll") for (int k = 0; k < 2; ++k)             \
;       dst[m][k] = *reinterpret_cast<const bf16x8*>((char*)SA(b, h) + lds_byte(wr * 64 + m * 16 + fr, k * 32 + fq * 8))
; #define LDB(dst, b, h)                                                                                    \
;   _Pragma("unroll") for (int n = 0; n < 2; ++n) _Pragma("unroll") for (int k = 0; k < 2; ++k)             \
;       dst[n][k] = *reinterpret_cast<const bf16x8*>((char*)SB(b, h) + lds_byte(wc * 32 + n * 16 + fr, k * 32 + fq * 8))
; #define WAIT_V(n) asm volatile("s_waitcnt vmcnt(" #n ")" ::: "memory")
; #define WAIT_L(n) asm volatile("s_waitcnt lgkmcnt(" #n ")" ::: "memory")
; #define BAR __builtin_amdgcn_s_barrier()
; template <int EPI> ...
;     ...
;     LDA(At, 0, 1); WAIT_V(4); BAR; WAIT_L(0); MMA(1, 0, At, B0); MMA(1, 1, At, B1); BAR;
;   }
;   {
;     LDB(B0, 1, 0); LDA(At, 1, 0); WAIT_V(2); BAR; WAIT_L(0); MMA(0, 0, At, B0); BAR;
	s_nop 0
	ds_read_b128 v[64:67], v135 offset:16384
	ds_read_b128 v[68:71], v135 offset:17408
	ds_read_b128 v[72:75], v156 offset:16384
	ds_read_b128 v[76:79], v156 offset:17408
	ds_read_b128 v[80:83], v157 offset:16384
	ds_read_b128 v[84:87], v157 offset:17408
	ds_read_b128 v[92:95], v158 offset:16384
	ds_read_b128 v[210:213], v158 offset:17408
	s_waitcnt vmcnt(4)
	s_barrier
	s_waitcnt lgkmcnt(0)
	s_setprio 1
	v_mfma_f32_16x16x32_bf16 v[60:63], v[64:67], v[142:145], v[60:63]
	v_mfma_f32_16x16x32_bf16 v[56:59], v[64:67], v[178:181], v[56:59]
	v_mfma_f32_16x16x32_bf16 v[52:55], v[72:75], v[142:145], v[52:55]
	v_mfma_f32_16x16x32_bf16 v[48:51], v[72:75], v[178:181], v[48:51]
	v_mfma_f32_16x16x32_bf16 v[44:47], v[80:83], v[142:145], v[44:47]
	v_mfma_f32_16x16x32_bf16 v[40:43], v[80:83], v[178:181], v[40:43]
	v_mfma_f32_16x16x32_bf16 v[36:39], v[92:95], v[142:145], v[36:39]
	v_mfma_f32_16x16x32_bf16 v[32:35], v[92:95], v[178:181], v[32:35]
	v_mfma_f32_16x16x32_bf16 v[60:63], v[68:71], v[162:165], v[60:63]
	v_mfma_f32_16x16x32_bf16 v[56:59], v[68:71], v[182:185], v[56:59]
	v_mfma_f32_16x16x32_bf16 v[52:55], v[76:79], v[162:165], v[52:55]
	v_mfma_f32_16x16x32_bf16 v[48:51], v[76:79], v[182:185], v[48:51]
	v_mfma_f32_16x16x32_bf16 v[44:47], v[84:87], v[162:165], v[44:47]
	v_mfma_f32_16x16x32_bf16 v[40:43], v[84:87], v[182:185], v[40:43]
	v_mfma_f32_16x16x32_bf16 v[36:39], v[210:213], v[162:165], v[36:39]
	v_mfma_f32_16x16x32_bf16 v[32:35], v[210:213], v[182:185], v[32:35]
	s_setprio 0
	s_setprio 1
	v_mfma_f32_16x16x32_bf16 v[28:31], v[64:67], v[100:103], v[28:31]
	v_mfma_f32_16x16x32_bf16 v[24:27], v[64:67], v[222:225], v[24:27]
	v_mfma_f32_16x16x32_bf16 v[20:23], v[72:75], v[100:103], v[20:23]
	v_mfma_f32_16x16x32_bf16 v[16:19], v[72:75], v[222:225], v[16:19]
	v_mfma_f32_16x16x32_bf16 v[12:15], v[80:83], v[100:103], v[12:15]
	v_mfma_f32_16x16x32_bf16 v[8:11], v[80:83], v[222:225], v[8:11]
	v_mfma_f32_16x16x32_bf16 v[4:7], v[92:95], v[100:103], v[4:7]
	v_mfma_f32_16x16x32_bf16 v[0:3], v[92:95], v[222:225], v[0:3]
	v_mfma_f32_16x16x32_bf16 v[142:145], v[68:71], v[218:221], v[28:31]
	v_mfma_f32_16x16x32_bf16 v[160:163], v[68:71], v[152:155], v[24:27]
	v_mfma_f32_16x16x32_bf16 v[164:167], v[76:79], v[218:221], v[20:23]
	v_mfma_f32_16x16x32_bf16 v[178:181], v[76:79], v[152:155], v[16:19]
	v_mfma_f32_16x16x32_bf16 v[182:185], v[84:87], v[218:221], v[12:15]
	v_mfma_f32_16x16x32_bf16 v[214:217], v[84:87], v[152:155], v[8:11]
	v_mfma_f32_16x16x32_bf16 v[218:221], v[210:213], v[218:221], v[4:7]
	v_mfma_f32_16x16x32_bf16 v[152:155], v[210:213], v[152:155], v[0:3]
	s_setprio 0
	s_barrier
	s_nop 0
	ds_read_b128 v[0:3], v140
	ds_read_b128 v[4:7], v140 offset:1024
	ds_read_b128 v[210:213], v140 offset:2048
	ds_read_b128 v[138:141], v140 offset:3072
	ds_read_b128 v[8:11], v135 offset:32768
	ds_read_b128 v[12:15], v135 offset:33792
	ds_read_b128 v[16:19], v156 offset:32768
	ds_read_b128 v[20:23], v156 offset:33792
	ds_read_b128 v[24:27], v157 offset:32768
	ds_read_b128 v[28:31], v157 offset:33792
	ds_read_b128 v[222:225], v158 offset:32768
	ds_read_b128 v[230:233], v158 offset:33792
	s_waitcnt vmcnt(2)
	s_barrier
	s_waitcnt lgkmcnt(0)
	s_setprio 1
	v_mfma_f32_16x16x32_bf16 v[64:67], v[8:11], v[0:3], v[124:127]
	v_mfma_f32_16x16x32_bf16 v[92:95], v[12:15], v[4:7], v[64:67]
	v_mfma_f32_16x16x32_bf16 v[64:67], v[8:11], v[210:213], v[120:123]
	v_mfma_f32_16x16x32_bf16 v[100:103], v[12:15], v[138:141], v[64:67]
	v_mfma_f32_16x16x32_bf16 v[64:67], v[16:19], v[0:3], v[116:119]
	v_mfma_f32_16x16x32_bf16 v[80:83], v[20:23], v[4:7], v[64:67]
	v_mfma_f32_16x16x32_bf16 v[64:67], v[16:19], v[210:213], v[112:115]
	v_mfma_f32_16x16x32_bf16 v[84:87], v[20:23], v[138:141], v[64:67]
	v_mfma_f32_16x16x32_bf16 v[64:67], v[24:27], v[0:3], v[108:111]
	v_mfma_f32_16x16x32_bf16 v[72:75], v[28:31], v[4:7], v[64:67]
	v_mfma_f32_16x16x32_bf16 v[64:67], v[24:27], v[210:213], v[104:107]
	v_mfma_f32_16x16x32_bf16 v[76:79], v[28:31], v[138:141], v[64:67]
	v_mfma_f32_16x16x32_bf16 v[64:67], v[222:225], v[0:3], v[128:131]
	v_mfma_f32_16x16x32_bf16 v[68:71], v[222:225], v[210:213], v[96:99]
	v_mfma_f32_16x16x32_bf16 v[64:67], v[230:233], v[4:7], v[64:67]
	v_mfma_f32_16x16x32_bf16 v[68:71], v[230:233], v[138:141], v[68:71]
	s_setprio 0
	s_barrier
; #define LDA(dst, b, h)                                                                                    \
;   _Pragma("unroll") for (int m = 0; m < 4; ++m) _Pragma("unroll") for (int k = 0; k < 2; ++k)             \
;       dst[m][k] = *reinterpret_cast<const bf16x8*>((char*)SA(b, h) + lds_byte(wr * 64 + m * 16 + fr, k * 32 + fq * 8))
; #define LDB(dst, b, h)                                                                                    \
;   _Pragma("unroll") for (int n = 0; n < 2; ++n) _Pragma("unroll") for (int k = 0; k < 2; ++k)             \
;       dst[n][k] = *reinterpret_cast<const bf16x8*>((char*)SB(b, h) + lds_byte(wc * 32 + n * 16 + fr, k * 32 + fq * 8))
; #define WAIT_V(n) asm volatile("s_waitcnt vmcnt(" #n ")" ::: "memory")
; #define WAIT_L(n) asm volatile("s_waitcnt lgkmcnt(" #n ")" ::: "memory")
; #define BAR __builtin_amdgcn_s_barrier()
; template <int EPI> ...
;     ...
;     LDB(B1, 1, 1); WAIT_V(0); BAR; WAIT_L(0); MMA(0, 1, At, B1); BAR;
;     LDA(At, 1, 1); BAR; WAIT_L(0); MMA(1, 0, At, B0); MMA(1, 1, At, B1); BAR;
;   }
;   if (wr == 0) BAR;
	ds_read_b128 v[128:131], v137
	ds_read_b128 v[234:237], v137 offset:1024
	ds_read_b128 v[238:241], v137 offset:2048
	ds_read_b128 v[242:245], v137 offset:3072
	s_waitcnt vmcnt(0)
	s_barrier
	s_waitcnt lgkmcnt(0)
	s_setprio 1
	v_mfma_f32_16x16x32_bf16 v[96:99], v[8:11], v[128:131], v[226:229]
	v_mfma_f32_16x16x32_bf16 v[8:11], v[8:11], v[238:241], v[88:91]
	v_mfma_f32_16x16x32_bf16 v[124:127], v[12:15], v[242:245], v[8:11]
	v_mfma_f32_16x16x32_bf16 v[8:11], v[16:19], v[128:131], v[186:189]
	v_mfma_f32_16x16x32_bf16 v[112:115], v[20:23], v[234:237], v[8:11]
	v_mfma_f32_16x16x32_bf16 v[8:11], v[16:19], v[238:241], v[190:193]
	v_mfma_f32_16x16x32_bf16 v[116:119], v[20:23], v[242:245], v[8:11]
	v_mfma_f32_16x16x32_bf16 v[8:11], v[24:27], v[128:131], v[194:197]
	v_mfma_f32_16x16x32_bf16 v[104:107], v[28:31], v[234:237], v[8:11]
	v_mfma_f32_16x16x32_bf16 v[8:11], v[24:27], v[238:241], v[198:201]
	v_mfma_f32_16x16x32_bf16 v[108:111], v[28:31], v[242:245], v[8:11]
	v_mfma_f32_16x16x32_bf16 v[8:11], v[222:225], v[128:131], v[202:205]
	v_mfma_f32_16x16x32_bf16 v[88:91], v[230:233], v[234:237], v[8:11]
	v_mfma_f32_16x16x32_bf16 v[8:11], v[222:225], v[238:241], v[206:209]
	v_mfma_f32_16x16x32_bf16 v[120:123], v[12:15], v[234:237], v[96:99]
	v_mfma_f32_16x16x32_bf16 v[96:99], v[230:233], v[242:245], v[8:11]
	s_setprio 0
	s_barrier
	ds_read_b128 v[186:189], v135 offset:49152
	ds_read_b128 v[134:137], v135 offset:50176
	ds_read_b128 v[190:193], v156 offset:49152
	ds_read_b128 v[194:197], v156 offset:50176
	ds_read_b128 v[198:201], v157 offset:49152
	ds_read_b128 v[202:205], v157 offset:50176
	ds_read_b128 v[206:209], v158 offset:49152
	ds_read_b128 v[156:159], v158 offset:50176
	s_barrier
	s_waitcnt lgkmcnt(0)
	s_setprio 1
	v_mfma_f32_16x16x32_bf16 v[8:11], v[186:189], v[0:3], v[60:63]
	v_mfma_f32_16x16x32_bf16 v[24:27], v[134:137], v[4:7], v[8:11]
	v_mfma_f32_16x16x32_bf16 v[8:11], v[186:189], v[210:213], v[56:59]
	v_mfma_f32_16x16x32_bf16 v[28:31], v[134:137], v[138:141], v[8:11]
	v_mfma_f32_16x16x32_bf16 v[8:11], v[190:193], v[0:3], v[52:55]
	v_mfma_f32_16x16x32_bf16 v[16:19], v[194:197], v[4:7], v[8:11]
	v_mfma_f32_16x16x32_bf16 v[8:11], v[190:193], v[210:213], v[48:51]
	v_mfma_f32_16x16x32_bf16 v[20:23], v[194:197], v[138:141], v[8:11]
	v_mfma_f32_16x16x32_bf16 v[8:11], v[198:201], v[0:3], v[44:47]
	v_mfma_f32_16x16x32_bf16 v[0:3], v[206:209], v[0:3], v[36:39]
	v_mfma_f32_16x16x32_bf16 v[8:11], v[202:205], v[4:7], v[8:11]
	v_mfma_f32_16x16x32_bf16 v[12:15], v[198:201], v[210:213], v[40:43]
	v_mfma_f32_16x16x32_bf16 v[0:3], v[156:159], v[4:7], v[0:3]
	v_mfma_f32_16x16x32_bf16 v[4:7], v[206:209], v[210:213], v[32:35]
	v_mfma_f32_16x16x32_bf16 v[12:15], v[202:205], v[138:141], v[12:15]
	v_mfma_f32_16x16x32_bf16 v[4:7], v[156:159], v[138:141], v[4:7]
	s_setprio 0
	s_setprio 1
	v_mfma_f32_16x16x32_bf16 v[32:35], v[186:189], v[128:131], v[142:145]
	v_mfma_f32_16x16x32_bf16 v[56:59], v[134:137], v[234:237], v[32:35]
	v_mfma_f32_16x16x32_bf16 v[32:35], v[186:189], v[238:241], v[160:163]
	v_mfma_f32_16x16x32_bf16 v[60:63], v[134:137], v[242:245], v[32:35]
	v_mfma_f32_16x16x32_bf16 v[32:35], v[190:193], v[128:131], v[164:167]
	v_mfma_f32_16x16x32_bf16 v[48:51], v[194:197], v[234:237], v[32:35]
	v_mfma_f32_16x16x32_bf16 v[32:35], v[190:193], v[238:241], v[178:181]
	v_mfma_f32_16x16x32_bf16 v[52:55], v[194:197], v[242:245], v[32:35]
	v_mfma_f32_16x16x32_bf16 v[32:35], v[198:201], v[128:131], v[182:185]
	v_mfma_f32_16x16x32_bf16 v[40:43], v[202:205], v[234:237], v[32:35]
	v_mfma_f32_16x16x32_bf16 v[32:35], v[198:201], v[238:241], v[214:217]
	v_mfma_f32_16x16x32_bf16 v[44:47], v[202:205], v[242:245], v[32:35]
	v_mfma_f32_16x16x32_bf16 v[32:35], v[206:209], v[128:131], v[218:221]
	v_mfma_f32_16x16x32_bf16 v[36:39], v[206:209], v[238:241], v[152:155]
	v_mfma_f32_16x16x32_bf16 v[32:35], v[156:159], v[234:237], v[32:35]
	v_mfma_f32_16x16x32_bf16 v[36:39], v[156:159], v[242:245], v[36:39]
	s_setprio 0
	s_cmpk_gt_u32 s30, 0xff
	s_barrier
	s_cbranch_scc1 .LBB0_1669
	s_barrier

; #define LDA(dst, b, h)                                                                                    \
;   _Pragma("unroll") for (int m = 0; m < 4; ++m) _Pragma("unroll") for (int k = 0; k < 2; ++k)             \
;       dst[m][k] = *reinterpret_cast<const bf16x8*>((char*)SA(b, h) + lds_byte(wr * 64 + m * 16 + fr, k * 32 + fq * 8))
; #define LDB(dst, b, h)                                                                                    \
;   _Pragma("unroll") for (int n = 0; n < 2; ++n) _Pragma("unroll") for (int k = 0; k < 2; ++k)             \
;       dst[n][k] = *reinterpret_cast<const bf16x8*>((char*)SB(b, h) + lds_byte(wc * 32 + n * 16 + fr, k * 32 + fq * 8))
; #define WAIT_V(n) asm volatile("s_waitcnt vmcnt(" #n ")" ::: "memory")
; #define WAIT_L(n) asm volatile("s_waitcnt lgkmcnt(" #n ")" ::: "memory")
; #define BAR __builtin_amdgcn_s_barrier()
; #define SCHED __builtin_amdgcn_sched_barrier(0)
; template <int EPI> ...
;     ...
;     LDB(B0, 0, 0); SCHED; LDA(At, 0, 0); STAGE(SA(1, 1), A, brow + HALF, t + 1);
;     WAIT_L(8); BAR; WAIT_L(0); MMA(0, 0, At, B0); BAR; SCHED;
;     LDB(B1, 0, 1); STAGE(SB(0, 0), Bt, bcol, t + 2);
;     BAR; WAIT_L(0); MMA(0, 1, At, B1); BAR;
;     LDA(At, 0, 1); STAGE(SA(0, 0), A, brow, t + 2);
;     BAR; WAIT_L(0); MMA(1, 0, At, B0); BAR; SCHED;
;     STAGE(SB(0, 1), Bt, bcol + HALF, t + 2);
;     WAIT_V(6); BAR; MMA(1, 1, At, B1); BAR;
.LBB0_1754:
	ds_read_b128 v[162:165], v155
	ds_read_b128 v[174:177], v155 offset:1024
	ds_read_b128 v[178:181], v155 offset:2048
	ds_read_b128 v[182:185], v155 offset:3072
	s_add_u32 s18, s12, s16
	v_add_u32_e32 v156, s65, v154
	v_add_u32_e32 v157, s66, v154
	v_add_u32_e32 v158, s67, v154
	s_addc_u32 s19, s13, s17
	ds_read_b128 v[186:189], v135
	ds_read_b128 v[190:193], v135 offset:1024
	ds_read_b128 v[194:197], v156
	ds_read_b128 v[198:201], v156 offset:1024
	ds_read_b128 v[202:205], v157
	ds_read_b128 v[206:209], v157 offset:1024
	ds_read_b128 v[210:213], v158
	ds_read_b128 v[214:217], v158 offset:1024
	v_add_u32_e32 v159, 0xe000, v133
	v_add_u32_e32 v160, 0xc000, v133
	s_add_u32 m0, s32, 0xc000
	s_add_u32 s98, s18, 0x40080
	s_addc_u32 s99, s19, 0
	global_load_lds_dwordx4 v253, s[98:99]
	s_add_u32 m0, s32, 0xe000
	s_nop 0
	global_load_lds_dwordx4 v252, s[98:99]
	s_waitcnt lgkmcnt(8)
	s_barrier
	s_waitcnt lgkmcnt(0)
	s_setprio 1
	v_mfma_f32_16x16x32_bf16 v[124:127], v[186:189], v[162:165], v[124:127]
	v_mfma_f32_16x16x32_bf16 v[120:123], v[186:189], v[178:181], v[120:123]
	v_mfma_f32_16x16x32_bf16 v[116:119], v[194:197], v[162:165], v[116:119]
	v_mfma_f32_16x16x32_bf16 v[112:115], v[194:197], v[178:181], v[112:115]
	v_mfma_f32_16x16x32_bf16 v[108:111], v[202:205], v[162:165], v[108:111]
	v_mfma_f32_16x16x32_bf16 v[104:107], v[202:205], v[178:181], v[104:107]
	v_mfma_f32_16x16x32_bf16 v[100:103], v[210:213], v[162:165], v[100:103]
	v_mfma_f32_16x16x32_bf16 v[96:99], v[210:213], v[178:181], v[96:99]
	v_mfma_f32_16x16x32_bf16 v[124:127], v[190:193], v[174:177], v[124:127]
	v_mfma_f32_16x16x32_bf16 v[120:123], v[190:193], v[182:185], v[120:123]
	v_mfma_f32_16x16x32_bf16 v[116:119], v[198:201], v[174:177], v[116:119]
	v_mfma_f32_16x16x32_bf16 v[112:115], v[198:201], v[182:185], v[112:115]
	v_mfma_f32_16x16x32_bf16 v[108:111], v[206:209], v[174:177], v[108:111]
	v_mfma_f32_16x16x32_bf16 v[104:107], v[206:209], v[182:185], v[104:107]
	v_mfma_f32_16x16x32_bf16 v[100:103], v[214:217], v[174:177], v[100:103]
	v_mfma_f32_16x16x32_bf16 v[96:99], v[214:217], v[182:185], v[96:99]
	s_setprio 0
	s_barrier
	s_add_u32 s20, s10, s16
	s_addc_u32 s21, s11, s17
	ds_read_b128 v[218:221], v152
	ds_read_b128 v[222:225], v152 offset:1024
	ds_read_b128 v[226:229], v152 offset:2048
	ds_read_b128 v[230:233], v152 offset:3072
	s_add_u32 m0, s32, 0x10000
	s_add_u32 s98, s20, 0x100
	s_addc_u32 s99, s21, 0
	global_load_lds_dwordx4 v253, s[98:99]
	s_add_u32 m0, s32, 0x12000
	s_nop 0
	global_load_lds_dwordx4 v252, s[98:99]
	s_barrier
	s_waitcnt lgkmcnt(0)
	s_setprio 1
	v_mfma_f32_16x16x32_bf16 v[92:95], v[186:189], v[218:221], v[92:95]
	v_mfma_f32_16x16x32_bf16 v[88:91], v[186:189], v[226:229], v[88:91]
	v_mfma_f32_16x16x32_bf16 v[84:87], v[194:197], v[218:221], v[84:87]
	v_mfma_f32_16x16x32_bf16 v[80:83], v[194:197], v[226:229], v[80:83]
	v_mfma_f32_16x16x32_bf16 v[76:79], v[202:205], v[218:221], v[76:79]
	v_mfma_f32_16x16x32_bf16 v[72:75], v[202:205], v[226:229], v[72:75]
	v_mfma_f32_16x16x32_bf16 v[68:71], v[210:213], v[218:221], v[68:71]
	v_mfma_f32_16x16x32_bf16 v[64:67], v[210:213], v[226:229], v[64:67]
	v_mfma_f32_16x16x32_bf16 v[92:95], v[190:193], v[222:225], v[92:95]
	v_mfma_f32_16x16x32_bf16 v[88:91], v[190:193], v[230:233], v[88:91]
	v_mfma_f32_16x16x32_bf16 v[84:87], v[198:201], v[222:225], v[84:87]
	v_mfma_f32_16x16x32_bf16 v[80:83], v[198:201], v[230:233], v[80:83]
	v_mfma_f32_16x16x32_bf16 v[76:79], v[206:209], v[222:225], v[76:79]
	v_mfma_f32_16x16x32_bf16 v[72:75], v[206:209], v[230:233], v[72:75]
	v_mfma_f32_16x16x32_bf16 v[68:71], v[214:217], v[222:225], v[68:71]
	v_mfma_f32_16x16x32_bf16 v[64:67], v[214:217], v[230:233], v[64:67]
	s_setprio 0
	s_barrier
	ds_read_b128 v[186:189], v135 offset:16384
	ds_read_b128 v[190:193], v135 offset:17408
	ds_read_b128 v[194:197], v156 offset:16384
	ds_read_b128 v[198:201], v156 offset:17408
	ds_read_b128 v[202:205], v157 offset:16384
	ds_read_b128 v[206:209], v157 offset:17408
	ds_read_b128 v[210:213], v158 offset:16384
	ds_read_b128 v[214:217], v158 offset:17408
	s_mov_b32 m0, s32
	s_add_u32 s98, s18, 0x100
	s_addc_u32 s99, s19, 0
	global_load_lds_dwordx4 v253, s[98:99]
	s_add_u32 m0, s32, 0x2000
	s_nop 0
	global_load_lds_dwordx4 v252, s[98:99]
	s_barrier
	s_waitcnt lgkmcnt(0)
	s_setprio 1
	v_mfma_f32_16x16x32_bf16 v[60:63], v[186:189], v[162:165], v[60:63]
	v_mfma_f32_16x16x32_bf16 v[56:59], v[186:189], v[178:181], v[56:59]
	v_mfma_f32_16x16x32_bf16 v[52:55], v[194:197], v[162:165], v[52:55]
	v_mfma_f32_16x16x32_bf16 v[48:51], v[194:197], v[178:181], v[48:51]
	v_mfma_f32_16x16x32_bf16 v[44:47], v[202:205], v[162:165], v[44:47]
	v_mfma_f32_16x16x32_bf16 v[40:43], v[202:205], v[178:181], v[40:43]
	v_mfma_f32_16x16x32_bf16 v[36:39], v[210:213], v[162:165], v[36:39]
	v_mfma_f32_16x16x32_bf16 v[32:35], v[210:213], v[178:181], v[32:35]
	v_mfma_f32_16x16x32_bf16 v[60:63], v[190:193], v[174:177], v[60:63]
	v_mfma_f32_16x16x32_bf16 v[56:59], v[190:193], v[182:185], v[56:59]
	v_mfma_f32_16x16x32_bf16 v[52:55], v[198:201], v[174:177], v[52:55]
	v_mfma_f32_16x16x32_bf16 v[48:51], v[198:201], v[182:185], v[48:51]
	v_mfma_f32_16x16x32_bf16 v[44:47], v[206:209], v[174:177], v[44:47]
	v_mfma_f32_16x16x32_bf16 v[40:43], v[206:209], v[182:185], v[40:43]
	v_mfma_f32_16x16x32_bf16 v[36:39], v[214:217], v[174:177], v[36:39]
	v_mfma_f32_16x16x32_bf16 v[32:35], v[214:217], v[182:185], v[32:35]
	s_setprio 0
	s_barrier
	s_add_u32 m0, s32, 0x14000
	s_add_u32 s98, s20, 0x40100
	s_addc_u32 s99, s21, 0
	global_load_lds_dwordx4 v253, s[98:99]
	s_add_u32 m0, s32, 0x16000
	s_nop 0
	global_load_lds_dwordx4 v252, s[98:99]
	s_waitcnt vmcnt(6)
	s_barrier
; #define LDA(dst, b, h)                                                                                    \
;   _Pragma("unroll") for (int m = 0; m < 4; ++m) _Pragma("unroll") for (int k = 0; k < 2; ++k)             \
;       dst[m][k] = *reinterpret_cast<const bf16x8*>((char*)SA(b, h) + lds_byte(wr * 64 + m * 16 + fr, k * 32 + fq * 8))
; #define LDB(dst, b, h)                                                                                    \
;   _Pragma("unroll") for (int n = 0; n < 2; ++n) _Pragma("unroll") for (int k = 0; k < 2; ++k)             \
;       dst[n][k] = *reinterpret_cast<const bf16x8*>((char*)SB(b, h) + lds_byte(wc * 32 + n * 16 + fr, k * 32 + fq * 8))
; #define WAIT_V(n) asm volatile("s_waitcnt vmcnt(" #n ")" ::: "memory")
; #define WAIT_L(n) asm volatile("s_waitcnt lgkmcnt(" #n ")" ::: "memory")
; #define BAR __builtin_amdgcn_s_barrier()
; #define SCHED __builtin_amdgcn_sched_barrier(0)
; template <int EPI> ...
;     ...
;     WAIT_V(6); BAR; MMA(1, 1, At, B1); BAR;
;     LDB(B0, 1, 0); SCHED; LDA(At, 1, 0); STAGE(SA(0, 1), A, brow + HALF, t + 2);
;     WAIT_L(8); BAR; WAIT_L(0); MMA(0, 0, At, B0); BAR; SCHED;
;     LDB(B1, 1, 1); STAGE(SB(1, 0), Bt, bcol, t + 3);
;     BAR; WAIT_L(0); MMA(0, 1, At, B1); BAR;
;     LDA(At, 1, 1); STAGE(SA(1, 0), A, brow, t + 3);
;     BAR; WAIT_L(0); MMA(1, 0, At, B0); BAR; SCHED;
	s_setprio 1
	v_mfma_f32_16x16x32_bf16 v[28:31], v[186:189], v[218:221], v[28:31]
	v_mfma_f32_16x16x32_bf16 v[24:27], v[186:189], v[226:229], v[24:27]
	v_mfma_f32_16x16x32_bf16 v[20:23], v[194:197], v[218:221], v[20:23]
	v_mfma_f32_16x16x32_bf16 v[16:19], v[194:197], v[226:229], v[16:19]
	v_mfma_f32_16x16x32_bf16 v[12:15], v[202:205], v[218:221], v[12:15]
	v_mfma_f32_16x16x32_bf16 v[8:11], v[202:205], v[226:229], v[8:11]
	v_mfma_f32_16x16x32_bf16 v[4:7], v[210:213], v[218:221], v[4:7]
	v_mfma_f32_16x16x32_bf16 v[0:3], v[210:213], v[226:229], v[0:3]
	v_mfma_f32_16x16x32_bf16 v[28:31], v[190:193], v[222:225], v[28:31]
	v_mfma_f32_16x16x32_bf16 v[24:27], v[190:193], v[230:233], v[24:27]
	v_mfma_f32_16x16x32_bf16 v[20:23], v[198:201], v[222:225], v[20:23]
	v_mfma_f32_16x16x32_bf16 v[16:19], v[198:201], v[230:233], v[16:19]
	v_mfma_f32_16x16x32_bf16 v[12:15], v[206:209], v[222:225], v[12:15]
	v_mfma_f32_16x16x32_bf16 v[8:11], v[206:209], v[230:233], v[8:11]
	v_mfma_f32_16x16x32_bf16 v[4:7], v[214:217], v[222:225], v[4:7]
	v_mfma_f32_16x16x32_bf16 v[0:3], v[214:217], v[230:233], v[0:3]
	s_setprio 0
	s_barrier
	ds_read_b128 v[162:165], v140
	ds_read_b128 v[174:177], v140 offset:1024
	ds_read_b128 v[178:181], v140 offset:2048
	ds_read_b128 v[182:185], v140 offset:3072
	ds_read_b128 v[186:189], v135 offset:32768
	ds_read_b128 v[190:193], v135 offset:33792
	ds_read_b128 v[194:197], v156 offset:32768
	ds_read_b128 v[198:201], v156 offset:33792
	ds_read_b128 v[202:205], v157 offset:32768
	ds_read_b128 v[206:209], v157 offset:33792
	ds_read_b128 v[210:213], v158 offset:32768
	ds_read_b128 v[214:217], v158 offset:33792
	s_add_u32 m0, s32, 0x4000
	s_add_u32 s98, s18, 0x40100
	s_addc_u32 s99, s19, 0
	global_load_lds_dwordx4 v253, s[98:99]
	s_add_u32 m0, s32, 0x6000
	s_nop 0
	global_load_lds_dwordx4 v252, s[98:99]
	s_waitcnt lgkmcnt(8)
	s_barrier
	s_waitcnt lgkmcnt(0)
	s_setprio 1
	v_mfma_f32_16x16x32_bf16 v[124:127], v[186:189], v[162:165], v[124:127]
	v_mfma_f32_16x16x32_bf16 v[120:123], v[186:189], v[178:181], v[120:123]
	v_mfma_f32_16x16x32_bf16 v[116:119], v[194:197], v[162:165], v[116:119]
	v_mfma_f32_16x16x32_bf16 v[112:115], v[194:197], v[178:181], v[112:115]
	v_mfma_f32_16x16x32_bf16 v[108:111], v[202:205], v[162:165], v[108:111]
	v_mfma_f32_16x16x32_bf16 v[104:107], v[202:205], v[178:181], v[104:107]
	v_mfma_f32_16x16x32_bf16 v[100:103], v[210:213], v[162:165], v[100:103]
	v_mfma_f32_16x16x32_bf16 v[96:99], v[210:213], v[178:181], v[96:99]
	v_mfma_f32_16x16x32_bf16 v[124:127], v[190:193], v[174:177], v[124:127]
	v_mfma_f32_16x16x32_bf16 v[120:123], v[190:193], v[182:185], v[120:123]
	v_mfma_f32_16x16x32_bf16 v[116:119], v[198:201], v[174:177], v[116:119]
	v_mfma_f32_16x16x32_bf16 v[112:115], v[198:201], v[182:185], v[112:115]
	v_mfma_f32_16x16x32_bf16 v[108:111], v[206:209], v[174:177], v[108:111]
	v_mfma_f32_16x16x32_bf16 v[104:107], v[206:209], v[182:185], v[104:107]
	v_mfma_f32_16x16x32_bf16 v[100:103], v[214:217], v[174:177], v[100:103]
	v_mfma_f32_16x16x32_bf16 v[96:99], v[214:217], v[182:185], v[96:99]
	s_setprio 0
	s_barrier
	ds_read_b128 v[218:221], v137
	ds_read_b128 v[222:225], v137 offset:1024
	ds_read_b128 v[226:229], v137 offset:2048
	ds_read_b128 v[230:233], v137 offset:3072
	s_add_u32 m0, s32, 0x18000
	s_add_u32 s98, s20, 0x180
	s_addc_u32 s99, s21, 0
	global_load_lds_dwordx4 v253, s[98:99]
	s_add_u32 m0, s32, 0x1a000
	s_nop 0
	global_load_lds_dwordx4 v252, s[98:99]
	s_barrier
	s_waitcnt lgkmcnt(0)
	s_setprio 1
	v_mfma_f32_16x16x32_bf16 v[92:95], v[186:189], v[218:221], v[92:95]
	v_mfma_f32_16x16x32_bf16 v[88:91], v[186:189], v[226:229], v[88:91]
	v_mfma_f32_16x16x32_bf16 v[84:87], v[194:197], v[218:221], v[84:87]
	v_mfma_f32_16x16x32_bf16 v[80:83], v[194:197], v[226:229], v[80:83]
	v_mfma_f32_16x16x32_bf16 v[76:79], v[202:205], v[218:221], v[76:79]
	v_mfma_f32_16x16x32_bf16 v[72:75], v[202:205], v[226:229], v[72:75]
	v_mfma_f32_16x16x32_bf16 v[68:71], v[210:213], v[218:221], v[68:71]
	v_mfma_f32_16x16x32_bf16 v[64:67], v[210:213], v[226:229], v[64:67]
	v_mfma_f32_16x16x32_bf16 v[92:95], v[190:193], v[222:225], v[92:95]
	v_mfma_f32_16x16x32_bf16 v[88:91], v[190:193], v[230:233], v[88:91]
	v_mfma_f32_16x16x32_bf16 v[84:87], v[198:201], v[222:225], v[84:87]
	v_mfma_f32_16x16x32_bf16 v[80:83], v[198:201], v[230:233], v[80:83]
	v_mfma_f32_16x16x32_bf16 v[76:79], v[206:209], v[222:225], v[76:79]
	v_mfma_f32_16x16x32_bf16 v[72:75], v[206:209], v[230:233], v[72:75]
	v_mfma_f32_16x16x32_bf16 v[68:71], v[214:217], v[222:225], v[68:71]
	v_mfma_f32_16x16x32_bf16 v[64:67], v[214:217], v[230:233], v[64:67]
	s_setprio 0
	s_barrier
	ds_read_b128 v[186:189], v135 offset:49152
	ds_read_b128 v[190:193], v135 offset:50176
	ds_read_b128 v[194:197], v156 offset:49152
	ds_read_b128 v[198:201], v156 offset:50176
	ds_read_b128 v[202:205], v157 offset:49152
	ds_read_b128 v[206:209], v157 offset:50176
	ds_read_b128 v[210:213], v158 offset:49152
	ds_read_b128 v[214:217], v158 offset:50176
	s_add_u32 m0, s32, 0x8000
	s_add_u32 s98, s18, 0x180
	s_addc_u32 s99, s19, 0
	global_load_lds_dwordx4 v253, s[98:99]
	s_nop 0
	s_add_u32 m0, s32, 0xa000
	s_nop 0
	global_load_lds_dwordx4 v252, s[98:99]
	s_barrier
; #define LDA(dst, b, h)                                                                                    \
;   _Pragma("unroll") for (int m = 0; m < 4; ++m) _Pragma("unroll") for (int k = 0; k < 2; ++k)             \
;       dst[m][k] = *reinterpret_cast<const bf16x8*>((char*)SA(b, h) + lds_byte(wr * 64 + m * 16 + fr, k * 32 + fq * 8))
; #define LDB(dst, b, h)                                                                                    \
;   _Pragma("unroll") for (int n = 0; n < 2; ++n) _Pragma("unroll") for (int k = 0; k < 2; ++k)             \
;       dst[n][k] = *reinterpret_cast<const bf16x8*>((char*)SB(b, h) + lds_byte(wc * 32 + n * 16 + fr, k * 32 + fq * 8))
; #define WAIT_V(n) asm volatile("s_waitcnt vmcnt(" #n ")" ::: "memory")
; #define WAIT_L(n) asm volatile("s_waitcnt lgkmcnt(" #n ")" ::: "memory")
; #define BAR __builtin_amdgcn_s_barrier()
; #define SCHED __builtin_amdgcn_sched_barrier(0)
; template <int EPI> ...
;     ...
;     LDA(At, 1, 1); STAGE(SA(1, 0), A, brow, t + 3);
;     BAR; WAIT_L(0); MMA(1, 0, At, B0); BAR; SCHED;
;     STAGE(SB(1, 1), Bt, bcol + HALF, t + 3);
;     WAIT_V(6); BAR; MMA(1, 1, At, B1); BAR;
;   }
;   {
;     LDB(B0, 0, 0); LDA(At, 0, 0); STAGE(SA(1, 1), A, brow + HALF, nt - 1);
;     BAR; WAIT_L(0); MMA(0, 0, At, B0); BAR;
;     LDB(B1, 0, 1); BAR; WAIT_L(0); MMA(0, 1, At, B1); BAR;
	s_waitcnt lgkmcnt(0)
	s_setprio 1
	v_mfma_f32_16x16x32_bf16 v[60:63], v[186:189], v[162:165], v[60:63]
	v_mfma_f32_16x16x32_bf16 v[56:59], v[186:189], v[178:181], v[56:59]
	v_mfma_f32_16x16x32_bf16 v[52:55], v[194:197], v[162:165], v[52:55]
	v_mfma_f32_16x16x32_bf16 v[48:51], v[194:197], v[178:181], v[48:51]
	v_mfma_f32_16x16x32_bf16 v[44:47], v[202:205], v[162:165], v[44:47]
	v_mfma_f32_16x16x32_bf16 v[40:43], v[202:205], v[178:181], v[40:43]
	v_mfma_f32_16x16x32_bf16 v[36:39], v[210:213], v[162:165], v[36:39]
	v_mfma_f32_16x16x32_bf16 v[32:35], v[210:213], v[178:181], v[32:35]
	v_mfma_f32_16x16x32_bf16 v[60:63], v[190:193], v[174:177], v[60:63]
	v_mfma_f32_16x16x32_bf16 v[56:59], v[190:193], v[182:185], v[56:59]
	v_mfma_f32_16x16x32_bf16 v[52:55], v[198:201], v[174:177], v[52:55]
	v_mfma_f32_16x16x32_bf16 v[48:51], v[198:201], v[182:185], v[48:51]
	v_mfma_f32_16x16x32_bf16 v[44:47], v[206:209], v[174:177], v[44:47]
	v_mfma_f32_16x16x32_bf16 v[40:43], v[206:209], v[182:185], v[40:43]
	v_mfma_f32_16x16x32_bf16 v[36:39], v[214:217], v[174:177], v[36:39]
	v_mfma_f32_16x16x32_bf16 v[32:35], v[214:217], v[182:185], v[32:35]
	s_setprio 0
	s_barrier
	s_add_u32 m0, s32, 0x1c000
	s_add_u32 s98, s20, 0x40180
	s_addc_u32 s99, s21, 0
	global_load_lds_dwordx4 v253, s[98:99]
	s_add_u32 m0, s32, 0x1e000
	s_nop 0
	global_load_lds_dwordx4 v252, s[98:99]
	s_waitcnt vmcnt(6)
	s_barrier
	s_setprio 1
	v_mfma_f32_16x16x32_bf16 v[28:31], v[186:189], v[218:221], v[28:31]
	v_mfma_f32_16x16x32_bf16 v[24:27], v[186:189], v[226:229], v[24:27]
	v_mfma_f32_16x16x32_bf16 v[20:23], v[194:197], v[218:221], v[20:23]
	v_mfma_f32_16x16x32_bf16 v[16:19], v[194:197], v[226:229], v[16:19]
	v_mfma_f32_16x16x32_bf16 v[12:15], v[202:205], v[218:221], v[12:15]
	v_mfma_f32_16x16x32_bf16 v[8:11], v[202:205], v[226:229], v[8:11]
	v_mfma_f32_16x16x32_bf16 v[4:7], v[210:213], v[218:221], v[4:7]
	v_mfma_f32_16x16x32_bf16 v[0:3], v[210:213], v[226:229], v[0:3]
	v_mfma_f32_16x16x32_bf16 v[28:31], v[190:193], v[222:225], v[28:31]
	v_mfma_f32_16x16x32_bf16 v[24:27], v[190:193], v[230:233], v[24:27]
	v_mfma_f32_16x16x32_bf16 v[20:23], v[198:201], v[222:225], v[20:23]
	v_mfma_f32_16x16x32_bf16 v[16:19], v[198:201], v[230:233], v[16:19]
	v_mfma_f32_16x16x32_bf16 v[12:15], v[206:209], v[222:225], v[12:15]
	v_mfma_f32_16x16x32_bf16 v[8:11], v[206:209], v[230:233], v[8:11]
	v_mfma_f32_16x16x32_bf16 v[4:7], v[214:217], v[222:225], v[4:7]
	v_mfma_f32_16x16x32_bf16 v[0:3], v[214:217], v[230:233], v[0:3]
	s_setprio 0
	s_add_i32 s68, s68, 2
	s_add_u32 s16, s16, 0x100
	s_addc_u32 s17, s17, 0
	s_cmp_lt_u32 s68, 12
	s_barrier
	s_cbranch_scc1 .LBB0_1754
	ds_read_b128 v[142:145], v155
	ds_read_b128 v[162:165], v155 offset:1024
	ds_read_b128 v[174:177], v155 offset:2048
	ds_read_b128 v[178:181], v155 offset:3072
	ds_read_b128 v[182:185], v135
	ds_read_b128 v[186:189], v135 offset:1024
	ds_read_b128 v[190:193], v156
	ds_read_b128 v[194:197], v156 offset:1024
	ds_read_b128 v[198:201], v157
	ds_read_b128 v[202:205], v157 offset:1024
	ds_read_b128 v[206:209], v158
	ds_read_b128 v[210:213], v158 offset:1024
	v_mov_b32_e32 v129, v149
	v_lshl_add_u64 v[128:129], v[128:129], 1, s[14:15]
	s_mov_b64 s[12:13], 0x780
	v_readfirstlane_b32 s10, v160
	v_lshl_add_u64 v[128:129], v[128:129], 0, s[12:13]
	s_mov_b32 m0, s10
	v_mov_b32_e32 v131, v149
	global_load_lds_dwordx4 v[128:129], off
	v_readfirstlane_b32 s10, v159
	v_lshl_add_u64 v[128:129], v[130:131], 1, s[14:15]
	v_lshl_add_u64 v[128:129], v[128:129], 0, s[12:13]
	s_mov_b32 m0, s10
	s_nop 0
	global_load_lds_dwordx4 v[128:129], off
	s_barrier
	s_waitcnt lgkmcnt(0)
	s_setprio 1
	v_mfma_f32_16x16x32_bf16 v[124:127], v[182:185], v[142:145], v[124:127]
	v_mfma_f32_16x16x32_bf16 v[120:123], v[182:185], v[174:177], v[120:123]
	v_mfma_f32_16x16x32_bf16 v[116:119], v[190:193], v[142:145], v[116:119]
	v_mfma_f32_16x16x32_bf16 v[112:115], v[190:193], v[174:177], v[112:115]
	v_mfma_f32_16x16x32_bf16 v[108:111], v[198:201], v[142:145], v[108:111]
	v_mfma_f32_16x16x32_bf16 v[104:107], v[198:201], v[174:177], v[104:107]
	v_mfma_f32_16x16x32_bf16 v[96:99], v[206:209], v[174:177], v[96:99]
	v_mfma_f32_16x16x32_bf16 v[124:127], v[186:189], v[162:165], v[124:127]
	v_mfma_f32_16x16x32_bf16 v[120:123], v[186:189], v[178:181], v[120:123]
	v_mfma_f32_16x16x32_bf16 v[116:119], v[194:197], v[162:165], v[116:119]
	v_mfma_f32_16x16x32_bf16 v[112:115], v[194:197], v[178:181], v[112:115]
	v_mfma_f32_16x16x32_bf16 v[108:111], v[202:205], v[162:165], v[108:111]
	v_mfma_f32_16x16x32_bf16 v[104:107], v[202:205], v[178:181], v[104:107]
	v_mfma_f32_16x16x32_bf16 v[100:103], v[206:209], v[142:145], v[100:103]
	v_mfma_f32_16x16x32_bf16 v[96:99], v[210:213], v[178:181], v[96:99]
	v_mfma_f32_16x16x32_bf16 v[128:131], v[210:213], v[162:165], v[100:103]
	s_setprio 0
	s_barrier
	s_nop 3
	ds_read_b128 v[100:103], v152
	ds_read_b128 v[214:217], v152 offset:1024
	ds_read_b128 v[218:221], v152 offset:2048
	ds_read_b128 v[152:155], v152 offset:3072
	s_barrier
	s_waitcnt lgkmcnt(0)
	s_setprio 1
	v_mfma_f32_16x16x32_bf16 v[88:91], v[182:185], v[218:221], v[88:91]
	v_mfma_f32_16x16x32_bf16 v[92:95], v[182:185], v[100:103], v[92:95]
	v_mfma_f32_16x16x32_bf16 v[88:91], v[186:189], v[152:155], v[88:91]
	v_mfma_f32_16x16x32_bf16 v[84:87], v[190:193], v[100:103], v[84:87]
	v_mfma_f32_16x16x32_bf16 v[80:83], v[190:193], v[218:221], v[80:83]
	v_mfma_f32_16x16x32_bf16 v[76:79], v[198:201], v[100:103], v[76:79]
	v_mfma_f32_16x16x32_bf16 v[72:75], v[198:201], v[218:221], v[72:75]
	v_mfma_f32_16x16x32_bf16 v[68:71], v[206:209], v[100:103], v[68:71]
	v_mfma_f32_16x16x32_bf16 v[64:67], v[206:209], v[218:221], v[64:67]
	v_mfma_f32_16x16x32_bf16 v[222:225], v[186:189], v[214:217], v[92:95]
	v_mfma_f32_16x16x32_bf16 v[182:185], v[194:197], v[214:217], v[84:87]
	v_mfma_f32_16x16x32_bf16 v[186:189], v[194:197], v[152:155], v[80:83]
	v_mfma_f32_16x16x32_bf16 v[190:193], v[202:205], v[214:217], v[76:79]
	v_mfma_f32_16x16x32_bf16 v[194:197], v[202:205], v[152:155], v[72:75]
	v_mfma_f32_16x16x32_bf16 v[198:201], v[210:213], v[214:217], v[68:71]
	v_mfma_f32_16x16x32_bf16 v[202:205], v[210:213], v[152:155], v[64:67]
	s_setprio 0
	s_barrier
; #define LDA(dst, b, h)                                                                                    \
;   _Pragma("unroll") for (int m = 0; m < 4; ++m) _Pragma("unroll") for (int k = 0; k < 2; ++k)             \
;       dst[m][k] = *reinterpret_cast<const bf16x8*>((char*)SA(b, h) + lds_byte(wr * 64 + m * 16 + fr, k * 32 + fq * 8))
; #define LDB(dst, b, h)                                                                                    \
;   _Pragma("unroll") for (int n = 0; n < 2; ++n) _Pragma("unroll") for (int k = 0; k < 2; ++k)             \
;       dst[n][k] = *reinterpret_cast<const bf16x8*>((char*)SB(b, h) + lds_byte(wc * 32 + n * 16 + fr, k * 32 + fq * 8))
; #define WAIT_V(n) asm volatile("s_waitcnt vmcnt(" #n ")" ::: "memory")
; #define WAIT_L(n) asm volatile("s_waitcnt lgkmcnt(" #n ")" ::: "memory")
; #define BAR __builtin_amdgcn_s_barrier()
; template <int EPI> ...
;     ...
;     LDA(At, 0, 1); WAIT_V(4); BAR; WAIT_L(0); MMA(1, 0, At, B0); MMA(1, 1, At, B1); BAR;
;   }
;   {
;     LDB(B0, 1, 0); LDA(At, 1, 0); WAIT_V(2); BAR; WAIT_L(0); MMA(0, 0, At, B0); BAR;
	s_nop 0
	ds_read_b128 v[64:67], v135 offset:16384
	ds_read_b128 v[68:71], v135 offset:17408
	ds_read_b128 v[72:75], v156 offset:16384
	ds_read_b128 v[76:79], v156 offset:17408
	ds_read_b128 v[80:83], v157 offset:16384
	ds_read_b128 v[84:87], v157 offset:17408
	ds_read_b128 v[92:95], v158 offset:16384
	ds_read_b128 v[206:209], v158 offset:17408
	s_waitcnt vmcnt(4)
	s_barrier
	s_waitcnt lgkmcnt(0)
	s_setprio 1
	v_mfma_f32_16x16x32_bf16 v[60:63], v[64:67], v[142:145], v[60:63]
	v_mfma_f32_16x16x32_bf16 v[56:59], v[64:67], v[174:177], v[56:59]
	v_mfma_f32_16x16x32_bf16 v[52:55], v[72:75], v[142:145], v[52:55]
	v_mfma_f32_16x16x32_bf16 v[48:51], v[72:75], v[174:177], v[48:51]
	v_mfma_f32_16x16x32_bf16 v[44:47], v[80:83], v[142:145], v[44:47]
	v_mfma_f32_16x16x32_bf16 v[40:43], v[80:83], v[174:177], v[40:43]
	v_mfma_f32_16x16x32_bf16 v[36:39], v[92:95], v[142:145], v[36:39]
	v_mfma_f32_16x16x32_bf16 v[32:35], v[92:95], v[174:177], v[32:35]
	v_mfma_f32_16x16x32_bf16 v[60:63], v[68:71], v[162:165], v[60:63]
	v_mfma_f32_16x16x32_bf16 v[56:59], v[68:71], v[178:181], v[56:59]
	v_mfma_f32_16x16x32_bf16 v[52:55], v[76:79], v[162:165], v[52:55]
	v_mfma_f32_16x16x32_bf16 v[48:51], v[76:79], v[178:181], v[48:51]
	v_mfma_f32_16x16x32_bf16 v[44:47], v[84:87], v[162:165], v[44:47]
	v_mfma_f32_16x16x32_bf16 v[40:43], v[84:87], v[178:181], v[40:43]
	v_mfma_f32_16x16x32_bf16 v[36:39], v[206:209], v[162:165], v[36:39]
	v_mfma_f32_16x16x32_bf16 v[32:35], v[206:209], v[178:181], v[32:35]
	s_setprio 0
	s_setprio 1
	v_mfma_f32_16x16x32_bf16 v[28:31], v[64:67], v[100:103], v[28:31]
	v_mfma_f32_16x16x32_bf16 v[24:27], v[64:67], v[218:221], v[24:27]
	v_mfma_f32_16x16x32_bf16 v[20:23], v[72:75], v[100:103], v[20:23]
	v_mfma_f32_16x16x32_bf16 v[16:19], v[72:75], v[218:221], v[16:19]
	v_mfma_f32_16x16x32_bf16 v[12:15], v[80:83], v[100:103], v[12:15]
	v_mfma_f32_16x16x32_bf16 v[8:11], v[80:83], v[218:221], v[8:11]
	v_mfma_f32_16x16x32_bf16 v[4:7], v[92:95], v[100:103], v[4:7]
	v_mfma_f32_16x16x32_bf16 v[0:3], v[92:95], v[218:221], v[0:3]
	v_mfma_f32_16x16x32_bf16 v[142:145], v[68:71], v[214:217], v[28:31]
	v_mfma_f32_16x16x32_bf16 v[160:163], v[68:71], v[152:155], v[24:27]
	v_mfma_f32_16x16x32_bf16 v[164:167], v[76:79], v[214:217], v[20:23]
	v_mfma_f32_16x16x32_bf16 v[174:177], v[76:79], v[152:155], v[16:19]
	v_mfma_f32_16x16x32_bf16 v[178:181], v[84:87], v[214:217], v[12:15]
	v_mfma_f32_16x16x32_bf16 v[210:213], v[84:87], v[152:155], v[8:11]
	v_mfma_f32_16x16x32_bf16 v[214:217], v[206:209], v[214:217], v[4:7]
	v_mfma_f32_16x16x32_bf16 v[152:155], v[206:209], v[152:155], v[0:3]
	s_setprio 0
	s_barrier
	s_nop 0
	ds_read_b128 v[0:3], v140
	ds_read_b128 v[4:7], v140 offset:1024
	ds_read_b128 v[206:209], v140 offset:2048
	ds_read_b128 v[138:141], v140 offset:3072
	ds_read_b128 v[8:11], v135 offset:32768
	ds_read_b128 v[12:15], v135 offset:33792
	ds_read_b128 v[16:19], v156 offset:32768
	ds_read_b128 v[20:23], v156 offset:33792
	ds_read_b128 v[24:27], v157 offset:32768
	ds_read_b128 v[28:31], v157 offset:33792
	ds_read_b128 v[218:221], v158 offset:32768
	ds_read_b128 v[226:229], v158 offset:33792
	s_waitcnt vmcnt(2)
	s_barrier
	s_waitcnt lgkmcnt(0)
	s_setprio 1
	v_mfma_f32_16x16x32_bf16 v[64:67], v[8:11], v[0:3], v[124:127]
	v_mfma_f32_16x16x32_bf16 v[92:95], v[12:15], v[4:7], v[64:67]
	v_mfma_f32_16x16x32_bf16 v[64:67], v[8:11], v[206:209], v[120:123]
	v_mfma_f32_16x16x32_bf16 v[100:103], v[12:15], v[138:141], v[64:67]
	v_mfma_f32_16x16x32_bf16 v[64:67], v[16:19], v[0:3], v[116:119]
	v_mfma_f32_16x16x32_bf16 v[80:83], v[20:23], v[4:7], v[64:67]
	v_mfma_f32_16x16x32_bf16 v[64:67], v[16:19], v[206:209], v[112:115]
	v_mfma_f32_16x16x32_bf16 v[84:87], v[20:23], v[138:141], v[64:67]
	v_mfma_f32_16x16x32_bf16 v[64:67], v[24:27], v[0:3], v[108:111]
	v_mfma_f32_16x16x32_bf16 v[72:75], v[28:31], v[4:7], v[64:67]
	v_mfma_f32_16x16x32_bf16 v[64:67], v[24:27], v[206:209], v[104:107]
	v_mfma_f32_16x16x32_bf16 v[76:79], v[28:31], v[138:141], v[64:67]
	v_mfma_f32_16x16x32_bf16 v[64:67], v[218:221], v[0:3], v[128:131]
	v_mfma_f32_16x16x32_bf16 v[68:71], v[218:221], v[206:209], v[96:99]
	v_mfma_f32_16x16x32_bf16 v[64:67], v[226:229], v[4:7], v[64:67]
	v_mfma_f32_16x16x32_bf16 v[68:71], v[226:229], v[138:141], v[68:71]
	s_setprio 0
	s_barrier
; #define LDA(dst, b, h)                                                                                    \
;   _Pragma("unroll") for (int m = 0; m < 4; ++m) _Pragma("unroll") for (int k = 0; k < 2; ++k)             \
;       dst[m][k] = *reinterpret_cast<const bf16x8*>((char*)SA(b, h) + lds_byte(wr * 64 + m * 16 + fr, k * 32 + fq * 8))
; #define LDB(dst, b, h)                                                                                    \
;   _Pragma("unroll") for (int n = 0; n < 2; ++n) _Pragma("unroll") for (int k = 0; k < 2; ++k)             \
;       dst[n][k] = *reinterpret_cast<const bf16x8*>((char*)SB(b, h) + lds_byte(wc * 32 + n * 16 + fr, k * 32 + fq * 8))
; #define WAIT_V(n) asm volatile("s_waitcnt vmcnt(" #n ")" ::: "memory")
; #define WAIT_L(n) asm volatile("s_waitcnt lgkmcnt(" #n ")" ::: "memory")
; #define BAR __builtin_amdgcn_s_barrier()
; template <int EPI> ...
;     ...
;     LDB(B1, 1, 1); WAIT_V(0); BAR; WAIT_L(0); MMA(0, 1, At, B1); BAR;
;     LDA(At, 1, 1); BAR; WAIT_L(0); MMA(1, 0, At, B0); MMA(1, 1, At, B1); BAR;
;   }
;   if (wr == 0) BAR;
; template <int EPI>
; DEVI void gemm_phase(int wv, const Params& p, char* smem, const u16* A, int lda, const u16* Bt, int K, int ntn, float scale,
;                      const float* ssin = nullptr, float* ssout = nullptr, u16* xbout = nullptr) {
;     ...
;   while (t < total) {
;     const int tn = t + nb;
;     int mtn = 0, ntn2 = 0;
;     if (tn < total) {
;       const int band = tn / (8 * ntn), rem = tn - band * 8 * ntn;
;       ntn2 = rem >> 3; mtn = band * 8 + (rem & 7);
;     }
;     gemm_tile<EPI>(wv, p, smem, A, lda, Bt, K, mt * 256, nt * 256, scale, ssin, ssout, xbout, true, false, 0, 0);
;     first = false;
;     t = tn; mt = mtn; nt = ntn2;
;   }
	ds_read_b128 v[128:131], v137
	ds_read_b128 v[230:233], v137 offset:1024
	ds_read_b128 v[234:237], v137 offset:2048
	ds_read_b128 v[238:241], v137 offset:3072
	s_waitcnt vmcnt(0)
	s_barrier
	s_waitcnt lgkmcnt(0)
	s_setprio 1
	v_mfma_f32_16x16x32_bf16 v[96:99], v[8:11], v[128:131], v[222:225]
	v_mfma_f32_16x16x32_bf16 v[8:11], v[8:11], v[234:237], v[88:91]
	v_mfma_f32_16x16x32_bf16 v[124:127], v[12:15], v[238:241], v[8:11]
	v_mfma_f32_16x16x32_bf16 v[8:11], v[16:19], v[128:131], v[182:185]
	v_mfma_f32_16x16x32_bf16 v[112:115], v[20:23], v[230:233], v[8:11]
	v_mfma_f32_16x16x32_bf16 v[8:11], v[16:19], v[234:237], v[186:189]
	v_mfma_f32_16x16x32_bf16 v[116:119], v[20:23], v[238:241], v[8:11]
	v_mfma_f32_16x16x32_bf16 v[8:11], v[24:27], v[128:131], v[190:193]
	v_mfma_f32_16x16x32_bf16 v[104:107], v[28:31], v[230:233], v[8:11]
	v_mfma_f32_16x16x32_bf16 v[8:11], v[24:27], v[234:237], v[194:197]
	v_mfma_f32_16x16x32_bf16 v[108:111], v[28:31], v[238:241], v[8:11]
	v_mfma_f32_16x16x32_bf16 v[8:11], v[218:221], v[128:131], v[198:201]
	v_mfma_f32_16x16x32_bf16 v[88:91], v[226:229], v[230:233], v[8:11]
	v_mfma_f32_16x16x32_bf16 v[8:11], v[218:221], v[234:237], v[202:205]
	v_mfma_f32_16x16x32_bf16 v[120:123], v[12:15], v[230:233], v[96:99]
	v_mfma_f32_16x16x32_bf16 v[96:99], v[226:229], v[238:241], v[8:11]
	s_setprio 0
	s_barrier
	ds_read_b128 v[182:185], v135 offset:49152
	ds_read_b128 v[186:189], v135 offset:50176
	ds_read_b128 v[190:193], v156 offset:49152
	ds_read_b128 v[194:197], v156 offset:50176
	ds_read_b128 v[198:201], v157 offset:49152
	ds_read_b128 v[202:205], v157 offset:50176
	ds_read_b128 v[218:221], v158 offset:49152
	ds_read_b128 v[156:159], v158 offset:50176
	s_barrier
	s_waitcnt lgkmcnt(0)
	s_setprio 1
	v_mfma_f32_16x16x32_bf16 v[8:11], v[182:185], v[0:3], v[60:63]
	v_mfma_f32_16x16x32_bf16 v[24:27], v[186:189], v[4:7], v[8:11]
	v_mfma_f32_16x16x32_bf16 v[8:11], v[182:185], v[206:209], v[56:59]
	v_mfma_f32_16x16x32_bf16 v[28:31], v[186:189], v[138:141], v[8:11]
	v_mfma_f32_16x16x32_bf16 v[8:11], v[190:193], v[0:3], v[52:55]
	v_mfma_f32_16x16x32_bf16 v[16:19], v[194:197], v[4:7], v[8:11]
	v_mfma_f32_16x16x32_bf16 v[8:11], v[190:193], v[206:209], v[48:51]
	v_mfma_f32_16x16x32_bf16 v[20:23], v[194:197], v[138:141], v[8:11]
	v_mfma_f32_16x16x32_bf16 v[8:11], v[198:201], v[0:3], v[44:47]
	v_mfma_f32_16x16x32_bf16 v[0:3], v[218:221], v[0:3], v[36:39]
	v_mfma_f32_16x16x32_bf16 v[8:11], v[202:205], v[4:7], v[8:11]
	v_mfma_f32_16x16x32_bf16 v[12:15], v[198:201], v[206:209], v[40:43]
	v_mfma_f32_16x16x32_bf16 v[0:3], v[156:159], v[4:7], v[0:3]
	v_mfma_f32_16x16x32_bf16 v[4:7], v[218:221], v[206:209], v[32:35]
	v_mfma_f32_16x16x32_bf16 v[12:15], v[202:205], v[138:141], v[12:15]
	v_mfma_f32_16x16x32_bf16 v[4:7], v[156:159], v[138:141], v[4:7]
	s_setprio 0
	s_setprio 1
	v_mfma_f32_16x16x32_bf16 v[32:35], v[182:185], v[128:131], v[142:145]
	v_mfma_f32_16x16x32_bf16 v[56:59], v[186:189], v[230:233], v[32:35]
	v_mfma_f32_16x16x32_bf16 v[32:35], v[182:185], v[234:237], v[160:163]
	v_mfma_f32_16x16x32_bf16 v[60:63], v[186:189], v[238:241], v[32:35]
	v_mfma_f32_16x16x32_bf16 v[32:35], v[190:193], v[128:131], v[164:167]
	v_mfma_f32_16x16x32_bf16 v[48:51], v[194:197], v[230:233], v[32:35]
	v_mfma_f32_16x16x32_bf16 v[32:35], v[190:193], v[234:237], v[174:177]
	v_mfma_f32_16x16x32_bf16 v[52:55], v[194:197], v[238:241], v[32:35]
	v_mfma_f32_16x16x32_bf16 v[32:35], v[198:201], v[128:131], v[178:181]
	v_mfma_f32_16x16x32_bf16 v[40:43], v[202:205], v[230:233], v[32:35]
	v_mfma_f32_16x16x32_bf16 v[32:35], v[198:201], v[234:237], v[210:213]
	v_mfma_f32_16x16x32_bf16 v[44:47], v[202:205], v[238:241], v[32:35]
	v_mfma_f32_16x16x32_bf16 v[32:35], v[218:221], v[128:131], v[214:217]
	v_mfma_f32_16x16x32_bf16 v[36:39], v[218:221], v[234:237], v[152:155]
	v_mfma_f32_16x16x32_bf16 v[32:35], v[156:159], v[230:233], v[32:35]
	v_mfma_f32_16x16x32_bf16 v[36:39], v[156:159], v[238:241], v[36:39]
	s_setprio 0
	s_cmpk_gt_u32 s62, 0xff
	s_barrier
	s_cbranch_scc1 .LBB0_1748
	s_barrier
	s_branch .LBB0_1748

; #define LDA(dst, b, h)                                                                                    \
;   _Pragma("unroll") for (int m = 0; m < 4; ++m) _Pragma("unroll") for (int k = 0; k < 2; ++k)             \
;       dst[m][k] = *reinterpret_cast<const bf16x8*>((char*)SA(b, h) + lds_byte(wr * 64 + m * 16 + fr, k * 32 + fq * 8))
; #define LDB(dst, b, h)                                                                                    \
;   _Pragma("unroll") for (int n = 0; n < 2; ++n) _Pragma("unroll") for (int k = 0; k < 2; ++k)             \
;       dst[n][k] = *reinterpret_cast<const bf16x8*>((char*)SB(b, h) + lds_byte(wc * 32 + n * 16 + fr, k * 32 + fq * 8))
; #define WAIT_V(n) asm volatile("s_waitcnt vmcnt(" #n ")" ::: "memory")
; #define WAIT_L(n) asm volatile("s_waitcnt lgkmcnt(" #n ")" ::: "memory")
; #define BAR __builtin_amdgcn_s_barrier()
; #define SCHED __builtin_amdgcn_sched_barrier(0)
; template <int EPI> ...
;     ...
;     LDB(B0, 0, 0); SCHED; LDA(At, 0, 0); STAGE(SA(1, 1), A, brow + HALF, t + 1);
;     WAIT_L(8); BAR; WAIT_L(0); MMA(0, 0, At, B0); BAR; SCHED;
;     LDB(B1, 0, 1); STAGE(SB(0, 0), Bt, bcol, t + 2);
;     BAR; WAIT_L(0); MMA(0, 1, At, B1); BAR;
;     LDA(At, 0, 1); STAGE(SA(0, 0), A, brow, t + 2);
;     BAR; WAIT_L(0); MMA(1, 0, At, B0); BAR; SCHED;
;     STAGE(SB(0, 1), Bt, bcol + HALF, t + 2);
;     WAIT_V(6); BAR; MMA(1, 1, At, B1); BAR;
.LBB0_1779:
	ds_read_b128 v[162:165], v155
	ds_read_b128 v[174:177], v155 offset:1024
	ds_read_b128 v[178:181], v155 offset:2048
	ds_read_b128 v[182:185], v155 offset:3072
	s_add_u32 s18, s12, s16
	v_add_u32_e32 v156, s63, v154
	v_add_u32_e32 v157, s68, v154
	v_add_u32_e32 v158, s69, v154
	s_addc_u32 s19, s13, s17
	v_add_u32_e32 v159, 0xc000, v129
	ds_read_b128 v[186:189], v135
	ds_read_b128 v[190:193], v135 offset:1024
	ds_read_b128 v[194:197], v156
	ds_read_b128 v[198:201], v156 offset:1024
	ds_read_b128 v[202:205], v157
	ds_read_b128 v[206:209], v157 offset:1024
	ds_read_b128 v[210:213], v158
	ds_read_b128 v[214:217], v158 offset:1024
	s_add_u32 m0, s32, 0xc000
	s_add_u32 s98, s18, 0xb0080
	s_addc_u32 s99, s19, 0
	global_load_lds_dwordx4 v253, s[98:99]
	s_nop 0
	v_add_u32_e32 v160, 0xe000, v129
	s_nop 0
	s_add_u32 m0, s32, 0xe000
	s_nop 0
	global_load_lds_dwordx4 v252, s[98:99]
	s_waitcnt lgkmcnt(8)
	s_barrier
	s_waitcnt lgkmcnt(0)
	s_setprio 1
	v_mfma_f32_16x16x32_bf16 v[124:127], v[186:189], v[162:165], v[124:127]
	v_mfma_f32_16x16x32_bf16 v[120:123], v[186:189], v[178:181], v[120:123]
	v_mfma_f32_16x16x32_bf16 v[116:119], v[194:197], v[162:165], v[116:119]
	v_mfma_f32_16x16x32_bf16 v[112:115], v[194:197], v[178:181], v[112:115]
	v_mfma_f32_16x16x32_bf16 v[108:111], v[202:205], v[162:165], v[108:111]
	v_mfma_f32_16x16x32_bf16 v[104:107], v[202:205], v[178:181], v[104:107]
	v_mfma_f32_16x16x32_bf16 v[100:103], v[210:213], v[162:165], v[100:103]
	v_mfma_f32_16x16x32_bf16 v[96:99], v[210:213], v[178:181], v[96:99]
	v_mfma_f32_16x16x32_bf16 v[124:127], v[190:193], v[174:177], v[124:127]
	v_mfma_f32_16x16x32_bf16 v[120:123], v[190:193], v[182:185], v[120:123]
	v_mfma_f32_16x16x32_bf16 v[116:119], v[198:201], v[174:177], v[116:119]
	v_mfma_f32_16x16x32_bf16 v[112:115], v[198:201], v[182:185], v[112:115]
	v_mfma_f32_16x16x32_bf16 v[108:111], v[206:209], v[174:177], v[108:111]
	v_mfma_f32_16x16x32_bf16 v[104:107], v[206:209], v[182:185], v[104:107]
	v_mfma_f32_16x16x32_bf16 v[100:103], v[214:217], v[174:177], v[100:103]
	v_mfma_f32_16x16x32_bf16 v[96:99], v[214:217], v[182:185], v[96:99]
	s_setprio 0
	s_barrier
	s_add_u32 s20, s10, s16
	s_addc_u32 s21, s11, s17
	ds_read_b128 v[218:221], v152
	ds_read_b128 v[222:225], v152 offset:1024
	ds_read_b128 v[226:229], v152 offset:2048
	ds_read_b128 v[230:233], v152 offset:3072
	s_add_u32 m0, s32, 0x10000
	s_add_u32 s98, s20, 0x100
	s_addc_u32 s99, s21, 0
	global_load_lds_dwordx4 v253, s[98:99]
	s_add_u32 m0, s32, 0x12000
	s_nop 0
	global_load_lds_dwordx4 v252, s[98:99]
	s_barrier
	s_waitcnt lgkmcnt(0)
	s_setprio 1
	v_mfma_f32_16x16x32_bf16 v[92:95], v[186:189], v[218:221], v[92:95]
	v_mfma_f32_16x16x32_bf16 v[88:91], v[186:189], v[226:229], v[88:91]
	v_mfma_f32_16x16x32_bf16 v[84:87], v[194:197], v[218:221], v[84:87]
	v_mfma_f32_16x16x32_bf16 v[80:83], v[194:197], v[226:229], v[80:83]
	v_mfma_f32_16x16x32_bf16 v[76:79], v[202:205], v[218:221], v[76:79]
	v_mfma_f32_16x16x32_bf16 v[72:75], v[202:205], v[226:229], v[72:75]
	v_mfma_f32_16x16x32_bf16 v[68:71], v[210:213], v[218:221], v[68:71]
	v_mfma_f32_16x16x32_bf16 v[64:67], v[210:213], v[226:229], v[64:67]
	v_mfma_f32_16x16x32_bf16 v[92:95], v[190:193], v[222:225], v[92:95]
	v_mfma_f32_16x16x32_bf16 v[88:91], v[190:193], v[230:233], v[88:91]
	v_mfma_f32_16x16x32_bf16 v[84:87], v[198:201], v[222:225], v[84:87]
	v_mfma_f32_16x16x32_bf16 v[80:83], v[198:201], v[230:233], v[80:83]
	v_mfma_f32_16x16x32_bf16 v[76:79], v[206:209], v[222:225], v[76:79]
	v_mfma_f32_16x16x32_bf16 v[72:75], v[206:209], v[230:233], v[72:75]
	v_mfma_f32_16x16x32_bf16 v[68:71], v[214:217], v[222:225], v[68:71]
	v_mfma_f32_16x16x32_bf16 v[64:67], v[214:217], v[230:233], v[64:67]
	s_setprio 0
	s_barrier
	ds_read_b128 v[186:189], v135 offset:16384
	ds_read_b128 v[190:193], v135 offset:17408
	ds_read_b128 v[194:197], v156 offset:16384
	ds_read_b128 v[198:201], v156 offset:17408
	ds_read_b128 v[202:205], v157 offset:16384
	ds_read_b128 v[206:209], v157 offset:17408
	ds_read_b128 v[210:213], v158 offset:16384
	ds_read_b128 v[214:217], v158 offset:17408
	s_mov_b32 m0, s32
	s_add_u32 s98, s18, 0x100
	s_addc_u32 s99, s19, 0
	global_load_lds_dwordx4 v253, s[98:99]
	s_add_u32 m0, s32, 0x2000
	s_nop 0
	global_load_lds_dwordx4 v252, s[98:99]
	s_barrier
	s_waitcnt lgkmcnt(0)
	s_setprio 1
	v_mfma_f32_16x16x32_bf16 v[60:63], v[186:189], v[162:165], v[60:63]
	v_mfma_f32_16x16x32_bf16 v[56:59], v[186:189], v[178:181], v[56:59]
	v_mfma_f32_16x16x32_bf16 v[52:55], v[194:197], v[162:165], v[52:55]
	v_mfma_f32_16x16x32_bf16 v[48:51], v[194:197], v[178:181], v[48:51]
	v_mfma_f32_16x16x32_bf16 v[44:47], v[202:205], v[162:165], v[44:47]
	v_mfma_f32_16x16x32_bf16 v[40:43], v[202:205], v[178:181], v[40:43]
	v_mfma_f32_16x16x32_bf16 v[36:39], v[210:213], v[162:165], v[36:39]
	v_mfma_f32_16x16x32_bf16 v[32:35], v[210:213], v[178:181], v[32:35]
	v_mfma_f32_16x16x32_bf16 v[60:63], v[190:193], v[174:177], v[60:63]
	v_mfma_f32_16x16x32_bf16 v[56:59], v[190:193], v[182:185], v[56:59]
	v_mfma_f32_16x16x32_bf16 v[52:55], v[198:201], v[174:177], v[52:55]
	v_mfma_f32_16x16x32_bf16 v[48:51], v[198:201], v[182:185], v[48:51]
	v_mfma_f32_16x16x32_bf16 v[44:47], v[206:209], v[174:177], v[44:47]
	v_mfma_f32_16x16x32_bf16 v[40:43], v[206:209], v[182:185], v[40:43]
	v_mfma_f32_16x16x32_bf16 v[36:39], v[214:217], v[174:177], v[36:39]
	v_mfma_f32_16x16x32_bf16 v[32:35], v[214:217], v[182:185], v[32:35]
	s_setprio 0
	s_barrier
	s_add_u32 m0, s32, 0x14000
	s_add_u32 s98, s20, 0xb0100
	s_addc_u32 s99, s21, 0
	global_load_lds_dwordx4 v253, s[98:99]
	s_add_u32 m0, s32, 0x16000
	s_nop 0
	global_load_lds_dwordx4 v252, s[98:99]
	s_waitcnt vmcnt(6)
	s_barrier
; #define LDA(dst, b, h)                                                                                    \
;   _Pragma("unroll") for (int m = 0; m < 4; ++m) _Pragma("unroll") for (int k = 0; k < 2; ++k)             \
;       dst[m][k] = *reinterpret_cast<const bf16x8*>((char*)SA(b, h) + lds_byte(wr * 64 + m * 16 + fr, k * 32 + fq * 8))
; #define LDB(dst, b, h)                                                                                    \
;   _Pragma("unroll") for (int n = 0; n < 2; ++n) _Pragma("unroll") for (int k = 0; k < 2; ++k)             \
;       dst[n][k] = *reinterpret_cast<const bf16x8*>((char*)SB(b, h) + lds_byte(wc * 32 + n * 16 + fr, k * 32 + fq * 8))
; #define WAIT_V(n) asm volatile("s_waitcnt vmcnt(" #n ")" ::: "memory")
; #define WAIT_L(n) asm volatile("s_waitcnt lgkmcnt(" #n ")" ::: "memory")
; #define BAR __builtin_amdgcn_s_barrier()
; #define SCHED __builtin_amdgcn_sched_barrier(0)
; template <int EPI> ...
;     ...
;     WAIT_V(6); BAR; MMA(1, 1, At, B1); BAR;
;     LDB(B0, 1, 0); SCHED; LDA(At, 1, 0); STAGE(SA(0, 1), A, brow + HALF, t + 2);
;     WAIT_L(8); BAR; WAIT_L(0); MMA(0, 0, At, B0); BAR; SCHED;
;     LDB(B1, 1, 1); STAGE(SB(1, 0), Bt, bcol, t + 3);
;     BAR; WAIT_L(0); MMA(0, 1, At, B1); BAR;
;     LDA(At, 1, 1); STAGE(SA(1, 0), A, brow, t + 3);
;     BAR; WAIT_L(0); MMA(1, 0, At, B0); BAR; SCHED;
	s_setprio 1
	v_mfma_f32_16x16x32_bf16 v[28:31], v[186:189], v[218:221], v[28:31]
	v_mfma_f32_16x16x32_bf16 v[24:27], v[186:189], v[226:229], v[24:27]
	v_mfma_f32_16x16x32_bf16 v[20:23], v[194:197], v[218:221], v[20:23]
	v_mfma_f32_16x16x32_bf16 v[16:19], v[194:197], v[226:229], v[16:19]
	v_mfma_f32_16x16x32_bf16 v[12:15], v[202:205], v[218:221], v[12:15]
	v_mfma_f32_16x16x32_bf16 v[8:11], v[202:205], v[226:229], v[8:11]
	v_mfma_f32_16x16x32_bf16 v[4:7], v[210:213], v[218:221], v[4:7]
	v_mfma_f32_16x16x32_bf16 v[0:3], v[210:213], v[226:229], v[0:3]
	v_mfma_f32_16x16x32_bf16 v[28:31], v[190:193], v[222:225], v[28:31]
	v_mfma_f32_16x16x32_bf16 v[24:27], v[190:193], v[230:233], v[24:27]
	v_mfma_f32_16x16x32_bf16 v[20:23], v[198:201], v[222:225], v[20:23]
	v_mfma_f32_16x16x32_bf16 v[16:19], v[198:201], v[230:233], v[16:19]
	v_mfma_f32_16x16x32_bf16 v[12:15], v[206:209], v[222:225], v[12:15]
	v_mfma_f32_16x16x32_bf16 v[8:11], v[206:209], v[230:233], v[8:11]
	v_mfma_f32_16x16x32_bf16 v[4:7], v[214:217], v[222:225], v[4:7]
	v_mfma_f32_16x16x32_bf16 v[0:3], v[214:217], v[230:233], v[0:3]
	s_setprio 0
	s_barrier
	ds_read_b128 v[162:165], v140
	ds_read_b128 v[174:177], v140 offset:1024
	ds_read_b128 v[178:181], v140 offset:2048
	ds_read_b128 v[182:185], v140 offset:3072
	ds_read_b128 v[186:189], v135 offset:32768
	ds_read_b128 v[190:193], v135 offset:33792
	ds_read_b128 v[194:197], v156 offset:32768
	ds_read_b128 v[198:201], v156 offset:33792
	ds_read_b128 v[202:205], v157 offset:32768
	ds_read_b128 v[206:209], v157 offset:33792
	ds_read_b128 v[210:213], v158 offset:32768
	ds_read_b128 v[214:217], v158 offset:33792
	s_add_u32 m0, s32, 0x4000
	s_add_u32 s98, s18, 0xb0100
	s_addc_u32 s99, s19, 0
	global_load_lds_dwordx4 v253, s[98:99]
	s_add_u32 m0, s32, 0x6000
	s_nop 0
	global_load_lds_dwordx4 v252, s[98:99]
	s_waitcnt lgkmcnt(8)
	s_barrier
	s_waitcnt lgkmcnt(0)
	s_setprio 1
	v_mfma_f32_16x16x32_bf16 v[124:127], v[186:189], v[162:165], v[124:127]
	v_mfma_f32_16x16x32_bf16 v[120:123], v[186:189], v[178:181], v[120:123]
	v_mfma_f32_16x16x32_bf16 v[116:119], v[194:197], v[162:165], v[116:119]
	v_mfma_f32_16x16x32_bf16 v[112:115], v[194:197], v[178:181], v[112:115]
	v_mfma_f32_16x16x32_bf16 v[108:111], v[202:205], v[162:165], v[108:111]
	v_mfma_f32_16x16x32_bf16 v[104:107], v[202:205], v[178:181], v[104:107]
	v_mfma_f32_16x16x32_bf16 v[100:103], v[210:213], v[162:165], v[100:103]
	v_mfma_f32_16x16x32_bf16 v[96:99], v[210:213], v[178:181], v[96:99]
	v_mfma_f32_16x16x32_bf16 v[124:127], v[190:193], v[174:177], v[124:127]
	v_mfma_f32_16x16x32_bf16 v[120:123], v[190:193], v[182:185], v[120:123]
	v_mfma_f32_16x16x32_bf16 v[116:119], v[198:201], v[174:177], v[116:119]
	v_mfma_f32_16x16x32_bf16 v[112:115], v[198:201], v[182:185], v[112:115]
	v_mfma_f32_16x16x32_bf16 v[108:111], v[206:209], v[174:177], v[108:111]
	v_mfma_f32_16x16x32_bf16 v[104:107], v[206:209], v[182:185], v[104:107]
	v_mfma_f32_16x16x32_bf16 v[100:103], v[214:217], v[174:177], v[100:103]
	v_mfma_f32_16x16x32_bf16 v[96:99], v[214:217], v[182:185], v[96:99]
	s_setprio 0
	s_barrier
	ds_read_b128 v[218:221], v137
	ds_read_b128 v[222:225], v137 offset:1024
	ds_read_b128 v[226:229], v137 offset:2048
	ds_read_b128 v[230:233], v137 offset:3072
	s_add_u32 m0, s32, 0x18000
	s_add_u32 s98, s20, 0x180
	s_addc_u32 s99, s21, 0
	global_load_lds_dwordx4 v253, s[98:99]
	s_add_u32 m0, s32, 0x1a000
	s_nop 0
	global_load_lds_dwordx4 v252, s[98:99]
	s_barrier
	s_waitcnt lgkmcnt(0)
	s_setprio 1
	v_mfma_f32_16x16x32_bf16 v[92:95], v[186:189], v[218:221], v[92:95]
	v_mfma_f32_16x16x32_bf16 v[88:91], v[186:189], v[226:229], v[88:91]
	v_mfma_f32_16x16x32_bf16 v[84:87], v[194:197], v[218:221], v[84:87]
	v_mfma_f32_16x16x32_bf16 v[80:83], v[194:197], v[226:229], v[80:83]
	v_mfma_f32_16x16x32_bf16 v[76:79], v[202:205], v[218:221], v[76:79]
	v_mfma_f32_16x16x32_bf16 v[72:75], v[202:205], v[226:229], v[72:75]
	v_mfma_f32_16x16x32_bf16 v[68:71], v[210:213], v[218:221], v[68:71]
	v_mfma_f32_16x16x32_bf16 v[64:67], v[210:213], v[226:229], v[64:67]
	v_mfma_f32_16x16x32_bf16 v[92:95], v[190:193], v[222:225], v[92:95]
	v_mfma_f32_16x16x32_bf16 v[88:91], v[190:193], v[230:233], v[88:91]
	v_mfma_f32_16x16x32_bf16 v[84:87], v[198:201], v[222:225], v[84:87]
	v_mfma_f32_16x16x32_bf16 v[80:83], v[198:201], v[230:233], v[80:83]
	v_mfma_f32_16x16x32_bf16 v[76:79], v[206:209], v[222:225], v[76:79]
	v_mfma_f32_16x16x32_bf16 v[72:75], v[206:209], v[230:233], v[72:75]
	v_mfma_f32_16x16x32_bf16 v[68:71], v[214:217], v[222:225], v[68:71]
	v_mfma_f32_16x16x32_bf16 v[64:67], v[214:217], v[230:233], v[64:67]
	s_setprio 0
	s_barrier
	ds_read_b128 v[186:189], v135 offset:49152
	ds_read_b128 v[190:193], v135 offset:50176
	ds_read_b128 v[194:197], v156 offset:49152
	ds_read_b128 v[198:201], v156 offset:50176
	ds_read_b128 v[202:205], v157 offset:49152
	ds_read_b128 v[206:209], v157 offset:50176
	ds_read_b128 v[210:213], v158 offset:49152
	ds_read_b128 v[214:217], v158 offset:50176
	s_add_u32 m0, s32, 0x8000
	s_add_u32 s98, s18, 0x180
	s_addc_u32 s99, s19, 0
	global_load_lds_dwordx4 v253, s[98:99]
	s_nop 0
	s_add_u32 m0, s32, 0xa000
	s_nop 0
	global_load_lds_dwordx4 v252, s[98:99]
	s_barrier
; #define LDA(dst, b, h)                                                                                    \
;   _Pragma("unroll") for (int m = 0; m < 4; ++m) _Pragma("unroll") for (int k = 0; k < 2; ++k)             \
;       dst[m][k] = *reinterpret_cast<const bf16x8*>((char*)SA(b, h) + lds_byte(wr * 64 + m * 16 + fr, k * 32 + fq * 8))
; #define LDB(dst, b, h)                                                                                    \
;   _Pragma("unroll") for (int n = 0; n < 2; ++n) _Pragma("unroll") for (int k = 0; k < 2; ++k)             \
;       dst[n][k] = *reinterpret_cast<const bf16x8*>((char*)SB(b, h) + lds_byte(wc * 32 + n * 16 + fr, k * 32 + fq * 8))
; #define WAIT_V(n) asm volatile("s_waitcnt vmcnt(" #n ")" ::: "memory")
; #define WAIT_L(n) asm volatile("s_waitcnt lgkmcnt(" #n ")" ::: "memory")
; #define BAR __builtin_amdgcn_s_barrier()
; #define SCHED __builtin_amdgcn_sched_barrier(0)
; template <int EPI> ...
;     ...
;     LDA(At, 1, 1); STAGE(SA(1, 0), A, brow, t + 3);
;     BAR; WAIT_L(0); MMA(1, 0, At, B0); BAR; SCHED;
;     STAGE(SB(1, 1), Bt, bcol + HALF, t + 3);
;     WAIT_V(6); BAR; MMA(1, 1, At, B1); BAR;
;   }
;   {
;     LDB(B0, 0, 0); LDA(At, 0, 0); STAGE(SA(1, 1), A, brow + HALF, nt - 1);
;     BAR; WAIT_L(0); MMA(0, 0, At, B0); BAR;
;     LDB(B1, 0, 1); BAR; WAIT_L(0); MMA(0, 1, At, B1); BAR;
	s_waitcnt lgkmcnt(0)
	s_setprio 1
	v_mfma_f32_16x16x32_bf16 v[60:63], v[186:189], v[162:165], v[60:63]
	v_mfma_f32_16x16x32_bf16 v[56:59], v[186:189], v[178:181], v[56:59]
	v_mfma_f32_16x16x32_bf16 v[52:55], v[194:197], v[162:165], v[52:55]
	v_mfma_f32_16x16x32_bf16 v[48:51], v[194:197], v[178:181], v[48:51]
	v_mfma_f32_16x16x32_bf16 v[44:47], v[202:205], v[162:165], v[44:47]
	v_mfma_f32_16x16x32_bf16 v[40:43], v[202:205], v[178:181], v[40:43]
	v_mfma_f32_16x16x32_bf16 v[36:39], v[210:213], v[162:165], v[36:39]
	v_mfma_f32_16x16x32_bf16 v[32:35], v[210:213], v[178:181], v[32:35]
	v_mfma_f32_16x16x32_bf16 v[60:63], v[190:193], v[174:177], v[60:63]
	v_mfma_f32_16x16x32_bf16 v[56:59], v[190:193], v[182:185], v[56:59]
	v_mfma_f32_16x16x32_bf16 v[52:55], v[198:201], v[174:177], v[52:55]
	v_mfma_f32_16x16x32_bf16 v[48:51], v[198:201], v[182:185], v[48:51]
	v_mfma_f32_16x16x32_bf16 v[44:47], v[206:209], v[174:177], v[44:47]
	v_mfma_f32_16x16x32_bf16 v[40:43], v[206:209], v[182:185], v[40:43]
	v_mfma_f32_16x16x32_bf16 v[36:39], v[214:217], v[174:177], v[36:39]
	v_mfma_f32_16x16x32_bf16 v[32:35], v[214:217], v[182:185], v[32:35]
	s_setprio 0
	s_barrier
	s_add_u32 m0, s32, 0x1c000
	s_add_u32 s98, s20, 0xb0180
	s_addc_u32 s99, s21, 0
	global_load_lds_dwordx4 v253, s[98:99]
	s_add_u32 m0, s32, 0x1e000
	s_nop 0
	global_load_lds_dwordx4 v252, s[98:99]
	s_waitcnt vmcnt(6)
	s_barrier
	s_setprio 1
	v_mfma_f32_16x16x32_bf16 v[28:31], v[186:189], v[218:221], v[28:31]
	v_mfma_f32_16x16x32_bf16 v[24:27], v[186:189], v[226:229], v[24:27]
	v_mfma_f32_16x16x32_bf16 v[20:23], v[194:197], v[218:221], v[20:23]
	v_mfma_f32_16x16x32_bf16 v[16:19], v[194:197], v[226:229], v[16:19]
	v_mfma_f32_16x16x32_bf16 v[12:15], v[202:205], v[218:221], v[12:15]
	v_mfma_f32_16x16x32_bf16 v[8:11], v[202:205], v[226:229], v[8:11]
	v_mfma_f32_16x16x32_bf16 v[4:7], v[210:213], v[218:221], v[4:7]
	v_mfma_f32_16x16x32_bf16 v[0:3], v[210:213], v[226:229], v[0:3]
	v_mfma_f32_16x16x32_bf16 v[28:31], v[190:193], v[222:225], v[28:31]
	v_mfma_f32_16x16x32_bf16 v[24:27], v[190:193], v[230:233], v[24:27]
	v_mfma_f32_16x16x32_bf16 v[20:23], v[198:201], v[222:225], v[20:23]
	v_mfma_f32_16x16x32_bf16 v[16:19], v[198:201], v[230:233], v[16:19]
	v_mfma_f32_16x16x32_bf16 v[12:15], v[206:209], v[222:225], v[12:15]
	v_mfma_f32_16x16x32_bf16 v[8:11], v[206:209], v[230:233], v[8:11]
	v_mfma_f32_16x16x32_bf16 v[4:7], v[214:217], v[222:225], v[4:7]
	v_mfma_f32_16x16x32_bf16 v[0:3], v[214:217], v[230:233], v[0:3]
	s_setprio 0
	s_add_i32 s70, s70, 2
	s_add_u32 s16, s16, 0x100
	s_addc_u32 s17, s17, 0
	s_cmp_lt_u32 s70, 40
	s_barrier
	s_cbranch_scc1 .LBB0_1779
	s_add_u32 s10, s14, 0x1580
	ds_read_b128 v[142:145], v155
	ds_read_b128 v[162:165], v155 offset:1024
	ds_read_b128 v[174:177], v155 offset:2048
	ds_read_b128 v[178:181], v155 offset:3072
	ds_read_b128 v[182:185], v135
	ds_read_b128 v[186:189], v135 offset:1024
	ds_read_b128 v[190:193], v156
	ds_read_b128 v[194:197], v156 offset:1024
	ds_read_b128 v[198:201], v157
	ds_read_b128 v[202:205], v157 offset:1024
	ds_read_b128 v[206:209], v158
	ds_read_b128 v[210:213], v158 offset:1024
	s_addc_u32 s11, s15, 0
	v_mov_b32_e32 v129, v149
	v_readfirstlane_b32 s12, v159
	v_lshl_add_u64 v[128:129], v[128:129], 1, s[10:11]
	s_mov_b32 m0, s12
	v_mov_b32_e32 v131, v149
	global_load_lds_dwordx4 v[128:129], off
	s_nop 0
	v_lshl_add_u64 v[128:129], v[130:131], 1, s[10:11]
	v_readfirstlane_b32 s10, v160
	s_mov_b32 m0, s10
	s_nop 0
	global_load_lds_dwordx4 v[128:129], off
	s_barrier
	s_waitcnt lgkmcnt(0)
	s_setprio 1
	v_mfma_f32_16x16x32_bf16 v[124:127], v[182:185], v[142:145], v[124:127]
	v_mfma_f32_16x16x32_bf16 v[120:123], v[182:185], v[174:177], v[120:123]
	v_mfma_f32_16x16x32_bf16 v[116:119], v[190:193], v[142:145], v[116:119]
	v_mfma_f32_16x16x32_bf16 v[112:115], v[190:193], v[174:177], v[112:115]
	v_mfma_f32_16x16x32_bf16 v[108:111], v[198:201], v[142:145], v[108:111]
	v_mfma_f32_16x16x32_bf16 v[104:107], v[198:201], v[174:177], v[104:107]
	v_mfma_f32_16x16x32_bf16 v[96:99], v[206:209], v[174:177], v[96:99]
	v_mfma_f32_16x16x32_bf16 v[124:127], v[186:189], v[162:165], v[124:127]
	v_mfma_f32_16x16x32_bf16 v[120:123], v[186:189], v[178:181], v[120:123]
	v_mfma_f32_16x16x32_bf16 v[116:119], v[194:197], v[162:165], v[116:119]
	v_mfma_f32_16x16x32_bf16 v[112:115], v[194:197], v[178:181], v[112:115]
	v_mfma_f32_16x16x32_bf16 v[108:111], v[202:205], v[162:165], v[108:111]
	v_mfma_f32_16x16x32_bf16 v[104:107], v[202:205], v[178:181], v[104:107]
	v_mfma_f32_16x16x32_bf16 v[100:103], v[206:209], v[142:145], v[100:103]
	v_mfma_f32_16x16x32_bf16 v[96:99], v[210:213], v[178:181], v[96:99]
	v_mfma_f32_16x16x32_bf16 v[128:131], v[210:213], v[162:165], v[100:103]
	s_setprio 0
	s_barrier
	s_nop 3
	ds_read_b128 v[100:103], v152
	ds_read_b128 v[214:217], v152 offset:1024
	ds_read_b128 v[218:221], v152 offset:2048
	ds_read_b128 v[152:155], v152 offset:3072
	s_barrier
	s_waitcnt lgkmcnt(0)
	s_setprio 1
	v_mfma_f32_16x16x32_bf16 v[88:91], v[182:185], v[218:221], v[88:91]
	v_mfma_f32_16x16x32_bf16 v[92:95], v[182:185], v[100:103], v[92:95]
	v_mfma_f32_16x16x32_bf16 v[88:91], v[186:189], v[152:155], v[88:91]
	v_mfma_f32_16x16x32_bf16 v[84:87], v[190:193], v[100:103], v[84:87]
	v_mfma_f32_16x16x32_bf16 v[80:83], v[190:193], v[218:221], v[80:83]
	v_mfma_f32_16x16x32_bf16 v[76:79], v[198:201], v[100:103], v[76:79]
	v_mfma_f32_16x16x32_bf16 v[72:75], v[198:201], v[218:221], v[72:75]
	v_mfma_f32_16x16x32_bf16 v[68:71], v[206:209], v[100:103], v[68:71]
	v_mfma_f32_16x16x32_bf16 v[64:67], v[206:209], v[218:221], v[64:67]
	v_mfma_f32_16x16x32_bf16 v[222:225], v[186:189], v[214:217], v[92:95]
	v_mfma_f32_16x16x32_bf16 v[182:185], v[194:197], v[214:217], v[84:87]
	v_mfma_f32_16x16x32_bf16 v[186:189], v[194:197], v[152:155], v[80:83]
	v_mfma_f32_16x16x32_bf16 v[190:193], v[202:205], v[214:217], v[76:79]
	v_mfma_f32_16x16x32_bf16 v[194:197], v[202:205], v[152:155], v[72:75]
	v_mfma_f32_16x16x32_bf16 v[198:201], v[210:213], v[214:217], v[68:71]
	v_mfma_f32_16x16x32_bf16 v[202:205], v[210:213], v[152:155], v[64:67]
	s_setprio 0
	s_barrier
; #define LDA(dst, b, h)                                                                                    \
;   _Pragma("unroll") for (int m = 0; m < 4; ++m) _Pragma("unroll") for (int k = 0; k < 2; ++k)             \
;       dst[m][k] = *reinterpret_cast<const bf16x8*>((char*)SA(b, h) + lds_byte(wr * 64 + m * 16 + fr, k * 32 + fq * 8))
; #define LDB(dst, b, h)                                                                                    \
;   _Pragma("unroll") for (int n = 0; n < 2; ++n) _Pragma("unroll") for (int k = 0; k < 2; ++k)             \
;       dst[n][k] = *reinterpret_cast<const bf16x8*>((char*)SB(b, h) + lds_byte(wc * 32 + n * 16 + fr, k * 32 + fq * 8))
; #define WAIT_V(n) asm volatile("s_waitcnt vmcnt(" #n ")" ::: "memory")
; #define WAIT_L(n) asm volatile("s_waitcnt lgkmcnt(" #n ")" ::: "memory")
; #define BAR __builtin_amdgcn_s_barrier()
; template <int EPI> ...
;     ...
;     LDA(At, 0, 1); WAIT_V(4); BAR; WAIT_L(0); MMA(1, 0, At, B0); MMA(1, 1, At, B1); BAR;
;   }
;   {
;     LDB(B0, 1, 0); LDA(At, 1, 0); WAIT_V(2); BAR; WAIT_L(0); MMA(0, 0, At, B0); BAR;
	s_nop 0
	ds_read_b128 v[64:67], v135 offset:16384
	ds_read_b128 v[68:71], v135 offset:17408
	ds_read_b128 v[72:75], v156 offset:16384
	ds_read_b128 v[76:79], v156 offset:17408
	ds_read_b128 v[80:83], v157 offset:16384
	ds_read_b128 v[84:87], v157 offset:17408
	ds_read_b128 v[92:95], v158 offset:16384
	ds_read_b128 v[206:209], v158 offset:17408
	s_waitcnt vmcnt(4)
	s_barrier
	s_waitcnt lgkmcnt(0)
	s_setprio 1
	v_mfma_f32_16x16x32_bf16 v[60:63], v[64:67], v[142:145], v[60:63]
	v_mfma_f32_16x16x32_bf16 v[56:59], v[64:67], v[174:177], v[56:59]
	v_mfma_f32_16x16x32_bf16 v[52:55], v[72:75], v[142:145], v[52:55]
	v_mfma_f32_16x16x32_bf16 v[48:51], v[72:75], v[174:177], v[48:51]
	v_mfma_f32_16x16x32_bf16 v[44:47], v[80:83], v[142:145], v[44:47]
	v_mfma_f32_16x16x32_bf16 v[40:43], v[80:83], v[174:177], v[40:43]
	v_mfma_f32_16x16x32_bf16 v[36:39], v[92:95], v[142:145], v[36:39]
	v_mfma_f32_16x16x32_bf16 v[32:35], v[92:95], v[174:177], v[32:35]
	v_mfma_f32_16x16x32_bf16 v[60:63], v[68:71], v[162:165], v[60:63]
	v_mfma_f32_16x16x32_bf16 v[56:59], v[68:71], v[178:181], v[56:59]
	v_mfma_f32_16x16x32_bf16 v[52:55], v[76:79], v[162:165], v[52:55]
	v_mfma_f32_16x16x32_bf16 v[48:51], v[76:79], v[178:181], v[48:51]
	v_mfma_f32_16x16x32_bf16 v[44:47], v[84:87], v[162:165], v[44:47]
	v_mfma_f32_16x16x32_bf16 v[40:43], v[84:87], v[178:181], v[40:43]
	v_mfma_f32_16x16x32_bf16 v[36:39], v[206:209], v[162:165], v[36:39]
	v_mfma_f32_16x16x32_bf16 v[32:35], v[206:209], v[178:181], v[32:35]
	s_setprio 0
	s_setprio 1
	v_mfma_f32_16x16x32_bf16 v[28:31], v[64:67], v[100:103], v[28:31]
	v_mfma_f32_16x16x32_bf16 v[24:27], v[64:67], v[218:221], v[24:27]
	v_mfma_f32_16x16x32_bf16 v[20:23], v[72:75], v[100:103], v[20:23]
	v_mfma_f32_16x16x32_bf16 v[16:19], v[72:75], v[218:221], v[16:19]
	v_mfma_f32_16x16x32_bf16 v[12:15], v[80:83], v[100:103], v[12:15]
	v_mfma_f32_16x16x32_bf16 v[8:11], v[80:83], v[218:221], v[8:11]
	v_mfma_f32_16x16x32_bf16 v[4:7], v[92:95], v[100:103], v[4:7]
	v_mfma_f32_16x16x32_bf16 v[0:3], v[92:95], v[218:221], v[0:3]
	v_mfma_f32_16x16x32_bf16 v[142:145], v[68:71], v[214:217], v[28:31]
	v_mfma_f32_16x16x32_bf16 v[160:163], v[68:71], v[152:155], v[24:27]
	v_mfma_f32_16x16x32_bf16 v[164:167], v[76:79], v[214:217], v[20:23]
	v_mfma_f32_16x16x32_bf16 v[174:177], v[76:79], v[152:155], v[16:19]
	v_mfma_f32_16x16x32_bf16 v[178:181], v[84:87], v[214:217], v[12:15]
	v_mfma_f32_16x16x32_bf16 v[210:213], v[84:87], v[152:155], v[8:11]
	v_mfma_f32_16x16x32_bf16 v[214:217], v[206:209], v[214:217], v[4:7]
	v_mfma_f32_16x16x32_bf16 v[152:155], v[206:209], v[152:155], v[0:3]
	s_setprio 0
	s_barrier
	s_nop 0
	ds_read_b128 v[0:3], v140
	ds_read_b128 v[4:7], v140 offset:1024
	ds_read_b128 v[206:209], v140 offset:2048
	ds_read_b128 v[138:141], v140 offset:3072
	ds_read_b128 v[8:11], v135 offset:32768
	ds_read_b128 v[12:15], v135 offset:33792
	ds_read_b128 v[16:19], v156 offset:32768
	ds_read_b128 v[20:23], v156 offset:33792
	ds_read_b128 v[24:27], v157 offset:32768
	ds_read_b128 v[28:31], v157 offset:33792
	ds_read_b128 v[218:221], v158 offset:32768
	ds_read_b128 v[226:229], v158 offset:33792
	s_waitcnt vmcnt(2)
	s_barrier
	s_waitcnt lgkmcnt(0)
	s_setprio 1
	v_mfma_f32_16x16x32_bf16 v[64:67], v[8:11], v[0:3], v[124:127]
	v_mfma_f32_16x16x32_bf16 v[92:95], v[12:15], v[4:7], v[64:67]
	v_mfma_f32_16x16x32_bf16 v[64:67], v[8:11], v[206:209], v[120:123]
	v_mfma_f32_16x16x32_bf16 v[100:103], v[12:15], v[138:141], v[64:67]
	v_mfma_f32_16x16x32_bf16 v[64:67], v[16:19], v[0:3], v[116:119]
	v_mfma_f32_16x16x32_bf16 v[80:83], v[20:23], v[4:7], v[64:67]
	v_mfma_f32_16x16x32_bf16 v[64:67], v[16:19], v[206:209], v[112:115]
	v_mfma_f32_16x16x32_bf16 v[84:87], v[20:23], v[138:141], v[64:67]
	v_mfma_f32_16x16x32_bf16 v[64:67], v[24:27], v[0:3], v[108:111]
	v_mfma_f32_16x16x32_bf16 v[72:75], v[28:31], v[4:7], v[64:67]
	v_mfma_f32_16x16x32_bf16 v[64:67], v[24:27], v[206:209], v[104:107]
	v_mfma_f32_16x16x32_bf16 v[76:79], v[28:31], v[138:141], v[64:67]
	v_mfma_f32_16x16x32_bf16 v[64:67], v[218:221], v[0:3], v[128:131]
	v_mfma_f32_16x16x32_bf16 v[68:71], v[218:221], v[206:209], v[96:99]
	v_mfma_f32_16x16x32_bf16 v[64:67], v[226:229], v[4:7], v[64:67]
	v_mfma_f32_16x16x32_bf16 v[68:71], v[226:229], v[138:141], v[68:71]
	s_setprio 0
	s_barrier
; #define LDA(dst, b, h)                                                                                    \
;   _Pragma("unroll") for (int m = 0; m < 4; ++m) _Pragma("unroll") for (int k = 0; k < 2; ++k)             \
;       dst[m][k] = *reinterpret_cast<const bf16x8*>((char*)SA(b, h) + lds_byte(wr * 64 + m * 16 + fr, k * 32 + fq * 8))
; #define LDB(dst, b, h)                                                                                    \
;   _Pragma("unroll") for (int n = 0; n < 2; ++n) _Pragma("unroll") for (int k = 0; k < 2; ++k)             \
;       dst[n][k] = *reinterpret_cast<const bf16x8*>((char*)SB(b, h) + lds_byte(wc * 32 + n * 16 + fr, k * 32 + fq * 8))
; #define WAIT_V(n) asm volatile("s_waitcnt vmcnt(" #n ")" ::: "memory")
; #define WAIT_L(n) asm volatile("s_waitcnt lgkmcnt(" #n ")" ::: "memory")
; #define BAR __builtin_amdgcn_s_barrier()
; template <int EPI> ...
;     ...
;     LDB(B1, 1, 1); WAIT_V(0); BAR; WAIT_L(0); MMA(0, 1, At, B1); BAR;
;     LDA(At, 1, 1); BAR; WAIT_L(0); MMA(1, 0, At, B0); MMA(1, 1, At, B1); BAR;
;   }
;   if (wr == 0) BAR;
	ds_read_b128 v[128:131], v137
	ds_read_b128 v[230:233], v137 offset:1024
	ds_read_b128 v[234:237], v137 offset:2048
	ds_read_b128 v[238:241], v137 offset:3072
	s_waitcnt vmcnt(0)
	s_barrier
	s_waitcnt lgkmcnt(0)
	s_setprio 1
	v_mfma_f32_16x16x32_bf16 v[96:99], v[8:11], v[128:131], v[222:225]
	v_mfma_f32_16x16x32_bf16 v[8:11], v[8:11], v[234:237], v[88:91]
	v_mfma_f32_16x16x32_bf16 v[124:127], v[12:15], v[238:241], v[8:11]
	v_mfma_f32_16x16x32_bf16 v[8:11], v[16:19], v[128:131], v[182:185]
	v_mfma_f32_16x16x32_bf16 v[112:115], v[20:23], v[230:233], v[8:11]
	v_mfma_f32_16x16x32_bf16 v[8:11], v[16:19], v[234:237], v[186:189]
	v_mfma_f32_16x16x32_bf16 v[116:119], v[20:23], v[238:241], v[8:11]
	v_mfma_f32_16x16x32_bf16 v[8:11], v[24:27], v[128:131], v[190:193]
	v_mfma_f32_16x16x32_bf16 v[104:107], v[28:31], v[230:233], v[8:11]
	v_mfma_f32_16x16x32_bf16 v[8:11], v[24:27], v[234:237], v[194:197]
	v_mfma_f32_16x16x32_bf16 v[108:111], v[28:31], v[238:241], v[8:11]
	v_mfma_f32_16x16x32_bf16 v[8:11], v[218:221], v[128:131], v[198:201]
	v_mfma_f32_16x16x32_bf16 v[88:91], v[226:229], v[230:233], v[8:11]
	v_mfma_f32_16x16x32_bf16 v[8:11], v[218:221], v[234:237], v[202:205]
	v_mfma_f32_16x16x32_bf16 v[120:123], v[12:15], v[230:233], v[96:99]
	v_mfma_f32_16x16x32_bf16 v[96:99], v[226:229], v[238:241], v[8:11]
	s_setprio 0
	s_barrier
	ds_read_b128 v[182:185], v135 offset:49152
	ds_read_b128 v[134:137], v135 offset:50176
	ds_read_b128 v[186:189], v156 offset:49152
	ds_read_b128 v[190:193], v156 offset:50176
	ds_read_b128 v[194:197], v157 offset:49152
	ds_read_b128 v[198:201], v157 offset:50176
	ds_read_b128 v[202:205], v158 offset:49152
	ds_read_b128 v[156:159], v158 offset:50176
	s_barrier
	s_waitcnt lgkmcnt(0)
	s_setprio 1
	v_mfma_f32_16x16x32_bf16 v[8:11], v[182:185], v[0:3], v[60:63]
	v_mfma_f32_16x16x32_bf16 v[24:27], v[134:137], v[4:7], v[8:11]
	v_mfma_f32_16x16x32_bf16 v[8:11], v[182:185], v[206:209], v[56:59]
	v_mfma_f32_16x16x32_bf16 v[28:31], v[134:137], v[138:141], v[8:11]
	v_mfma_f32_16x16x32_bf16 v[8:11], v[186:189], v[0:3], v[52:55]
	v_mfma_f32_16x16x32_bf16 v[16:19], v[190:193], v[4:7], v[8:11]
	v_mfma_f32_16x16x32_bf16 v[8:11], v[186:189], v[206:209], v[48:51]
	v_mfma_f32_16x16x32_bf16 v[20:23], v[190:193], v[138:141], v[8:11]
	v_mfma_f32_16x16x32_bf16 v[8:11], v[194:197], v[0:3], v[44:47]
	v_mfma_f32_16x16x32_bf16 v[0:3], v[202:205], v[0:3], v[36:39]
	v_mfma_f32_16x16x32_bf16 v[8:11], v[198:201], v[4:7], v[8:11]
	v_mfma_f32_16x16x32_bf16 v[12:15], v[194:197], v[206:209], v[40:43]
	v_mfma_f32_16x16x32_bf16 v[0:3], v[156:159], v[4:7], v[0:3]
	v_mfma_f32_16x16x32_bf16 v[4:7], v[202:205], v[206:209], v[32:35]
	v_mfma_f32_16x16x32_bf16 v[12:15], v[198:201], v[138:141], v[12:15]
	v_mfma_f32_16x16x32_bf16 v[4:7], v[156:159], v[138:141], v[4:7]
	s_setprio 0
	s_setprio 1
	v_mfma_f32_16x16x32_bf16 v[32:35], v[182:185], v[128:131], v[142:145]
	v_mfma_f32_16x16x32_bf16 v[56:59], v[134:137], v[230:233], v[32:35]
	v_mfma_f32_16x16x32_bf16 v[32:35], v[182:185], v[234:237], v[160:163]
	v_mfma_f32_16x16x32_bf16 v[60:63], v[134:137], v[238:241], v[32:35]
	v_mfma_f32_16x16x32_bf16 v[32:35], v[186:189], v[128:131], v[164:167]
	v_mfma_f32_16x16x32_bf16 v[48:51], v[190:193], v[230:233], v[32:35]
	v_mfma_f32_16x16x32_bf16 v[32:35], v[186:189], v[234:237], v[174:177]
	v_mfma_f32_16x16x32_bf16 v[52:55], v[190:193], v[238:241], v[32:35]
	v_mfma_f32_16x16x32_bf16 v[32:35], v[194:197], v[128:131], v[178:181]
	v_mfma_f32_16x16x32_bf16 v[40:43], v[198:201], v[230:233], v[32:35]
	v_mfma_f32_16x16x32_bf16 v[32:35], v[194:197], v[234:237], v[210:213]
	v_mfma_f32_16x16x32_bf16 v[44:47], v[198:201], v[238:241], v[32:35]
	v_mfma_f32_16x16x32_bf16 v[32:35], v[202:205], v[128:131], v[214:217]
	v_mfma_f32_16x16x32_bf16 v[36:39], v[202:205], v[234:237], v[152:155]
	v_mfma_f32_16x16x32_bf16 v[32:35], v[156:159], v[230:233], v[32:35]
	v_mfma_f32_16x16x32_bf16 v[36:39], v[156:159], v[238:241], v[36:39]
	s_setprio 0
	s_cmpk_gt_u32 s30, 0xff
	s_barrier
	s_cbranch_scc1 .LBB0_1782
	s_barrier

; #define LDA(dst, b, h)                                                                                    \
;   _Pragma("unroll") for (int m = 0; m < 4; ++m) _Pragma("unroll") for (int k = 0; k < 2; ++k)             \
;       dst[m][k] = *reinterpret_cast<const bf16x8*>((char*)SA(b, h) + lds_byte(wr * 64 + m * 16 + fr, k * 32 + fq * 8))
; #define LDB(dst, b, h)                                                                                    \
;   _Pragma("unroll") for (int n = 0; n < 2; ++n) _Pragma("unroll") for (int k = 0; k < 2; ++k)             \
;       dst[n][k] = *reinterpret_cast<const bf16x8*>((char*)SB(b, h) + lds_byte(wc * 32 + n * 16 + fr, k * 32 + fq * 8))
; #define WAIT_V(n) asm volatile("s_waitcnt vmcnt(" #n ")" ::: "memory")
; #define WAIT_L(n) asm volatile("s_waitcnt lgkmcnt(" #n ")" ::: "memory")
; #define BAR __builtin_amdgcn_s_barrier()
; #define SCHED __builtin_amdgcn_sched_barrier(0)
; template <int EPI> ...
;     ...
;   if (wr == 1) BAR;
;   WAIT_V(10); BAR;
;   WAIT_V(6); BAR;
;   for (int t = 0; t < nt - 2; t += 2) {
;     LDB(B0, 0, 0); SCHED; LDA(At, 0, 0); STAGE(SA(1, 1), A, brow + HALF, t + 1);
;     WAIT_L(8); BAR; WAIT_L(0); MMA(0, 0, At, B0); BAR; SCHED;
;     LDB(B1, 0, 1); STAGE(SB(0, 0), Bt, bcol, t + 2);
;     BAR; WAIT_L(0); MMA(0, 1, At, B1); BAR;
.LBB0_1856:
	s_ashr_i32 s11, s31, 6
	s_and_b32 s34, s11, 3
	v_and_b32_e32 v129, 15, v128
	v_and_b32_e32 v9, 48, v128
	v_lshlrev_b32_e32 v130, 2, v128
	s_lshl_b32 s35, s34, 12
	v_lshl_or_b32 v8, v129, 6, v9
	v_and_b32_e32 v46, 32, v130
	v_bitop3_b32 v126, s35, v8, v46 bitop3:0xf6
	v_or_b32_e32 v127, 0x10000, v126
	v_or_b32_e32 v222, 0x10800, v126
	s_waitcnt vmcnt(10)
	s_barrier
	s_waitcnt vmcnt(6)
	s_barrier
	v_or_b32_e32 v131, 0x10400, v126
	ds_read_b128 v[22:25], v127
	ds_read_b128 v[26:29], v131
	v_or_b32_e32 v223, 0x10c00, v126
	ds_read_b128 v[30:33], v222
	ds_read_b128 v[34:37], v223
	v_mov_b32_e32 v1, v0
	v_mov_b32_e32 v2, v0
	v_mov_b32_e32 v3, v0
	v_lshlrev_b32_e32 v47, 6, v128
	s_movk_i32 s62, 0x3c0
	s_lshl_b32 s35, s30, 13
	v_and_or_b32 v9, v47, s62, v9
	v_bitop3_b32 v8, s35, v8, v46 bitop3:0xf6
	v_bitop3_b32 v9, s35, v9, v46 bitop3:0xf6
	v_mov_b32_e32 v148, v4
	v_add_u32_e32 v72, 0xc000, v12
	ds_read_b128 v[38:41], v8
	ds_read_b128 v[42:45], v8 offset:1024
	ds_read_b128 v[46:49], v9 offset:2048
	ds_read_b128 v[50:53], v9 offset:3072
	ds_read_b128 v[54:57], v9 offset:4096
	ds_read_b128 v[58:61], v9 offset:5120
	ds_read_b128 v[62:65], v9 offset:6144
	ds_read_b128 v[66:69], v9 offset:7168
	v_readfirstlane_b32 s62, v72
	v_lshl_add_u64 v[70:71], v[148:149], 1, s[12:13]
	v_lshl_add_u64 v[70:71], v[70:71], 0, s[46:47]
	s_mov_b32 m0, s62
	v_mov_b32_e32 v148, v6
	v_add_u32_e32 v72, 0xe000, v12
	global_load_lds_dwordx4 v[70:71], off
	v_readfirstlane_b32 s35, v72
	v_lshl_add_u64 v[70:71], v[148:149], 1, s[12:13]
	v_lshl_add_u64 v[70:71], v[70:71], 0, s[46:47]
	s_mov_b32 m0, s35
	s_nop 0
	global_load_lds_dwordx4 v[70:71], off
	s_waitcnt lgkmcnt(8)
	s_barrier
	s_waitcnt lgkmcnt(0)
	s_setprio 1
	v_mfma_f32_16x16x32_bf16 v[70:73], v[38:41], v[22:25], v[0:3]
	v_mfma_f32_16x16x32_bf16 v[74:77], v[38:41], v[30:33], v[0:3]
	v_mfma_f32_16x16x32_bf16 v[78:81], v[46:49], v[22:25], v[0:3]
	v_mfma_f32_16x16x32_bf16 v[82:85], v[46:49], v[30:33], v[0:3]
	v_mfma_f32_16x16x32_bf16 v[86:89], v[54:57], v[22:25], v[0:3]
	v_mfma_f32_16x16x32_bf16 v[90:93], v[54:57], v[30:33], v[0:3]
	v_mfma_f32_16x16x32_bf16 v[94:97], v[62:65], v[22:25], v[0:3]
	v_mfma_f32_16x16x32_bf16 v[98:101], v[62:65], v[30:33], v[0:3]
	v_mfma_f32_16x16x32_bf16 v[70:73], v[42:45], v[26:29], v[70:73]
	v_mfma_f32_16x16x32_bf16 v[74:77], v[42:45], v[34:37], v[74:77]
	v_mfma_f32_16x16x32_bf16 v[78:81], v[50:53], v[26:29], v[78:81]
	v_mfma_f32_16x16x32_bf16 v[82:85], v[50:53], v[34:37], v[82:85]
	v_mfma_f32_16x16x32_bf16 v[86:89], v[58:61], v[26:29], v[86:89]
	v_mfma_f32_16x16x32_bf16 v[90:93], v[58:61], v[34:37], v[90:93]
	v_mfma_f32_16x16x32_bf16 v[94:97], v[66:69], v[26:29], v[94:97]
	v_mfma_f32_16x16x32_bf16 v[98:101], v[66:69], v[34:37], v[98:101]
	s_setprio 0
	s_barrier
	v_or_b32_e32 v224, 0x14000, v126
	v_or_b32_e32 v226, 0x14800, v126
	v_mov_b32_e32 v148, v4
	v_or_b32_e32 v225, 0x14400, v126
	ds_read_b128 v[102:105], v224
	ds_read_b128 v[106:109], v225
	v_or_b32_e32 v227, 0x14c00, v126
	ds_read_b128 v[110:113], v226
	ds_read_b128 v[114:117], v227
	v_readfirstlane_b32 s63, v20
	v_lshl_add_u64 v[118:119], v[148:149], 1, s[18:19]
	v_lshl_add_u64 v[118:119], v[118:119], 0, s[50:51]
	s_mov_b32 m0, s63
	v_mov_b32_e32 v148, v6
	global_load_lds_dwordx4 v[118:119], off
	v_readfirstlane_b32 s63, v21
	v_lshl_add_u64 v[118:119], v[148:149], 1, s[18:19]
	v_lshl_add_u64 v[118:119], v[118:119], 0, s[50:51]
	s_mov_b32 m0, s63
	s_nop 0
	global_load_lds_dwordx4 v[118:119], off
	s_barrier
	s_waitcnt lgkmcnt(0)
	s_setprio 1
	v_mfma_f32_16x16x32_bf16 v[118:121], v[38:41], v[102:105], v[0:3]
	v_mfma_f32_16x16x32_bf16 v[38:41], v[38:41], v[110:113], v[0:3]
	v_mfma_f32_16x16x32_bf16 v[118:121], v[42:45], v[106:109], v[118:121]
	v_mfma_f32_16x16x32_bf16 v[38:41], v[42:45], v[114:117], v[38:41]
	v_mfma_f32_16x16x32_bf16 v[42:45], v[46:49], v[102:105], v[0:3]
	v_mfma_f32_16x16x32_bf16 v[46:49], v[46:49], v[110:113], v[0:3]
	v_mfma_f32_16x16x32_bf16 v[42:45], v[50:53], v[106:109], v[42:45]
	v_mfma_f32_16x16x32_bf16 v[46:49], v[50:53], v[114:117], v[46:49]
	v_mfma_f32_16x16x32_bf16 v[50:53], v[54:57], v[102:105], v[0:3]
	v_mfma_f32_16x16x32_bf16 v[54:57], v[54:57], v[110:113], v[0:3]
	v_mfma_f32_16x16x32_bf16 v[50:53], v[58:61], v[106:109], v[50:53]
	v_mfma_f32_16x16x32_bf16 v[54:57], v[58:61], v[114:117], v[54:57]
	v_mfma_f32_16x16x32_bf16 v[58:61], v[62:65], v[102:105], v[0:3]
	v_mfma_f32_16x16x32_bf16 v[62:65], v[62:65], v[110:113], v[0:3]
	v_mfma_f32_16x16x32_bf16 v[58:61], v[66:69], v[106:109], v[58:61]
	v_mfma_f32_16x16x32_bf16 v[62:65], v[66:69], v[114:117], v[62:65]
	s_setprio 0
	v_mov_b32_e32 v148, v4
	s_barrier
	ds_read_b128 v[66:69], v8 offset:16384
	ds_read_b128 v[122:125], v8 offset:17408
	ds_read_b128 v[132:135], v9 offset:18432
	ds_read_b128 v[136:139], v9 offset:19456
	ds_read_b128 v[140:143], v9 offset:20480
	ds_read_b128 v[144:147], v9 offset:21504
	ds_read_b128 v[152:155], v9 offset:22528
	ds_read_b128 v[156:159], v9 offset:23552
	v_readfirstlane_b32 s63, v12
	v_lshl_add_u64 v[20:21], v[148:149], 1, s[16:17]
	v_lshl_add_u64 v[20:21], v[20:21], 0, s[50:51]
	s_mov_b32 m0, s63
	v_mov_b32_e32 v148, v6
	global_load_lds_dwordx4 v[20:21], off
	v_readfirstlane_b32 s63, v15
	v_lshl_add_u64 v[20:21], v[148:149], 1, s[16:17]
	v_lshl_add_u64 v[20:21], v[20:21], 0, s[50:51]
	s_mov_b32 m0, s63
	s_nop 0
	global_load_lds_dwordx4 v[20:21], off
	s_barrier
; #define LDA(dst, b, h)                                                                                    \
;   _Pragma("unroll") for (int m = 0; m < 4; ++m) _Pragma("unroll") for (int k = 0; k < 2; ++k)             \
;       dst[m][k] = *reinterpret_cast<const bf16x8*>((char*)SA(b, h) + lds_byte(wr * 64 + m * 16 + fr, k * 32 + fq * 8))
; #define LDB(dst, b, h)                                                                                    \
;   _Pragma("unroll") for (int n = 0; n < 2; ++n) _Pragma("unroll") for (int k = 0; k < 2; ++k)             \
;       dst[n][k] = *reinterpret_cast<const bf16x8*>((char*)SB(b, h) + lds_byte(wc * 32 + n * 16 + fr, k * 32 + fq * 8))
; #define WAIT_V(n) asm volatile("s_waitcnt vmcnt(" #n ")" ::: "memory")
; #define WAIT_L(n) asm volatile("s_waitcnt lgkmcnt(" #n ")" ::: "memory")
; #define BAR __builtin_amdgcn_s_barrier()
; #define SCHED __builtin_amdgcn_sched_barrier(0)
; template <int EPI> ...
;     ...
;     LDA(At, 0, 1); STAGE(SA(0, 0), A, brow, t + 2);
;     BAR; WAIT_L(0); MMA(1, 0, At, B0); BAR; SCHED;
;     STAGE(SB(0, 1), Bt, bcol + HALF, t + 2);
;     WAIT_V(6); BAR; MMA(1, 1, At, B1); BAR;
;     LDB(B0, 1, 0); SCHED; LDA(At, 1, 0); STAGE(SA(0, 1), A, brow + HALF, t + 2);
;     WAIT_L(8); BAR; WAIT_L(0); MMA(0, 0, At, B0); BAR; SCHED;
;     LDB(B1, 1, 1); STAGE(SB(1, 0), Bt, bcol, t + 3);
	s_waitcnt lgkmcnt(0)
	s_setprio 1
	v_mfma_f32_16x16x32_bf16 v[160:163], v[66:69], v[22:25], v[0:3]
	v_mfma_f32_16x16x32_bf16 v[174:177], v[132:135], v[22:25], v[0:3]
	v_mfma_f32_16x16x32_bf16 v[182:185], v[140:143], v[22:25], v[0:3]
	v_mfma_f32_16x16x32_bf16 v[20:23], v[152:155], v[22:25], v[0:3]
	v_mfma_f32_16x16x32_bf16 v[160:163], v[122:125], v[26:29], v[160:163]
	v_mfma_f32_16x16x32_bf16 v[174:177], v[136:139], v[26:29], v[174:177]
	v_mfma_f32_16x16x32_bf16 v[182:185], v[144:147], v[26:29], v[182:185]
	v_mfma_f32_16x16x32_bf16 v[20:23], v[156:159], v[26:29], v[20:23]
	v_mfma_f32_16x16x32_bf16 v[24:27], v[152:155], v[30:33], v[0:3]
	v_mfma_f32_16x16x32_bf16 v[164:167], v[66:69], v[30:33], v[0:3]
	v_mfma_f32_16x16x32_bf16 v[178:181], v[132:135], v[30:33], v[0:3]
	v_mfma_f32_16x16x32_bf16 v[186:189], v[140:143], v[30:33], v[0:3]
	v_mfma_f32_16x16x32_bf16 v[24:27], v[156:159], v[34:37], v[24:27]
	v_mfma_f32_16x16x32_bf16 v[164:167], v[122:125], v[34:37], v[164:167]
	v_mfma_f32_16x16x32_bf16 v[178:181], v[136:139], v[34:37], v[178:181]
	v_mfma_f32_16x16x32_bf16 v[186:189], v[144:147], v[34:37], v[186:189]
	s_setprio 0
	s_barrier
	v_mov_b32_e32 v148, v4
	v_readfirstlane_b32 s63, v18
	v_lshl_add_u64 v[28:29], v[148:149], 1, s[14:15]
	v_lshl_add_u64 v[28:29], v[28:29], 0, s[50:51]
	s_mov_b32 m0, s63
	v_mov_b32_e32 v148, v6
	global_load_lds_dwordx4 v[28:29], off
	v_readfirstlane_b32 s63, v19
	v_lshl_add_u64 v[28:29], v[148:149], 1, s[14:15]
	v_lshl_add_u64 v[28:29], v[28:29], 0, s[50:51]
	s_mov_b32 m0, s63
	s_nop 0
	global_load_lds_dwordx4 v[28:29], off
	s_waitcnt vmcnt(6)
	s_barrier
	s_setprio 1
	v_mfma_f32_16x16x32_bf16 v[28:31], v[66:69], v[102:105], v[0:3]
	v_mfma_f32_16x16x32_bf16 v[32:35], v[66:69], v[110:113], v[0:3]
	v_mfma_f32_16x16x32_bf16 v[28:31], v[122:125], v[106:109], v[28:31]
	v_mfma_f32_16x16x32_bf16 v[32:35], v[122:125], v[114:117], v[32:35]
	v_mfma_f32_16x16x32_bf16 v[66:69], v[132:135], v[102:105], v[0:3]
	v_mfma_f32_16x16x32_bf16 v[122:125], v[132:135], v[110:113], v[0:3]
	v_mfma_f32_16x16x32_bf16 v[66:69], v[136:139], v[106:109], v[66:69]
	v_mfma_f32_16x16x32_bf16 v[122:125], v[136:139], v[114:117], v[122:125]
	v_mfma_f32_16x16x32_bf16 v[132:135], v[140:143], v[102:105], v[0:3]
	v_mfma_f32_16x16x32_bf16 v[136:139], v[140:143], v[110:113], v[0:3]
	v_mfma_f32_16x16x32_bf16 v[102:105], v[152:155], v[102:105], v[0:3]
	v_mfma_f32_16x16x32_bf16 v[0:3], v[152:155], v[110:113], v[0:3]
	v_mfma_f32_16x16x32_bf16 v[102:105], v[156:159], v[106:109], v[102:105]
	v_mfma_f32_16x16x32_bf16 v[0:3], v[156:159], v[114:117], v[0:3]
	v_mfma_f32_16x16x32_bf16 v[132:135], v[144:147], v[106:109], v[132:135]
	v_mfma_f32_16x16x32_bf16 v[136:139], v[144:147], v[114:117], v[136:139]
	s_setprio 0
	v_or_b32_e32 v228, 0x18000, v126
	v_or_b32_e32 v230, 0x18800, v126
	s_barrier
	v_or_b32_e32 v229, 0x18400, v126
	ds_read_b128 v[106:109], v228
	ds_read_b128 v[110:113], v229
	v_or_b32_e32 v231, 0x18c00, v126
	ds_read_b128 v[114:117], v230
	ds_read_b128 v[140:143], v231
	v_mov_b32_e32 v148, v4
	ds_read_b128 v[144:147], v8 offset:32768
	ds_read_b128 v[152:155], v8 offset:33792
	ds_read_b128 v[156:159], v9 offset:34816
	ds_read_b128 v[190:193], v9 offset:35840
	ds_read_b128 v[194:197], v9 offset:36864
	ds_read_b128 v[198:201], v9 offset:37888
	ds_read_b128 v[202:205], v9 offset:38912
	ds_read_b128 v[206:209], v9 offset:39936
	v_readfirstlane_b32 s63, v16
	v_lshl_add_u64 v[18:19], v[148:149], 1, s[12:13]
	v_lshl_add_u64 v[18:19], v[18:19], 0, s[50:51]
	s_mov_b32 m0, s63
	v_mov_b32_e32 v148, v6
	global_load_lds_dwordx4 v[18:19], off
	v_readfirstlane_b32 s63, v17
	v_lshl_add_u64 v[18:19], v[148:149], 1, s[12:13]
	v_lshl_add_u64 v[18:19], v[18:19], 0, s[50:51]
	s_mov_b32 m0, s63
	s_nop 0
	global_load_lds_dwordx4 v[18:19], off
	s_waitcnt lgkmcnt(8)
	s_barrier
	s_waitcnt lgkmcnt(0)
	s_setprio 1
	v_mfma_f32_16x16x32_bf16 v[16:19], v[144:147], v[106:109], v[70:73]
	v_mfma_f32_16x16x32_bf16 v[70:73], v[144:147], v[114:117], v[74:77]
	v_mfma_f32_16x16x32_bf16 v[74:77], v[156:159], v[106:109], v[78:81]
	v_mfma_f32_16x16x32_bf16 v[78:81], v[156:159], v[114:117], v[82:85]
	v_mfma_f32_16x16x32_bf16 v[82:85], v[194:197], v[106:109], v[86:89]
	v_mfma_f32_16x16x32_bf16 v[86:89], v[194:197], v[114:117], v[90:93]
	v_mfma_f32_16x16x32_bf16 v[90:93], v[202:205], v[106:109], v[94:97]
	v_mfma_f32_16x16x32_bf16 v[94:97], v[202:205], v[114:117], v[98:101]
	v_mfma_f32_16x16x32_bf16 v[16:19], v[152:155], v[110:113], v[16:19]
	v_mfma_f32_16x16x32_bf16 v[70:73], v[152:155], v[140:143], v[70:73]
	v_mfma_f32_16x16x32_bf16 v[74:77], v[190:193], v[110:113], v[74:77]
	v_mfma_f32_16x16x32_bf16 v[78:81], v[190:193], v[140:143], v[78:81]
	v_mfma_f32_16x16x32_bf16 v[82:85], v[198:201], v[110:113], v[82:85]
	v_mfma_f32_16x16x32_bf16 v[86:89], v[198:201], v[140:143], v[86:89]
	v_mfma_f32_16x16x32_bf16 v[90:93], v[206:209], v[110:113], v[90:93]
	v_mfma_f32_16x16x32_bf16 v[94:97], v[206:209], v[140:143], v[94:97]
	s_setprio 0
	s_barrier
	v_or_b32_e32 v234, 0x1c000, v126
	v_or_b32_e32 v236, 0x1c800, v126
	v_mov_b32_e32 v148, v4
	v_or_b32_e32 v235, 0x1c400, v126
	ds_read_b128 v[98:101], v234
	ds_read_b128 v[210:213], v235
	v_or_b32_e32 v126, 0x1cc00, v126
	ds_read_b128 v[214:217], v236
	ds_read_b128 v[218:221], v126
	v_readfirstlane_b32 s63, v13
	v_lshl_add_u64 v[36:37], v[148:149], 1, s[18:19]
	v_lshl_add_u64 v[36:37], v[36:37], 0, s[54:55]
	s_mov_b32 m0, s63
	v_mov_b32_e32 v148, v6
	global_load_lds_dwordx4 v[36:37], off
	s_nop 0
	v_lshl_add_u64 v[12:13], v[148:149], 1, s[18:19]
	v_readfirstlane_b32 s18, v14
	v_lshl_add_u64 v[12:13], v[12:13], 0, s[54:55]
	s_mov_b32 m0, s18
	s_nop 0
	global_load_lds_dwordx4 v[12:13], off
	s_barrier
; #define LDA(dst, b, h)                                                                                    \
;   _Pragma("unroll") for (int m = 0; m < 4; ++m) _Pragma("unroll") for (int k = 0; k < 2; ++k)             \
;       dst[m][k] = *reinterpret_cast<const bf16x8*>((char*)SA(b, h) + lds_byte(wr * 64 + m * 16 + fr, k * 32 + fq * 8))
; #define LDB(dst, b, h)                                                                                    \
;   _Pragma("unroll") for (int n = 0; n < 2; ++n) _Pragma("unroll") for (int k = 0; k < 2; ++k)             \
;       dst[n][k] = *reinterpret_cast<const bf16x8*>((char*)SB(b, h) + lds_byte(wc * 32 + n * 16 + fr, k * 32 + fq * 8))
; #define WAIT_V(n) asm volatile("s_waitcnt vmcnt(" #n ")" ::: "memory")
; #define WAIT_L(n) asm volatile("s_waitcnt lgkmcnt(" #n ")" ::: "memory")
; #define BAR __builtin_amdgcn_s_barrier()
; #define SCHED __builtin_amdgcn_sched_barrier(0)
; template <int EPI> ...
;     ...
;     BAR; WAIT_L(0); MMA(0, 1, At, B1); BAR;
;     LDA(At, 1, 1); STAGE(SA(1, 0), A, brow, t + 3);
;     BAR; WAIT_L(0); MMA(1, 0, At, B0); BAR; SCHED;
;     STAGE(SB(1, 1), Bt, bcol + HALF, t + 3);
;     WAIT_V(6); BAR; MMA(1, 1, At, B1); BAR;
;   }
;   {
;     LDB(B0, 0, 0); LDA(At, 0, 0); STAGE(SA(1, 1), A, brow + HALF, nt - 1);
	s_waitcnt lgkmcnt(0)
	s_setprio 1
	v_mfma_f32_16x16x32_bf16 v[12:15], v[144:147], v[98:101], v[118:121]
	v_mfma_f32_16x16x32_bf16 v[36:39], v[144:147], v[214:217], v[38:41]
	v_mfma_f32_16x16x32_bf16 v[40:43], v[156:159], v[98:101], v[42:45]
	v_mfma_f32_16x16x32_bf16 v[44:47], v[156:159], v[214:217], v[46:49]
	v_mfma_f32_16x16x32_bf16 v[48:51], v[194:197], v[98:101], v[50:53]
	v_mfma_f32_16x16x32_bf16 v[52:55], v[194:197], v[214:217], v[54:57]
	v_mfma_f32_16x16x32_bf16 v[56:59], v[202:205], v[98:101], v[58:61]
	v_mfma_f32_16x16x32_bf16 v[60:63], v[202:205], v[214:217], v[62:65]
	v_mfma_f32_16x16x32_bf16 v[12:15], v[152:155], v[210:213], v[12:15]
	v_mfma_f32_16x16x32_bf16 v[36:39], v[152:155], v[218:221], v[36:39]
	v_mfma_f32_16x16x32_bf16 v[40:43], v[190:193], v[210:213], v[40:43]
	v_mfma_f32_16x16x32_bf16 v[44:47], v[190:193], v[218:221], v[44:47]
	v_mfma_f32_16x16x32_bf16 v[48:51], v[198:201], v[210:213], v[48:51]
	v_mfma_f32_16x16x32_bf16 v[52:55], v[198:201], v[218:221], v[52:55]
	v_mfma_f32_16x16x32_bf16 v[56:59], v[206:209], v[210:213], v[56:59]
	v_mfma_f32_16x16x32_bf16 v[60:63], v[206:209], v[218:221], v[60:63]
	s_setprio 0
	v_mov_b32_e32 v148, v4
	s_barrier
	ds_read_b128 v[118:121], v8 offset:49152
	ds_read_b128 v[144:147], v8 offset:50176
	ds_read_b128 v[152:155], v9 offset:51200
	ds_read_b128 v[156:159], v9 offset:52224
	ds_read_b128 v[190:193], v9 offset:53248
	ds_read_b128 v[194:197], v9 offset:54272
	ds_read_b128 v[198:201], v9 offset:55296
	ds_read_b128 v[202:205], v9 offset:56320
	v_readfirstlane_b32 s18, v10
	v_lshl_add_u64 v[64:65], v[148:149], 1, s[16:17]
	v_lshl_add_u64 v[64:65], v[64:65], 0, s[54:55]
	s_mov_b32 m0, s18
	v_mov_b32_e32 v148, v6
	global_load_lds_dwordx4 v[64:65], off
	s_nop 0
	v_lshl_add_u64 v[64:65], v[148:149], 1, s[16:17]
	v_readfirstlane_b32 s16, v11
	v_lshl_add_u64 v[64:65], v[64:65], 0, s[54:55]
	s_mov_b32 m0, s16
	s_nop 0
	global_load_lds_dwordx4 v[64:65], off
	s_barrier
	s_waitcnt lgkmcnt(0)
	s_setprio 1
	v_mfma_f32_16x16x32_bf16 v[20:23], v[198:201], v[106:109], v[20:23]
	v_mfma_f32_16x16x32_bf16 v[24:27], v[198:201], v[114:117], v[24:27]
	v_mfma_f32_16x16x32_bf16 v[160:163], v[118:121], v[106:109], v[160:163]
	v_mfma_f32_16x16x32_bf16 v[164:167], v[118:121], v[114:117], v[164:167]
	v_mfma_f32_16x16x32_bf16 v[174:177], v[152:155], v[106:109], v[174:177]
	v_mfma_f32_16x16x32_bf16 v[178:181], v[152:155], v[114:117], v[178:181]
	v_mfma_f32_16x16x32_bf16 v[182:185], v[190:193], v[106:109], v[182:185]
	v_mfma_f32_16x16x32_bf16 v[186:189], v[190:193], v[114:117], v[186:189]
	v_mfma_f32_16x16x32_bf16 v[20:23], v[202:205], v[110:113], v[20:23]
	v_mfma_f32_16x16x32_bf16 v[24:27], v[202:205], v[140:143], v[24:27]
	v_mfma_f32_16x16x32_bf16 v[160:163], v[144:147], v[110:113], v[160:163]
	v_mfma_f32_16x16x32_bf16 v[164:167], v[144:147], v[140:143], v[164:167]
	v_mfma_f32_16x16x32_bf16 v[174:177], v[156:159], v[110:113], v[174:177]
	v_mfma_f32_16x16x32_bf16 v[178:181], v[156:159], v[140:143], v[178:181]
	v_mfma_f32_16x16x32_bf16 v[182:185], v[194:197], v[110:113], v[182:185]
	v_mfma_f32_16x16x32_bf16 v[186:189], v[194:197], v[140:143], v[186:189]
	s_setprio 0
	s_barrier
	v_mov_b32_e32 v148, v4
	v_readfirstlane_b32 s16, v5
	v_lshl_add_u64 v[10:11], v[148:149], 1, s[14:15]
	v_lshl_add_u64 v[10:11], v[10:11], 0, s[54:55]
	s_mov_b32 m0, s16
	v_mov_b32_e32 v148, v6
	global_load_lds_dwordx4 v[10:11], off
	s_nop 0
	v_lshl_add_u64 v[10:11], v[148:149], 1, s[14:15]
	v_readfirstlane_b32 s14, v7
	v_lshl_add_u64 v[10:11], v[10:11], 0, s[54:55]
	s_mov_b32 m0, s14
	s_nop 0
	global_load_lds_dwordx4 v[10:11], off
	s_waitcnt vmcnt(6)
	s_barrier
	s_setprio 1
	v_mfma_f32_16x16x32_bf16 v[28:31], v[118:121], v[98:101], v[28:31]
	v_mfma_f32_16x16x32_bf16 v[32:35], v[118:121], v[214:217], v[32:35]
	v_mfma_f32_16x16x32_bf16 v[64:67], v[152:155], v[98:101], v[66:69]
	v_mfma_f32_16x16x32_bf16 v[106:109], v[152:155], v[214:217], v[122:125]
	v_mfma_f32_16x16x32_bf16 v[110:113], v[190:193], v[98:101], v[132:135]
	v_mfma_f32_16x16x32_bf16 v[114:117], v[190:193], v[214:217], v[136:139]
	v_mfma_f32_16x16x32_bf16 v[98:101], v[198:201], v[98:101], v[102:105]
	v_mfma_f32_16x16x32_bf16 v[0:3], v[198:201], v[214:217], v[0:3]
	v_mfma_f32_16x16x32_bf16 v[28:31], v[144:147], v[210:213], v[28:31]
	v_mfma_f32_16x16x32_bf16 v[32:35], v[144:147], v[218:221], v[32:35]
	v_mfma_f32_16x16x32_bf16 v[64:67], v[156:159], v[210:213], v[64:67]
	v_mfma_f32_16x16x32_bf16 v[106:109], v[156:159], v[218:221], v[106:109]
	v_mfma_f32_16x16x32_bf16 v[110:113], v[194:197], v[210:213], v[110:113]
	v_mfma_f32_16x16x32_bf16 v[114:117], v[194:197], v[218:221], v[114:117]
	v_mfma_f32_16x16x32_bf16 v[98:101], v[202:205], v[210:213], v[98:101]
	v_mfma_f32_16x16x32_bf16 v[0:3], v[202:205], v[218:221], v[0:3]
	s_setprio 0
	s_barrier
	ds_read_b128 v[102:105], v127
	ds_read_b128 v[118:121], v131
	ds_read_b128 v[122:125], v222
	ds_read_b128 v[132:135], v223
	ds_read_b128 v[136:139], v8
	ds_read_b128 v[140:143], v8 offset:1024
	ds_read_b128 v[144:147], v9 offset:2048
	ds_read_b128 v[152:155], v9 offset:3072
	ds_read_b128 v[156:159], v9 offset:4096
	ds_read_b128 v[190:193], v9 offset:5120
	ds_read_b128 v[194:197], v9 offset:6144
	ds_read_b128 v[198:201], v9 offset:7168
	v_mov_b32_e32 v5, v149
	v_lshl_add_u64 v[4:5], v[4:5], 1, s[12:13]
	s_mov_b32 m0, s62
	v_lshl_add_u64 v[4:5], v[4:5], 0, s[54:55]
	v_mov_b32_e32 v7, v149
	global_load_lds_dwordx4 v[4:5], off
	s_mov_b32 m0, s35
	v_lshl_add_u64 v[4:5], v[6:7], 1, s[12:13]
	v_lshl_add_u64 v[4:5], v[4:5], 0, s[54:55]
	global_load_lds_dwordx4 v[4:5], off
	s_barrier
; #define LDA(dst, b, h)                                                                                    \
;   _Pragma("unroll") for (int m = 0; m < 4; ++m) _Pragma("unroll") for (int k = 0; k < 2; ++k)             \
;       dst[m][k] = *reinterpret_cast<const bf16x8*>((char*)SA(b, h) + lds_byte(wr * 64 + m * 16 + fr, k * 32 + fq * 8))
; #define LDB(dst, b, h)                                                                                    \
;   _Pragma("unroll") for (int n = 0; n < 2; ++n) _Pragma("unroll") for (int k = 0; k < 2; ++k)             \
;       dst[n][k] = *reinterpret_cast<const bf16x8*>((char*)SB(b, h) + lds_byte(wc * 32 + n * 16 + fr, k * 32 + fq * 8))
; #define WAIT_V(n) asm volatile("s_waitcnt vmcnt(" #n ")" ::: "memory")
; #define WAIT_L(n) asm volatile("s_waitcnt lgkmcnt(" #n ")" ::: "memory")
; #define BAR __builtin_amdgcn_s_barrier()
; template <int EPI> ...
;     ...
;     BAR; WAIT_L(0); MMA(0, 0, At, B0); BAR;
;     LDB(B1, 0, 1); BAR; WAIT_L(0); MMA(0, 1, At, B1); BAR;
;     LDA(At, 0, 1); WAIT_V(4); BAR; WAIT_L(0); MMA(1, 0, At, B0); MMA(1, 1, At, B1); BAR;
	s_waitcnt lgkmcnt(0)
	s_setprio 1
	v_mfma_f32_16x16x32_bf16 v[4:7], v[136:139], v[102:105], v[16:19]
	v_mfma_f32_16x16x32_bf16 v[16:19], v[136:139], v[122:125], v[70:73]
	v_mfma_f32_16x16x32_bf16 v[68:71], v[144:147], v[102:105], v[74:77]
	v_mfma_f32_16x16x32_bf16 v[72:75], v[144:147], v[122:125], v[78:81]
	v_mfma_f32_16x16x32_bf16 v[76:79], v[156:159], v[102:105], v[82:85]
	v_mfma_f32_16x16x32_bf16 v[80:83], v[156:159], v[122:125], v[86:89]
	v_mfma_f32_16x16x32_bf16 v[202:205], v[190:193], v[132:135], v[80:83]
	v_mfma_f32_16x16x32_bf16 v[80:83], v[194:197], v[102:105], v[90:93]
	v_mfma_f32_16x16x32_bf16 v[4:7], v[140:143], v[118:121], v[4:7]
	v_mfma_f32_16x16x32_bf16 v[16:19], v[140:143], v[132:135], v[16:19]
	v_mfma_f32_16x16x32_bf16 v[68:71], v[152:155], v[118:121], v[68:71]
	v_mfma_f32_16x16x32_bf16 v[72:75], v[152:155], v[132:135], v[72:75]
	v_mfma_f32_16x16x32_bf16 v[76:79], v[190:193], v[118:121], v[76:79]
	v_mfma_f32_16x16x32_bf16 v[88:91], v[198:201], v[118:121], v[80:83]
	v_mfma_f32_16x16x32_bf16 v[80:83], v[194:197], v[122:125], v[94:97]
	v_mfma_f32_16x16x32_bf16 v[206:209], v[198:201], v[132:135], v[80:83]
	s_setprio 0
	s_barrier
	s_nop 4
	ds_read_b128 v[80:83], v224
	ds_read_b128 v[84:87], v225
	ds_read_b128 v[92:95], v226
	ds_read_b128 v[210:213], v227
	s_barrier
	s_waitcnt lgkmcnt(0)
	s_setprio 1
	v_mfma_f32_16x16x32_bf16 v[10:13], v[136:139], v[80:83], v[12:15]
	v_mfma_f32_16x16x32_bf16 v[36:39], v[136:139], v[92:95], v[36:39]
	v_mfma_f32_16x16x32_bf16 v[40:43], v[144:147], v[80:83], v[40:43]
	v_mfma_f32_16x16x32_bf16 v[44:47], v[144:147], v[92:95], v[44:47]
	v_mfma_f32_16x16x32_bf16 v[48:51], v[156:159], v[80:83], v[48:51]
	v_mfma_f32_16x16x32_bf16 v[52:55], v[156:159], v[92:95], v[52:55]
	v_mfma_f32_16x16x32_bf16 v[56:59], v[194:197], v[80:83], v[56:59]
	v_mfma_f32_16x16x32_bf16 v[60:63], v[194:197], v[92:95], v[60:63]
	v_mfma_f32_16x16x32_bf16 v[10:13], v[140:143], v[84:87], v[10:13]
	v_mfma_f32_16x16x32_bf16 v[36:39], v[140:143], v[210:213], v[36:39]
	v_mfma_f32_16x16x32_bf16 v[40:43], v[152:155], v[84:87], v[40:43]
	v_mfma_f32_16x16x32_bf16 v[44:47], v[152:155], v[210:213], v[44:47]
	v_mfma_f32_16x16x32_bf16 v[48:51], v[190:193], v[84:87], v[48:51]
	v_mfma_f32_16x16x32_bf16 v[52:55], v[190:193], v[210:213], v[52:55]
	v_mfma_f32_16x16x32_bf16 v[56:59], v[198:201], v[84:87], v[56:59]
	v_mfma_f32_16x16x32_bf16 v[60:63], v[198:201], v[210:213], v[60:63]
	s_setprio 0
	s_barrier
	ds_read_b128 v[136:139], v8 offset:16384
	ds_read_b128 v[140:143], v8 offset:17408
	ds_read_b128 v[144:147], v9 offset:18432
	ds_read_b128 v[152:155], v9 offset:19456
	ds_read_b128 v[156:159], v9 offset:20480
	ds_read_b128 v[190:193], v9 offset:21504
	ds_read_b128 v[194:197], v9 offset:22528
	ds_read_b128 v[198:201], v9 offset:23552
	s_waitcnt vmcnt(4)
	s_barrier
	s_waitcnt lgkmcnt(0)
	s_setprio 1
	v_mfma_f32_16x16x32_bf16 v[20:23], v[194:197], v[102:105], v[20:23]
	v_mfma_f32_16x16x32_bf16 v[160:163], v[136:139], v[102:105], v[160:163]
	v_mfma_f32_16x16x32_bf16 v[164:167], v[136:139], v[122:125], v[164:167]
	v_mfma_f32_16x16x32_bf16 v[174:177], v[144:147], v[102:105], v[174:177]
	v_mfma_f32_16x16x32_bf16 v[178:181], v[144:147], v[122:125], v[178:181]
	v_mfma_f32_16x16x32_bf16 v[182:185], v[156:159], v[102:105], v[182:185]
	v_mfma_f32_16x16x32_bf16 v[186:189], v[156:159], v[122:125], v[186:189]
	v_mfma_f32_16x16x32_bf16 v[214:217], v[198:201], v[118:121], v[20:23]
	v_mfma_f32_16x16x32_bf16 v[20:23], v[194:197], v[122:125], v[24:27]
	v_mfma_f32_16x16x32_bf16 v[160:163], v[140:143], v[118:121], v[160:163]
	v_mfma_f32_16x16x32_bf16 v[164:167], v[140:143], v[132:135], v[164:167]
	v_mfma_f32_16x16x32_bf16 v[174:177], v[152:155], v[118:121], v[174:177]
	v_mfma_f32_16x16x32_bf16 v[178:181], v[152:155], v[132:135], v[178:181]
	v_mfma_f32_16x16x32_bf16 v[182:185], v[190:193], v[118:121], v[182:185]
	v_mfma_f32_16x16x32_bf16 v[186:189], v[190:193], v[132:135], v[186:189]
	v_mfma_f32_16x16x32_bf16 v[132:135], v[198:201], v[132:135], v[20:23]
	s_setprio 0
	s_setprio 1
	v_mfma_f32_16x16x32_bf16 v[20:23], v[136:139], v[80:83], v[28:31]
	v_mfma_f32_16x16x32_bf16 v[218:221], v[140:143], v[84:87], v[20:23]
	v_mfma_f32_16x16x32_bf16 v[20:23], v[136:139], v[92:95], v[32:35]
	v_mfma_f32_16x16x32_bf16 v[32:35], v[140:143], v[210:213], v[20:23]
	v_mfma_f32_16x16x32_bf16 v[20:23], v[144:147], v[80:83], v[64:67]
	v_mfma_f32_16x16x32_bf16 v[136:139], v[152:155], v[84:87], v[20:23]
	v_mfma_f32_16x16x32_bf16 v[20:23], v[144:147], v[92:95], v[106:109]
	v_mfma_f32_16x16x32_bf16 v[140:143], v[152:155], v[210:213], v[20:23]
	v_mfma_f32_16x16x32_bf16 v[20:23], v[156:159], v[80:83], v[110:113]
	v_mfma_f32_16x16x32_bf16 v[144:147], v[190:193], v[84:87], v[20:23]
	v_mfma_f32_16x16x32_bf16 v[20:23], v[156:159], v[92:95], v[114:117]
	v_mfma_f32_16x16x32_bf16 v[152:155], v[190:193], v[210:213], v[20:23]
	v_mfma_f32_16x16x32_bf16 v[20:23], v[194:197], v[80:83], v[98:101]
	v_mfma_f32_16x16x32_bf16 v[0:3], v[194:197], v[92:95], v[0:3]
	v_mfma_f32_16x16x32_bf16 v[156:159], v[198:201], v[84:87], v[20:23]
	v_mfma_f32_16x16x32_bf16 v[190:193], v[198:201], v[210:213], v[0:3]
	s_setprio 0
	s_barrier
; #define LDA(dst, b, h)                                                                                    \
;   _Pragma("unroll") for (int m = 0; m < 4; ++m) _Pragma("unroll") for (int k = 0; k < 2; ++k)             \
;       dst[m][k] = *reinterpret_cast<const bf16x8*>((char*)SA(b, h) + lds_byte(wr * 64 + m * 16 + fr, k * 32 + fq * 8))
; #define LDB(dst, b, h)                                                                                    \
;   _Pragma("unroll") for (int n = 0; n < 2; ++n) _Pragma("unroll") for (int k = 0; k < 2; ++k)             \
;       dst[n][k] = *reinterpret_cast<const bf16x8*>((char*)SB(b, h) + lds_byte(wc * 32 + n * 16 + fr, k * 32 + fq * 8))
; #define WAIT_V(n) asm volatile("s_waitcnt vmcnt(" #n ")" ::: "memory")
; #define WAIT_L(n) asm volatile("s_waitcnt lgkmcnt(" #n ")" ::: "memory")
; #define BAR __builtin_amdgcn_s_barrier()
; template <int EPI> ...
;     ...
;     LDB(B0, 1, 0); LDA(At, 1, 0); WAIT_V(2); BAR; WAIT_L(0); MMA(0, 0, At, B0); BAR;
;     LDB(B1, 1, 1); WAIT_V(0); BAR; WAIT_L(0); MMA(0, 1, At, B1); BAR;
;     LDA(At, 1, 1); BAR; WAIT_L(0); MMA(1, 0, At, B0); MMA(1, 1, At, B1); BAR;
;   }
;   if (wr == 0) BAR;
	s_nop 3
	ds_read_b128 v[0:3], v228
	ds_read_b128 v[194:197], v229
	ds_read_b128 v[198:201], v230
	ds_read_b128 v[210:213], v231
	ds_read_b128 v[20:23], v8 offset:32768
	ds_read_b128 v[24:27], v8 offset:33792
	ds_read_b128 v[28:31], v9 offset:34816
	ds_read_b128 v[96:99], v9 offset:35840
	ds_read_b128 v[108:111], v9 offset:36864
	ds_read_b128 v[222:225], v9 offset:37888
	ds_read_b128 v[226:229], v9 offset:38912
	ds_read_b128 v[230:233], v9 offset:39936
	s_waitcnt vmcnt(2)
	s_barrier
	s_waitcnt lgkmcnt(0)
	s_setprio 1
	v_mfma_f32_16x16x32_bf16 v[4:7], v[20:23], v[0:3], v[4:7]
	v_mfma_f32_16x16x32_bf16 v[92:95], v[24:27], v[194:197], v[4:7]
	v_mfma_f32_16x16x32_bf16 v[4:7], v[20:23], v[198:201], v[16:19]
	v_mfma_f32_16x16x32_bf16 v[100:103], v[24:27], v[210:213], v[4:7]
	v_mfma_f32_16x16x32_bf16 v[4:7], v[28:31], v[0:3], v[68:71]
	v_mfma_f32_16x16x32_bf16 v[80:83], v[96:99], v[194:197], v[4:7]
	v_mfma_f32_16x16x32_bf16 v[4:7], v[28:31], v[198:201], v[72:75]
	v_mfma_f32_16x16x32_bf16 v[84:87], v[96:99], v[210:213], v[4:7]
	v_mfma_f32_16x16x32_bf16 v[4:7], v[108:111], v[0:3], v[76:79]
	v_mfma_f32_16x16x32_bf16 v[72:75], v[222:225], v[194:197], v[4:7]
	v_mfma_f32_16x16x32_bf16 v[4:7], v[108:111], v[198:201], v[202:205]
	v_mfma_f32_16x16x32_bf16 v[76:79], v[222:225], v[210:213], v[4:7]
	v_mfma_f32_16x16x32_bf16 v[4:7], v[226:229], v[0:3], v[88:91]
	v_mfma_f32_16x16x32_bf16 v[64:67], v[230:233], v[194:197], v[4:7]
	v_mfma_f32_16x16x32_bf16 v[4:7], v[226:229], v[198:201], v[206:209]
	v_mfma_f32_16x16x32_bf16 v[68:71], v[230:233], v[210:213], v[4:7]
	s_setprio 0
	s_barrier
	ds_read_b128 v[202:205], v234
	ds_read_b128 v[206:209], v235
	ds_read_b128 v[234:237], v236
	ds_read_b128 v[238:241], v126
	s_waitcnt vmcnt(0)
	s_barrier
	s_waitcnt lgkmcnt(0)
	s_setprio 1
	v_mfma_f32_16x16x32_bf16 v[4:7], v[20:23], v[202:205], v[10:13]
	v_mfma_f32_16x16x32_bf16 v[120:123], v[24:27], v[206:209], v[4:7]
	v_mfma_f32_16x16x32_bf16 v[4:7], v[20:23], v[234:237], v[36:39]
	v_mfma_f32_16x16x32_bf16 v[124:127], v[24:27], v[238:241], v[4:7]
	v_mfma_f32_16x16x32_bf16 v[4:7], v[28:31], v[202:205], v[40:43]
	v_mfma_f32_16x16x32_bf16 v[112:115], v[96:99], v[206:209], v[4:7]
	v_mfma_f32_16x16x32_bf16 v[4:7], v[28:31], v[234:237], v[44:47]
	v_mfma_f32_16x16x32_bf16 v[116:119], v[96:99], v[238:241], v[4:7]
	v_mfma_f32_16x16x32_bf16 v[4:7], v[108:111], v[202:205], v[48:51]
	v_mfma_f32_16x16x32_bf16 v[104:107], v[222:225], v[206:209], v[4:7]
	v_mfma_f32_16x16x32_bf16 v[4:7], v[108:111], v[234:237], v[52:55]
	v_mfma_f32_16x16x32_bf16 v[108:111], v[222:225], v[238:241], v[4:7]
	v_mfma_f32_16x16x32_bf16 v[4:7], v[226:229], v[202:205], v[56:59]
	v_mfma_f32_16x16x32_bf16 v[88:91], v[230:233], v[206:209], v[4:7]
	v_mfma_f32_16x16x32_bf16 v[4:7], v[226:229], v[234:237], v[60:63]
	v_mfma_f32_16x16x32_bf16 v[96:99], v[230:233], v[238:241], v[4:7]
	s_setprio 0
	s_barrier
	ds_read_b128 v[36:39], v8 offset:49152
	ds_read_b128 v[40:43], v8 offset:50176
	ds_read_b128 v[44:47], v9 offset:51200
	ds_read_b128 v[52:55], v9 offset:52224
	ds_read_b128 v[222:225], v9 offset:53248
	ds_read_b128 v[226:229], v9 offset:54272
	ds_read_b128 v[230:233], v9 offset:55296
	ds_read_b128 v[242:245], v9 offset:56320
	s_barrier
	s_waitcnt lgkmcnt(0)
	s_setprio 1
	v_mfma_f32_16x16x32_bf16 v[4:7], v[36:39], v[0:3], v[160:163]
	v_mfma_f32_16x16x32_bf16 v[24:27], v[40:43], v[194:197], v[4:7]
	v_mfma_f32_16x16x32_bf16 v[4:7], v[36:39], v[198:201], v[164:167]
	v_mfma_f32_16x16x32_bf16 v[28:31], v[40:43], v[210:213], v[4:7]
	v_mfma_f32_16x16x32_bf16 v[4:7], v[44:47], v[0:3], v[174:177]
	v_mfma_f32_16x16x32_bf16 v[16:19], v[52:55], v[194:197], v[4:7]
	v_mfma_f32_16x16x32_bf16 v[4:7], v[44:47], v[198:201], v[178:181]
	v_mfma_f32_16x16x32_bf16 v[20:23], v[52:55], v[210:213], v[4:7]
	v_mfma_f32_16x16x32_bf16 v[4:7], v[222:225], v[0:3], v[182:185]
	v_mfma_f32_16x16x32_bf16 v[8:11], v[226:229], v[194:197], v[4:7]
	v_mfma_f32_16x16x32_bf16 v[4:7], v[222:225], v[198:201], v[186:189]
	v_mfma_f32_16x16x32_bf16 v[12:15], v[226:229], v[210:213], v[4:7]
	v_mfma_f32_16x16x32_bf16 v[0:3], v[230:233], v[0:3], v[214:217]
	v_mfma_f32_16x16x32_bf16 v[4:7], v[230:233], v[198:201], v[132:135]
	v_mfma_f32_16x16x32_bf16 v[0:3], v[242:245], v[194:197], v[0:3]
	v_mfma_f32_16x16x32_bf16 v[4:7], v[242:245], v[210:213], v[4:7]
	s_setprio 0
	s_setprio 1
	v_mfma_f32_16x16x32_bf16 v[32:35], v[36:39], v[234:237], v[32:35]
	v_mfma_f32_16x16x32_bf16 v[48:51], v[36:39], v[202:205], v[218:221]
	v_mfma_f32_16x16x32_bf16 v[60:63], v[40:43], v[238:241], v[32:35]
	v_mfma_f32_16x16x32_bf16 v[32:35], v[44:47], v[202:205], v[136:139]
	v_mfma_f32_16x16x32_bf16 v[56:59], v[40:43], v[206:209], v[48:51]
	v_mfma_f32_16x16x32_bf16 v[48:51], v[52:55], v[206:209], v[32:35]
	v_mfma_f32_16x16x32_bf16 v[32:35], v[44:47], v[234:237], v[140:143]
	v_mfma_f32_16x16x32_bf16 v[52:55], v[52:55], v[238:241], v[32:35]
	v_mfma_f32_16x16x32_bf16 v[32:35], v[222:225], v[202:205], v[144:147]
	v_mfma_f32_16x16x32_bf16 v[40:43], v[226:229], v[206:209], v[32:35]
	v_mfma_f32_16x16x32_bf16 v[32:35], v[222:225], v[234:237], v[152:155]
	v_mfma_f32_16x16x32_bf16 v[44:47], v[226:229], v[238:241], v[32:35]
	v_mfma_f32_16x16x32_bf16 v[32:35], v[230:233], v[202:205], v[156:159]
	v_mfma_f32_16x16x32_bf16 v[36:39], v[230:233], v[234:237], v[190:193]
	v_mfma_f32_16x16x32_bf16 v[32:35], v[242:245], v[206:209], v[32:35]
	v_mfma_f32_16x16x32_bf16 v[36:39], v[242:245], v[238:241], v[36:39]
	s_setprio 0
	s_cmpk_gt_u32 s31, 0xff
	s_barrier
	s_cbranch_scc1 .LBB0_1851
	s_barrier
	s_branch .LBB0_1851

; #define LDA(dst, b, h)                                                                                    \
;   _Pragma("unroll") for (int m = 0; m < 4; ++m) _Pragma("unroll") for (int k = 0; k < 2; ++k)             \
;       dst[m][k] = *reinterpret_cast<const bf16x8*>((char*)SA(b, h) + lds_byte(wr * 64 + m * 16 + fr, k * 32 + fq * 8))
; #define LDB(dst, b, h)                                                                                    \
;   _Pragma("unroll") for (int n = 0; n < 2; ++n) _Pragma("unroll") for (int k = 0; k < 2; ++k)             \
;       dst[n][k] = *reinterpret_cast<const bf16x8*>((char*)SB(b, h) + lds_byte(wc * 32 + n * 16 + fr, k * 32 + fq * 8))
; #define WAIT_V(n) asm volatile("s_waitcnt vmcnt(" #n ")" ::: "memory")
; #define WAIT_L(n) asm volatile("s_waitcnt lgkmcnt(" #n ")" ::: "memory")
; #define BAR __builtin_amdgcn_s_barrier()
; #define SCHED __builtin_amdgcn_sched_barrier(0)
; template <int EPI> ...
;     ...
;     LDB(B0, 0, 0); SCHED; LDA(At, 0, 0); STAGE(SA(1, 1), A, brow + HALF, t + 1);
;     WAIT_L(8); BAR; WAIT_L(0); MMA(0, 0, At, B0); BAR; SCHED;
;     LDB(B1, 0, 1); STAGE(SB(0, 0), Bt, bcol, t + 2);
;     BAR; WAIT_L(0); MMA(0, 1, At, B1); BAR;
;     LDA(At, 0, 1); STAGE(SA(0, 0), A, brow, t + 2);
;     BAR; WAIT_L(0); MMA(1, 0, At, B0); BAR; SCHED;
;     STAGE(SB(0, 1), Bt, bcol + HALF, t + 2);
;     WAIT_V(6); BAR; MMA(1, 1, At, B1); BAR;
.LBB0_1883:
	ds_read_b128 v[162:165], v155
	ds_read_b128 v[174:177], v155 offset:1024
	ds_read_b128 v[178:181], v155 offset:2048
	ds_read_b128 v[182:185], v155 offset:3072
	s_add_u32 s34, s20, s30
	v_add_u32_e32 v156, s67, v154
	v_add_u32_e32 v157, s68, v154
	v_add_u32_e32 v158, s69, v154
	s_addc_u32 s35, s21, s31
	ds_read_b128 v[186:189], v134
	ds_read_b128 v[190:193], v134 offset:1024
	ds_read_b128 v[194:197], v156
	ds_read_b128 v[198:201], v156 offset:1024
	ds_read_b128 v[202:205], v157
	ds_read_b128 v[206:209], v157 offset:1024
	ds_read_b128 v[210:213], v158
	ds_read_b128 v[214:217], v158 offset:1024
	v_add_u32_e32 v159, 0xe000, v129
	v_add_u32_e32 v160, 0xc000, v129
	s_add_u32 m0, s32, 0xc000
	s_add_u32 s98, s34, 0x40080
	s_addc_u32 s99, s35, 0
	global_load_lds_dwordx4 v253, s[98:99]
	s_add_u32 m0, s32, 0xe000
	s_nop 0
	global_load_lds_dwordx4 v252, s[98:99]
	s_waitcnt lgkmcnt(8)
	s_barrier
	s_waitcnt lgkmcnt(0)
	s_setprio 1
	v_mfma_f32_16x16x32_bf16 v[124:127], v[186:189], v[162:165], v[124:127]
	v_mfma_f32_16x16x32_bf16 v[120:123], v[186:189], v[178:181], v[120:123]
	v_mfma_f32_16x16x32_bf16 v[116:119], v[194:197], v[162:165], v[116:119]
	v_mfma_f32_16x16x32_bf16 v[112:115], v[194:197], v[178:181], v[112:115]
	v_mfma_f32_16x16x32_bf16 v[108:111], v[202:205], v[162:165], v[108:111]
	v_mfma_f32_16x16x32_bf16 v[104:107], v[202:205], v[178:181], v[104:107]
	v_mfma_f32_16x16x32_bf16 v[100:103], v[210:213], v[162:165], v[100:103]
	v_mfma_f32_16x16x32_bf16 v[96:99], v[210:213], v[178:181], v[96:99]
	v_mfma_f32_16x16x32_bf16 v[124:127], v[190:193], v[174:177], v[124:127]
	v_mfma_f32_16x16x32_bf16 v[120:123], v[190:193], v[182:185], v[120:123]
	v_mfma_f32_16x16x32_bf16 v[116:119], v[198:201], v[174:177], v[116:119]
	v_mfma_f32_16x16x32_bf16 v[112:115], v[198:201], v[182:185], v[112:115]
	v_mfma_f32_16x16x32_bf16 v[108:111], v[206:209], v[174:177], v[108:111]
	v_mfma_f32_16x16x32_bf16 v[104:107], v[206:209], v[182:185], v[104:107]
	v_mfma_f32_16x16x32_bf16 v[100:103], v[214:217], v[174:177], v[100:103]
	v_mfma_f32_16x16x32_bf16 v[96:99], v[214:217], v[182:185], v[96:99]
	s_setprio 0
	s_barrier
	s_add_u32 s62, s18, s30
	s_addc_u32 s63, s19, s31
	ds_read_b128 v[218:221], v152
	ds_read_b128 v[222:225], v152 offset:1024
	ds_read_b128 v[226:229], v152 offset:2048
	ds_read_b128 v[230:233], v152 offset:3072
	s_add_u32 m0, s32, 0x10000
	s_add_u32 s98, s62, 0x100
	s_addc_u32 s99, s63, 0
	global_load_lds_dwordx4 v253, s[98:99]
	s_add_u32 m0, s32, 0x12000
	s_nop 0
	global_load_lds_dwordx4 v252, s[98:99]
	s_barrier
	s_waitcnt lgkmcnt(0)
	s_setprio 1
	v_mfma_f32_16x16x32_bf16 v[92:95], v[186:189], v[218:221], v[92:95]
	v_mfma_f32_16x16x32_bf16 v[88:91], v[186:189], v[226:229], v[88:91]
	v_mfma_f32_16x16x32_bf16 v[84:87], v[194:197], v[218:221], v[84:87]
	v_mfma_f32_16x16x32_bf16 v[80:83], v[194:197], v[226:229], v[80:83]
	v_mfma_f32_16x16x32_bf16 v[76:79], v[202:205], v[218:221], v[76:79]
	v_mfma_f32_16x16x32_bf16 v[72:75], v[202:205], v[226:229], v[72:75]
	v_mfma_f32_16x16x32_bf16 v[68:71], v[210:213], v[218:221], v[68:71]
	v_mfma_f32_16x16x32_bf16 v[64:67], v[210:213], v[226:229], v[64:67]
	v_mfma_f32_16x16x32_bf16 v[92:95], v[190:193], v[222:225], v[92:95]
	v_mfma_f32_16x16x32_bf16 v[88:91], v[190:193], v[230:233], v[88:91]
	v_mfma_f32_16x16x32_bf16 v[84:87], v[198:201], v[222:225], v[84:87]
	v_mfma_f32_16x16x32_bf16 v[80:83], v[198:201], v[230:233], v[80:83]
	v_mfma_f32_16x16x32_bf16 v[76:79], v[206:209], v[222:225], v[76:79]
	v_mfma_f32_16x16x32_bf16 v[72:75], v[206:209], v[230:233], v[72:75]
	v_mfma_f32_16x16x32_bf16 v[68:71], v[214:217], v[222:225], v[68:71]
	v_mfma_f32_16x16x32_bf16 v[64:67], v[214:217], v[230:233], v[64:67]
	s_setprio 0
	s_barrier
	ds_read_b128 v[186:189], v134 offset:16384
	ds_read_b128 v[190:193], v134 offset:17408
	ds_read_b128 v[194:197], v156 offset:16384
	ds_read_b128 v[198:201], v156 offset:17408
	ds_read_b128 v[202:205], v157 offset:16384
	ds_read_b128 v[206:209], v157 offset:17408
	ds_read_b128 v[210:213], v158 offset:16384
	ds_read_b128 v[214:217], v158 offset:17408
	s_mov_b32 m0, s32
	s_add_u32 s98, s34, 0x100
	s_addc_u32 s99, s35, 0
	global_load_lds_dwordx4 v253, s[98:99]
	s_add_u32 m0, s32, 0x2000
	s_nop 0
	global_load_lds_dwordx4 v252, s[98:99]
	s_barrier
	s_waitcnt lgkmcnt(0)
	s_setprio 1
	v_mfma_f32_16x16x32_bf16 v[60:63], v[186:189], v[162:165], v[60:63]
	v_mfma_f32_16x16x32_bf16 v[56:59], v[186:189], v[178:181], v[56:59]
	v_mfma_f32_16x16x32_bf16 v[52:55], v[194:197], v[162:165], v[52:55]
	v_mfma_f32_16x16x32_bf16 v[48:51], v[194:197], v[178:181], v[48:51]
	v_mfma_f32_16x16x32_bf16 v[44:47], v[202:205], v[162:165], v[44:47]
	v_mfma_f32_16x16x32_bf16 v[40:43], v[202:205], v[178:181], v[40:43]
	v_mfma_f32_16x16x32_bf16 v[36:39], v[210:213], v[162:165], v[36:39]
	v_mfma_f32_16x16x32_bf16 v[32:35], v[210:213], v[178:181], v[32:35]
	v_mfma_f32_16x16x32_bf16 v[60:63], v[190:193], v[174:177], v[60:63]
	v_mfma_f32_16x16x32_bf16 v[56:59], v[190:193], v[182:185], v[56:59]
	v_mfma_f32_16x16x32_bf16 v[52:55], v[198:201], v[174:177], v[52:55]
	v_mfma_f32_16x16x32_bf16 v[48:51], v[198:201], v[182:185], v[48:51]
	v_mfma_f32_16x16x32_bf16 v[44:47], v[206:209], v[174:177], v[44:47]
	v_mfma_f32_16x16x32_bf16 v[40:43], v[206:209], v[182:185], v[40:43]
	v_mfma_f32_16x16x32_bf16 v[36:39], v[214:217], v[174:177], v[36:39]
	v_mfma_f32_16x16x32_bf16 v[32:35], v[214:217], v[182:185], v[32:35]
	s_setprio 0
	s_barrier
	s_add_u32 m0, s32, 0x14000
	s_add_u32 s98, s62, 0x40100
	s_addc_u32 s99, s63, 0
	global_load_lds_dwordx4 v253, s[98:99]
	s_add_u32 m0, s32, 0x16000
	s_nop 0
	global_load_lds_dwordx4 v252, s[98:99]
	s_waitcnt vmcnt(6)
	s_barrier
; #define LDA(dst, b, h)                                                                                    \
;   _Pragma("unroll") for (int m = 0; m < 4; ++m) _Pragma("unroll") for (int k = 0; k < 2; ++k)             \
;       dst[m][k] = *reinterpret_cast<const bf16x8*>((char*)SA(b, h) + lds_byte(wr * 64 + m * 16 + fr, k * 32 + fq * 8))
; #define LDB(dst, b, h)                                                                                    \
;   _Pragma("unroll") for (int n = 0; n < 2; ++n) _Pragma("unroll") for (int k = 0; k < 2; ++k)             \
;       dst[n][k] = *reinterpret_cast<const bf16x8*>((char*)SB(b, h) + lds_byte(wc * 32 + n * 16 + fr, k * 32 + fq * 8))
; #define WAIT_V(n) asm volatile("s_waitcnt vmcnt(" #n ")" ::: "memory")
; #define WAIT_L(n) asm volatile("s_waitcnt lgkmcnt(" #n ")" ::: "memory")
; #define BAR __builtin_amdgcn_s_barrier()
; #define SCHED __builtin_amdgcn_sched_barrier(0)
; template <int EPI> ...
;     ...
;     WAIT_V(6); BAR; MMA(1, 1, At, B1); BAR;
;     LDB(B0, 1, 0); SCHED; LDA(At, 1, 0); STAGE(SA(0, 1), A, brow + HALF, t + 2);
;     WAIT_L(8); BAR; WAIT_L(0); MMA(0, 0, At, B0); BAR; SCHED;
;     LDB(B1, 1, 1); STAGE(SB(1, 0), Bt, bcol, t + 3);
;     BAR; WAIT_L(0); MMA(0, 1, At, B1); BAR;
;     LDA(At, 1, 1); STAGE(SA(1, 0), A, brow, t + 3);
	s_setprio 1
	v_mfma_f32_16x16x32_bf16 v[28:31], v[186:189], v[218:221], v[28:31]
	v_mfma_f32_16x16x32_bf16 v[24:27], v[186:189], v[226:229], v[24:27]
	v_mfma_f32_16x16x32_bf16 v[20:23], v[194:197], v[218:221], v[20:23]
	v_mfma_f32_16x16x32_bf16 v[16:19], v[194:197], v[226:229], v[16:19]
	v_mfma_f32_16x16x32_bf16 v[12:15], v[202:205], v[218:221], v[12:15]
	v_mfma_f32_16x16x32_bf16 v[8:11], v[202:205], v[226:229], v[8:11]
	v_mfma_f32_16x16x32_bf16 v[4:7], v[210:213], v[218:221], v[4:7]
	v_mfma_f32_16x16x32_bf16 v[0:3], v[210:213], v[226:229], v[0:3]
	v_mfma_f32_16x16x32_bf16 v[28:31], v[190:193], v[222:225], v[28:31]
	v_mfma_f32_16x16x32_bf16 v[24:27], v[190:193], v[230:233], v[24:27]
	v_mfma_f32_16x16x32_bf16 v[20:23], v[198:201], v[222:225], v[20:23]
	v_mfma_f32_16x16x32_bf16 v[16:19], v[198:201], v[230:233], v[16:19]
	v_mfma_f32_16x16x32_bf16 v[12:15], v[206:209], v[222:225], v[12:15]
	v_mfma_f32_16x16x32_bf16 v[8:11], v[206:209], v[230:233], v[8:11]
	v_mfma_f32_16x16x32_bf16 v[4:7], v[214:217], v[222:225], v[4:7]
	v_mfma_f32_16x16x32_bf16 v[0:3], v[214:217], v[230:233], v[0:3]
	s_setprio 0
	s_barrier
	ds_read_b128 v[162:165], v139
	ds_read_b128 v[174:177], v139 offset:1024
	ds_read_b128 v[178:181], v139 offset:2048
	ds_read_b128 v[182:185], v139 offset:3072
	ds_read_b128 v[186:189], v134 offset:32768
	ds_read_b128 v[190:193], v134 offset:33792
	ds_read_b128 v[194:197], v156 offset:32768
	ds_read_b128 v[198:201], v156 offset:33792
	ds_read_b128 v[202:205], v157 offset:32768
	ds_read_b128 v[206:209], v157 offset:33792
	ds_read_b128 v[210:213], v158 offset:32768
	ds_read_b128 v[214:217], v158 offset:33792
	s_add_u32 m0, s32, 0x4000
	s_add_u32 s98, s34, 0x40100
	s_addc_u32 s99, s35, 0
	global_load_lds_dwordx4 v253, s[98:99]
	s_add_u32 m0, s32, 0x6000
	s_nop 0
	global_load_lds_dwordx4 v252, s[98:99]
	s_waitcnt lgkmcnt(8)
	s_barrier
	s_waitcnt lgkmcnt(0)
	s_setprio 1
	v_mfma_f32_16x16x32_bf16 v[124:127], v[186:189], v[162:165], v[124:127]
	v_mfma_f32_16x16x32_bf16 v[120:123], v[186:189], v[178:181], v[120:123]
	v_mfma_f32_16x16x32_bf16 v[116:119], v[194:197], v[162:165], v[116:119]
	v_mfma_f32_16x16x32_bf16 v[112:115], v[194:197], v[178:181], v[112:115]
	v_mfma_f32_16x16x32_bf16 v[108:111], v[202:205], v[162:165], v[108:111]
	v_mfma_f32_16x16x32_bf16 v[104:107], v[202:205], v[178:181], v[104:107]
	v_mfma_f32_16x16x32_bf16 v[100:103], v[210:213], v[162:165], v[100:103]
	v_mfma_f32_16x16x32_bf16 v[96:99], v[210:213], v[178:181], v[96:99]
	v_mfma_f32_16x16x32_bf16 v[124:127], v[190:193], v[174:177], v[124:127]
	v_mfma_f32_16x16x32_bf16 v[120:123], v[190:193], v[182:185], v[120:123]
	v_mfma_f32_16x16x32_bf16 v[116:119], v[198:201], v[174:177], v[116:119]
	v_mfma_f32_16x16x32_bf16 v[112:115], v[198:201], v[182:185], v[112:115]
	v_mfma_f32_16x16x32_bf16 v[108:111], v[206:209], v[174:177], v[108:111]
	v_mfma_f32_16x16x32_bf16 v[104:107], v[206:209], v[182:185], v[104:107]
	v_mfma_f32_16x16x32_bf16 v[100:103], v[214:217], v[174:177], v[100:103]
	v_mfma_f32_16x16x32_bf16 v[96:99], v[214:217], v[182:185], v[96:99]
	s_setprio 0
	s_barrier
	ds_read_b128 v[218:221], v136
	ds_read_b128 v[222:225], v136 offset:1024
	ds_read_b128 v[226:229], v136 offset:2048
	ds_read_b128 v[230:233], v136 offset:3072
	s_add_u32 m0, s32, 0x18000
	s_add_u32 s98, s62, 0x180
	s_addc_u32 s99, s63, 0
	global_load_lds_dwordx4 v253, s[98:99]
	s_add_u32 m0, s32, 0x1a000
	s_nop 0
	global_load_lds_dwordx4 v252, s[98:99]
	s_barrier
	s_waitcnt lgkmcnt(0)
	s_setprio 1
	v_mfma_f32_16x16x32_bf16 v[92:95], v[186:189], v[218:221], v[92:95]
	v_mfma_f32_16x16x32_bf16 v[88:91], v[186:189], v[226:229], v[88:91]
	v_mfma_f32_16x16x32_bf16 v[84:87], v[194:197], v[218:221], v[84:87]
	v_mfma_f32_16x16x32_bf16 v[80:83], v[194:197], v[226:229], v[80:83]
	v_mfma_f32_16x16x32_bf16 v[76:79], v[202:205], v[218:221], v[76:79]
	v_mfma_f32_16x16x32_bf16 v[72:75], v[202:205], v[226:229], v[72:75]
	v_mfma_f32_16x16x32_bf16 v[68:71], v[210:213], v[218:221], v[68:71]
	v_mfma_f32_16x16x32_bf16 v[64:67], v[210:213], v[226:229], v[64:67]
	v_mfma_f32_16x16x32_bf16 v[92:95], v[190:193], v[222:225], v[92:95]
	v_mfma_f32_16x16x32_bf16 v[88:91], v[190:193], v[230:233], v[88:91]
	v_mfma_f32_16x16x32_bf16 v[84:87], v[198:201], v[222:225], v[84:87]
	v_mfma_f32_16x16x32_bf16 v[80:83], v[198:201], v[230:233], v[80:83]
	v_mfma_f32_16x16x32_bf16 v[76:79], v[206:209], v[222:225], v[76:79]
	v_mfma_f32_16x16x32_bf16 v[72:75], v[206:209], v[230:233], v[72:75]
	v_mfma_f32_16x16x32_bf16 v[68:71], v[214:217], v[222:225], v[68:71]
	v_mfma_f32_16x16x32_bf16 v[64:67], v[214:217], v[230:233], v[64:67]
	s_setprio 0
	s_barrier
	ds_read_b128 v[186:189], v134 offset:49152
	ds_read_b128 v[190:193], v134 offset:50176
	ds_read_b128 v[194:197], v156 offset:49152
	ds_read_b128 v[198:201], v156 offset:50176
	ds_read_b128 v[202:205], v157 offset:49152
	ds_read_b128 v[206:209], v157 offset:50176
	ds_read_b128 v[210:213], v158 offset:49152
	ds_read_b128 v[214:217], v158 offset:50176
	s_add_u32 m0, s32, 0x8000
	s_add_u32 s98, s34, 0x180
	s_addc_u32 s99, s35, 0
	global_load_lds_dwordx4 v253, s[98:99]
	s_nop 0
	s_add_u32 m0, s32, 0xa000
	s_nop 0
	global_load_lds_dwordx4 v252, s[98:99]
	s_barrier
; #define LDA(dst, b, h)                                                                                    \
;   _Pragma("unroll") for (int m = 0; m < 4; ++m) _Pragma("unroll") for (int k = 0; k < 2; ++k)             \
;       dst[m][k] = *reinterpret_cast<const bf16x8*>((char*)SA(b, h) + lds_byte(wr * 64 + m * 16 + fr, k * 32 + fq * 8))
; #define LDB(dst, b, h)                                                                                    \
;   _Pragma("unroll") for (int n = 0; n < 2; ++n) _Pragma("unroll") for (int k = 0; k < 2; ++k)             \
;       dst[n][k] = *reinterpret_cast<const bf16x8*>((char*)SB(b, h) + lds_byte(wc * 32 + n * 16 + fr, k * 32 + fq * 8))
; #define WAIT_V(n) asm volatile("s_waitcnt vmcnt(" #n ")" ::: "memory")
; #define WAIT_L(n) asm volatile("s_waitcnt lgkmcnt(" #n ")" ::: "memory")
; #define BAR __builtin_amdgcn_s_barrier()
; #define SCHED __builtin_amdgcn_sched_barrier(0)
; template <int EPI> ...
;     ...
;     BAR; WAIT_L(0); MMA(1, 0, At, B0); BAR; SCHED;
;     STAGE(SB(1, 1), Bt, bcol + HALF, t + 3);
;     WAIT_V(6); BAR; MMA(1, 1, At, B1); BAR;
;   }
;   {
;     LDB(B0, 0, 0); LDA(At, 0, 0); STAGE(SA(1, 1), A, brow + HALF, nt - 1);
;     BAR; WAIT_L(0); MMA(0, 0, At, B0); BAR;
;     LDB(B1, 0, 1); BAR; WAIT_L(0); MMA(0, 1, At, B1); BAR;
	s_waitcnt lgkmcnt(0)
	s_setprio 1
	v_mfma_f32_16x16x32_bf16 v[60:63], v[186:189], v[162:165], v[60:63]
	v_mfma_f32_16x16x32_bf16 v[56:59], v[186:189], v[178:181], v[56:59]
	v_mfma_f32_16x16x32_bf16 v[52:55], v[194:197], v[162:165], v[52:55]
	v_mfma_f32_16x16x32_bf16 v[48:51], v[194:197], v[178:181], v[48:51]
	v_mfma_f32_16x16x32_bf16 v[44:47], v[202:205], v[162:165], v[44:47]
	v_mfma_f32_16x16x32_bf16 v[40:43], v[202:205], v[178:181], v[40:43]
	v_mfma_f32_16x16x32_bf16 v[36:39], v[210:213], v[162:165], v[36:39]
	v_mfma_f32_16x16x32_bf16 v[32:35], v[210:213], v[178:181], v[32:35]
	v_mfma_f32_16x16x32_bf16 v[60:63], v[190:193], v[174:177], v[60:63]
	v_mfma_f32_16x16x32_bf16 v[56:59], v[190:193], v[182:185], v[56:59]
	v_mfma_f32_16x16x32_bf16 v[52:55], v[198:201], v[174:177], v[52:55]
	v_mfma_f32_16x16x32_bf16 v[48:51], v[198:201], v[182:185], v[48:51]
	v_mfma_f32_16x16x32_bf16 v[44:47], v[206:209], v[174:177], v[44:47]
	v_mfma_f32_16x16x32_bf16 v[40:43], v[206:209], v[182:185], v[40:43]
	v_mfma_f32_16x16x32_bf16 v[36:39], v[214:217], v[174:177], v[36:39]
	v_mfma_f32_16x16x32_bf16 v[32:35], v[214:217], v[182:185], v[32:35]
	s_setprio 0
	s_barrier
	s_add_u32 m0, s32, 0x1c000
	s_add_u32 s98, s62, 0x40180
	s_addc_u32 s99, s63, 0
	global_load_lds_dwordx4 v253, s[98:99]
	s_add_u32 m0, s32, 0x1e000
	s_nop 0
	global_load_lds_dwordx4 v252, s[98:99]
	s_waitcnt vmcnt(6)
	s_barrier
	s_setprio 1
	v_mfma_f32_16x16x32_bf16 v[28:31], v[186:189], v[218:221], v[28:31]
	v_mfma_f32_16x16x32_bf16 v[24:27], v[186:189], v[226:229], v[24:27]
	v_mfma_f32_16x16x32_bf16 v[20:23], v[194:197], v[218:221], v[20:23]
	v_mfma_f32_16x16x32_bf16 v[16:19], v[194:197], v[226:229], v[16:19]
	v_mfma_f32_16x16x32_bf16 v[12:15], v[202:205], v[218:221], v[12:15]
	v_mfma_f32_16x16x32_bf16 v[8:11], v[202:205], v[226:229], v[8:11]
	v_mfma_f32_16x16x32_bf16 v[4:7], v[210:213], v[218:221], v[4:7]
	v_mfma_f32_16x16x32_bf16 v[0:3], v[210:213], v[226:229], v[0:3]
	v_mfma_f32_16x16x32_bf16 v[28:31], v[190:193], v[222:225], v[28:31]
	v_mfma_f32_16x16x32_bf16 v[24:27], v[190:193], v[230:233], v[24:27]
	v_mfma_f32_16x16x32_bf16 v[20:23], v[198:201], v[222:225], v[20:23]
	v_mfma_f32_16x16x32_bf16 v[16:19], v[198:201], v[230:233], v[16:19]
	v_mfma_f32_16x16x32_bf16 v[12:15], v[206:209], v[222:225], v[12:15]
	v_mfma_f32_16x16x32_bf16 v[8:11], v[206:209], v[230:233], v[8:11]
	v_mfma_f32_16x16x32_bf16 v[4:7], v[214:217], v[222:225], v[4:7]
	v_mfma_f32_16x16x32_bf16 v[0:3], v[214:217], v[230:233], v[0:3]
	s_setprio 0
	s_add_i32 s70, s70, 2
	s_add_u32 s30, s30, 0x100
	s_addc_u32 s31, s31, 0
	s_cmp_lt_u32 s70, 12
	s_barrier
	s_cbranch_scc1 .LBB0_1883
	ds_read_b128 v[144:147], v155
	ds_read_b128 v[162:165], v155 offset:1024
	ds_read_b128 v[174:177], v155 offset:2048
	ds_read_b128 v[178:181], v155 offset:3072
	ds_read_b128 v[182:185], v134
	ds_read_b128 v[186:189], v134 offset:1024
	ds_read_b128 v[190:193], v156
	ds_read_b128 v[194:197], v156 offset:1024
	ds_read_b128 v[198:201], v157
	ds_read_b128 v[202:205], v157 offset:1024
	ds_read_b128 v[206:209], v158
	ds_read_b128 v[210:213], v158 offset:1024
	v_mov_b32_e32 v129, v149
	v_lshl_add_u64 v[128:129], v[128:129], 1, s[22:23]
	s_mov_b64 s[20:21], 0x780
	v_readfirstlane_b32 s18, v160
	v_lshl_add_u64 v[128:129], v[128:129], 0, s[20:21]
	s_mov_b32 m0, s18
	v_mov_b32_e32 v131, v149
	global_load_lds_dwordx4 v[128:129], off
	v_readfirstlane_b32 s18, v159
	v_lshl_add_u64 v[128:129], v[130:131], 1, s[22:23]
	v_lshl_add_u64 v[128:129], v[128:129], 0, s[20:21]
	s_mov_b32 m0, s18
	s_nop 0
	global_load_lds_dwordx4 v[128:129], off
	s_barrier
	s_waitcnt lgkmcnt(0)
	s_setprio 1
	v_mfma_f32_16x16x32_bf16 v[124:127], v[182:185], v[144:147], v[124:127]
	v_mfma_f32_16x16x32_bf16 v[120:123], v[182:185], v[174:177], v[120:123]
	v_mfma_f32_16x16x32_bf16 v[116:119], v[190:193], v[144:147], v[116:119]
	v_mfma_f32_16x16x32_bf16 v[112:115], v[190:193], v[174:177], v[112:115]
	v_mfma_f32_16x16x32_bf16 v[108:111], v[198:201], v[144:147], v[108:111]
	v_mfma_f32_16x16x32_bf16 v[104:107], v[198:201], v[174:177], v[104:107]
	v_mfma_f32_16x16x32_bf16 v[96:99], v[206:209], v[174:177], v[96:99]
	v_mfma_f32_16x16x32_bf16 v[124:127], v[186:189], v[162:165], v[124:127]
	v_mfma_f32_16x16x32_bf16 v[120:123], v[186:189], v[178:181], v[120:123]
	v_mfma_f32_16x16x32_bf16 v[116:119], v[194:197], v[162:165], v[116:119]
	v_mfma_f32_16x16x32_bf16 v[112:115], v[194:197], v[178:181], v[112:115]
	v_mfma_f32_16x16x32_bf16 v[108:111], v[202:205], v[162:165], v[108:111]
	v_mfma_f32_16x16x32_bf16 v[104:107], v[202:205], v[178:181], v[104:107]
	v_mfma_f32_16x16x32_bf16 v[100:103], v[206:209], v[144:147], v[100:103]
	v_mfma_f32_16x16x32_bf16 v[96:99], v[210:213], v[178:181], v[96:99]
	v_mfma_f32_16x16x32_bf16 v[128:131], v[210:213], v[162:165], v[100:103]
	s_setprio 0
	s_barrier
	s_nop 3
	ds_read_b128 v[100:103], v152
	ds_read_b128 v[214:217], v152 offset:1024
	ds_read_b128 v[218:221], v152 offset:2048
	ds_read_b128 v[152:155], v152 offset:3072
	s_barrier
	s_waitcnt lgkmcnt(0)
	s_setprio 1
	v_mfma_f32_16x16x32_bf16 v[88:91], v[182:185], v[218:221], v[88:91]
	v_mfma_f32_16x16x32_bf16 v[92:95], v[182:185], v[100:103], v[92:95]
	v_mfma_f32_16x16x32_bf16 v[88:91], v[186:189], v[152:155], v[88:91]
	v_mfma_f32_16x16x32_bf16 v[84:87], v[190:193], v[100:103], v[84:87]
	v_mfma_f32_16x16x32_bf16 v[80:83], v[190:193], v[218:221], v[80:83]
	v_mfma_f32_16x16x32_bf16 v[76:79], v[198:201], v[100:103], v[76:79]
	v_mfma_f32_16x16x32_bf16 v[72:75], v[198:201], v[218:221], v[72:75]
	v_mfma_f32_16x16x32_bf16 v[68:71], v[206:209], v[100:103], v[68:71]
	v_mfma_f32_16x16x32_bf16 v[64:67], v[206:209], v[218:221], v[64:67]
	v_mfma_f32_16x16x32_bf16 v[222:225], v[186:189], v[214:217], v[92:95]
	v_mfma_f32_16x16x32_bf16 v[182:185], v[194:197], v[214:217], v[84:87]
	v_mfma_f32_16x16x32_bf16 v[186:189], v[194:197], v[152:155], v[80:83]
	v_mfma_f32_16x16x32_bf16 v[190:193], v[202:205], v[214:217], v[76:79]
	v_mfma_f32_16x16x32_bf16 v[194:197], v[202:205], v[152:155], v[72:75]
	v_mfma_f32_16x16x32_bf16 v[198:201], v[210:213], v[214:217], v[68:71]
	v_mfma_f32_16x16x32_bf16 v[202:205], v[210:213], v[152:155], v[64:67]
	s_setprio 0
	s_barrier
; #define LDA(dst, b, h)                                                                                    \
;   _Pragma("unroll") for (int m = 0; m < 4; ++m) _Pragma("unroll") for (int k = 0; k < 2; ++k)             \
;       dst[m][k] = *reinterpret_cast<const bf16x8*>((char*)SA(b, h) + lds_byte(wr * 64 + m * 16 + fr, k * 32 + fq * 8))
; #define LDB(dst, b, h)                                                                                    \
;   _Pragma("unroll") for (int n = 0; n < 2; ++n) _Pragma("unroll") for (int k = 0; k < 2; ++k)             \
;       dst[n][k] = *reinterpret_cast<const bf16x8*>((char*)SB(b, h) + lds_byte(wc * 32 + n * 16 + fr, k * 32 + fq * 8))
; #define WAIT_V(n) asm volatile("s_waitcnt vmcnt(" #n ")" ::: "memory")
; #define WAIT_L(n) asm volatile("s_waitcnt lgkmcnt(" #n ")" ::: "memory")
; #define BAR __builtin_amdgcn_s_barrier()
; template <int EPI> ...
;     ...
;     LDA(At, 0, 1); WAIT_V(4); BAR; WAIT_L(0); MMA(1, 0, At, B0); MMA(1, 1, At, B1); BAR;
;   }
;   {
;     LDB(B0, 1, 0); LDA(At, 1, 0); WAIT_V(2); BAR; WAIT_L(0); MMA(0, 0, At, B0); BAR;
	s_nop 0
	ds_read_b128 v[64:67], v134 offset:16384
	ds_read_b128 v[68:71], v134 offset:17408
	ds_read_b128 v[72:75], v156 offset:16384
	ds_read_b128 v[76:79], v156 offset:17408
	ds_read_b128 v[80:83], v157 offset:16384
	ds_read_b128 v[84:87], v157 offset:17408
	ds_read_b128 v[92:95], v158 offset:16384
	ds_read_b128 v[206:209], v158 offset:17408
	s_waitcnt vmcnt(4)
	s_barrier
	s_waitcnt lgkmcnt(0)
	s_setprio 1
	v_mfma_f32_16x16x32_bf16 v[60:63], v[64:67], v[144:147], v[60:63]
	v_mfma_f32_16x16x32_bf16 v[56:59], v[64:67], v[174:177], v[56:59]
	v_mfma_f32_16x16x32_bf16 v[52:55], v[72:75], v[144:147], v[52:55]
	v_mfma_f32_16x16x32_bf16 v[48:51], v[72:75], v[174:177], v[48:51]
	v_mfma_f32_16x16x32_bf16 v[44:47], v[80:83], v[144:147], v[44:47]
	v_mfma_f32_16x16x32_bf16 v[40:43], v[80:83], v[174:177], v[40:43]
	v_mfma_f32_16x16x32_bf16 v[36:39], v[92:95], v[144:147], v[36:39]
	v_mfma_f32_16x16x32_bf16 v[32:35], v[92:95], v[174:177], v[32:35]
	v_mfma_f32_16x16x32_bf16 v[60:63], v[68:71], v[162:165], v[60:63]
	v_mfma_f32_16x16x32_bf16 v[56:59], v[68:71], v[178:181], v[56:59]
	v_mfma_f32_16x16x32_bf16 v[52:55], v[76:79], v[162:165], v[52:55]
	v_mfma_f32_16x16x32_bf16 v[48:51], v[76:79], v[178:181], v[48:51]
	v_mfma_f32_16x16x32_bf16 v[44:47], v[84:87], v[162:165], v[44:47]
	v_mfma_f32_16x16x32_bf16 v[40:43], v[84:87], v[178:181], v[40:43]
	v_mfma_f32_16x16x32_bf16 v[36:39], v[206:209], v[162:165], v[36:39]
	v_mfma_f32_16x16x32_bf16 v[32:35], v[206:209], v[178:181], v[32:35]
	s_setprio 0
	s_setprio 1
	v_mfma_f32_16x16x32_bf16 v[28:31], v[64:67], v[100:103], v[28:31]
	v_mfma_f32_16x16x32_bf16 v[24:27], v[64:67], v[218:221], v[24:27]
	v_mfma_f32_16x16x32_bf16 v[20:23], v[72:75], v[100:103], v[20:23]
	v_mfma_f32_16x16x32_bf16 v[16:19], v[72:75], v[218:221], v[16:19]
	v_mfma_f32_16x16x32_bf16 v[12:15], v[80:83], v[100:103], v[12:15]
	v_mfma_f32_16x16x32_bf16 v[8:11], v[80:83], v[218:221], v[8:11]
	v_mfma_f32_16x16x32_bf16 v[4:7], v[92:95], v[100:103], v[4:7]
	v_mfma_f32_16x16x32_bf16 v[0:3], v[92:95], v[218:221], v[0:3]
	v_mfma_f32_16x16x32_bf16 v[144:147], v[68:71], v[214:217], v[28:31]
	v_mfma_f32_16x16x32_bf16 v[160:163], v[68:71], v[152:155], v[24:27]
	v_mfma_f32_16x16x32_bf16 v[164:167], v[76:79], v[214:217], v[20:23]
	v_mfma_f32_16x16x32_bf16 v[174:177], v[76:79], v[152:155], v[16:19]
	v_mfma_f32_16x16x32_bf16 v[178:181], v[84:87], v[214:217], v[12:15]
	v_mfma_f32_16x16x32_bf16 v[210:213], v[84:87], v[152:155], v[8:11]
	v_mfma_f32_16x16x32_bf16 v[214:217], v[206:209], v[214:217], v[4:7]
	v_mfma_f32_16x16x32_bf16 v[152:155], v[206:209], v[152:155], v[0:3]
	s_setprio 0
	s_barrier
	s_nop 0
	ds_read_b128 v[0:3], v139
	ds_read_b128 v[4:7], v139 offset:1024
	ds_read_b128 v[206:209], v139 offset:2048
	ds_read_b128 v[138:141], v139 offset:3072
	ds_read_b128 v[8:11], v134 offset:32768
	ds_read_b128 v[12:15], v134 offset:33792
	ds_read_b128 v[16:19], v156 offset:32768
	ds_read_b128 v[20:23], v156 offset:33792
	ds_read_b128 v[24:27], v157 offset:32768
	ds_read_b128 v[28:31], v157 offset:33792
	ds_read_b128 v[218:221], v158 offset:32768
	ds_read_b128 v[226:229], v158 offset:33792
	s_waitcnt vmcnt(2)
	s_barrier
	s_waitcnt lgkmcnt(0)
	s_setprio 1
	v_mfma_f32_16x16x32_bf16 v[64:67], v[8:11], v[0:3], v[124:127]
	v_mfma_f32_16x16x32_bf16 v[92:95], v[12:15], v[4:7], v[64:67]
	v_mfma_f32_16x16x32_bf16 v[64:67], v[8:11], v[206:209], v[120:123]
	v_mfma_f32_16x16x32_bf16 v[100:103], v[12:15], v[138:141], v[64:67]
	v_mfma_f32_16x16x32_bf16 v[64:67], v[16:19], v[0:3], v[116:119]
	v_mfma_f32_16x16x32_bf16 v[80:83], v[20:23], v[4:7], v[64:67]
	v_mfma_f32_16x16x32_bf16 v[64:67], v[16:19], v[206:209], v[112:115]
	v_mfma_f32_16x16x32_bf16 v[84:87], v[20:23], v[138:141], v[64:67]
	v_mfma_f32_16x16x32_bf16 v[64:67], v[24:27], v[0:3], v[108:111]
	v_mfma_f32_16x16x32_bf16 v[72:75], v[28:31], v[4:7], v[64:67]
	v_mfma_f32_16x16x32_bf16 v[64:67], v[24:27], v[206:209], v[104:107]
	v_mfma_f32_16x16x32_bf16 v[76:79], v[28:31], v[138:141], v[64:67]
	v_mfma_f32_16x16x32_bf16 v[64:67], v[218:221], v[0:3], v[128:131]
	v_mfma_f32_16x16x32_bf16 v[68:71], v[218:221], v[206:209], v[96:99]
	v_mfma_f32_16x16x32_bf16 v[64:67], v[226:229], v[4:7], v[64:67]
	v_mfma_f32_16x16x32_bf16 v[68:71], v[226:229], v[138:141], v[68:71]
	s_setprio 0
	s_barrier
; #define LDA(dst, b, h)                                                                                    \
;   _Pragma("unroll") for (int m = 0; m < 4; ++m) _Pragma("unroll") for (int k = 0; k < 2; ++k)             \
;       dst[m][k] = *reinterpret_cast<const bf16x8*>((char*)SA(b, h) + lds_byte(wr * 64 + m * 16 + fr, k * 32 + fq * 8))
; #define LDB(dst, b, h)                                                                                    \
;   _Pragma("unroll") for (int n = 0; n < 2; ++n) _Pragma("unroll") for (int k = 0; k < 2; ++k)             \
;       dst[n][k] = *reinterpret_cast<const bf16x8*>((char*)SB(b, h) + lds_byte(wc * 32 + n * 16 + fr, k * 32 + fq * 8))
; #define WAIT_V(n) asm volatile("s_waitcnt vmcnt(" #n ")" ::: "memory")
; #define WAIT_L(n) asm volatile("s_waitcnt lgkmcnt(" #n ")" ::: "memory")
; #define BAR __builtin_amdgcn_s_barrier()
; template <int EPI> ...
;     ...
;     LDB(B1, 1, 1); WAIT_V(0); BAR; WAIT_L(0); MMA(0, 1, At, B1); BAR;
;     LDA(At, 1, 1); BAR; WAIT_L(0); MMA(1, 0, At, B0); MMA(1, 1, At, B1); BAR;
;   }
;   if (wr == 0) BAR;
	ds_read_b128 v[128:131], v136
	ds_read_b128 v[230:233], v136 offset:1024
	ds_read_b128 v[234:237], v136 offset:2048
	ds_read_b128 v[238:241], v136 offset:3072
	s_waitcnt vmcnt(0)
	s_barrier
	s_waitcnt lgkmcnt(0)
	s_setprio 1
	v_mfma_f32_16x16x32_bf16 v[96:99], v[8:11], v[128:131], v[222:225]
	v_mfma_f32_16x16x32_bf16 v[8:11], v[8:11], v[234:237], v[88:91]
	v_mfma_f32_16x16x32_bf16 v[124:127], v[12:15], v[238:241], v[8:11]
	v_mfma_f32_16x16x32_bf16 v[8:11], v[16:19], v[128:131], v[182:185]
	v_mfma_f32_16x16x32_bf16 v[112:115], v[20:23], v[230:233], v[8:11]
	v_mfma_f32_16x16x32_bf16 v[8:11], v[16:19], v[234:237], v[186:189]
	v_mfma_f32_16x16x32_bf16 v[116:119], v[20:23], v[238:241], v[8:11]
	v_mfma_f32_16x16x32_bf16 v[8:11], v[24:27], v[128:131], v[190:193]
	v_mfma_f32_16x16x32_bf16 v[104:107], v[28:31], v[230:233], v[8:11]
	v_mfma_f32_16x16x32_bf16 v[8:11], v[24:27], v[234:237], v[194:197]
	v_mfma_f32_16x16x32_bf16 v[108:111], v[28:31], v[238:241], v[8:11]
	v_mfma_f32_16x16x32_bf16 v[8:11], v[218:221], v[128:131], v[198:201]
	v_mfma_f32_16x16x32_bf16 v[88:91], v[226:229], v[230:233], v[8:11]
	v_mfma_f32_16x16x32_bf16 v[8:11], v[218:221], v[234:237], v[202:205]
	v_mfma_f32_16x16x32_bf16 v[120:123], v[12:15], v[230:233], v[96:99]
	v_mfma_f32_16x16x32_bf16 v[96:99], v[226:229], v[238:241], v[8:11]
	s_setprio 0
	s_barrier
	ds_read_b128 v[182:185], v134 offset:49152
	ds_read_b128 v[134:137], v134 offset:50176
	ds_read_b128 v[186:189], v156 offset:49152
	ds_read_b128 v[190:193], v156 offset:50176
	ds_read_b128 v[194:197], v157 offset:49152
	ds_read_b128 v[198:201], v157 offset:50176
	ds_read_b128 v[202:205], v158 offset:49152
	ds_read_b128 v[156:159], v158 offset:50176
	s_barrier
	s_waitcnt lgkmcnt(0)
	s_setprio 1
	v_mfma_f32_16x16x32_bf16 v[8:11], v[182:185], v[0:3], v[60:63]
	v_mfma_f32_16x16x32_bf16 v[24:27], v[134:137], v[4:7], v[8:11]
	v_mfma_f32_16x16x32_bf16 v[8:11], v[182:185], v[206:209], v[56:59]
	v_mfma_f32_16x16x32_bf16 v[28:31], v[134:137], v[138:141], v[8:11]
	v_mfma_f32_16x16x32_bf16 v[8:11], v[186:189], v[0:3], v[52:55]
	v_mfma_f32_16x16x32_bf16 v[16:19], v[190:193], v[4:7], v[8:11]
	v_mfma_f32_16x16x32_bf16 v[8:11], v[186:189], v[206:209], v[48:51]
	v_mfma_f32_16x16x32_bf16 v[20:23], v[190:193], v[138:141], v[8:11]
	v_mfma_f32_16x16x32_bf16 v[8:11], v[194:197], v[0:3], v[44:47]
	v_mfma_f32_16x16x32_bf16 v[0:3], v[202:205], v[0:3], v[36:39]
	v_mfma_f32_16x16x32_bf16 v[8:11], v[198:201], v[4:7], v[8:11]
	v_mfma_f32_16x16x32_bf16 v[12:15], v[194:197], v[206:209], v[40:43]
	v_mfma_f32_16x16x32_bf16 v[0:3], v[156:159], v[4:7], v[0:3]
	v_mfma_f32_16x16x32_bf16 v[4:7], v[202:205], v[206:209], v[32:35]
	v_mfma_f32_16x16x32_bf16 v[12:15], v[198:201], v[138:141], v[12:15]
	v_mfma_f32_16x16x32_bf16 v[4:7], v[156:159], v[138:141], v[4:7]
	s_setprio 0
	s_setprio 1
	v_mfma_f32_16x16x32_bf16 v[32:35], v[182:185], v[128:131], v[144:147]
	v_mfma_f32_16x16x32_bf16 v[56:59], v[134:137], v[230:233], v[32:35]
	v_mfma_f32_16x16x32_bf16 v[32:35], v[182:185], v[234:237], v[160:163]
	v_mfma_f32_16x16x32_bf16 v[60:63], v[134:137], v[238:241], v[32:35]
	v_mfma_f32_16x16x32_bf16 v[32:35], v[186:189], v[128:131], v[164:167]
	v_mfma_f32_16x16x32_bf16 v[48:51], v[190:193], v[230:233], v[32:35]
	v_mfma_f32_16x16x32_bf16 v[32:35], v[186:189], v[234:237], v[174:177]
	v_mfma_f32_16x16x32_bf16 v[52:55], v[190:193], v[238:241], v[32:35]
	v_mfma_f32_16x16x32_bf16 v[32:35], v[194:197], v[128:131], v[178:181]
	v_mfma_f32_16x16x32_bf16 v[40:43], v[198:201], v[230:233], v[32:35]
	v_mfma_f32_16x16x32_bf16 v[32:35], v[194:197], v[234:237], v[210:213]
	v_mfma_f32_16x16x32_bf16 v[44:47], v[198:201], v[238:241], v[32:35]
	v_mfma_f32_16x16x32_bf16 v[32:35], v[202:205], v[128:131], v[214:217]
	v_mfma_f32_16x16x32_bf16 v[36:39], v[202:205], v[234:237], v[152:155]
	v_mfma_f32_16x16x32_bf16 v[32:35], v[156:159], v[230:233], v[32:35]
	v_mfma_f32_16x16x32_bf16 v[36:39], v[156:159], v[238:241], v[36:39]
	s_setprio 0
	s_cmpk_gt_u32 s64, 0xff
	s_barrier
	s_cbranch_scc1 .LBB0_1886
	s_barrier
